# GEMM tiles: first K-step MFMAs take C=0, the 128 accumulator-zeroing v_mov per tile head removed (all 11 K-loop sites)
# speedup vs baseline: 1.0073x; 1.0014x over previous
.LBB0_149:
	s_or_b64 exec, exec, s[4:5]
	s_and_b64 s[4:5], exec, s[28:29]
	s_cselect_b32 s4, 0x8000, 0
	s_add_i32 s4, s66, s4
	v_mov_b32_e32 v10, v132
	s_ashr_i32 s5, s4, 31
	s_lshl_b64 s[4:5], s[4:5], 11
	v_lshlrev_b32_e32 v1, 4, v10
	v_and_b32_e32 v0, 32, v10
	v_lshrrev_b32_e32 v2, 1, v10
	v_bitop3_b32 v0, v1, v0, 48 bitop3:0x6c
	s_add_u32 s42, s6, s4
	v_bfe_u32 v11, v10, 2, 4
	v_and_b32_e32 v12, 32, v2
	v_lshrrev_b32_e32 v13, 1, v0
	v_ashrrev_i32_e32 v14, 3, v10
	s_addc_u32 s43, s36, s5
	v_or_b32_e32 v4, v13, v12
	v_and_or_b32 v0, v14, s48, v11
	s_add_u32 s38, s42, 0x2400000
	v_and_b32_e32 v3, 0xfffffc00, v1
	v_lshl_or_b32 v134, v0, 10, v4
	v_add_u32_e32 v0, 0x2000, v1
	v_add_u32_e32 v2, 0x4000, v1
	v_add_u32_e32 v1, 0x6000, v1
	s_addc_u32 s39, s43, 0
	s_ashr_i32 s27, s26, 31
	v_ashrrev_i32_e32 v15, 7, v0
	v_ashrrev_i32_e32 v16, 7, v2
	v_ashrrev_i32_e32 v17, 7, v1
	s_lshl_b64 s[4:5], s[26:27], 19
	v_and_or_b32 v0, v15, s48, v11
	v_and_or_b32 v2, v16, s48, v11
	v_and_or_b32 v1, v17, s48, v11
	v_add_u32_e32 v148, 0, v3
	s_add_u32 s4, s6, s4
	v_lshl_or_b32 v0, v0, 10, v4
	v_lshl_or_b32 v2, v2, 10, v4
	v_lshl_or_b32 v4, v1, 10, v4
	v_add_u32_e32 v1, 0x8000, v148
	v_lshlrev_b64 v[6:7], 1, v[134:135]
	v_readfirstlane_b32 s27, v148
	s_addc_u32 s5, s36, s5
	v_lshl_add_u64 v[8:9], s[38:39], 0, v[6:7]
	s_mov_b32 m0, s27
	v_readfirstlane_b32 s27, v1
	v_mov_b32_e32 v1, v135
	v_add_u32_e32 v3, 0x2000, v148
	global_load_lds_dwordx4 v[8:9], off
	v_lshl_add_u64 v[6:7], s[4:5], 0, v[6:7]
	s_mov_b32 m0, s27
	v_lshlrev_b64 v[0:1], 1, v[0:1]
	v_readfirstlane_b32 s27, v3
	v_add_u32_e32 v3, 0xa000, v148
	global_load_lds_dwordx4 v[6:7], off
	v_lshl_add_u64 v[6:7], s[38:39], 0, v[0:1]
	s_mov_b32 m0, s27
	v_readfirstlane_b32 s27, v3
	global_load_lds_dwordx4 v[6:7], off
	v_lshl_add_u64 v[0:1], s[4:5], 0, v[0:1]
	s_mov_b32 m0, s27
	v_mov_b32_e32 v3, v135
	v_add_u32_e32 v5, 0x4000, v148
	global_load_lds_dwordx4 v[0:1], off
	v_lshlrev_b64 v[0:1], 1, v[2:3]
	v_readfirstlane_b32 s27, v5
	v_lshl_add_u64 v[2:3], s[38:39], 0, v[0:1]
	s_mov_b32 m0, s27
	v_lshl_add_u64 v[0:1], s[4:5], 0, v[0:1]
	global_load_lds_dwordx4 v[2:3], off
	v_add_u32_e32 v2, 0xc000, v148
	v_mov_b32_e32 v5, v135
	v_readfirstlane_b32 s27, v2
	s_mov_b32 m0, s27
	v_lshlrev_b32_e32 v6, 10, v11
	global_load_lds_dwordx4 v[0:1], off
	v_lshlrev_b64 v[0:1], 1, v[4:5]
	v_add_u32_e32 v4, 0x6000, v148
	v_lshl_add_u64 v[2:3], s[38:39], 0, v[0:1]
	v_readfirstlane_b32 s27, v4
	s_mov_b32 m0, s27
	v_lshl_add_u64 v[0:1], s[4:5], 0, v[0:1]
	global_load_lds_dwordx4 v[2:3], off
	v_add_u32_e32 v2, 0xe000, v148
	v_lshlrev_b32_e32 v4, 10, v15
	v_readfirstlane_b32 s27, v2
	s_mov_b32 m0, s27
	v_lshlrev_b32_e32 v2, 2, v10
	global_load_lds_dwordx4 v[0:1], off
	v_and_b32_e32 v0, 15, v10
	v_and_b32_e32 v1, 48, v10
	v_lshlrev_b32_e32 v0, 6, v0
	v_and_b32_e32 v2, 32, v2
	v_bitop3_b32 v149, v0, v2, v1 bitop3:0x36
	v_lshlrev_b32_e32 v0, 7, v10
	v_and_b32_e32 v150, 0x6000, v0
	v_lshlrev_b32_e32 v0, 6, v10
	v_and_b32_e32 v151, 0xffffc000, v0
	v_and_b32_e32 v0, 0x3c0, v0
	v_bitop3_b32 v153, v0, v2, v1 bitop3:0x36
	v_lshlrev_b32_e32 v0, 10, v17
	v_and_or_b32 v0, v0, s49, v13
	v_lshlrev_b32_e32 v2, 10, v16
	v_or3_b32 v134, v0, v6, v12
	v_and_or_b32 v2, v2, s49, v13
	v_lshlrev_b64 v[0:1], 1, v[134:135]
	v_or3_b32 v134, v2, v6, v12
	v_and_or_b32 v4, v4, s49, v13
	v_lshlrev_b32_e32 v7, 10, v14
	v_lshlrev_b64 v[2:3], 1, v[134:135]
	v_or3_b32 v134, v4, v6, v12
	v_and_or_b32 v7, v7, s49, v13
	s_add_u32 s4, s4, 0x80
	v_lshlrev_b64 v[4:5], 1, v[134:135]
	v_or3_b32 v134, v7, v6, v12
	s_addc_u32 s5, s5, 0
	v_lshlrev_b64 v[6:7], 1, v[134:135]
	s_nop 0
	v_lshl_add_u64 v[128:129], s[4:5], 0, v[0:1]
	v_lshl_add_u64 v[130:131], s[4:5], 0, v[2:3]
	v_lshl_add_u64 v[136:137], s[4:5], 0, v[4:5]
	v_lshl_add_u64 v[138:139], s[4:5], 0, v[6:7]
	s_add_u32 s4, s42, 0x2400080
	s_addc_u32 s5, s43, 0
	s_mov_b32 s37, 0
	v_or_b32_e32 v152, 0x800, v151
	v_or_b32_e32 v154, 0x1000, v151
	v_or_b32_e32 v155, 0x1800, v151
	v_or_b32_e32 v156, 0x2000, v151
	v_or_b32_e32 v157, 0x2800, v151
	v_or_b32_e32 v158, 0x3000, v151
	v_or_b32_e32 v159, 0x3800, v151
	v_lshl_add_u64 v[140:141], s[4:5], 0, v[0:1]
	v_lshl_add_u64 v[142:143], s[4:5], 0, v[2:3]
	v_lshl_add_u64 v[144:145], s[4:5], 0, v[4:5]
	v_lshl_add_u64 v[146:147], s[4:5], 0, v[6:7]
	s_mov_b64 s[4:5], 0
	s_waitcnt vmcnt(0) lgkmcnt(0)
	s_barrier
	v_readfirstlane_b32 s100, v148
	s_and_b32 s27, s37, 0x10000
	s_xor_b32 s38, s27, 0x10000
	s_add_i32 s27, s27, 0
	v_add3_u32 v134, s27, v149, v150
	v_add3_u32 v196, s27, v149, v151
	v_add3_u32 v197, s27, v153, v152
	v_add3_u32 v198, s27, v153, v154
	v_add3_u32 v199, s27, v153, v155
	v_add3_u32 v200, s27, v153, v156
	v_add3_u32 v201, s27, v153, v157
	v_add3_u32 v202, s27, v153, v158
	v_add3_u32 v203, s27, v153, v159
	ds_read_b128 v[180:183], v134 offset:32768
	ds_read_b128 v[160:163], v196
	ds_read_b128 v[168:171], v197
	ds_read_b128 v[172:175], v198
	ds_read_b128 v[176:179], v199
	ds_read_b128 v[184:187], v134 offset:34816
	ds_read_b128 v[188:191], v134 offset:36864
	ds_read_b128 v[192:195], v134 offset:38912
	s_add_i32 s101, s100, s38
	v_readfirstlane_b32 s98, v146
	v_readfirstlane_b32 s99, v147
	v_readfirstlane_b32 vcc_lo, v138
	v_readfirstlane_b32 vcc_hi, v139
	s_sub_u32 s98, s98, 0x1000000
	s_subb_u32 s99, s99, 0
	s_sub_u32 vcc_lo, vcc_lo, 0x1000000
	s_subb_u32 vcc_hi, vcc_hi, 0
	v_subrev_u32_e32 v146, s98, v146
	v_subrev_u32_e32 v138, vcc_lo, v138
	v_subrev_u32_e32 v144, s98, v144
	v_subrev_u32_e32 v136, vcc_lo, v136
	v_subrev_u32_e32 v142, s98, v142
	v_subrev_u32_e32 v130, vcc_lo, v130
	v_subrev_u32_e32 v140, s98, v140
	v_subrev_u32_e32 v128, vcc_lo, v128
	s_mov_b32 m0, s101
	s_nop 0
	global_load_lds_dwordx4 v146, s[98:99]
	s_add_i32 m0, s101, 0x8000
	s_nop 0
	global_load_lds_dwordx4 v138, vcc
	s_add_i32 m0, s101, 0x2000
	s_nop 0
	global_load_lds_dwordx4 v144, s[98:99]
	s_add_i32 m0, s101, 0xa000
	s_nop 0
	global_load_lds_dwordx4 v136, vcc
	s_add_i32 m0, s101, 0x4000
	s_nop 0
	global_load_lds_dwordx4 v142, s[98:99]
	s_add_i32 m0, s101, 0xc000
	s_nop 0
	global_load_lds_dwordx4 v130, vcc
	s_add_i32 m0, s101, 0x6000
	s_nop 0
	global_load_lds_dwordx4 v140, s[98:99]
	s_add_i32 m0, s101, 0xe000
	s_nop 0
	global_load_lds_dwordx4 v128, vcc

.Lg2b_150:
	s_waitcnt lgkmcnt(3)
	v_mfma_f32_16x16x32_bf16 v[124:127], v[160:163], v[180:183], v[124:127]
	v_mfma_f32_16x16x32_bf16 v[108:111], v[168:171], v[180:183], v[108:111]
	v_mfma_f32_16x16x32_bf16 v[92:95], v[172:175], v[180:183], v[92:95]
	v_mfma_f32_16x16x32_bf16 v[76:79], v[176:179], v[180:183], v[76:79]
	ds_read_b128 v[240:243], v200 offset:1024
	ds_read_b128 v[244:247], v201 offset:1024
	s_waitcnt lgkmcnt(4)
	v_mfma_f32_16x16x32_bf16 v[120:123], v[160:163], v[184:187], v[120:123]
	v_mfma_f32_16x16x32_bf16 v[104:107], v[168:171], v[184:187], v[104:107]
	v_mfma_f32_16x16x32_bf16 v[88:91], v[172:175], v[184:187], v[88:91]
	v_mfma_f32_16x16x32_bf16 v[72:75], v[176:179], v[184:187], v[72:75]
	ds_read_b128 v[248:251], v202 offset:1024
	ds_read_b128 v[252:255], v203 offset:1024
	s_waitcnt lgkmcnt(5)
	v_mfma_f32_16x16x32_bf16 v[116:119], v[160:163], v[188:191], v[116:119]
	v_mfma_f32_16x16x32_bf16 v[100:103], v[168:171], v[188:191], v[100:103]
	v_mfma_f32_16x16x32_bf16 v[84:87], v[172:175], v[188:191], v[84:87]
	v_mfma_f32_16x16x32_bf16 v[68:71], v[176:179], v[188:191], v[68:71]
	s_waitcnt lgkmcnt(4)
	v_mfma_f32_16x16x32_bf16 v[112:115], v[160:163], v[192:195], v[112:115]
	v_mfma_f32_16x16x32_bf16 v[96:99], v[168:171], v[192:195], v[96:99]
	v_mfma_f32_16x16x32_bf16 v[80:83], v[172:175], v[192:195], v[80:83]
	v_mfma_f32_16x16x32_bf16 v[64:67], v[176:179], v[192:195], v[64:67]
	s_add_i32 s101, s100, s27
	s_cmpk_eq_i32 s4, 0x700
	s_cbranch_scc1 .Lg4n_150
	s_waitcnt vmcnt(0) lgkmcnt(0)
	s_barrier
	s_add_u32 s98, s98, 0x80
	s_addc_u32 s99, s99, 0
	s_add_u32 vcc_lo, vcc_lo, 0x80
	s_addc_u32 vcc_hi, vcc_hi, 0
	v_mfma_f32_16x16x32_bf16 v[60:63], v[240:243], v[180:183], v[60:63]
	v_mfma_f32_16x16x32_bf16 v[44:47], v[244:247], v[180:183], v[44:47]
	v_mfma_f32_16x16x32_bf16 v[16:19], v[248:251], v[180:183], v[16:19]
	v_mfma_f32_16x16x32_bf16 v[36:39], v[252:255], v[180:183], v[36:39]
	v_add3_u32 v134, s38, v149, v150
	ds_read_b128 v[180:183], v134 offset:32768
	v_add3_u32 v196, s38, v149, v151
	v_add3_u32 v197, s38, v153, v152
	v_add3_u32 v198, s38, v153, v154
	v_add3_u32 v199, s38, v153, v155
	ds_read_b128 v[160:163], v196
	ds_read_b128 v[168:171], v197
	ds_read_b128 v[172:175], v198
	ds_read_b128 v[176:179], v199
	s_mov_b32 m0, s101
	s_nop 0
	global_load_lds_dwordx4 v146, s[98:99]
	v_mfma_f32_16x16x32_bf16 v[56:59], v[240:243], v[184:187], v[56:59]
	v_mfma_f32_16x16x32_bf16 v[40:43], v[244:247], v[184:187], v[40:43]
	v_mfma_f32_16x16x32_bf16 v[12:15], v[248:251], v[184:187], v[12:15]
	v_mfma_f32_16x16x32_bf16 v[28:31], v[252:255], v[184:187], v[28:31]
	ds_read_b128 v[184:187], v134 offset:34816
	v_add3_u32 v200, s38, v153, v156
	v_add3_u32 v201, s38, v153, v157
	v_add3_u32 v202, s38, v153, v158
	v_add3_u32 v203, s38, v153, v159
	s_add_i32 m0, s101, 0x8000
	s_nop 0
	global_load_lds_dwordx4 v138, vcc
	v_mfma_f32_16x16x32_bf16 v[52:55], v[240:243], v[188:191], v[52:55]
	v_mfma_f32_16x16x32_bf16 v[32:35], v[244:247], v[188:191], v[32:35]
	v_mfma_f32_16x16x32_bf16 v[4:7], v[248:251], v[188:191], v[4:7]
	v_mfma_f32_16x16x32_bf16 v[20:23], v[252:255], v[188:191], v[20:23]
	ds_read_b128 v[188:191], v134 offset:36864
	s_add_i32 m0, s101, 0x2000
	s_nop 0
	global_load_lds_dwordx4 v144, s[98:99]
	v_mfma_f32_16x16x32_bf16 v[48:51], v[240:243], v[192:195], v[48:51]
	v_mfma_f32_16x16x32_bf16 v[24:27], v[244:247], v[192:195], v[24:27]
	v_mfma_f32_16x16x32_bf16 v[0:3], v[248:251], v[192:195], v[0:3]
	v_mfma_f32_16x16x32_bf16 v[8:11], v[252:255], v[192:195], v[8:11]
	ds_read_b128 v[192:195], v134 offset:38912
	s_add_i32 m0, s101, 0xa000
	s_nop 0
	global_load_lds_dwordx4 v136, vcc

.Lg1n_150:
	s_waitcnt lgkmcnt(3)
	v_mfma_f32_16x16x32_bf16 v[124:127], v[160:163], v[180:183], 0
	v_mfma_f32_16x16x32_bf16 v[108:111], v[168:171], v[180:183], 0
	v_mfma_f32_16x16x32_bf16 v[92:95], v[172:175], v[180:183], 0
	v_mfma_f32_16x16x32_bf16 v[76:79], v[176:179], v[180:183], 0
	ds_read_b128 v[240:243], v200
	ds_read_b128 v[244:247], v201
	s_waitcnt lgkmcnt(4)
	v_mfma_f32_16x16x32_bf16 v[120:123], v[160:163], v[184:187], 0
	v_mfma_f32_16x16x32_bf16 v[104:107], v[168:171], v[184:187], 0
	v_mfma_f32_16x16x32_bf16 v[88:91], v[172:175], v[184:187], 0
	v_mfma_f32_16x16x32_bf16 v[72:75], v[176:179], v[184:187], 0
	ds_read_b128 v[248:251], v202
	ds_read_b128 v[252:255], v203
	s_waitcnt lgkmcnt(5)
	v_mfma_f32_16x16x32_bf16 v[116:119], v[160:163], v[188:191], 0
	v_mfma_f32_16x16x32_bf16 v[100:103], v[168:171], v[188:191], 0
	v_mfma_f32_16x16x32_bf16 v[84:87], v[172:175], v[188:191], 0
	v_mfma_f32_16x16x32_bf16 v[68:71], v[176:179], v[188:191], 0
	s_waitcnt lgkmcnt(4)
	v_mfma_f32_16x16x32_bf16 v[112:115], v[160:163], v[192:195], 0
	v_mfma_f32_16x16x32_bf16 v[96:99], v[168:171], v[192:195], 0
	v_mfma_f32_16x16x32_bf16 v[80:83], v[172:175], v[192:195], 0
	v_mfma_f32_16x16x32_bf16 v[64:67], v[176:179], v[192:195], 0
	ds_read_b128 v[160:163], v196 offset:1024
	ds_read_b128 v[168:171], v197 offset:1024
	ds_read_b128 v[172:175], v198 offset:1024
	ds_read_b128 v[176:179], v199 offset:1024
	s_waitcnt lgkmcnt(4)
	v_mfma_f32_16x16x32_bf16 v[60:63], v[240:243], v[180:183], 0
	v_mfma_f32_16x16x32_bf16 v[44:47], v[244:247], v[180:183], 0
	v_mfma_f32_16x16x32_bf16 v[16:19], v[248:251], v[180:183], 0
	v_mfma_f32_16x16x32_bf16 v[36:39], v[252:255], v[180:183], 0
	ds_read_b128 v[180:183], v134 offset:33792
	v_mfma_f32_16x16x32_bf16 v[56:59], v[240:243], v[184:187], 0
	v_mfma_f32_16x16x32_bf16 v[40:43], v[244:247], v[184:187], 0
	v_mfma_f32_16x16x32_bf16 v[12:15], v[248:251], v[184:187], 0
	v_mfma_f32_16x16x32_bf16 v[28:31], v[252:255], v[184:187], 0
	ds_read_b128 v[184:187], v134 offset:35840
	v_mfma_f32_16x16x32_bf16 v[52:55], v[240:243], v[188:191], 0
	v_mfma_f32_16x16x32_bf16 v[32:35], v[244:247], v[188:191], 0
	v_mfma_f32_16x16x32_bf16 v[4:7], v[248:251], v[188:191], 0
	v_mfma_f32_16x16x32_bf16 v[20:23], v[252:255], v[188:191], 0
	ds_read_b128 v[188:191], v134 offset:37888
	v_mfma_f32_16x16x32_bf16 v[48:51], v[240:243], v[192:195], 0
	v_mfma_f32_16x16x32_bf16 v[24:27], v[244:247], v[192:195], 0
	v_mfma_f32_16x16x32_bf16 v[0:3], v[248:251], v[192:195], 0
	v_mfma_f32_16x16x32_bf16 v[8:11], v[252:255], v[192:195], 0
	ds_read_b128 v[192:195], v134 offset:39936
	s_branch .Lg2b_150

.LBB0_163:
	s_cmp_lg_u32 s67, 5
	s_cselect_b64 s[4:5], -1, 0
	s_and_b32 s6, s26, -10
	s_cmp_lg_u32 s6, 4
	s_cselect_b64 s[30:31], -1, 0
	v_mov_b32_e32 v0, s19
	s_and_b64 s[34:35], s[30:31], s[4:5]
	ds_read_b64 v[0:1], v0
	s_and_b64 s[4:5], exec, s[28:29]
	s_cselect_b32 s4, 0x8000, 0
	s_add_i32 s4, s66, s4
	s_ashr_i32 s5, s4, 31
	s_lshl_b64 s[4:5], s[4:5], 11
	s_waitcnt lgkmcnt(0)
	v_readfirstlane_b32 s38, v0
	v_readfirstlane_b32 s39, v1
	v_lshl_add_u64 v[0:1], v[0:1], 0, s[4:5]
	v_lshl_add_u64 v[128:129], v[0:1], 0, s[8:9]
	s_mov_b64 s[30:31], -1
	s_and_b64 vcc, exec, s[34:35]
	s_cbranch_vccz .LBB0_175
	v_mov_b32_e32 v10, v132
	s_ashr_i32 s27, s26, 31
	v_lshlrev_b32_e32 v1, 4, v10
	v_and_b32_e32 v0, 32, v10
	v_lshrrev_b32_e32 v2, 1, v10
	v_bitop3_b32 v0, v1, v0, 48 bitop3:0x6c
	v_bfe_u32 v11, v10, 2, 4
	v_and_b32_e32 v12, 32, v2
	v_lshrrev_b32_e32 v13, 1, v0
	v_ashrrev_i32_e32 v14, 3, v10
	v_or_b32_e32 v4, v13, v12
	v_and_or_b32 v0, v14, s48, v11
	v_and_b32_e32 v3, 0xfffffc00, v1
	v_lshl_or_b32 v134, v0, 10, v4
	v_add_u32_e32 v0, 0x2000, v1
	v_add_u32_e32 v2, 0x4000, v1
	v_add_u32_e32 v1, 0x6000, v1
	v_ashrrev_i32_e32 v15, 7, v0
	v_ashrrev_i32_e32 v16, 7, v2
	v_ashrrev_i32_e32 v17, 7, v1
	s_lshl_b64 s[30:31], s[26:27], 19
	v_and_or_b32 v0, v15, s48, v11
	v_and_or_b32 v2, v16, s48, v11
	v_and_or_b32 v1, v17, s48, v11
	v_add_u32_e32 v150, 0, v3
	s_add_u32 s30, s38, s30
	v_lshl_or_b32 v0, v0, 10, v4
	v_lshl_or_b32 v2, v2, 10, v4
	v_lshl_or_b32 v4, v1, 10, v4
	v_add_u32_e32 v1, 0x8000, v150
	v_lshlrev_b64 v[6:7], 1, v[134:135]
	v_readfirstlane_b32 s6, v150
	s_addc_u32 s31, s39, s31
	v_lshl_add_u64 v[8:9], v[128:129], 0, v[6:7]
	s_mov_b32 m0, s6
	v_readfirstlane_b32 s6, v1
	v_mov_b32_e32 v1, v135
	v_add_u32_e32 v3, 0x2000, v150
	global_load_lds_dwordx4 v[8:9], off
	v_lshl_add_u64 v[6:7], s[30:31], 0, v[6:7]
	s_mov_b32 m0, s6
	v_lshlrev_b64 v[0:1], 1, v[0:1]
	v_readfirstlane_b32 s6, v3
	v_add_u32_e32 v3, 0xa000, v150
	global_load_lds_dwordx4 v[6:7], off
	v_lshl_add_u64 v[6:7], v[128:129], 0, v[0:1]
	s_mov_b32 m0, s6
	v_readfirstlane_b32 s6, v3
	global_load_lds_dwordx4 v[6:7], off
	v_lshl_add_u64 v[0:1], s[30:31], 0, v[0:1]
	s_mov_b32 m0, s6
	v_mov_b32_e32 v3, v135
	v_add_u32_e32 v5, 0x4000, v150
	global_load_lds_dwordx4 v[0:1], off
	v_lshlrev_b64 v[0:1], 1, v[2:3]
	v_readfirstlane_b32 s6, v5
	v_lshl_add_u64 v[2:3], v[128:129], 0, v[0:1]
	s_mov_b32 m0, s6
	v_lshl_add_u64 v[0:1], s[30:31], 0, v[0:1]
	global_load_lds_dwordx4 v[2:3], off
	v_add_u32_e32 v2, 0xc000, v150
	v_mov_b32_e32 v5, v135
	v_readfirstlane_b32 s6, v2
	s_mov_b32 m0, s6
	v_and_b32_e32 v18, 15, v10
	global_load_lds_dwordx4 v[0:1], off
	v_lshlrev_b64 v[0:1], 1, v[4:5]
	v_add_u32_e32 v4, 0x6000, v150
	v_lshl_add_u64 v[2:3], v[128:129], 0, v[0:1]
	v_readfirstlane_b32 s6, v4
	s_mov_b32 m0, s6
	v_lshl_add_u64 v[0:1], s[30:31], 0, v[0:1]
	global_load_lds_dwordx4 v[2:3], off
	v_add_u32_e32 v2, 0xe000, v150
	v_lshlrev_b32_e32 v6, 10, v11
	v_readfirstlane_b32 s6, v2
	s_mov_b32 m0, s6
	v_lshlrev_b32_e32 v2, 2, v10
	global_load_lds_dwordx4 v[0:1], off
	v_and_b32_e32 v0, 48, v10
	v_lshlrev_b32_e32 v1, 6, v18
	v_and_b32_e32 v2, 32, v2
	v_bitop3_b32 v151, v1, v2, v0 bitop3:0x36
	v_lshlrev_b32_e32 v1, 7, v10
	v_and_b32_e32 v152, 0x6000, v1
	v_lshlrev_b32_e32 v1, 6, v10
	v_and_b32_e32 v153, 0xffffc000, v1
	v_and_b32_e32 v1, 0x3c0, v1
	v_bitop3_b32 v155, v1, v2, v0 bitop3:0x36
	v_lshlrev_b32_e32 v0, 10, v17
	v_and_or_b32 v0, v0, s49, v13
	v_lshlrev_b32_e32 v2, 10, v16
	v_or3_b32 v134, v0, v6, v12
	v_and_or_b32 v2, v2, s49, v13
	v_lshlrev_b32_e32 v4, 10, v15
	v_lshlrev_b64 v[0:1], 1, v[134:135]
	s_add_u32 s30, s30, 0x80
	v_or3_b32 v134, v2, v6, v12
	v_and_or_b32 v4, v4, s49, v13
	v_lshlrev_b32_e32 v7, 10, v14
	s_addc_u32 s31, s31, 0
	v_lshlrev_b64 v[2:3], 1, v[134:135]
	v_or3_b32 v134, v4, v6, v12
	v_and_or_b32 v7, v7, s49, v13
	v_lshlrev_b64 v[4:5], 1, v[134:135]
	v_or3_b32 v134, v7, v6, v12
	s_add_u32 s6, s38, s4
	v_lshlrev_b64 v[6:7], 1, v[134:135]
	s_addc_u32 s27, s39, s5
	v_lshl_add_u64 v[130:131], s[30:31], 0, v[0:1]
	v_lshl_add_u64 v[136:137], s[30:31], 0, v[2:3]
	v_lshl_add_u64 v[138:139], s[30:31], 0, v[4:5]
	v_lshl_add_u64 v[140:141], s[30:31], 0, v[6:7]
	s_add_u32 s30, s6, 0x2400080
	s_nop 0
	s_addc_u32 s31, s27, 0
	v_lshl_add_u64 v[142:143], s[30:31], 0, v[0:1]
	v_or_b32_e32 v154, 0x800, v153
	v_or_b32_e32 v156, 0x1000, v153
	v_or_b32_e32 v157, 0x1800, v153
	v_or_b32_e32 v158, 0x2000, v153
	v_or_b32_e32 v159, 0x2800, v153
	v_or_b32_e32 v160, 0x3000, v153
	v_or_b32_e32 v161, 0x3800, v153
	v_lshl_add_u64 v[144:145], s[30:31], 0, v[2:3]
	v_lshl_add_u64 v[146:147], s[30:31], 0, v[4:5]
	v_lshl_add_u64 v[148:149], s[30:31], 0, v[6:7]
	s_mov_b32 s6, 0
	s_mov_b64 s[30:31], 0
	s_waitcnt vmcnt(0) lgkmcnt(0)
	s_barrier
	v_readfirstlane_b32 s100, v150
	s_and_b32 s27, s6, 0x10000
	s_xor_b32 s34, s27, 0x10000
	s_add_i32 s27, s27, 0
	v_add3_u32 v134, s27, v151, v152
	v_add3_u32 v162, s27, v151, v153
	v_add3_u32 v163, s27, v155, v154
	v_add3_u32 v200, s27, v155, v156
	v_add3_u32 v201, s27, v155, v157
	v_add3_u32 v202, s27, v155, v158
	v_add3_u32 v203, s27, v155, v159
	v_add3_u32 v204, s27, v155, v160
	v_add3_u32 v205, s27, v155, v161
	ds_read_b128 v[184:187], v134 offset:32768
	ds_read_b128 v[168:171], v162
	ds_read_b128 v[172:175], v163
	ds_read_b128 v[176:179], v200
	ds_read_b128 v[180:183], v201
	ds_read_b128 v[188:191], v134 offset:34816
	ds_read_b128 v[192:195], v134 offset:36864
	ds_read_b128 v[196:199], v134 offset:38912
	s_add_i32 s101, s100, s34
	v_readfirstlane_b32 s98, v148
	v_readfirstlane_b32 s99, v149
	v_readfirstlane_b32 vcc_lo, v140
	v_readfirstlane_b32 vcc_hi, v141
	s_sub_u32 s98, s98, 0x1000000
	s_subb_u32 s99, s99, 0
	s_sub_u32 vcc_lo, vcc_lo, 0x1000000
	s_subb_u32 vcc_hi, vcc_hi, 0
	v_subrev_u32_e32 v148, s98, v148
	v_subrev_u32_e32 v140, vcc_lo, v140
	v_subrev_u32_e32 v146, s98, v146
	v_subrev_u32_e32 v138, vcc_lo, v138
	v_subrev_u32_e32 v144, s98, v144
	v_subrev_u32_e32 v136, vcc_lo, v136
	v_subrev_u32_e32 v142, s98, v142
	v_subrev_u32_e32 v130, vcc_lo, v130
	s_mov_b32 m0, s101
	s_nop 0
	global_load_lds_dwordx4 v148, s[98:99]
	s_add_i32 m0, s101, 0x8000
	s_nop 0
	global_load_lds_dwordx4 v140, vcc
	s_add_i32 m0, s101, 0x2000
	s_nop 0
	global_load_lds_dwordx4 v146, s[98:99]
	s_add_i32 m0, s101, 0xa000
	s_nop 0
	global_load_lds_dwordx4 v138, vcc
	s_add_i32 m0, s101, 0x4000
	s_nop 0
	global_load_lds_dwordx4 v144, s[98:99]
	s_add_i32 m0, s101, 0xc000
	s_nop 0
	global_load_lds_dwordx4 v136, vcc
	s_add_i32 m0, s101, 0x6000
	s_nop 0
	global_load_lds_dwordx4 v142, s[98:99]
	s_add_i32 m0, s101, 0xe000
	s_nop 0
	global_load_lds_dwordx4 v130, vcc

.Lg2b_165:
	s_waitcnt lgkmcnt(3)
	v_mfma_f32_16x16x32_bf16 v[108:111], v[184:187], v[168:171], v[108:111]
	v_mfma_f32_16x16x32_bf16 v[92:95], v[184:187], v[172:175], v[92:95]
	v_mfma_f32_16x16x32_bf16 v[76:79], v[184:187], v[176:179], v[76:79]
	v_mfma_f32_16x16x32_bf16 v[60:63], v[184:187], v[180:183], v[60:63]
	ds_read_b128 v[240:243], v202 offset:1024
	ds_read_b128 v[244:247], v203 offset:1024
	s_waitcnt lgkmcnt(4)
	v_mfma_f32_16x16x32_bf16 v[104:107], v[188:191], v[168:171], v[104:107]
	v_mfma_f32_16x16x32_bf16 v[88:91], v[188:191], v[172:175], v[88:91]
	v_mfma_f32_16x16x32_bf16 v[72:75], v[188:191], v[176:179], v[72:75]
	v_mfma_f32_16x16x32_bf16 v[56:59], v[188:191], v[180:183], v[56:59]
	ds_read_b128 v[248:251], v204 offset:1024
	ds_read_b128 v[252:255], v205 offset:1024
	s_waitcnt lgkmcnt(5)
	v_mfma_f32_16x16x32_bf16 v[100:103], v[192:195], v[168:171], v[100:103]
	v_mfma_f32_16x16x32_bf16 v[84:87], v[192:195], v[172:175], v[84:87]
	v_mfma_f32_16x16x32_bf16 v[68:71], v[192:195], v[176:179], v[68:71]
	v_mfma_f32_16x16x32_bf16 v[52:55], v[192:195], v[180:183], v[52:55]
	s_waitcnt lgkmcnt(4)
	v_mfma_f32_16x16x32_bf16 v[96:99], v[196:199], v[168:171], v[96:99]
	v_mfma_f32_16x16x32_bf16 v[80:83], v[196:199], v[172:175], v[80:83]
	v_mfma_f32_16x16x32_bf16 v[64:67], v[196:199], v[176:179], v[64:67]
	v_mfma_f32_16x16x32_bf16 v[48:51], v[196:199], v[180:183], v[48:51]
	s_add_i32 s101, s100, s27
	s_cmpk_eq_i32 s30, 0x700
	s_cbranch_scc1 .Lg4n_165
	s_waitcnt vmcnt(0) lgkmcnt(0)
	s_barrier
	s_add_u32 s98, s98, 0x80
	s_addc_u32 s99, s99, 0
	s_add_u32 vcc_lo, vcc_lo, 0x80
	s_addc_u32 vcc_hi, vcc_hi, 0
	v_mfma_f32_16x16x32_bf16 v[44:47], v[184:187], v[240:243], v[44:47]
	v_mfma_f32_16x16x32_bf16 v[28:31], v[184:187], v[244:247], v[28:31]
	v_mfma_f32_16x16x32_bf16 v[12:15], v[184:187], v[248:251], v[12:15]
	v_mfma_f32_16x16x32_bf16 v[112:115], v[184:187], v[252:255], v[112:115]
	v_add3_u32 v134, s34, v151, v152
	ds_read_b128 v[184:187], v134 offset:32768
	v_add3_u32 v162, s34, v151, v153
	v_add3_u32 v163, s34, v155, v154
	v_add3_u32 v200, s34, v155, v156
	v_add3_u32 v201, s34, v155, v157
	ds_read_b128 v[168:171], v162
	ds_read_b128 v[172:175], v163
	ds_read_b128 v[176:179], v200
	ds_read_b128 v[180:183], v201
	s_mov_b32 m0, s101
	s_nop 0
	global_load_lds_dwordx4 v148, s[98:99]
	v_mfma_f32_16x16x32_bf16 v[40:43], v[188:191], v[240:243], v[40:43]
	v_mfma_f32_16x16x32_bf16 v[24:27], v[188:191], v[244:247], v[24:27]
	v_mfma_f32_16x16x32_bf16 v[8:11], v[188:191], v[248:251], v[8:11]
	v_mfma_f32_16x16x32_bf16 v[116:119], v[188:191], v[252:255], v[116:119]
	ds_read_b128 v[188:191], v134 offset:34816
	v_add3_u32 v202, s34, v155, v158
	v_add3_u32 v203, s34, v155, v159
	v_add3_u32 v204, s34, v155, v160
	v_add3_u32 v205, s34, v155, v161
	s_add_i32 m0, s101, 0x8000
	s_nop 0
	global_load_lds_dwordx4 v140, vcc
	v_mfma_f32_16x16x32_bf16 v[36:39], v[192:195], v[240:243], v[36:39]
	v_mfma_f32_16x16x32_bf16 v[20:23], v[192:195], v[244:247], v[20:23]
	v_mfma_f32_16x16x32_bf16 v[4:7], v[192:195], v[248:251], v[4:7]
	v_mfma_f32_16x16x32_bf16 v[120:123], v[192:195], v[252:255], v[120:123]
	ds_read_b128 v[192:195], v134 offset:36864
	s_add_i32 m0, s101, 0x2000
	s_nop 0
	global_load_lds_dwordx4 v146, s[98:99]
	v_mfma_f32_16x16x32_bf16 v[32:35], v[196:199], v[240:243], v[32:35]
	v_mfma_f32_16x16x32_bf16 v[16:19], v[196:199], v[244:247], v[16:19]
	v_mfma_f32_16x16x32_bf16 v[0:3], v[196:199], v[248:251], v[0:3]
	v_mfma_f32_16x16x32_bf16 v[124:127], v[196:199], v[252:255], v[124:127]
	ds_read_b128 v[196:199], v134 offset:38912
	s_add_i32 m0, s101, 0xa000
	s_nop 0
	global_load_lds_dwordx4 v138, vcc

.Lg1n_165:
	s_waitcnt lgkmcnt(3)
	v_mfma_f32_16x16x32_bf16 v[108:111], v[184:187], v[168:171], 0
	v_mfma_f32_16x16x32_bf16 v[92:95], v[184:187], v[172:175], 0
	v_mfma_f32_16x16x32_bf16 v[76:79], v[184:187], v[176:179], 0
	v_mfma_f32_16x16x32_bf16 v[60:63], v[184:187], v[180:183], 0
	ds_read_b128 v[240:243], v202
	ds_read_b128 v[244:247], v203
	s_waitcnt lgkmcnt(4)
	v_mfma_f32_16x16x32_bf16 v[104:107], v[188:191], v[168:171], 0
	v_mfma_f32_16x16x32_bf16 v[88:91], v[188:191], v[172:175], 0
	v_mfma_f32_16x16x32_bf16 v[72:75], v[188:191], v[176:179], 0
	v_mfma_f32_16x16x32_bf16 v[56:59], v[188:191], v[180:183], 0
	ds_read_b128 v[248:251], v204
	ds_read_b128 v[252:255], v205
	s_waitcnt lgkmcnt(5)
	v_mfma_f32_16x16x32_bf16 v[100:103], v[192:195], v[168:171], 0
	v_mfma_f32_16x16x32_bf16 v[84:87], v[192:195], v[172:175], 0
	v_mfma_f32_16x16x32_bf16 v[68:71], v[192:195], v[176:179], 0
	v_mfma_f32_16x16x32_bf16 v[52:55], v[192:195], v[180:183], 0
	s_waitcnt lgkmcnt(4)
	v_mfma_f32_16x16x32_bf16 v[96:99], v[196:199], v[168:171], 0
	v_mfma_f32_16x16x32_bf16 v[80:83], v[196:199], v[172:175], 0
	v_mfma_f32_16x16x32_bf16 v[64:67], v[196:199], v[176:179], 0
	v_mfma_f32_16x16x32_bf16 v[48:51], v[196:199], v[180:183], 0
	ds_read_b128 v[168:171], v162 offset:1024
	ds_read_b128 v[172:175], v163 offset:1024
	ds_read_b128 v[176:179], v200 offset:1024
	ds_read_b128 v[180:183], v201 offset:1024
	s_waitcnt lgkmcnt(4)
	v_mfma_f32_16x16x32_bf16 v[44:47], v[184:187], v[240:243], 0
	v_mfma_f32_16x16x32_bf16 v[28:31], v[184:187], v[244:247], 0
	v_mfma_f32_16x16x32_bf16 v[12:15], v[184:187], v[248:251], 0
	v_mfma_f32_16x16x32_bf16 v[112:115], v[184:187], v[252:255], 0
	ds_read_b128 v[184:187], v134 offset:33792
	v_mfma_f32_16x16x32_bf16 v[40:43], v[188:191], v[240:243], 0
	v_mfma_f32_16x16x32_bf16 v[24:27], v[188:191], v[244:247], 0
	v_mfma_f32_16x16x32_bf16 v[8:11], v[188:191], v[248:251], 0
	v_mfma_f32_16x16x32_bf16 v[116:119], v[188:191], v[252:255], 0
	ds_read_b128 v[188:191], v134 offset:35840
	v_mfma_f32_16x16x32_bf16 v[36:39], v[192:195], v[240:243], 0
	v_mfma_f32_16x16x32_bf16 v[20:23], v[192:195], v[244:247], 0
	v_mfma_f32_16x16x32_bf16 v[4:7], v[192:195], v[248:251], 0
	v_mfma_f32_16x16x32_bf16 v[120:123], v[192:195], v[252:255], 0
	ds_read_b128 v[192:195], v134 offset:37888
	v_mfma_f32_16x16x32_bf16 v[32:35], v[196:199], v[240:243], 0
	v_mfma_f32_16x16x32_bf16 v[16:19], v[196:199], v[244:247], 0
	v_mfma_f32_16x16x32_bf16 v[0:3], v[196:199], v[248:251], 0
	v_mfma_f32_16x16x32_bf16 v[124:127], v[196:199], v[252:255], 0
	ds_read_b128 v[196:199], v134 offset:39936
	s_branch .Lg2b_165

.LBB0_175:
	s_and_b64 vcc, exec, s[30:31]
	s_cbranch_vccz .LBB0_179
	v_mov_b32_e32 v10, v132
	s_lshl_b32 s6, s26, 19
	v_lshlrev_b32_e32 v1, 4, v10
	v_and_b32_e32 v0, 32, v10
	v_lshrrev_b32_e32 v2, 1, v10
	v_bitop3_b32 v0, v1, v0, 48 bitop3:0x6c
	v_bfe_u32 v11, v10, 2, 4
	v_and_b32_e32 v12, 32, v2
	v_lshrrev_b32_e32 v13, 1, v0
	v_ashrrev_i32_e32 v14, 3, v10
	v_or_b32_e32 v4, v13, v12
	v_and_or_b32 v0, v14, s48, v11
	v_and_b32_e32 v3, 0xfffffc00, v1
	v_lshl_or_b32 v134, v0, 10, v4
	v_add_u32_e32 v0, 0x2000, v1
	v_add_u32_e32 v2, 0x4000, v1
	v_add_u32_e32 v1, 0x6000, v1
	v_ashrrev_i32_e32 v15, 7, v0
	v_ashrrev_i32_e32 v16, 7, v2
	v_ashrrev_i32_e32 v17, 7, v1
	v_and_or_b32 v0, v15, s48, v11
	v_and_or_b32 v2, v16, s48, v11
	v_and_or_b32 v1, v17, s48, v11
	v_add_u32_e32 v148, 0, v3
	s_add_u32 s30, s38, s6
	v_lshl_or_b32 v0, v0, 10, v4
	v_lshl_or_b32 v2, v2, 10, v4
	v_lshl_or_b32 v4, v1, 10, v4
	v_add_u32_e32 v1, 0x8000, v148
	v_lshlrev_b64 v[6:7], 1, v[134:135]
	v_readfirstlane_b32 s6, v148
	s_addc_u32 s31, s39, 0
	v_lshl_add_u64 v[8:9], v[128:129], 0, v[6:7]
	s_mov_b32 m0, s6
	v_readfirstlane_b32 s6, v1
	v_mov_b32_e32 v1, v135
	v_add_u32_e32 v3, 0x2000, v148
	global_load_lds_dwordx4 v[8:9], off
	v_lshl_add_u64 v[6:7], s[30:31], 0, v[6:7]
	s_mov_b32 m0, s6
	v_lshlrev_b64 v[0:1], 1, v[0:1]
	v_readfirstlane_b32 s6, v3
	v_add_u32_e32 v3, 0xa000, v148
	global_load_lds_dwordx4 v[6:7], off
	v_lshl_add_u64 v[6:7], v[128:129], 0, v[0:1]
	s_mov_b32 m0, s6
	v_readfirstlane_b32 s6, v3
	global_load_lds_dwordx4 v[6:7], off
	v_lshl_add_u64 v[0:1], s[30:31], 0, v[0:1]
	s_mov_b32 m0, s6
	v_mov_b32_e32 v3, v135
	v_add_u32_e32 v5, 0x4000, v148
	global_load_lds_dwordx4 v[0:1], off
	v_lshlrev_b64 v[0:1], 1, v[2:3]
	v_readfirstlane_b32 s6, v5
	v_lshl_add_u64 v[2:3], v[128:129], 0, v[0:1]
	s_mov_b32 m0, s6
	v_lshl_add_u64 v[0:1], s[30:31], 0, v[0:1]
	global_load_lds_dwordx4 v[2:3], off
	v_add_u32_e32 v2, 0xc000, v148
	v_mov_b32_e32 v5, v135
	v_readfirstlane_b32 s6, v2
	s_mov_b32 m0, s6
	v_lshlrev_b32_e32 v6, 10, v11
	global_load_lds_dwordx4 v[0:1], off
	v_lshlrev_b64 v[0:1], 1, v[4:5]
	v_add_u32_e32 v4, 0x6000, v148
	v_lshl_add_u64 v[2:3], v[128:129], 0, v[0:1]
	v_readfirstlane_b32 s6, v4
	s_mov_b32 m0, s6
	v_lshl_add_u64 v[0:1], s[30:31], 0, v[0:1]
	global_load_lds_dwordx4 v[2:3], off
	v_add_u32_e32 v2, 0xe000, v148
	s_add_u32 s30, s30, 0x80
	v_readfirstlane_b32 s6, v2
	s_mov_b32 m0, s6
	v_lshlrev_b32_e32 v2, 2, v10
	global_load_lds_dwordx4 v[0:1], off
	v_and_b32_e32 v0, 15, v10
	v_and_b32_e32 v1, 48, v10
	v_lshlrev_b32_e32 v0, 6, v0
	v_and_b32_e32 v2, 32, v2
	v_bitop3_b32 v149, v0, v2, v1 bitop3:0x36
	v_lshlrev_b32_e32 v0, 7, v10
	v_and_b32_e32 v150, 0x6000, v0
	v_lshlrev_b32_e32 v0, 6, v10
	v_and_b32_e32 v151, 0xffffc000, v0
	v_and_b32_e32 v0, 0x3c0, v0
	v_bitop3_b32 v153, v0, v2, v1 bitop3:0x36
	v_lshlrev_b32_e32 v0, 10, v17
	v_and_or_b32 v0, v0, s49, v13
	s_addc_u32 s31, s31, 0
	v_lshlrev_b32_e32 v2, 10, v16
	v_or3_b32 v134, v0, v6, v12
	v_and_or_b32 v2, v2, s49, v13
	v_lshlrev_b32_e32 v4, 10, v15
	s_add_u32 s4, s38, s4
	v_lshlrev_b64 v[0:1], 1, v[134:135]
	v_or3_b32 v134, v2, v6, v12
	v_and_or_b32 v4, v4, s49, v13
	v_lshlrev_b32_e32 v7, 10, v14
	s_addc_u32 s5, s39, s5
	v_lshlrev_b64 v[2:3], 1, v[134:135]
	v_or3_b32 v134, v4, v6, v12
	v_and_or_b32 v7, v7, s49, v13
	s_add_u32 s4, s4, 0x2400080
	s_nop 0
	v_lshlrev_b64 v[4:5], 1, v[134:135]
	v_or3_b32 v134, v7, v6, v12
	s_addc_u32 s5, s5, 0
	v_lshl_add_u64 v[128:129], s[30:31], 0, v[0:1]
	v_lshlrev_b64 v[6:7], 1, v[134:135]
	v_lshl_add_u64 v[140:141], s[4:5], 0, v[0:1]
	v_or_b32_e32 v152, 0x800, v151
	v_or_b32_e32 v154, 0x1000, v151
	v_or_b32_e32 v155, 0x1800, v151
	v_or_b32_e32 v156, 0x2000, v151
	v_or_b32_e32 v157, 0x2800, v151
	v_or_b32_e32 v158, 0x3000, v151
	v_or_b32_e32 v159, 0x3800, v151
	v_lshl_add_u64 v[130:131], s[30:31], 0, v[2:3]
	v_lshl_add_u64 v[136:137], s[30:31], 0, v[4:5]
	v_lshl_add_u64 v[138:139], s[30:31], 0, v[6:7]
	v_lshl_add_u64 v[142:143], s[4:5], 0, v[2:3]
	v_lshl_add_u64 v[144:145], s[4:5], 0, v[4:5]
	v_lshl_add_u64 v[146:147], s[4:5], 0, v[6:7]
	s_mov_b32 s6, 0
	s_mov_b64 s[4:5], 0
	s_waitcnt vmcnt(0) lgkmcnt(0)
	s_barrier
	v_readfirstlane_b32 s100, v148
	s_and_b32 s27, s6, 0x10000
	s_xor_b32 s30, s27, 0x10000
	s_add_i32 s27, s27, 0
	v_add3_u32 v134, s27, v149, v150
	v_add3_u32 v196, s27, v149, v151
	v_add3_u32 v197, s27, v153, v152
	v_add3_u32 v198, s27, v153, v154
	v_add3_u32 v199, s27, v153, v155
	v_add3_u32 v200, s27, v153, v156
	v_add3_u32 v201, s27, v153, v157
	v_add3_u32 v202, s27, v153, v158
	v_add3_u32 v203, s27, v153, v159
	ds_read_b128 v[180:183], v134 offset:32768
	ds_read_b128 v[160:163], v196
	ds_read_b128 v[168:171], v197
	ds_read_b128 v[172:175], v198
	ds_read_b128 v[176:179], v199
	ds_read_b128 v[184:187], v134 offset:34816
	ds_read_b128 v[188:191], v134 offset:36864
	ds_read_b128 v[192:195], v134 offset:38912
	s_add_i32 s101, s100, s30
	v_readfirstlane_b32 s98, v146
	v_readfirstlane_b32 s99, v147
	v_readfirstlane_b32 vcc_lo, v138
	v_readfirstlane_b32 vcc_hi, v139
	s_sub_u32 s98, s98, 0x1000000
	s_subb_u32 s99, s99, 0
	s_sub_u32 vcc_lo, vcc_lo, 0x1000000
	s_subb_u32 vcc_hi, vcc_hi, 0
	v_subrev_u32_e32 v146, s98, v146
	v_subrev_u32_e32 v138, vcc_lo, v138
	v_subrev_u32_e32 v144, s98, v144
	v_subrev_u32_e32 v136, vcc_lo, v136
	v_subrev_u32_e32 v142, s98, v142
	v_subrev_u32_e32 v130, vcc_lo, v130
	v_subrev_u32_e32 v140, s98, v140
	v_subrev_u32_e32 v128, vcc_lo, v128
	s_mov_b32 m0, s101
	s_nop 0
	global_load_lds_dwordx4 v146, s[98:99]
	s_add_i32 m0, s101, 0x8000
	s_nop 0
	global_load_lds_dwordx4 v138, vcc
	s_add_i32 m0, s101, 0x2000
	s_nop 0
	global_load_lds_dwordx4 v144, s[98:99]
	s_add_i32 m0, s101, 0xa000
	s_nop 0
	global_load_lds_dwordx4 v136, vcc
	s_add_i32 m0, s101, 0x4000
	s_nop 0
	global_load_lds_dwordx4 v142, s[98:99]
	s_add_i32 m0, s101, 0xc000
	s_nop 0
	global_load_lds_dwordx4 v130, vcc
	s_add_i32 m0, s101, 0x6000
	s_nop 0
	global_load_lds_dwordx4 v140, s[98:99]
	s_add_i32 m0, s101, 0xe000
	s_nop 0
	global_load_lds_dwordx4 v128, vcc

.Lg2b_177:
	s_waitcnt lgkmcnt(3)
	v_mfma_f32_16x16x32_bf16 v[108:111], v[160:163], v[180:183], v[108:111]
	v_mfma_f32_16x16x32_bf16 v[92:95], v[168:171], v[180:183], v[92:95]
	v_mfma_f32_16x16x32_bf16 v[76:79], v[172:175], v[180:183], v[76:79]
	v_mfma_f32_16x16x32_bf16 v[60:63], v[176:179], v[180:183], v[60:63]
	ds_read_b128 v[240:243], v200 offset:1024
	ds_read_b128 v[244:247], v201 offset:1024
	s_waitcnt lgkmcnt(4)
	v_mfma_f32_16x16x32_bf16 v[104:107], v[160:163], v[184:187], v[104:107]
	v_mfma_f32_16x16x32_bf16 v[88:91], v[168:171], v[184:187], v[88:91]
	v_mfma_f32_16x16x32_bf16 v[72:75], v[172:175], v[184:187], v[72:75]
	v_mfma_f32_16x16x32_bf16 v[56:59], v[176:179], v[184:187], v[56:59]
	ds_read_b128 v[248:251], v202 offset:1024
	ds_read_b128 v[252:255], v203 offset:1024
	s_waitcnt lgkmcnt(5)
	v_mfma_f32_16x16x32_bf16 v[100:103], v[160:163], v[188:191], v[100:103]
	v_mfma_f32_16x16x32_bf16 v[84:87], v[168:171], v[188:191], v[84:87]
	v_mfma_f32_16x16x32_bf16 v[68:71], v[172:175], v[188:191], v[68:71]
	v_mfma_f32_16x16x32_bf16 v[52:55], v[176:179], v[188:191], v[52:55]
	s_waitcnt lgkmcnt(4)
	v_mfma_f32_16x16x32_bf16 v[96:99], v[160:163], v[192:195], v[96:99]
	v_mfma_f32_16x16x32_bf16 v[80:83], v[168:171], v[192:195], v[80:83]
	v_mfma_f32_16x16x32_bf16 v[64:67], v[172:175], v[192:195], v[64:67]
	v_mfma_f32_16x16x32_bf16 v[48:51], v[176:179], v[192:195], v[48:51]
	s_add_i32 s101, s100, s27
	s_cmpk_eq_i32 s4, 0x700
	s_cbranch_scc1 .Lg4n_177
	s_waitcnt vmcnt(0) lgkmcnt(0)
	s_barrier
	s_add_u32 s98, s98, 0x80
	s_addc_u32 s99, s99, 0
	s_add_u32 vcc_lo, vcc_lo, 0x80
	s_addc_u32 vcc_hi, vcc_hi, 0
	v_mfma_f32_16x16x32_bf16 v[44:47], v[240:243], v[180:183], v[44:47]
	v_mfma_f32_16x16x32_bf16 v[28:31], v[244:247], v[180:183], v[28:31]
	v_mfma_f32_16x16x32_bf16 v[12:15], v[248:251], v[180:183], v[12:15]
	v_mfma_f32_16x16x32_bf16 v[112:115], v[252:255], v[180:183], v[112:115]
	v_add3_u32 v134, s30, v149, v150
	ds_read_b128 v[180:183], v134 offset:32768
	v_add3_u32 v196, s30, v149, v151
	v_add3_u32 v197, s30, v153, v152
	v_add3_u32 v198, s30, v153, v154
	v_add3_u32 v199, s30, v153, v155
	ds_read_b128 v[160:163], v196
	ds_read_b128 v[168:171], v197
	ds_read_b128 v[172:175], v198
	ds_read_b128 v[176:179], v199
	s_mov_b32 m0, s101
	s_nop 0
	global_load_lds_dwordx4 v146, s[98:99]
	v_mfma_f32_16x16x32_bf16 v[40:43], v[240:243], v[184:187], v[40:43]
	v_mfma_f32_16x16x32_bf16 v[24:27], v[244:247], v[184:187], v[24:27]
	v_mfma_f32_16x16x32_bf16 v[8:11], v[248:251], v[184:187], v[8:11]
	v_mfma_f32_16x16x32_bf16 v[116:119], v[252:255], v[184:187], v[116:119]
	ds_read_b128 v[184:187], v134 offset:34816
	v_add3_u32 v200, s30, v153, v156
	v_add3_u32 v201, s30, v153, v157
	v_add3_u32 v202, s30, v153, v158
	v_add3_u32 v203, s30, v153, v159
	s_add_i32 m0, s101, 0x8000
	s_nop 0
	global_load_lds_dwordx4 v138, vcc
	v_mfma_f32_16x16x32_bf16 v[36:39], v[240:243], v[188:191], v[36:39]
	v_mfma_f32_16x16x32_bf16 v[20:23], v[244:247], v[188:191], v[20:23]
	v_mfma_f32_16x16x32_bf16 v[4:7], v[248:251], v[188:191], v[4:7]
	v_mfma_f32_16x16x32_bf16 v[120:123], v[252:255], v[188:191], v[120:123]
	ds_read_b128 v[188:191], v134 offset:36864
	s_add_i32 m0, s101, 0x2000
	s_nop 0
	global_load_lds_dwordx4 v144, s[98:99]
	v_mfma_f32_16x16x32_bf16 v[32:35], v[240:243], v[192:195], v[32:35]
	v_mfma_f32_16x16x32_bf16 v[16:19], v[244:247], v[192:195], v[16:19]
	v_mfma_f32_16x16x32_bf16 v[0:3], v[248:251], v[192:195], v[0:3]
	v_mfma_f32_16x16x32_bf16 v[124:127], v[252:255], v[192:195], v[124:127]
	ds_read_b128 v[192:195], v134 offset:38912
	s_add_i32 m0, s101, 0xa000
	s_nop 0
	global_load_lds_dwordx4 v136, vcc

.Lg1n_177:
	s_waitcnt lgkmcnt(3)
	v_mfma_f32_16x16x32_bf16 v[108:111], v[160:163], v[180:183], 0
	v_mfma_f32_16x16x32_bf16 v[92:95], v[168:171], v[180:183], 0
	v_mfma_f32_16x16x32_bf16 v[76:79], v[172:175], v[180:183], 0
	v_mfma_f32_16x16x32_bf16 v[60:63], v[176:179], v[180:183], 0
	ds_read_b128 v[240:243], v200
	ds_read_b128 v[244:247], v201
	s_waitcnt lgkmcnt(4)
	v_mfma_f32_16x16x32_bf16 v[104:107], v[160:163], v[184:187], 0
	v_mfma_f32_16x16x32_bf16 v[88:91], v[168:171], v[184:187], 0
	v_mfma_f32_16x16x32_bf16 v[72:75], v[172:175], v[184:187], 0
	v_mfma_f32_16x16x32_bf16 v[56:59], v[176:179], v[184:187], 0
	ds_read_b128 v[248:251], v202
	ds_read_b128 v[252:255], v203
	s_waitcnt lgkmcnt(5)
	v_mfma_f32_16x16x32_bf16 v[100:103], v[160:163], v[188:191], 0
	v_mfma_f32_16x16x32_bf16 v[84:87], v[168:171], v[188:191], 0
	v_mfma_f32_16x16x32_bf16 v[68:71], v[172:175], v[188:191], 0
	v_mfma_f32_16x16x32_bf16 v[52:55], v[176:179], v[188:191], 0
	s_waitcnt lgkmcnt(4)
	v_mfma_f32_16x16x32_bf16 v[96:99], v[160:163], v[192:195], 0
	v_mfma_f32_16x16x32_bf16 v[80:83], v[168:171], v[192:195], 0
	v_mfma_f32_16x16x32_bf16 v[64:67], v[172:175], v[192:195], 0
	v_mfma_f32_16x16x32_bf16 v[48:51], v[176:179], v[192:195], 0
	ds_read_b128 v[160:163], v196 offset:1024
	ds_read_b128 v[168:171], v197 offset:1024
	ds_read_b128 v[172:175], v198 offset:1024
	ds_read_b128 v[176:179], v199 offset:1024
	s_waitcnt lgkmcnt(4)
	v_mfma_f32_16x16x32_bf16 v[44:47], v[240:243], v[180:183], 0
	v_mfma_f32_16x16x32_bf16 v[28:31], v[244:247], v[180:183], 0
	v_mfma_f32_16x16x32_bf16 v[12:15], v[248:251], v[180:183], 0
	v_mfma_f32_16x16x32_bf16 v[112:115], v[252:255], v[180:183], 0
	ds_read_b128 v[180:183], v134 offset:33792
	v_mfma_f32_16x16x32_bf16 v[40:43], v[240:243], v[184:187], 0
	v_mfma_f32_16x16x32_bf16 v[24:27], v[244:247], v[184:187], 0
	v_mfma_f32_16x16x32_bf16 v[8:11], v[248:251], v[184:187], 0
	v_mfma_f32_16x16x32_bf16 v[116:119], v[252:255], v[184:187], 0
	ds_read_b128 v[184:187], v134 offset:35840
	v_mfma_f32_16x16x32_bf16 v[36:39], v[240:243], v[188:191], 0
	v_mfma_f32_16x16x32_bf16 v[20:23], v[244:247], v[188:191], 0
	v_mfma_f32_16x16x32_bf16 v[4:7], v[248:251], v[188:191], 0
	v_mfma_f32_16x16x32_bf16 v[120:123], v[252:255], v[188:191], 0
	ds_read_b128 v[188:191], v134 offset:37888
	v_mfma_f32_16x16x32_bf16 v[32:35], v[240:243], v[192:195], 0
	v_mfma_f32_16x16x32_bf16 v[16:19], v[244:247], v[192:195], 0
	v_mfma_f32_16x16x32_bf16 v[0:3], v[248:251], v[192:195], 0
	v_mfma_f32_16x16x32_bf16 v[124:127], v[252:255], v[192:195], 0
	ds_read_b128 v[192:195], v134 offset:39936
	s_branch .Lg2b_177

.LBB0_180:
	s_nop 0
	v_mov_b32_e32 v0, s19
	v_mov_b32_e32 v16, v132
	ds_read_b64 v[128:129], v0
	s_and_b64 s[4:5], exec, s[28:29]
	v_lshlrev_b32_e32 v7, 4, v16
	v_and_b32_e32 v6, 32, v16
	v_lshrrev_b32_e32 v8, 1, v16
	v_bitop3_b32 v6, v7, v6, 48 bitop3:0x6c
	s_cselect_b32 s4, 0x8000, 0
	v_bfe_u32 v17, v16, 2, 4
	v_and_b32_e32 v18, 32, v8
	v_lshrrev_b32_e32 v19, 1, v6
	v_ashrrev_i32_e32 v20, 3, v16
	s_add_i32 s4, s66, s4
	v_or_b32_e32 v10, v19, v18
	v_and_or_b32 v6, v20, s48, v17
	s_ashr_i32 s5, s4, 31
	v_and_b32_e32 v9, 0xfffffc00, v7
	v_lshl_or_b32 v134, v6, 10, v10
	v_add_u32_e32 v6, 0x2000, v7
	v_add_u32_e32 v8, 0x4000, v7
	v_add_u32_e32 v7, 0x6000, v7
	s_lshl_b64 s[4:5], s[4:5], 11
	s_ashr_i32 s27, s26, 31
	v_ashrrev_i32_e32 v21, 7, v6
	v_ashrrev_i32_e32 v22, 7, v8
	v_ashrrev_i32_e32 v23, 7, v7
	s_waitcnt lgkmcnt(0)
	v_lshl_add_u64 v[0:1], v[128:129], 0, s[4:5]
	s_lshl_b64 s[4:5], s[26:27], 19
	v_and_or_b32 v6, v21, s48, v17
	v_and_or_b32 v8, v22, s48, v17
	v_and_or_b32 v7, v23, s48, v17
	v_add_u32_e32 v150, 0, v9
	v_lshl_add_u64 v[2:3], v[0:1], 0, s[8:9]
	v_lshl_add_u64 v[4:5], v[128:129], 0, s[4:5]
	v_lshl_or_b32 v6, v6, 10, v10
	v_lshl_or_b32 v8, v8, 10, v10
	v_lshl_or_b32 v10, v7, 10, v10
	v_add_u32_e32 v7, 0x8000, v150
	v_lshlrev_b64 v[12:13], 1, v[134:135]
	v_readfirstlane_b32 s4, v150
	v_lshl_add_u64 v[14:15], v[2:3], 0, v[12:13]
	s_mov_b32 m0, s4
	v_readfirstlane_b32 s4, v7
	v_mov_b32_e32 v7, v135
	v_add_u32_e32 v9, 0x2000, v150
	global_load_lds_dwordx4 v[14:15], off
	v_lshl_add_u64 v[12:13], v[4:5], 0, v[12:13]
	s_mov_b32 m0, s4
	v_lshlrev_b64 v[6:7], 1, v[6:7]
	v_readfirstlane_b32 s4, v9
	v_add_u32_e32 v9, 0xa000, v150
	global_load_lds_dwordx4 v[12:13], off
	v_lshl_add_u64 v[12:13], v[2:3], 0, v[6:7]
	s_mov_b32 m0, s4
	v_readfirstlane_b32 s4, v9
	global_load_lds_dwordx4 v[12:13], off
	v_lshl_add_u64 v[6:7], v[4:5], 0, v[6:7]
	s_mov_b32 m0, s4
	v_mov_b32_e32 v9, v135
	v_add_u32_e32 v11, 0x4000, v150
	global_load_lds_dwordx4 v[6:7], off
	v_lshlrev_b64 v[6:7], 1, v[8:9]
	v_readfirstlane_b32 s4, v11
	v_lshl_add_u64 v[8:9], v[2:3], 0, v[6:7]
	s_mov_b32 m0, s4
	v_lshl_add_u64 v[6:7], v[4:5], 0, v[6:7]
	global_load_lds_dwordx4 v[8:9], off
	v_add_u32_e32 v8, 0xc000, v150
	v_mov_b32_e32 v11, v135
	v_readfirstlane_b32 s4, v8
	s_mov_b32 m0, s4
	v_add_u32_e32 v8, 0x6000, v150
	global_load_lds_dwordx4 v[6:7], off
	v_lshlrev_b64 v[6:7], 1, v[10:11]
	v_readfirstlane_b32 s4, v8
	v_lshl_add_u64 v[2:3], v[2:3], 0, v[6:7]
	s_mov_b32 m0, s4
	v_and_b32_e32 v24, 15, v16
	global_load_lds_dwordx4 v[2:3], off
	v_lshl_add_u64 v[2:3], v[4:5], 0, v[6:7]
	v_add_u32_e32 v6, 0xe000, v150
	v_lshlrev_b32_e32 v10, 10, v17
	v_readfirstlane_b32 s4, v6
	s_mov_b32 m0, s4
	v_lshlrev_b32_e32 v6, 2, v16
	global_load_lds_dwordx4 v[2:3], off
	v_and_b32_e32 v2, 48, v16
	v_lshlrev_b32_e32 v3, 6, v24
	v_and_b32_e32 v6, 32, v6
	v_bitop3_b32 v151, v3, v6, v2 bitop3:0x36
	v_lshlrev_b32_e32 v3, 7, v16
	v_and_b32_e32 v152, 0x6000, v3
	v_lshlrev_b32_e32 v3, 6, v16
	v_and_b32_e32 v153, 0xffffc000, v3
	v_and_b32_e32 v3, 0x3c0, v3
	v_bitop3_b32 v154, v3, v6, v2 bitop3:0x36
	v_lshlrev_b32_e32 v2, 10, v23
	v_and_or_b32 v2, v2, s49, v19
	v_lshlrev_b32_e32 v6, 10, v22
	v_or3_b32 v134, v2, v10, v18
	v_and_or_b32 v6, v6, s49, v19
	v_lshlrev_b32_e32 v8, 10, v21
	v_lshlrev_b64 v[2:3], 1, v[134:135]
	v_or3_b32 v134, v6, v10, v18
	v_and_or_b32 v8, v8, s49, v19
	v_lshlrev_b32_e32 v11, 10, v20
	v_lshlrev_b64 v[6:7], 1, v[134:135]
	v_or3_b32 v134, v8, v10, v18
	v_and_or_b32 v11, v11, s49, v19
	s_nop 0
	v_lshl_add_u64 v[4:5], v[4:5], 0, s[10:11]
	v_lshlrev_b64 v[8:9], 1, v[134:135]
	v_or3_b32 v134, v11, v10, v18
	v_lshl_add_u64 v[0:1], v[0:1], 0, s[12:13]
	v_lshl_add_u64 v[138:139], v[4:5], 0, v[8:9]
	v_lshlrev_b64 v[10:11], 1, v[134:135]
	v_lshl_add_u64 v[146:147], v[0:1], 0, v[8:9]
	s_mov_b32 s6, 0
	v_lshl_add_u64 v[130:131], v[4:5], 0, v[2:3]
	v_lshl_add_u64 v[136:137], v[4:5], 0, v[6:7]
	v_lshl_add_u64 v[140:141], v[4:5], 0, v[10:11]
	v_lshl_add_u64 v[142:143], v[0:1], 0, v[2:3]
	v_lshl_add_u64 v[144:145], v[0:1], 0, v[6:7]
	v_lshl_add_u64 v[148:149], v[0:1], 0, v[10:11]
	s_mov_b64 s[4:5], 0
	v_or_b32_e32 v134, 0x800, v153
	v_or_b32_e32 v155, 0x1000, v153
	v_or_b32_e32 v156, 0x1800, v153
	v_or_b32_e32 v157, 0x2000, v153
	v_or_b32_e32 v158, 0x2800, v153
	v_or_b32_e32 v159, 0x3000, v153
	v_or_b32_e32 v160, 0x3800, v153
	s_waitcnt vmcnt(0) lgkmcnt(0)
	s_barrier
	v_readfirstlane_b32 s100, v150
	s_and_b32 s27, s6, 0x10000
	s_xor_b32 s28, s27, 0x10000
	s_add_i32 s27, s27, 0
	v_add3_u32 v161, s27, v151, v152
	v_add3_u32 v162, s27, v151, v153
	v_add3_u32 v163, s27, v154, v134
	v_add3_u32 v200, s27, v154, v155
	v_add3_u32 v201, s27, v154, v156
	v_add3_u32 v202, s27, v154, v157
	v_add3_u32 v203, s27, v154, v158
	v_add3_u32 v204, s27, v154, v159
	v_add3_u32 v205, s27, v154, v160
	ds_read_b128 v[184:187], v161 offset:32768
	ds_read_b128 v[168:171], v162
	ds_read_b128 v[172:175], v163
	ds_read_b128 v[176:179], v200
	ds_read_b128 v[180:183], v201
	ds_read_b128 v[188:191], v161 offset:34816
	ds_read_b128 v[192:195], v161 offset:36864
	ds_read_b128 v[196:199], v161 offset:38912
	s_add_i32 s101, s100, s28
	v_readfirstlane_b32 s98, v148
	v_readfirstlane_b32 s99, v149
	v_readfirstlane_b32 vcc_lo, v140
	v_readfirstlane_b32 vcc_hi, v141
	s_sub_u32 s98, s98, 0x1000000
	s_subb_u32 s99, s99, 0
	s_sub_u32 vcc_lo, vcc_lo, 0x1000000
	s_subb_u32 vcc_hi, vcc_hi, 0
	v_subrev_u32_e32 v148, s98, v148
	v_subrev_u32_e32 v140, vcc_lo, v140
	v_subrev_u32_e32 v146, s98, v146
	v_subrev_u32_e32 v138, vcc_lo, v138
	v_subrev_u32_e32 v144, s98, v144
	v_subrev_u32_e32 v136, vcc_lo, v136
	v_subrev_u32_e32 v142, s98, v142
	v_subrev_u32_e32 v130, vcc_lo, v130
	s_mov_b32 m0, s101
	s_nop 0
	global_load_lds_dwordx4 v148, s[98:99]
	s_add_i32 m0, s101, 0x8000
	s_nop 0
	global_load_lds_dwordx4 v140, vcc
	s_add_i32 m0, s101, 0x2000
	s_nop 0
	global_load_lds_dwordx4 v146, s[98:99]
	s_add_i32 m0, s101, 0xa000
	s_nop 0
	global_load_lds_dwordx4 v138, vcc
	s_add_i32 m0, s101, 0x4000
	s_nop 0
	global_load_lds_dwordx4 v144, s[98:99]
	s_add_i32 m0, s101, 0xc000
	s_nop 0
	global_load_lds_dwordx4 v136, vcc
	s_add_i32 m0, s101, 0x6000
	s_nop 0
	global_load_lds_dwordx4 v142, s[98:99]
	s_add_i32 m0, s101, 0xe000
	s_nop 0
	global_load_lds_dwordx4 v130, vcc

.Lg2b_181:
	s_waitcnt lgkmcnt(3)
	v_mfma_f32_16x16x32_bf16 v[124:127], v[184:187], v[168:171], v[124:127]
	v_mfma_f32_16x16x32_bf16 v[108:111], v[184:187], v[172:175], v[108:111]
	v_mfma_f32_16x16x32_bf16 v[92:95], v[184:187], v[176:179], v[92:95]
	v_mfma_f32_16x16x32_bf16 v[76:79], v[184:187], v[180:183], v[76:79]
	ds_read_b128 v[240:243], v202 offset:1024
	ds_read_b128 v[244:247], v203 offset:1024
	s_waitcnt lgkmcnt(4)
	v_mfma_f32_16x16x32_bf16 v[120:123], v[188:191], v[168:171], v[120:123]
	v_mfma_f32_16x16x32_bf16 v[104:107], v[188:191], v[172:175], v[104:107]
	v_mfma_f32_16x16x32_bf16 v[88:91], v[188:191], v[176:179], v[88:91]
	v_mfma_f32_16x16x32_bf16 v[72:75], v[188:191], v[180:183], v[72:75]
	ds_read_b128 v[248:251], v204 offset:1024
	ds_read_b128 v[252:255], v205 offset:1024
	s_waitcnt lgkmcnt(5)
	v_mfma_f32_16x16x32_bf16 v[116:119], v[192:195], v[168:171], v[116:119]
	v_mfma_f32_16x16x32_bf16 v[100:103], v[192:195], v[172:175], v[100:103]
	v_mfma_f32_16x16x32_bf16 v[84:87], v[192:195], v[176:179], v[84:87]
	v_mfma_f32_16x16x32_bf16 v[68:71], v[192:195], v[180:183], v[68:71]
	s_waitcnt lgkmcnt(4)
	v_mfma_f32_16x16x32_bf16 v[112:115], v[196:199], v[168:171], v[112:115]
	v_mfma_f32_16x16x32_bf16 v[96:99], v[196:199], v[172:175], v[96:99]
	v_mfma_f32_16x16x32_bf16 v[80:83], v[196:199], v[176:179], v[80:83]
	v_mfma_f32_16x16x32_bf16 v[64:67], v[196:199], v[180:183], v[64:67]
	s_add_i32 s101, s100, s27
	s_cmpk_eq_i32 s4, 0x700
	s_cbranch_scc1 .Lg4n_181
	s_waitcnt vmcnt(0) lgkmcnt(0)
	s_barrier
	s_add_u32 s98, s98, 0x80
	s_addc_u32 s99, s99, 0
	s_add_u32 vcc_lo, vcc_lo, 0x80
	s_addc_u32 vcc_hi, vcc_hi, 0
	v_mfma_f32_16x16x32_bf16 v[60:63], v[184:187], v[240:243], v[60:63]
	v_mfma_f32_16x16x32_bf16 v[44:47], v[184:187], v[244:247], v[44:47]
	v_mfma_f32_16x16x32_bf16 v[16:19], v[184:187], v[248:251], v[16:19]
	v_mfma_f32_16x16x32_bf16 v[36:39], v[184:187], v[252:255], v[36:39]
	v_add3_u32 v161, s28, v151, v152
	ds_read_b128 v[184:187], v161 offset:32768
	v_add3_u32 v162, s28, v151, v153
	v_add3_u32 v163, s28, v154, v134
	v_add3_u32 v200, s28, v154, v155
	v_add3_u32 v201, s28, v154, v156
	ds_read_b128 v[168:171], v162
	ds_read_b128 v[172:175], v163
	ds_read_b128 v[176:179], v200
	ds_read_b128 v[180:183], v201
	s_mov_b32 m0, s101
	s_nop 0
	global_load_lds_dwordx4 v148, s[98:99]
	v_mfma_f32_16x16x32_bf16 v[56:59], v[188:191], v[240:243], v[56:59]
	v_mfma_f32_16x16x32_bf16 v[40:43], v[188:191], v[244:247], v[40:43]
	v_mfma_f32_16x16x32_bf16 v[12:15], v[188:191], v[248:251], v[12:15]
	v_mfma_f32_16x16x32_bf16 v[28:31], v[188:191], v[252:255], v[28:31]
	ds_read_b128 v[188:191], v161 offset:34816
	v_add3_u32 v202, s28, v154, v157
	v_add3_u32 v203, s28, v154, v158
	v_add3_u32 v204, s28, v154, v159
	v_add3_u32 v205, s28, v154, v160
	s_add_i32 m0, s101, 0x8000
	s_nop 0
	global_load_lds_dwordx4 v140, vcc
	v_mfma_f32_16x16x32_bf16 v[52:55], v[192:195], v[240:243], v[52:55]
	v_mfma_f32_16x16x32_bf16 v[32:35], v[192:195], v[244:247], v[32:35]
	v_mfma_f32_16x16x32_bf16 v[4:7], v[192:195], v[248:251], v[4:7]
	v_mfma_f32_16x16x32_bf16 v[20:23], v[192:195], v[252:255], v[20:23]
	ds_read_b128 v[192:195], v161 offset:36864
	s_add_i32 m0, s101, 0x2000
	s_nop 0
	global_load_lds_dwordx4 v146, s[98:99]
	v_mfma_f32_16x16x32_bf16 v[48:51], v[196:199], v[240:243], v[48:51]
	v_mfma_f32_16x16x32_bf16 v[24:27], v[196:199], v[244:247], v[24:27]
	v_mfma_f32_16x16x32_bf16 v[0:3], v[196:199], v[248:251], v[0:3]
	v_mfma_f32_16x16x32_bf16 v[8:11], v[196:199], v[252:255], v[8:11]
	ds_read_b128 v[196:199], v161 offset:38912
	s_add_i32 m0, s101, 0xa000
	s_nop 0
	global_load_lds_dwordx4 v138, vcc

.Lg1n_181:
	s_waitcnt lgkmcnt(3)
	v_mfma_f32_16x16x32_bf16 v[124:127], v[184:187], v[168:171], 0
	v_mfma_f32_16x16x32_bf16 v[108:111], v[184:187], v[172:175], 0
	v_mfma_f32_16x16x32_bf16 v[92:95], v[184:187], v[176:179], 0
	v_mfma_f32_16x16x32_bf16 v[76:79], v[184:187], v[180:183], 0
	ds_read_b128 v[240:243], v202
	ds_read_b128 v[244:247], v203
	s_waitcnt lgkmcnt(4)
	v_mfma_f32_16x16x32_bf16 v[120:123], v[188:191], v[168:171], 0
	v_mfma_f32_16x16x32_bf16 v[104:107], v[188:191], v[172:175], 0
	v_mfma_f32_16x16x32_bf16 v[88:91], v[188:191], v[176:179], 0
	v_mfma_f32_16x16x32_bf16 v[72:75], v[188:191], v[180:183], 0
	ds_read_b128 v[248:251], v204
	ds_read_b128 v[252:255], v205
	s_waitcnt lgkmcnt(5)
	v_mfma_f32_16x16x32_bf16 v[116:119], v[192:195], v[168:171], 0
	v_mfma_f32_16x16x32_bf16 v[100:103], v[192:195], v[172:175], 0
	v_mfma_f32_16x16x32_bf16 v[84:87], v[192:195], v[176:179], 0
	v_mfma_f32_16x16x32_bf16 v[68:71], v[192:195], v[180:183], 0
	s_waitcnt lgkmcnt(4)
	v_mfma_f32_16x16x32_bf16 v[112:115], v[196:199], v[168:171], 0
	v_mfma_f32_16x16x32_bf16 v[96:99], v[196:199], v[172:175], 0
	v_mfma_f32_16x16x32_bf16 v[80:83], v[196:199], v[176:179], 0
	v_mfma_f32_16x16x32_bf16 v[64:67], v[196:199], v[180:183], 0
	ds_read_b128 v[168:171], v162 offset:1024
	ds_read_b128 v[172:175], v163 offset:1024
	ds_read_b128 v[176:179], v200 offset:1024
	ds_read_b128 v[180:183], v201 offset:1024
	s_waitcnt lgkmcnt(4)
	v_mfma_f32_16x16x32_bf16 v[60:63], v[184:187], v[240:243], 0
	v_mfma_f32_16x16x32_bf16 v[44:47], v[184:187], v[244:247], 0
	v_mfma_f32_16x16x32_bf16 v[16:19], v[184:187], v[248:251], 0
	v_mfma_f32_16x16x32_bf16 v[36:39], v[184:187], v[252:255], 0
	ds_read_b128 v[184:187], v161 offset:33792
	v_mfma_f32_16x16x32_bf16 v[56:59], v[188:191], v[240:243], 0
	v_mfma_f32_16x16x32_bf16 v[40:43], v[188:191], v[244:247], 0
	v_mfma_f32_16x16x32_bf16 v[12:15], v[188:191], v[248:251], 0
	v_mfma_f32_16x16x32_bf16 v[28:31], v[188:191], v[252:255], 0
	ds_read_b128 v[188:191], v161 offset:35840
	v_mfma_f32_16x16x32_bf16 v[52:55], v[192:195], v[240:243], 0
	v_mfma_f32_16x16x32_bf16 v[32:35], v[192:195], v[244:247], 0
	v_mfma_f32_16x16x32_bf16 v[4:7], v[192:195], v[248:251], 0
	v_mfma_f32_16x16x32_bf16 v[20:23], v[192:195], v[252:255], 0
	ds_read_b128 v[192:195], v161 offset:37888
	v_mfma_f32_16x16x32_bf16 v[48:51], v[196:199], v[240:243], 0
	v_mfma_f32_16x16x32_bf16 v[24:27], v[196:199], v[244:247], 0
	v_mfma_f32_16x16x32_bf16 v[0:3], v[196:199], v[248:251], 0
	v_mfma_f32_16x16x32_bf16 v[8:11], v[196:199], v[252:255], 0
	ds_read_b128 v[196:199], v161 offset:39936
	s_branch .Lg2b_181

.LBB0_792:
	s_ashr_i32 s0, s52, 31
	s_lshr_b32 s0, s0, 26
	s_add_i32 s0, s52, s0
	s_and_b32 s28, s0, 0xffc0
	s_sub_i32 s28, s52, s28
	s_bfe_i32 s29, s28, 0x80000
	s_bfe_u32 s29, s29, 0x4000b
	s_add_i32 s29, s28, s29
	v_mov_b32_e32 v150, v132
	s_bfe_i32 s30, s29, 0x80000
	s_and_b32 s29, s29, 0xf0
	ds_read_b128 v[0:3], v133
	s_sub_i32 s28, s28, s29
	s_sext_i32_i8 s28, s28
	s_lshl_b32 s0, s0, 6
	s_and_b32 s0, s0, 0xfffff000
	s_lshl_b32 s28, s28, 8
	s_sext_i32_i16 s30, s30
	s_add_i32 s28, s28, s0
	v_mov_b32_e32 v12, v132
	s_lshl_b32 s0, s30, 4
	s_waitcnt lgkmcnt(0)
	v_readfirstlane_b32 s31, v3
	v_readfirstlane_b32 s53, v2
	s_ashr_i32 s29, s28, 31
	s_and_b32 s30, s0, 0xffffff00
	v_lshlrev_b32_e32 v3, 4, v12
	v_and_b32_e32 v2, 32, v12
	s_lshl_b64 s[36:37], s[28:29], 11
	v_lshrrev_b32_e32 v4, 1, v12
	v_bitop3_b32 v2, v3, v2, 48 bitop3:0x6c
	s_add_u32 s54, s53, s36
	v_bfe_u32 v13, v12, 2, 4
	v_and_b32_e32 v14, 32, v4
	v_lshrrev_b32_e32 v15, 1, v2
	v_ashrrev_i32_e32 v16, 3, v12
	s_addc_u32 s55, s31, s37
	v_or_b32_e32 v6, v15, v14
	v_and_or_b32 v2, v16, s44, v13
	s_add_u32 s42, s54, 0x2400000
	v_and_b32_e32 v5, 0xfffffc00, v3
	v_lshl_or_b32 v130, v2, 10, v6
	v_add_u32_e32 v2, 0x2000, v3
	v_add_u32_e32 v4, 0x4000, v3
	v_add_u32_e32 v3, 0x6000, v3
	s_addc_u32 s43, s55, 0
	s_add_i32 s0, s30, 0x1200
	v_ashrrev_i32_e32 v17, 7, v2
	v_ashrrev_i32_e32 v18, 7, v4
	v_ashrrev_i32_e32 v19, 7, v3
	s_lshl_b64 s[38:39], s[0:1], 11
	v_and_or_b32 v2, v17, s44, v13
	v_and_or_b32 v4, v18, s44, v13
	v_and_or_b32 v3, v19, s44, v13
	v_add_u32_e32 v151, 0, v5
	s_add_u32 s38, s53, s38
	v_lshl_or_b32 v2, v2, 10, v6
	v_lshl_or_b32 v4, v4, 10, v6
	v_lshl_or_b32 v6, v3, 10, v6
	v_add_u32_e32 v3, 0x8000, v151
	v_lshlrev_b64 v[8:9], 1, v[130:131]
	v_readfirstlane_b32 s0, v151
	s_addc_u32 s39, s31, s39
	v_lshl_add_u64 v[10:11], s[42:43], 0, v[8:9]
	s_mov_b32 m0, s0
	v_readfirstlane_b32 s0, v3
	v_mov_b32_e32 v3, v131
	v_add_u32_e32 v5, 0x2000, v151
	global_load_lds_dwordx4 v[10:11], off
	v_lshl_add_u64 v[8:9], s[38:39], 0, v[8:9]
	s_mov_b32 m0, s0
	v_lshlrev_b64 v[2:3], 1, v[2:3]
	v_readfirstlane_b32 s0, v5
	v_add_u32_e32 v5, 0xa000, v151
	global_load_lds_dwordx4 v[8:9], off
	v_lshl_add_u64 v[8:9], s[42:43], 0, v[2:3]
	s_mov_b32 m0, s0
	v_readfirstlane_b32 s0, v5
	global_load_lds_dwordx4 v[8:9], off
	v_lshl_add_u64 v[2:3], s[38:39], 0, v[2:3]
	s_mov_b32 m0, s0
	v_mov_b32_e32 v5, v131
	v_add_u32_e32 v7, 0x4000, v151
	global_load_lds_dwordx4 v[2:3], off
	v_lshlrev_b64 v[2:3], 1, v[4:5]
	v_readfirstlane_b32 s0, v7
	v_lshl_add_u64 v[4:5], s[42:43], 0, v[2:3]
	s_mov_b32 m0, s0
	v_lshl_add_u64 v[2:3], s[38:39], 0, v[2:3]
	global_load_lds_dwordx4 v[4:5], off
	v_add_u32_e32 v4, 0xc000, v151
	v_mov_b32_e32 v7, v131
	v_readfirstlane_b32 s0, v4
	s_mov_b32 m0, s0
	v_and_b32_e32 v20, 15, v12
	global_load_lds_dwordx4 v[2:3], off
	v_lshlrev_b64 v[2:3], 1, v[6:7]
	v_add_u32_e32 v6, 0x6000, v151
	v_lshl_add_u64 v[4:5], s[42:43], 0, v[2:3]
	v_readfirstlane_b32 s0, v6
	s_mov_b32 m0, s0
	v_lshl_add_u64 v[2:3], s[38:39], 0, v[2:3]
	global_load_lds_dwordx4 v[4:5], off
	v_add_u32_e32 v4, 0xe000, v151
	v_lshlrev_b32_e32 v8, 10, v13
	v_readfirstlane_b32 s0, v4
	s_mov_b32 m0, s0
	v_lshlrev_b32_e32 v4, 2, v12
	global_load_lds_dwordx4 v[2:3], off
	v_and_b32_e32 v2, 48, v12
	v_lshlrev_b32_e32 v3, 6, v20
	v_and_b32_e32 v4, 32, v4
	v_bitop3_b32 v152, v3, v4, v2 bitop3:0x36
	v_lshlrev_b32_e32 v3, 7, v12
	v_and_b32_e32 v153, 0x6000, v3
	v_lshlrev_b32_e32 v3, 6, v12
	v_and_b32_e32 v154, 0xffffc000, v3
	v_and_b32_e32 v3, 0x3c0, v3
	v_bitop3_b32 v156, v3, v4, v2 bitop3:0x36
	v_lshlrev_b32_e32 v2, 10, v19
	v_and_or_b32 v2, v2, s45, v15
	v_lshlrev_b32_e32 v4, 10, v18
	v_or3_b32 v130, v2, v8, v14
	v_and_or_b32 v4, v4, s45, v15
	v_lshlrev_b32_e32 v6, 10, v17
	v_lshlrev_b64 v[2:3], 1, v[130:131]
	v_or3_b32 v130, v4, v8, v14
	v_and_or_b32 v6, v6, s45, v15
	v_lshlrev_b32_e32 v9, 10, v16
	v_lshlrev_b64 v[4:5], 1, v[130:131]
	v_or3_b32 v130, v6, v8, v14
	v_and_or_b32 v9, v9, s45, v15
	s_add_u32 s38, s38, 0x80
	v_lshlrev_b64 v[6:7], 1, v[130:131]
	v_or3_b32 v130, v9, v8, v14
	s_addc_u32 s39, s39, 0
	v_lshlrev_b64 v[8:9], 1, v[130:131]
	s_nop 0
	v_lshl_add_u64 v[134:135], s[38:39], 0, v[2:3]
	v_lshl_add_u64 v[136:137], s[38:39], 0, v[4:5]
	v_lshl_add_u64 v[138:139], s[38:39], 0, v[6:7]
	v_lshl_add_u64 v[140:141], s[38:39], 0, v[8:9]
	s_add_u32 s38, s54, 0x2400080
	s_addc_u32 s39, s55, 0
	v_or_b32_e32 v155, 0x800, v154
	v_or_b32_e32 v157, 0x1000, v154
	v_or_b32_e32 v158, 0x1800, v154
	v_or_b32_e32 v159, 0x2000, v154
	v_or_b32_e32 v160, 0x2800, v154
	v_or_b32_e32 v161, 0x3000, v154
	v_or_b32_e32 v162, 0x3800, v154
	v_lshl_add_u64 v[142:143], s[38:39], 0, v[2:3]
	v_lshl_add_u64 v[144:145], s[38:39], 0, v[4:5]
	v_lshl_add_u64 v[146:147], s[38:39], 0, v[6:7]
	v_lshl_add_u64 v[148:149], s[38:39], 0, v[8:9]
	s_mov_b64 s[38:39], 0
	s_mov_b32 s0, 0
	s_waitcnt vmcnt(0) lgkmcnt(0)
	s_barrier
	v_readfirstlane_b32 s100, v151
	s_and_b32 s31, s0, 0x10000
	s_xor_b32 s42, s31, 0x10000
	s_add_i32 s31, s31, 0
	v_add3_u32 v130, s31, v152, v153
	v_add3_u32 v163, s31, v152, v154
	v_add3_u32 v196, s31, v156, v155
	v_add3_u32 v197, s31, v156, v157
	v_add3_u32 v198, s31, v156, v158
	v_add3_u32 v199, s31, v156, v159
	v_add3_u32 v200, s31, v156, v160
	v_add3_u32 v201, s31, v156, v161
	v_add3_u32 v202, s31, v156, v162
	ds_read_b128 v[180:183], v130 offset:32768
	ds_read_b128 v[164:167], v163
	ds_read_b128 v[168:171], v196
	ds_read_b128 v[172:175], v197
	ds_read_b128 v[176:179], v198
	ds_read_b128 v[184:187], v130 offset:34816
	ds_read_b128 v[188:191], v130 offset:36864
	ds_read_b128 v[192:195], v130 offset:38912
	s_add_i32 s101, s100, s42
	v_readfirstlane_b32 s98, v148
	v_readfirstlane_b32 s99, v149
	v_readfirstlane_b32 vcc_lo, v140
	v_readfirstlane_b32 vcc_hi, v141
	s_sub_u32 s98, s98, 0x1000000
	s_subb_u32 s99, s99, 0
	s_sub_u32 vcc_lo, vcc_lo, 0x1000000
	s_subb_u32 vcc_hi, vcc_hi, 0
	v_subrev_u32_e32 v148, s98, v148
	v_subrev_u32_e32 v140, vcc_lo, v140
	v_subrev_u32_e32 v146, s98, v146
	v_subrev_u32_e32 v138, vcc_lo, v138
	v_subrev_u32_e32 v144, s98, v144
	v_subrev_u32_e32 v136, vcc_lo, v136
	v_subrev_u32_e32 v142, s98, v142
	v_subrev_u32_e32 v134, vcc_lo, v134
	s_mov_b32 m0, s101
	s_nop 0
	global_load_lds_dwordx4 v148, s[98:99]
	s_add_i32 m0, s101, 0x8000
	s_nop 0
	global_load_lds_dwordx4 v140, vcc
	s_add_i32 m0, s101, 0x2000
	s_nop 0
	global_load_lds_dwordx4 v146, s[98:99]
	s_add_i32 m0, s101, 0xa000
	s_nop 0
	global_load_lds_dwordx4 v138, vcc
	s_add_i32 m0, s101, 0x4000
	s_nop 0
	global_load_lds_dwordx4 v144, s[98:99]
	s_add_i32 m0, s101, 0xc000
	s_nop 0
	global_load_lds_dwordx4 v136, vcc
	s_add_i32 m0, s101, 0x6000
	s_nop 0
	global_load_lds_dwordx4 v142, s[98:99]
	s_add_i32 m0, s101, 0xe000
	s_nop 0
	global_load_lds_dwordx4 v134, vcc

.Lg2b_793:
	s_waitcnt lgkmcnt(3)
	v_mfma_f32_16x16x32_bf16 v[126:129], v[180:183], v[164:167], v[126:129]
	v_mfma_f32_16x16x32_bf16 v[110:113], v[180:183], v[168:171], v[110:113]
	v_mfma_f32_16x16x32_bf16 v[94:97], v[180:183], v[172:175], v[94:97]
	v_mfma_f32_16x16x32_bf16 v[78:81], v[180:183], v[176:179], v[78:81]
	ds_read_b128 v[240:243], v199 offset:1024
	ds_read_b128 v[244:247], v200 offset:1024
	s_waitcnt lgkmcnt(4)
	v_mfma_f32_16x16x32_bf16 v[122:125], v[184:187], v[164:167], v[122:125]
	v_mfma_f32_16x16x32_bf16 v[106:109], v[184:187], v[168:171], v[106:109]
	v_mfma_f32_16x16x32_bf16 v[90:93], v[184:187], v[172:175], v[90:93]
	v_mfma_f32_16x16x32_bf16 v[74:77], v[184:187], v[176:179], v[74:77]
	ds_read_b128 v[248:251], v201 offset:1024
	ds_read_b128 v[252:255], v202 offset:1024
	s_waitcnt lgkmcnt(5)
	v_mfma_f32_16x16x32_bf16 v[118:121], v[188:191], v[164:167], v[118:121]
	v_mfma_f32_16x16x32_bf16 v[102:105], v[188:191], v[168:171], v[102:105]
	v_mfma_f32_16x16x32_bf16 v[86:89], v[188:191], v[172:175], v[86:89]
	v_mfma_f32_16x16x32_bf16 v[70:73], v[188:191], v[176:179], v[70:73]
	s_waitcnt lgkmcnt(4)
	v_mfma_f32_16x16x32_bf16 v[114:117], v[192:195], v[164:167], v[114:117]
	v_mfma_f32_16x16x32_bf16 v[98:101], v[192:195], v[168:171], v[98:101]
	v_mfma_f32_16x16x32_bf16 v[82:85], v[192:195], v[172:175], v[82:85]
	v_mfma_f32_16x16x32_bf16 v[66:69], v[192:195], v[176:179], v[66:69]
	s_add_i32 s101, s100, s31
	s_cmpk_eq_i32 s38, 0x700
	s_cbranch_scc1 .Lg4n_793
	s_waitcnt vmcnt(0) lgkmcnt(0)
	s_barrier
	s_add_u32 s98, s98, 0x80
	s_addc_u32 s99, s99, 0
	s_add_u32 vcc_lo, vcc_lo, 0x80
	s_addc_u32 vcc_hi, vcc_hi, 0
	v_mfma_f32_16x16x32_bf16 v[62:65], v[180:183], v[240:243], v[62:65]
	v_mfma_f32_16x16x32_bf16 v[46:49], v[180:183], v[244:247], v[46:49]
	v_mfma_f32_16x16x32_bf16 v[18:21], v[180:183], v[248:251], v[18:21]
	v_mfma_f32_16x16x32_bf16 v[38:41], v[180:183], v[252:255], v[38:41]
	v_add3_u32 v130, s42, v152, v153
	ds_read_b128 v[180:183], v130 offset:32768
	v_add3_u32 v163, s42, v152, v154
	v_add3_u32 v196, s42, v156, v155
	v_add3_u32 v197, s42, v156, v157
	v_add3_u32 v198, s42, v156, v158
	ds_read_b128 v[164:167], v163
	ds_read_b128 v[168:171], v196
	ds_read_b128 v[172:175], v197
	ds_read_b128 v[176:179], v198
	s_mov_b32 m0, s101
	s_nop 0
	global_load_lds_dwordx4 v148, s[98:99]
	v_mfma_f32_16x16x32_bf16 v[58:61], v[184:187], v[240:243], v[58:61]
	v_mfma_f32_16x16x32_bf16 v[42:45], v[184:187], v[244:247], v[42:45]
	v_mfma_f32_16x16x32_bf16 v[10:13], v[184:187], v[248:251], v[10:13]
	v_mfma_f32_16x16x32_bf16 v[30:33], v[184:187], v[252:255], v[30:33]
	ds_read_b128 v[184:187], v130 offset:34816
	v_add3_u32 v199, s42, v156, v159
	v_add3_u32 v200, s42, v156, v160
	v_add3_u32 v201, s42, v156, v161
	v_add3_u32 v202, s42, v156, v162
	s_add_i32 m0, s101, 0x8000
	s_nop 0
	global_load_lds_dwordx4 v140, vcc
	v_mfma_f32_16x16x32_bf16 v[54:57], v[188:191], v[240:243], v[54:57]
	v_mfma_f32_16x16x32_bf16 v[34:37], v[188:191], v[244:247], v[34:37]
	v_mfma_f32_16x16x32_bf16 v[6:9], v[188:191], v[248:251], v[6:9]
	v_mfma_f32_16x16x32_bf16 v[22:25], v[188:191], v[252:255], v[22:25]
	ds_read_b128 v[188:191], v130 offset:36864
	s_add_i32 m0, s101, 0x2000
	s_nop 0
	global_load_lds_dwordx4 v146, s[98:99]
	v_mfma_f32_16x16x32_bf16 v[50:53], v[192:195], v[240:243], v[50:53]
	v_mfma_f32_16x16x32_bf16 v[26:29], v[192:195], v[244:247], v[26:29]
	v_mfma_f32_16x16x32_bf16 v[2:5], v[192:195], v[248:251], v[2:5]
	v_mfma_f32_16x16x32_bf16 v[14:17], v[192:195], v[252:255], v[14:17]
	ds_read_b128 v[192:195], v130 offset:38912
	s_add_i32 m0, s101, 0xa000
	s_nop 0
	global_load_lds_dwordx4 v138, vcc

.Lg1n_793:
	s_waitcnt lgkmcnt(3)
	v_mfma_f32_16x16x32_bf16 v[126:129], v[180:183], v[164:167], 0
	v_mfma_f32_16x16x32_bf16 v[110:113], v[180:183], v[168:171], 0
	v_mfma_f32_16x16x32_bf16 v[94:97], v[180:183], v[172:175], 0
	v_mfma_f32_16x16x32_bf16 v[78:81], v[180:183], v[176:179], 0
	ds_read_b128 v[240:243], v199
	ds_read_b128 v[244:247], v200
	s_waitcnt lgkmcnt(4)
	v_mfma_f32_16x16x32_bf16 v[122:125], v[184:187], v[164:167], 0
	v_mfma_f32_16x16x32_bf16 v[106:109], v[184:187], v[168:171], 0
	v_mfma_f32_16x16x32_bf16 v[90:93], v[184:187], v[172:175], 0
	v_mfma_f32_16x16x32_bf16 v[74:77], v[184:187], v[176:179], 0
	ds_read_b128 v[248:251], v201
	ds_read_b128 v[252:255], v202
	s_waitcnt lgkmcnt(5)
	v_mfma_f32_16x16x32_bf16 v[118:121], v[188:191], v[164:167], 0
	v_mfma_f32_16x16x32_bf16 v[102:105], v[188:191], v[168:171], 0
	v_mfma_f32_16x16x32_bf16 v[86:89], v[188:191], v[172:175], 0
	v_mfma_f32_16x16x32_bf16 v[70:73], v[188:191], v[176:179], 0
	s_waitcnt lgkmcnt(4)
	v_mfma_f32_16x16x32_bf16 v[114:117], v[192:195], v[164:167], 0
	v_mfma_f32_16x16x32_bf16 v[98:101], v[192:195], v[168:171], 0
	v_mfma_f32_16x16x32_bf16 v[82:85], v[192:195], v[172:175], 0
	v_mfma_f32_16x16x32_bf16 v[66:69], v[192:195], v[176:179], 0
	ds_read_b128 v[164:167], v163 offset:1024
	ds_read_b128 v[168:171], v196 offset:1024
	ds_read_b128 v[172:175], v197 offset:1024
	ds_read_b128 v[176:179], v198 offset:1024
	s_waitcnt lgkmcnt(4)
	v_mfma_f32_16x16x32_bf16 v[62:65], v[180:183], v[240:243], 0
	v_mfma_f32_16x16x32_bf16 v[46:49], v[180:183], v[244:247], 0
	v_mfma_f32_16x16x32_bf16 v[18:21], v[180:183], v[248:251], 0
	v_mfma_f32_16x16x32_bf16 v[38:41], v[180:183], v[252:255], 0
	ds_read_b128 v[180:183], v130 offset:33792
	v_mfma_f32_16x16x32_bf16 v[58:61], v[184:187], v[240:243], 0
	v_mfma_f32_16x16x32_bf16 v[42:45], v[184:187], v[244:247], 0
	v_mfma_f32_16x16x32_bf16 v[10:13], v[184:187], v[248:251], 0
	v_mfma_f32_16x16x32_bf16 v[30:33], v[184:187], v[252:255], 0
	ds_read_b128 v[184:187], v130 offset:35840
	v_mfma_f32_16x16x32_bf16 v[54:57], v[188:191], v[240:243], 0
	v_mfma_f32_16x16x32_bf16 v[34:37], v[188:191], v[244:247], 0
	v_mfma_f32_16x16x32_bf16 v[6:9], v[188:191], v[248:251], 0
	v_mfma_f32_16x16x32_bf16 v[22:25], v[188:191], v[252:255], 0
	ds_read_b128 v[188:191], v130 offset:37888
	v_mfma_f32_16x16x32_bf16 v[50:53], v[192:195], v[240:243], 0
	v_mfma_f32_16x16x32_bf16 v[26:29], v[192:195], v[244:247], 0
	v_mfma_f32_16x16x32_bf16 v[2:5], v[192:195], v[248:251], 0
	v_mfma_f32_16x16x32_bf16 v[14:17], v[192:195], v[252:255], 0
	ds_read_b128 v[192:195], v130 offset:39936
	s_branch .Lg2b_793

.Lex_793:
	s_waitcnt lgkmcnt(0)
	v_add3_u32 v130, s46, v156, v162
	v_add3_u32 v151, s46, v156, v161
	v_add3_u32 v202, s46, v156, v160
	v_add3_u32 v198, s46, v156, v159
	v_add3_u32 v186, s46, v156, v158
	v_add3_u32 v187, s46, v156, v157
	v_add3_u32 v188, s46, v156, v155
	v_add3_u32 v189, s46, v152, v154
	v_add3_u32 v190, s47, v152, v153
	ds_read_b128 v[134:137], v130
	ds_read_b128 v[138:141], v151
	ds_read_b128 v[142:145], v202
	ds_read_b128 v[146:149], v198
	ds_read_b128 v[158:161], v186
	ds_read_b128 v[162:165], v187
	ds_read_b128 v[166:169], v188
	ds_read_b128 v[154:157], v189
	ds_read_b128 v[170:173], v190
	s_waitcnt lgkmcnt(0)
	v_mfma_f32_16x16x32_bf16 v[18:21], v[170:173], v[138:141], v[18:21]
	v_mfma_f32_16x16x32_bf16 v[174:177], v[170:173], v[134:137], v[38:41]
	s_nop 2
	ds_read_b128 v[38:41], v190 offset:2048
	s_waitcnt lgkmcnt(0)
	v_mfma_f32_16x16x32_bf16 v[10:13], v[38:41], v[138:141], v[10:13]
	v_mfma_f32_16x16x32_bf16 v[62:65], v[170:173], v[146:149], v[62:65]
	v_mfma_f32_16x16x32_bf16 v[30:33], v[38:41], v[134:137], v[30:33]
	v_mfma_f32_16x16x32_bf16 v[58:61], v[38:41], v[146:149], v[58:61]
	ds_read_b128 v[178:181], v190 offset:4096
	s_waitcnt lgkmcnt(0)
	v_mfma_f32_16x16x32_bf16 v[182:185], v[178:181], v[134:137], v[22:25]
	v_mfma_f32_16x16x32_bf16 v[54:57], v[178:181], v[146:149], v[54:57]
	s_nop 1
	ds_read_b128 v[22:25], v190 offset:6144
	s_waitcnt lgkmcnt(0)
	v_mfma_f32_16x16x32_bf16 v[134:137], v[22:25], v[134:137], v[14:17]
	v_mfma_f32_16x16x32_bf16 v[14:17], v[22:25], v[154:157], v[114:117]
	v_mfma_f32_16x16x32_bf16 v[114:117], v[22:25], v[158:161], v[66:69]
	v_mfma_f32_16x16x32_bf16 v[66:69], v[178:181], v[154:157], v[118:121]
	v_mfma_f32_16x16x32_bf16 v[118:121], v[178:181], v[158:161], v[70:73]
	v_mfma_f32_16x16x32_bf16 v[70:73], v[38:41], v[154:157], v[122:125]
	v_mfma_f32_16x16x32_bf16 v[122:125], v[38:41], v[158:161], v[74:77]
	v_mfma_f32_16x16x32_bf16 v[74:77], v[170:173], v[154:157], v[126:129]
	v_mfma_f32_16x16x32_bf16 v[126:129], v[170:173], v[158:161], v[78:81]
	v_mfma_f32_16x16x32_bf16 v[50:53], v[22:25], v[146:149], v[50:53]
	v_mfma_f32_16x16x32_bf16 v[146:149], v[170:173], v[142:145], v[46:49]
	v_mfma_f32_16x16x32_bf16 v[152:155], v[38:41], v[142:145], v[42:45]
	v_mfma_f32_16x16x32_bf16 v[156:159], v[178:181], v[142:145], v[34:37]
	v_mfma_f32_16x16x32_bf16 v[26:29], v[22:25], v[142:145], v[26:29]
	v_mfma_f32_16x16x32_bf16 v[142:145], v[178:181], v[138:141], v[6:9]
	v_mfma_f32_16x16x32_bf16 v[110:113], v[170:173], v[166:169], v[110:113]
	v_mfma_f32_16x16x32_bf16 v[94:97], v[170:173], v[162:165], v[94:97]
	v_mfma_f32_16x16x32_bf16 v[106:109], v[38:41], v[166:169], v[106:109]
	v_mfma_f32_16x16x32_bf16 v[90:93], v[38:41], v[162:165], v[90:93]
	v_mfma_f32_16x16x32_bf16 v[102:105], v[178:181], v[166:169], v[102:105]
	v_mfma_f32_16x16x32_bf16 v[86:89], v[178:181], v[162:165], v[86:89]
	v_mfma_f32_16x16x32_bf16 v[98:101], v[22:25], v[166:169], v[98:101]
	v_mfma_f32_16x16x32_bf16 v[82:85], v[22:25], v[162:165], v[82:85]
	v_mfma_f32_16x16x32_bf16 v[22:25], v[22:25], v[138:141], v[2:5]
	ds_read_b128 v[138:141], v190 offset:1024
	ds_read_b128 v[160:163], v190 offset:3072
	ds_read_b128 v[164:167], v190 offset:5120
	ds_read_b128 v[168:171], v190 offset:7168
	ds_read_b128 v[2:5], v189 offset:1024
	ds_read_b128 v[6:9], v188 offset:1024
	ds_read_b128 v[34:37], v187 offset:1024
	ds_read_b128 v[38:41], v186 offset:1024
	s_waitcnt lgkmcnt(3)
	v_mfma_f32_16x16x32_bf16 v[178:181], v[138:141], v[2:5], v[74:77]
	v_mfma_f32_16x16x32_bf16 v[186:189], v[160:163], v[2:5], v[70:73]
	v_mfma_f32_16x16x32_bf16 v[190:193], v[164:167], v[2:5], v[66:69]
	v_mfma_f32_16x16x32_bf16 v[194:197], v[168:171], v[2:5], v[14:17]
	ds_read_b128 v[2:5], v198 offset:1024
	s_waitcnt lgkmcnt(3)
	v_mfma_f32_16x16x32_bf16 v[110:113], v[138:141], v[6:9], v[110:113]
	v_mfma_f32_16x16x32_bf16 v[106:109], v[160:163], v[6:9], v[106:109]
	v_mfma_f32_16x16x32_bf16 v[102:105], v[164:167], v[6:9], v[102:105]
	v_mfma_f32_16x16x32_bf16 v[198:201], v[168:171], v[6:9], v[98:101]
	ds_read_b128 v[6:9], v202 offset:1024
	s_waitcnt lgkmcnt(3)
	v_mfma_f32_16x16x32_bf16 v[66:69], v[138:141], v[34:37], v[94:97]
	v_mfma_f32_16x16x32_bf16 v[70:73], v[160:163], v[34:37], v[90:93]
	v_mfma_f32_16x16x32_bf16 v[74:77], v[164:167], v[34:37], v[86:89]
	v_mfma_f32_16x16x32_bf16 v[78:81], v[168:171], v[34:37], v[82:85]
	ds_read_b128 v[14:17], v151 offset:1024
	s_waitcnt lgkmcnt(3)
	v_mfma_f32_16x16x32_bf16 v[82:85], v[138:141], v[38:41], v[126:129]
	v_mfma_f32_16x16x32_bf16 v[86:89], v[160:163], v[38:41], v[122:125]
	v_mfma_f32_16x16x32_bf16 v[90:93], v[164:167], v[38:41], v[118:121]
	v_mfma_f32_16x16x32_bf16 v[94:97], v[168:171], v[38:41], v[114:117]
	ds_read_b128 v[98:101], v130 offset:1024
	s_waitcnt lgkmcnt(3)
	v_mfma_f32_16x16x32_bf16 v[34:37], v[138:141], v[2:5], v[62:65]
	v_mfma_f32_16x16x32_bf16 v[38:41], v[160:163], v[2:5], v[58:61]
	v_mfma_f32_16x16x32_bf16 v[42:45], v[164:167], v[2:5], v[54:57]
	v_mfma_f32_16x16x32_bf16 v[46:49], v[168:171], v[2:5], v[50:53]
	s_waitcnt lgkmcnt(2)
	v_mfma_f32_16x16x32_bf16 v[50:53], v[138:141], v[6:9], v[146:149]
	v_mfma_f32_16x16x32_bf16 v[54:57], v[160:163], v[6:9], v[152:155]
	v_mfma_f32_16x16x32_bf16 v[58:61], v[164:167], v[6:9], v[156:159]
	v_mfma_f32_16x16x32_bf16 v[62:65], v[168:171], v[6:9], v[26:29]
	s_waitcnt lgkmcnt(1)
	v_mfma_f32_16x16x32_bf16 v[2:5], v[138:141], v[14:17], v[18:21]
	v_mfma_f32_16x16x32_bf16 v[6:9], v[160:163], v[14:17], v[10:13]
	v_mfma_f32_16x16x32_bf16 v[10:13], v[164:167], v[14:17], v[142:145]
	v_mfma_f32_16x16x32_bf16 v[14:17], v[168:171], v[14:17], v[22:25]
	s_waitcnt lgkmcnt(0)
	v_mfma_f32_16x16x32_bf16 v[18:21], v[138:141], v[98:101], v[174:177]
	v_mfma_f32_16x16x32_bf16 v[22:25], v[160:163], v[98:101], v[30:33]
	v_mfma_f32_16x16x32_bf16 v[26:29], v[164:167], v[98:101], v[182:185]
	v_mfma_f32_16x16x32_bf16 v[30:33], v[168:171], v[98:101], v[134:137]
	v_lshrrev_b32_e32 v98, 6, v150
	v_mul_lo_u32 v98, v98, s48
	v_add_u32_e32 v101, s46, v98
	v_lshlrev_b32_e32 v98, 2, v150
	v_and_b32_e32 v100, 15, v150
	v_and_b32_e32 v115, 60, v98
	v_ashrrev_i32_e32 v98, 1, v150
	v_bfe_u32 v99, v150, 4, 2
	v_and_b32_e32 v114, 48, v150
	v_and_b32_e32 v116, 0xffffff80, v98
	v_lshlrev_b32_e32 v98, 2, v115
	v_mul_u32_u24_e32 v117, 0x110, v99
	v_mul_u32_u24_e32 v100, 0x110, v100
	v_add3_u32 v98, v101, v98, v117
	v_add3_u32 v101, v101, v114, v100
	s_waitcnt vmcnt(0)
	s_barrier
	ds_write_b128 v101, v[178:181]
	ds_write_b128 v101, v[186:189] offset:64
	ds_write_b128 v101, v[190:193] offset:128
	ds_write_b128 v101, v[194:197] offset:192
	ds_write_b128 v101, v[110:113] offset:4352
	ds_write_b128 v101, v[106:109] offset:4416
	ds_write_b128 v101, v[102:105] offset:4480
	ds_write_b128 v101, v[198:201] offset:4544
	ds_read_b128 v[102:105], v98
	v_add_u32_e32 v100, s28, v116
	s_ashr_i32 s31, s30, 31
	v_and_or_b32 v106, v150, s49, v115
	s_lshl_b64 s[38:39], s[30:31], 1
	s_waitcnt lgkmcnt(0)
	v_mul_f32_e32 v102, 0xbfb8aa3b, v102
	v_mul_f32_e32 v103, 0xbfb8aa3b, v103
	v_mul_f32_e32 v104, 0xbfb8aa3b, v104
	v_mul_f32_e32 v105, 0xbfb8aa3b, v105
	v_exp_f32_e32 v102, v102
	v_exp_f32_e32 v103, v103
	v_exp_f32_e32 v104, v104
	v_exp_f32_e32 v105, v105
	v_add_f32_e32 v102, 1.0, v102
	v_add_f32_e32 v103, 1.0, v103
	v_add_f32_e32 v104, 1.0, v104
	v_add_f32_e32 v105, 1.0, v105
	v_rcp_f32_e32 v102, v102
	v_rcp_f32_e32 v103, v103
	v_rcp_f32_e32 v104, v104
	v_rcp_f32_e32 v105, v105
	v_lshl_add_u64 v[0:1], v[0:1], 0, s[38:39]
	v_cvt_pk_bf16_f32 v102, v102, v103
	v_lshlrev_b32_e32 v130, 1, v106
	v_cvt_pk_bf16_f32 v103, v104, v105
	v_or_b32_e32 v104, v100, v99
	v_ashrrev_i32_e32 v105, 31, v104
	v_lshl_add_u64 v[0:1], v[0:1], 0, v[130:131]
	v_lshlrev_b64 v[104:105], 11, v[104:105]
	v_lshl_add_u64 v[104:105], v[0:1], 0, v[104:105]
	flat_store_dwordx2 v[104:105], v[102:103]
	ds_read_b128 v[102:105], v98 offset:1088
	s_lshl_b64 s[42:43], s[28:29], 10
	s_mov_b32 s29, 0
	s_waitcnt lgkmcnt(0)
	v_mul_f32_e32 v102, 0xbfb8aa3b, v102
	v_exp_f32_e32 v102, v102
	v_mul_f32_e32 v103, 0xbfb8aa3b, v103
	v_exp_f32_e32 v103, v103
	v_add_f32_e32 v102, 1.0, v102
	v_rcp_f32_e32 v106, v102
	v_add_f32_e32 v102, 1.0, v103
	v_mul_f32_e32 v103, 0xbfb8aa3b, v104
	v_exp_f32_e32 v103, v103
	v_mul_f32_e32 v104, 0xbfb8aa3b, v105
	v_exp_f32_e32 v104, v104
	v_rcp_f32_e32 v105, v102
	v_add_f32_e32 v102, 1.0, v103
	v_rcp_f32_e32 v103, v102
	v_add_f32_e32 v102, 1.0, v104
	v_rcp_f32_e32 v107, v102
	v_or_b32_e32 v102, 4, v99
	v_cvt_pk_bf16_f32 v104, v106, v105
	v_or_b32_e32 v106, v100, v102
	v_cvt_pk_bf16_f32 v105, v103, v107
	v_ashrrev_i32_e32 v107, 31, v106
	v_lshlrev_b64 v[106:107], 11, v[106:107]
	v_lshl_add_u64 v[106:107], v[0:1], 0, v[106:107]
	flat_store_dwordx2 v[106:107], v[104:105]
	ds_read_b128 v[104:107], v98 offset:2176
	s_waitcnt lgkmcnt(0)
	v_mul_f32_e32 v103, 0xbfb8aa3b, v104
	v_exp_f32_e32 v103, v103
	v_mul_f32_e32 v104, 0xbfb8aa3b, v105
	v_exp_f32_e32 v104, v104
	v_add_f32_e32 v103, 1.0, v103
	v_rcp_f32_e32 v105, v103
	v_add_f32_e32 v103, 1.0, v104
	v_mul_f32_e32 v104, 0xbfb8aa3b, v106
	v_exp_f32_e32 v104, v104
	v_mul_f32_e32 v106, 0xbfb8aa3b, v107
	v_exp_f32_e32 v106, v106
	v_rcp_f32_e32 v107, v103
	v_add_f32_e32 v103, 1.0, v104
	v_rcp_f32_e32 v108, v103
	v_add_f32_e32 v103, 1.0, v106
	v_rcp_f32_e32 v106, v103
	v_or_b32_e32 v103, 8, v99
	v_cvt_pk_bf16_f32 v104, v105, v107
	v_cvt_pk_bf16_f32 v105, v108, v106
	v_or_b32_e32 v106, v100, v103
	v_ashrrev_i32_e32 v107, 31, v106
	v_lshlrev_b64 v[106:107], 11, v[106:107]
	v_lshl_add_u64 v[106:107], v[0:1], 0, v[106:107]
	flat_store_dwordx2 v[106:107], v[104:105]
	ds_read_b128 v[104:107], v98 offset:3264
	s_waitcnt lgkmcnt(0)
	v_mul_f32_e32 v104, 0xbfb8aa3b, v104
	v_exp_f32_e32 v104, v104
	v_mul_f32_e32 v105, 0xbfb8aa3b, v105
	v_exp_f32_e32 v105, v105
	v_add_f32_e32 v104, 1.0, v104
	v_rcp_f32_e32 v108, v104
	v_add_f32_e32 v104, 1.0, v105
	v_mul_f32_e32 v105, 0xbfb8aa3b, v106
	v_exp_f32_e32 v105, v105
	v_mul_f32_e32 v106, 0xbfb8aa3b, v107
	v_exp_f32_e32 v106, v106
	v_rcp_f32_e32 v107, v104
	v_add_f32_e32 v104, 1.0, v105
	v_rcp_f32_e32 v105, v104
	v_add_f32_e32 v104, 1.0, v106
	v_rcp_f32_e32 v109, v104
	v_or_b32_e32 v104, 12, v99
	v_cvt_pk_bf16_f32 v106, v108, v107
	v_or_b32_e32 v108, v100, v104
	v_cvt_pk_bf16_f32 v107, v105, v109
	v_ashrrev_i32_e32 v109, 31, v108
	v_lshlrev_b64 v[108:109], 11, v[108:109]
	v_lshl_add_u64 v[108:109], v[0:1], 0, v[108:109]
	flat_store_dwordx2 v[108:109], v[106:107]
	ds_read_b128 v[106:109], v98 offset:4352
	s_waitcnt lgkmcnt(0)
	v_mul_f32_e32 v105, 0xbfb8aa3b, v106
	v_exp_f32_e32 v105, v105
	v_mul_f32_e32 v106, 0xbfb8aa3b, v107
	v_exp_f32_e32 v106, v106
	v_add_f32_e32 v105, 1.0, v105
	v_rcp_f32_e32 v107, v105
	v_add_f32_e32 v105, 1.0, v106
	v_mul_f32_e32 v106, 0xbfb8aa3b, v108
	v_exp_f32_e32 v106, v106
	v_mul_f32_e32 v108, 0xbfb8aa3b, v109
	v_exp_f32_e32 v108, v108
	v_rcp_f32_e32 v109, v105
	v_add_f32_e32 v105, 1.0, v106
	v_rcp_f32_e32 v110, v105
	v_add_f32_e32 v105, 1.0, v108
	v_rcp_f32_e32 v108, v105
	v_or_b32_e32 v105, 16, v99
	v_cvt_pk_bf16_f32 v106, v107, v109
	v_cvt_pk_bf16_f32 v107, v110, v108
	v_or_b32_e32 v108, v100, v105
	v_ashrrev_i32_e32 v109, 31, v108
	v_lshlrev_b64 v[108:109], 11, v[108:109]
	v_lshl_add_u64 v[108:109], v[0:1], 0, v[108:109]
	flat_store_dwordx2 v[108:109], v[106:107]
	ds_read_b128 v[106:109], v98 offset:5440
	s_waitcnt lgkmcnt(0)
	v_mul_f32_e32 v106, 0xbfb8aa3b, v106
	v_exp_f32_e32 v106, v106
	v_mul_f32_e32 v107, 0xbfb8aa3b, v107
	v_exp_f32_e32 v107, v107
	v_add_f32_e32 v106, 1.0, v106
	v_rcp_f32_e32 v110, v106
	v_add_f32_e32 v106, 1.0, v107
	v_mul_f32_e32 v107, 0xbfb8aa3b, v108
	v_exp_f32_e32 v107, v107
	v_mul_f32_e32 v108, 0xbfb8aa3b, v109
	v_exp_f32_e32 v108, v108
	v_rcp_f32_e32 v109, v106
	v_add_f32_e32 v106, 1.0, v107
	v_rcp_f32_e32 v107, v106
	v_add_f32_e32 v106, 1.0, v108
	v_rcp_f32_e32 v111, v106
	v_or_b32_e32 v106, 20, v99
	v_cvt_pk_bf16_f32 v108, v110, v109
	v_or_b32_e32 v110, v100, v106
	v_cvt_pk_bf16_f32 v109, v107, v111
	v_ashrrev_i32_e32 v111, 31, v110
	v_lshlrev_b64 v[110:111], 11, v[110:111]
	v_lshl_add_u64 v[110:111], v[0:1], 0, v[110:111]
	flat_store_dwordx2 v[110:111], v[108:109]
	ds_read_b128 v[108:111], v98 offset:6528
	s_waitcnt lgkmcnt(0)
	v_mul_f32_e32 v107, 0xbfb8aa3b, v108
	v_exp_f32_e32 v107, v107
	v_mul_f32_e32 v108, 0xbfb8aa3b, v109
	v_exp_f32_e32 v108, v108
	v_add_f32_e32 v107, 1.0, v107
	v_rcp_f32_e32 v109, v107
	v_add_f32_e32 v107, 1.0, v108
	v_mul_f32_e32 v108, 0xbfb8aa3b, v110
	v_exp_f32_e32 v108, v108
	v_mul_f32_e32 v110, 0xbfb8aa3b, v111
	v_exp_f32_e32 v110, v110
	v_rcp_f32_e32 v111, v107
	v_add_f32_e32 v107, 1.0, v108
	v_rcp_f32_e32 v112, v107
	v_add_f32_e32 v107, 1.0, v110
	v_rcp_f32_e32 v110, v107
	v_or_b32_e32 v107, 24, v99
	v_cvt_pk_bf16_f32 v108, v109, v111
	v_cvt_pk_bf16_f32 v109, v112, v110
	v_or_b32_e32 v110, v100, v107
	v_ashrrev_i32_e32 v111, 31, v110
	v_lshlrev_b64 v[110:111], 11, v[110:111]
	v_lshl_add_u64 v[110:111], v[0:1], 0, v[110:111]
	flat_store_dwordx2 v[110:111], v[108:109]
	ds_read_b128 v[108:111], v98 offset:7616
	s_waitcnt lgkmcnt(0)
	v_mul_f32_e32 v108, 0xbfb8aa3b, v108
	v_exp_f32_e32 v108, v108
	v_mul_f32_e32 v109, 0xbfb8aa3b, v109
	v_exp_f32_e32 v109, v109
	v_add_f32_e32 v108, 1.0, v108
	v_rcp_f32_e32 v112, v108
	v_add_f32_e32 v108, 1.0, v109
	v_mul_f32_e32 v109, 0xbfb8aa3b, v110
	v_exp_f32_e32 v109, v109
	v_mul_f32_e32 v110, 0xbfb8aa3b, v111
	v_exp_f32_e32 v110, v110
	v_rcp_f32_e32 v111, v108
	v_add_f32_e32 v108, 1.0, v109
	v_rcp_f32_e32 v109, v108
	v_add_f32_e32 v108, 1.0, v110
	v_rcp_f32_e32 v113, v108
	v_or_b32_e32 v108, 28, v99
	v_cvt_pk_bf16_f32 v110, v112, v111
	v_or_b32_e32 v112, v100, v108
	v_cvt_pk_bf16_f32 v111, v109, v113
	v_ashrrev_i32_e32 v113, 31, v112
	v_lshlrev_b64 v[112:113], 11, v[112:113]
	v_lshl_add_u64 v[112:113], v[0:1], 0, v[112:113]
	flat_store_dwordx2 v[112:113], v[110:111]
	ds_write_b128 v101, v[66:69]
	ds_write_b128 v101, v[70:73] offset:64
	ds_write_b128 v101, v[74:77] offset:128
	ds_write_b128 v101, v[78:81] offset:192
	ds_write_b128 v101, v[82:85] offset:4352
	ds_write_b128 v101, v[86:89] offset:4416
	ds_write_b128 v101, v[90:93] offset:4480
	ds_write_b128 v101, v[94:97] offset:4544
	ds_read_b128 v[66:69], v98
	v_or_b32_e32 v70, 32, v100
	s_waitcnt lgkmcnt(0)
	v_mul_f32_e32 v66, 0xbfb8aa3b, v66
	v_mul_f32_e32 v67, 0xbfb8aa3b, v67
	v_mul_f32_e32 v68, 0xbfb8aa3b, v68
	v_mul_f32_e32 v69, 0xbfb8aa3b, v69
	v_exp_f32_e32 v66, v66
	v_exp_f32_e32 v67, v67
	v_exp_f32_e32 v68, v68
	v_exp_f32_e32 v69, v69
	v_add_f32_e32 v66, 1.0, v66
	v_add_f32_e32 v67, 1.0, v67
	v_add_f32_e32 v68, 1.0, v68
	v_add_f32_e32 v69, 1.0, v69
	v_rcp_f32_e32 v66, v66
	v_rcp_f32_e32 v67, v67
	v_rcp_f32_e32 v68, v68
	v_rcp_f32_e32 v69, v69
	v_cvt_pk_bf16_f32 v66, v66, v67
	v_cvt_pk_bf16_f32 v67, v68, v69
	v_or_b32_e32 v68, v70, v99
	v_ashrrev_i32_e32 v69, 31, v68
	v_lshlrev_b64 v[68:69], 11, v[68:69]
	v_lshl_add_u64 v[68:69], v[0:1], 0, v[68:69]
	flat_store_dwordx2 v[68:69], v[66:67]
	ds_read_b128 v[66:69], v98 offset:1088
	s_waitcnt lgkmcnt(0)
	v_mul_f32_e32 v66, 0xbfb8aa3b, v66
	v_mul_f32_e32 v67, 0xbfb8aa3b, v67
	v_mul_f32_e32 v68, 0xbfb8aa3b, v68
	v_mul_f32_e32 v69, 0xbfb8aa3b, v69
	v_exp_f32_e32 v66, v66
	v_exp_f32_e32 v67, v67
	v_exp_f32_e32 v68, v68
	v_exp_f32_e32 v69, v69
	v_add_f32_e32 v66, 1.0, v66
	v_add_f32_e32 v67, 1.0, v67
	v_add_f32_e32 v68, 1.0, v68
	v_add_f32_e32 v69, 1.0, v69
	v_rcp_f32_e32 v66, v66
	v_rcp_f32_e32 v67, v67
	v_rcp_f32_e32 v68, v68
	v_rcp_f32_e32 v69, v69
	v_cvt_pk_bf16_f32 v66, v66, v67
	v_cvt_pk_bf16_f32 v67, v68, v69
	v_or_b32_e32 v68, v70, v102
	v_ashrrev_i32_e32 v69, 31, v68
	v_lshlrev_b64 v[68:69], 11, v[68:69]
	v_lshl_add_u64 v[68:69], v[0:1], 0, v[68:69]
	flat_store_dwordx2 v[68:69], v[66:67]
	ds_read_b128 v[66:69], v98 offset:2176
	s_waitcnt lgkmcnt(0)
	v_mul_f32_e32 v66, 0xbfb8aa3b, v66
	v_mul_f32_e32 v67, 0xbfb8aa3b, v67
	v_mul_f32_e32 v68, 0xbfb8aa3b, v68
	v_mul_f32_e32 v69, 0xbfb8aa3b, v69
	v_exp_f32_e32 v66, v66
	v_exp_f32_e32 v67, v67
	v_exp_f32_e32 v68, v68
	v_exp_f32_e32 v69, v69
	v_add_f32_e32 v66, 1.0, v66
	v_add_f32_e32 v67, 1.0, v67
	v_add_f32_e32 v68, 1.0, v68
	v_add_f32_e32 v69, 1.0, v69
	v_rcp_f32_e32 v66, v66
	v_rcp_f32_e32 v67, v67
	v_rcp_f32_e32 v68, v68
	v_rcp_f32_e32 v69, v69
	v_cvt_pk_bf16_f32 v66, v66, v67
	v_cvt_pk_bf16_f32 v67, v68, v69
	v_or_b32_e32 v68, v70, v103
	v_ashrrev_i32_e32 v69, 31, v68
	v_lshlrev_b64 v[68:69], 11, v[68:69]
	v_lshl_add_u64 v[68:69], v[0:1], 0, v[68:69]
	flat_store_dwordx2 v[68:69], v[66:67]
	ds_read_b128 v[66:69], v98 offset:3264
	s_waitcnt lgkmcnt(0)
	v_mul_f32_e32 v66, 0xbfb8aa3b, v66
	v_mul_f32_e32 v67, 0xbfb8aa3b, v67
	v_mul_f32_e32 v68, 0xbfb8aa3b, v68
	v_mul_f32_e32 v69, 0xbfb8aa3b, v69
	v_exp_f32_e32 v66, v66
	v_exp_f32_e32 v67, v67
	v_exp_f32_e32 v68, v68
	v_exp_f32_e32 v69, v69
	v_add_f32_e32 v66, 1.0, v66
	v_add_f32_e32 v67, 1.0, v67
	v_add_f32_e32 v68, 1.0, v68
	v_add_f32_e32 v69, 1.0, v69
	v_rcp_f32_e32 v66, v66
	v_rcp_f32_e32 v67, v67
	v_rcp_f32_e32 v68, v68
	v_rcp_f32_e32 v69, v69
	v_cvt_pk_bf16_f32 v66, v66, v67
	v_cvt_pk_bf16_f32 v67, v68, v69
	v_or_b32_e32 v68, v70, v104
	v_ashrrev_i32_e32 v69, 31, v68
	v_lshlrev_b64 v[68:69], 11, v[68:69]
	v_lshl_add_u64 v[68:69], v[0:1], 0, v[68:69]
	flat_store_dwordx2 v[68:69], v[66:67]
	ds_read_b128 v[66:69], v98 offset:4352
	s_waitcnt lgkmcnt(0)
	v_mul_f32_e32 v66, 0xbfb8aa3b, v66
	v_mul_f32_e32 v67, 0xbfb8aa3b, v67
	v_mul_f32_e32 v68, 0xbfb8aa3b, v68
	v_mul_f32_e32 v69, 0xbfb8aa3b, v69
	v_exp_f32_e32 v66, v66
	v_exp_f32_e32 v67, v67
	v_exp_f32_e32 v68, v68
	v_exp_f32_e32 v69, v69
	v_add_f32_e32 v66, 1.0, v66
	v_add_f32_e32 v67, 1.0, v67
	v_add_f32_e32 v68, 1.0, v68
	v_add_f32_e32 v69, 1.0, v69
	v_rcp_f32_e32 v66, v66
	v_rcp_f32_e32 v67, v67
	v_rcp_f32_e32 v68, v68
	v_rcp_f32_e32 v69, v69
	v_cvt_pk_bf16_f32 v66, v66, v67
	v_cvt_pk_bf16_f32 v67, v68, v69
	v_or_b32_e32 v68, v70, v105
	v_ashrrev_i32_e32 v69, 31, v68
	v_lshlrev_b64 v[68:69], 11, v[68:69]
	v_lshl_add_u64 v[68:69], v[0:1], 0, v[68:69]
	flat_store_dwordx2 v[68:69], v[66:67]
	ds_read_b128 v[66:69], v98 offset:5440
	s_waitcnt lgkmcnt(0)
	v_mul_f32_e32 v66, 0xbfb8aa3b, v66
	v_mul_f32_e32 v67, 0xbfb8aa3b, v67
	v_mul_f32_e32 v68, 0xbfb8aa3b, v68
	v_mul_f32_e32 v69, 0xbfb8aa3b, v69
	v_exp_f32_e32 v66, v66
	v_exp_f32_e32 v67, v67
	v_exp_f32_e32 v68, v68
	v_exp_f32_e32 v69, v69
	v_add_f32_e32 v66, 1.0, v66
	v_add_f32_e32 v67, 1.0, v67
	v_add_f32_e32 v68, 1.0, v68
	v_add_f32_e32 v69, 1.0, v69
	v_rcp_f32_e32 v66, v66
	v_rcp_f32_e32 v67, v67
	v_rcp_f32_e32 v68, v68
	v_rcp_f32_e32 v69, v69
	v_cvt_pk_bf16_f32 v66, v66, v67
	v_cvt_pk_bf16_f32 v67, v68, v69
	v_or_b32_e32 v68, v70, v106
	v_ashrrev_i32_e32 v69, 31, v68
	v_lshlrev_b64 v[68:69], 11, v[68:69]
	v_lshl_add_u64 v[68:69], v[0:1], 0, v[68:69]
	flat_store_dwordx2 v[68:69], v[66:67]
	ds_read_b128 v[66:69], v98 offset:6528
	s_waitcnt lgkmcnt(0)
	v_mul_f32_e32 v66, 0xbfb8aa3b, v66
	v_mul_f32_e32 v67, 0xbfb8aa3b, v67
	v_mul_f32_e32 v68, 0xbfb8aa3b, v68
	v_mul_f32_e32 v69, 0xbfb8aa3b, v69
	v_exp_f32_e32 v66, v66
	v_exp_f32_e32 v67, v67
	v_exp_f32_e32 v68, v68
	v_exp_f32_e32 v69, v69
	v_add_f32_e32 v66, 1.0, v66
	v_add_f32_e32 v67, 1.0, v67
	v_add_f32_e32 v68, 1.0, v68
	v_add_f32_e32 v69, 1.0, v69
	v_rcp_f32_e32 v66, v66
	v_rcp_f32_e32 v67, v67
	v_rcp_f32_e32 v68, v68
	v_rcp_f32_e32 v69, v69
	v_cvt_pk_bf16_f32 v66, v66, v67
	v_cvt_pk_bf16_f32 v67, v68, v69
	v_or_b32_e32 v68, v70, v107
	v_ashrrev_i32_e32 v69, 31, v68
	v_lshlrev_b64 v[68:69], 11, v[68:69]
	v_lshl_add_u64 v[68:69], v[0:1], 0, v[68:69]
	flat_store_dwordx2 v[68:69], v[66:67]
	ds_read_b128 v[66:69], v98 offset:7616
	s_waitcnt lgkmcnt(0)
	v_mul_f32_e32 v66, 0xbfb8aa3b, v66
	v_mul_f32_e32 v67, 0xbfb8aa3b, v67
	v_mul_f32_e32 v68, 0xbfb8aa3b, v68
	v_mul_f32_e32 v69, 0xbfb8aa3b, v69
	v_exp_f32_e32 v66, v66
	v_exp_f32_e32 v67, v67
	v_exp_f32_e32 v68, v68
	v_exp_f32_e32 v69, v69
	v_add_f32_e32 v66, 1.0, v66
	v_add_f32_e32 v67, 1.0, v67
	v_add_f32_e32 v68, 1.0, v68
	v_add_f32_e32 v69, 1.0, v69
	v_rcp_f32_e32 v66, v66
	v_rcp_f32_e32 v67, v67
	v_rcp_f32_e32 v68, v68
	v_rcp_f32_e32 v69, v69
	v_cvt_pk_bf16_f32 v66, v66, v67
	v_cvt_pk_bf16_f32 v67, v68, v69
	v_or_b32_e32 v68, v70, v108
	v_ashrrev_i32_e32 v69, 31, v68
	v_lshlrev_b64 v[68:69], 11, v[68:69]
	v_lshl_add_u64 v[68:69], v[0:1], 0, v[68:69]
	flat_store_dwordx2 v[68:69], v[66:67]
	ds_write_b128 v101, v[34:37]
	ds_write_b128 v101, v[38:41] offset:64
	ds_write_b128 v101, v[42:45] offset:128
	ds_write_b128 v101, v[46:49] offset:192
	ds_write_b128 v101, v[50:53] offset:4352
	ds_write_b128 v101, v[54:57] offset:4416
	ds_write_b128 v101, v[58:61] offset:4480
	ds_write_b128 v101, v[62:65] offset:4544
	ds_read_b128 v[34:37], v98
	v_or_b32_e32 v38, 64, v100
	s_waitcnt lgkmcnt(0)
	v_mul_f32_e32 v34, 0xbfb8aa3b, v34
	v_mul_f32_e32 v35, 0xbfb8aa3b, v35
	v_mul_f32_e32 v36, 0xbfb8aa3b, v36
	v_mul_f32_e32 v37, 0xbfb8aa3b, v37
	v_exp_f32_e32 v34, v34
	v_exp_f32_e32 v35, v35
	v_exp_f32_e32 v36, v36
	v_exp_f32_e32 v37, v37
	v_add_f32_e32 v34, 1.0, v34
	v_add_f32_e32 v35, 1.0, v35
	v_add_f32_e32 v36, 1.0, v36
	v_add_f32_e32 v37, 1.0, v37
	v_rcp_f32_e32 v34, v34
	v_rcp_f32_e32 v35, v35
	v_rcp_f32_e32 v36, v36
	v_rcp_f32_e32 v37, v37
	v_cvt_pk_bf16_f32 v34, v34, v35
	v_cvt_pk_bf16_f32 v35, v36, v37
	v_or_b32_e32 v36, v38, v99
	v_ashrrev_i32_e32 v37, 31, v36
	v_lshlrev_b64 v[36:37], 11, v[36:37]
	v_lshl_add_u64 v[36:37], v[0:1], 0, v[36:37]
	flat_store_dwordx2 v[36:37], v[34:35]
	ds_read_b128 v[34:37], v98 offset:1088
	s_waitcnt lgkmcnt(0)
	v_mul_f32_e32 v34, 0xbfb8aa3b, v34
	v_mul_f32_e32 v35, 0xbfb8aa3b, v35
	v_mul_f32_e32 v36, 0xbfb8aa3b, v36
	v_mul_f32_e32 v37, 0xbfb8aa3b, v37
	v_exp_f32_e32 v34, v34
	v_exp_f32_e32 v35, v35
	v_exp_f32_e32 v36, v36
	v_exp_f32_e32 v37, v37
	v_add_f32_e32 v34, 1.0, v34
	v_add_f32_e32 v35, 1.0, v35
	v_add_f32_e32 v36, 1.0, v36
	v_add_f32_e32 v37, 1.0, v37
	v_rcp_f32_e32 v34, v34
	v_rcp_f32_e32 v35, v35
	v_rcp_f32_e32 v36, v36
	v_rcp_f32_e32 v37, v37
	v_cvt_pk_bf16_f32 v34, v34, v35
	v_cvt_pk_bf16_f32 v35, v36, v37
	v_or_b32_e32 v36, v38, v102
	v_ashrrev_i32_e32 v37, 31, v36
	v_lshlrev_b64 v[36:37], 11, v[36:37]
	v_lshl_add_u64 v[36:37], v[0:1], 0, v[36:37]
	flat_store_dwordx2 v[36:37], v[34:35]
	ds_read_b128 v[34:37], v98 offset:2176
	s_waitcnt lgkmcnt(0)
	v_mul_f32_e32 v34, 0xbfb8aa3b, v34
	v_mul_f32_e32 v35, 0xbfb8aa3b, v35
	v_mul_f32_e32 v36, 0xbfb8aa3b, v36
	v_mul_f32_e32 v37, 0xbfb8aa3b, v37
	v_exp_f32_e32 v34, v34
	v_exp_f32_e32 v35, v35
	v_exp_f32_e32 v36, v36
	v_exp_f32_e32 v37, v37
	v_add_f32_e32 v34, 1.0, v34
	v_add_f32_e32 v35, 1.0, v35
	v_add_f32_e32 v36, 1.0, v36
	v_add_f32_e32 v37, 1.0, v37
	v_rcp_f32_e32 v34, v34
	v_rcp_f32_e32 v35, v35
	v_rcp_f32_e32 v36, v36
	v_rcp_f32_e32 v37, v37
	v_cvt_pk_bf16_f32 v34, v34, v35
	v_cvt_pk_bf16_f32 v35, v36, v37
	v_or_b32_e32 v36, v38, v103
	v_ashrrev_i32_e32 v37, 31, v36
	v_lshlrev_b64 v[36:37], 11, v[36:37]
	v_lshl_add_u64 v[36:37], v[0:1], 0, v[36:37]
	flat_store_dwordx2 v[36:37], v[34:35]
	ds_read_b128 v[34:37], v98 offset:3264
	s_waitcnt lgkmcnt(0)
	v_mul_f32_e32 v34, 0xbfb8aa3b, v34
	v_mul_f32_e32 v35, 0xbfb8aa3b, v35
	v_mul_f32_e32 v36, 0xbfb8aa3b, v36
	v_mul_f32_e32 v37, 0xbfb8aa3b, v37
	v_exp_f32_e32 v34, v34
	v_exp_f32_e32 v35, v35
	v_exp_f32_e32 v36, v36
	v_exp_f32_e32 v37, v37
	v_add_f32_e32 v34, 1.0, v34
	v_add_f32_e32 v35, 1.0, v35
	v_add_f32_e32 v36, 1.0, v36
	v_add_f32_e32 v37, 1.0, v37
	v_rcp_f32_e32 v34, v34
	v_rcp_f32_e32 v35, v35
	v_rcp_f32_e32 v36, v36
	v_rcp_f32_e32 v37, v37
	v_cvt_pk_bf16_f32 v34, v34, v35
	v_cvt_pk_bf16_f32 v35, v36, v37
	v_or_b32_e32 v36, v38, v104
	v_ashrrev_i32_e32 v37, 31, v36
	v_lshlrev_b64 v[36:37], 11, v[36:37]
	v_lshl_add_u64 v[36:37], v[0:1], 0, v[36:37]
	flat_store_dwordx2 v[36:37], v[34:35]
	ds_read_b128 v[34:37], v98 offset:4352
	s_waitcnt lgkmcnt(0)
	v_mul_f32_e32 v34, 0xbfb8aa3b, v34
	v_mul_f32_e32 v35, 0xbfb8aa3b, v35
	v_mul_f32_e32 v36, 0xbfb8aa3b, v36
	v_mul_f32_e32 v37, 0xbfb8aa3b, v37
	v_exp_f32_e32 v34, v34
	v_exp_f32_e32 v35, v35
	v_exp_f32_e32 v36, v36
	v_exp_f32_e32 v37, v37
	v_add_f32_e32 v34, 1.0, v34
	v_add_f32_e32 v35, 1.0, v35
	v_add_f32_e32 v36, 1.0, v36
	v_add_f32_e32 v37, 1.0, v37
	v_rcp_f32_e32 v34, v34
	v_rcp_f32_e32 v35, v35
	v_rcp_f32_e32 v36, v36
	v_rcp_f32_e32 v37, v37
	v_cvt_pk_bf16_f32 v34, v34, v35
	v_cvt_pk_bf16_f32 v35, v36, v37
	v_or_b32_e32 v36, v38, v105
	v_ashrrev_i32_e32 v37, 31, v36
	v_lshlrev_b64 v[36:37], 11, v[36:37]
	v_lshl_add_u64 v[36:37], v[0:1], 0, v[36:37]
	flat_store_dwordx2 v[36:37], v[34:35]
	ds_read_b128 v[34:37], v98 offset:5440
	s_waitcnt lgkmcnt(0)
	v_mul_f32_e32 v34, 0xbfb8aa3b, v34
	v_mul_f32_e32 v35, 0xbfb8aa3b, v35
	v_mul_f32_e32 v36, 0xbfb8aa3b, v36
	v_mul_f32_e32 v37, 0xbfb8aa3b, v37
	v_exp_f32_e32 v34, v34
	v_exp_f32_e32 v35, v35
	v_exp_f32_e32 v36, v36
	v_exp_f32_e32 v37, v37
	v_add_f32_e32 v34, 1.0, v34
	v_add_f32_e32 v35, 1.0, v35
	v_add_f32_e32 v36, 1.0, v36
	v_add_f32_e32 v37, 1.0, v37
	v_rcp_f32_e32 v34, v34
	v_rcp_f32_e32 v35, v35
	v_rcp_f32_e32 v36, v36
	v_rcp_f32_e32 v37, v37
	v_cvt_pk_bf16_f32 v34, v34, v35
	v_cvt_pk_bf16_f32 v35, v36, v37
	v_or_b32_e32 v36, v38, v106
	v_ashrrev_i32_e32 v37, 31, v36
	v_lshlrev_b64 v[36:37], 11, v[36:37]
	v_lshl_add_u64 v[36:37], v[0:1], 0, v[36:37]
	flat_store_dwordx2 v[36:37], v[34:35]
	ds_read_b128 v[34:37], v98 offset:6528
	s_waitcnt lgkmcnt(0)
	v_mul_f32_e32 v34, 0xbfb8aa3b, v34
	v_mul_f32_e32 v35, 0xbfb8aa3b, v35
	v_mul_f32_e32 v36, 0xbfb8aa3b, v36
	v_mul_f32_e32 v37, 0xbfb8aa3b, v37
	v_exp_f32_e32 v34, v34
	v_exp_f32_e32 v35, v35
	v_exp_f32_e32 v36, v36
	v_exp_f32_e32 v37, v37
	v_add_f32_e32 v34, 1.0, v34
	v_add_f32_e32 v35, 1.0, v35
	v_add_f32_e32 v36, 1.0, v36
	v_add_f32_e32 v37, 1.0, v37
	v_rcp_f32_e32 v34, v34
	v_rcp_f32_e32 v35, v35
	v_rcp_f32_e32 v36, v36
	v_rcp_f32_e32 v37, v37
	v_cvt_pk_bf16_f32 v34, v34, v35
	v_cvt_pk_bf16_f32 v35, v36, v37
	v_or_b32_e32 v36, v38, v107
	v_ashrrev_i32_e32 v37, 31, v36
	v_lshlrev_b64 v[36:37], 11, v[36:37]
	v_lshl_add_u64 v[36:37], v[0:1], 0, v[36:37]
	flat_store_dwordx2 v[36:37], v[34:35]
	ds_read_b128 v[34:37], v98 offset:7616
	s_waitcnt lgkmcnt(0)
	v_mul_f32_e32 v34, 0xbfb8aa3b, v34
	v_mul_f32_e32 v35, 0xbfb8aa3b, v35
	v_mul_f32_e32 v36, 0xbfb8aa3b, v36
	v_mul_f32_e32 v37, 0xbfb8aa3b, v37
	v_exp_f32_e32 v34, v34
	v_exp_f32_e32 v35, v35
	v_exp_f32_e32 v36, v36
	v_exp_f32_e32 v37, v37
	v_add_f32_e32 v34, 1.0, v34
	v_add_f32_e32 v35, 1.0, v35
	v_add_f32_e32 v36, 1.0, v36
	v_add_f32_e32 v37, 1.0, v37
	v_rcp_f32_e32 v34, v34
	v_rcp_f32_e32 v35, v35
	v_rcp_f32_e32 v36, v36
	v_rcp_f32_e32 v37, v37
	v_cvt_pk_bf16_f32 v34, v34, v35
	v_cvt_pk_bf16_f32 v35, v36, v37
	v_or_b32_e32 v36, v38, v108
	v_ashrrev_i32_e32 v37, 31, v36
	v_lshlrev_b64 v[36:37], 11, v[36:37]
	v_lshl_add_u64 v[36:37], v[0:1], 0, v[36:37]
	flat_store_dwordx2 v[36:37], v[34:35]
	ds_write_b128 v101, v[2:5]
	ds_write_b128 v101, v[6:9] offset:64
	ds_write_b128 v101, v[10:13] offset:128
	ds_write_b128 v101, v[14:17] offset:192
	ds_write_b128 v101, v[18:21] offset:4352
	ds_write_b128 v101, v[22:25] offset:4416
	ds_write_b128 v101, v[26:29] offset:4480
	ds_write_b128 v101, v[30:33] offset:4544
	ds_read_b128 v[2:5], v98
	v_or_b32_e32 v6, 0x60, v100
	v_mov_b32_e32 v20, v132
	v_mov_b32_e32 v7, v131
	v_mov_b32_e32 v11, v131
	s_waitcnt lgkmcnt(0)
	v_mul_f32_e32 v2, 0xbfb8aa3b, v2
	v_mul_f32_e32 v3, 0xbfb8aa3b, v3
	v_mul_f32_e32 v4, 0xbfb8aa3b, v4
	v_mul_f32_e32 v5, 0xbfb8aa3b, v5
	v_exp_f32_e32 v2, v2
	v_exp_f32_e32 v3, v3
	v_exp_f32_e32 v4, v4
	v_exp_f32_e32 v5, v5
	v_add_f32_e32 v2, 1.0, v2
	v_add_f32_e32 v3, 1.0, v3
	v_add_f32_e32 v4, 1.0, v4
	v_add_f32_e32 v5, 1.0, v5
	v_rcp_f32_e32 v2, v2
	v_rcp_f32_e32 v3, v3
	v_rcp_f32_e32 v4, v4
	v_rcp_f32_e32 v5, v5
	v_mov_b32_e32 v19, v131
	v_cvt_pk_bf16_f32 v2, v2, v3
	v_cvt_pk_bf16_f32 v3, v4, v5
	v_or_b32_e32 v4, v6, v99
	v_ashrrev_i32_e32 v5, 31, v4
	v_lshlrev_b64 v[4:5], 11, v[4:5]
	v_lshl_add_u64 v[4:5], v[0:1], 0, v[4:5]
	flat_store_dwordx2 v[4:5], v[2:3]
	ds_read_b128 v[2:5], v98 offset:1088
	s_waitcnt lgkmcnt(0)
	v_mul_f32_e32 v2, 0xbfb8aa3b, v2
	v_mul_f32_e32 v3, 0xbfb8aa3b, v3
	v_mul_f32_e32 v4, 0xbfb8aa3b, v4
	v_mul_f32_e32 v5, 0xbfb8aa3b, v5
	v_exp_f32_e32 v2, v2
	v_exp_f32_e32 v3, v3
	v_exp_f32_e32 v4, v4
	v_exp_f32_e32 v5, v5
	v_add_f32_e32 v2, 1.0, v2
	v_add_f32_e32 v3, 1.0, v3
	v_add_f32_e32 v4, 1.0, v4
	v_add_f32_e32 v5, 1.0, v5
	v_rcp_f32_e32 v2, v2
	v_rcp_f32_e32 v3, v3
	v_rcp_f32_e32 v4, v4
	v_rcp_f32_e32 v5, v5
	v_cvt_pk_bf16_f32 v2, v2, v3
	v_cvt_pk_bf16_f32 v3, v4, v5
	v_or_b32_e32 v4, v6, v102
	v_ashrrev_i32_e32 v5, 31, v4
	v_lshlrev_b64 v[4:5], 11, v[4:5]
	v_lshl_add_u64 v[4:5], v[0:1], 0, v[4:5]
	flat_store_dwordx2 v[4:5], v[2:3]
	ds_read_b128 v[2:5], v98 offset:2176
	s_waitcnt lgkmcnt(0)
	v_mul_f32_e32 v2, 0xbfb8aa3b, v2
	v_mul_f32_e32 v3, 0xbfb8aa3b, v3
	v_mul_f32_e32 v4, 0xbfb8aa3b, v4
	v_mul_f32_e32 v5, 0xbfb8aa3b, v5
	v_exp_f32_e32 v2, v2
	v_exp_f32_e32 v3, v3
	v_exp_f32_e32 v4, v4
	v_exp_f32_e32 v5, v5
	v_add_f32_e32 v2, 1.0, v2
	v_add_f32_e32 v3, 1.0, v3
	v_add_f32_e32 v4, 1.0, v4
	v_add_f32_e32 v5, 1.0, v5
	v_rcp_f32_e32 v2, v2
	v_rcp_f32_e32 v3, v3
	v_rcp_f32_e32 v4, v4
	v_rcp_f32_e32 v5, v5
	v_cvt_pk_bf16_f32 v2, v2, v3
	v_cvt_pk_bf16_f32 v3, v4, v5
	v_or_b32_e32 v4, v6, v103
	v_ashrrev_i32_e32 v5, 31, v4
	v_lshlrev_b64 v[4:5], 11, v[4:5]
	v_lshl_add_u64 v[4:5], v[0:1], 0, v[4:5]
	flat_store_dwordx2 v[4:5], v[2:3]
	ds_read_b128 v[2:5], v98 offset:3264
	s_waitcnt lgkmcnt(0)
	v_mul_f32_e32 v2, 0xbfb8aa3b, v2
	v_mul_f32_e32 v3, 0xbfb8aa3b, v3
	v_mul_f32_e32 v4, 0xbfb8aa3b, v4
	v_mul_f32_e32 v5, 0xbfb8aa3b, v5
	v_exp_f32_e32 v2, v2
	v_exp_f32_e32 v3, v3
	v_exp_f32_e32 v4, v4
	v_exp_f32_e32 v5, v5
	v_add_f32_e32 v2, 1.0, v2
	v_add_f32_e32 v3, 1.0, v3
	v_add_f32_e32 v4, 1.0, v4
	v_add_f32_e32 v5, 1.0, v5
	v_rcp_f32_e32 v2, v2
	v_rcp_f32_e32 v3, v3
	v_rcp_f32_e32 v4, v4
	v_rcp_f32_e32 v5, v5
	v_cvt_pk_bf16_f32 v2, v2, v3
	v_cvt_pk_bf16_f32 v3, v4, v5
	v_or_b32_e32 v4, v6, v104
	v_ashrrev_i32_e32 v5, 31, v4
	v_lshlrev_b64 v[4:5], 11, v[4:5]
	v_lshl_add_u64 v[4:5], v[0:1], 0, v[4:5]
	flat_store_dwordx2 v[4:5], v[2:3]
	ds_read_b128 v[2:5], v98 offset:4352
	s_waitcnt lgkmcnt(0)
	v_mul_f32_e32 v2, 0xbfb8aa3b, v2
	v_mul_f32_e32 v3, 0xbfb8aa3b, v3
	v_mul_f32_e32 v4, 0xbfb8aa3b, v4
	v_mul_f32_e32 v5, 0xbfb8aa3b, v5
	v_exp_f32_e32 v2, v2
	v_exp_f32_e32 v3, v3
	v_exp_f32_e32 v4, v4
	v_exp_f32_e32 v5, v5
	v_add_f32_e32 v2, 1.0, v2
	v_add_f32_e32 v3, 1.0, v3
	v_add_f32_e32 v4, 1.0, v4
	v_add_f32_e32 v5, 1.0, v5
	v_rcp_f32_e32 v2, v2
	v_rcp_f32_e32 v3, v3
	v_rcp_f32_e32 v4, v4
	v_rcp_f32_e32 v5, v5
	v_cvt_pk_bf16_f32 v2, v2, v3
	v_cvt_pk_bf16_f32 v3, v4, v5
	v_or_b32_e32 v4, v6, v105
	v_ashrrev_i32_e32 v5, 31, v4
	v_lshlrev_b64 v[4:5], 11, v[4:5]
	v_lshl_add_u64 v[4:5], v[0:1], 0, v[4:5]
	flat_store_dwordx2 v[4:5], v[2:3]
	ds_read_b128 v[2:5], v98 offset:5440
	s_waitcnt lgkmcnt(0)
	v_mul_f32_e32 v2, 0xbfb8aa3b, v2
	v_mul_f32_e32 v3, 0xbfb8aa3b, v3
	v_mul_f32_e32 v4, 0xbfb8aa3b, v4
	v_mul_f32_e32 v5, 0xbfb8aa3b, v5
	v_exp_f32_e32 v2, v2
	v_exp_f32_e32 v3, v3
	v_exp_f32_e32 v4, v4
	v_exp_f32_e32 v5, v5
	v_add_f32_e32 v2, 1.0, v2
	v_add_f32_e32 v3, 1.0, v3
	v_add_f32_e32 v4, 1.0, v4
	v_add_f32_e32 v5, 1.0, v5
	v_rcp_f32_e32 v2, v2
	v_rcp_f32_e32 v3, v3
	v_rcp_f32_e32 v4, v4
	v_rcp_f32_e32 v5, v5
	v_cvt_pk_bf16_f32 v2, v2, v3
	v_cvt_pk_bf16_f32 v3, v4, v5
	v_or_b32_e32 v4, v6, v106
	v_ashrrev_i32_e32 v5, 31, v4
	v_lshlrev_b64 v[4:5], 11, v[4:5]
	v_lshl_add_u64 v[4:5], v[0:1], 0, v[4:5]
	flat_store_dwordx2 v[4:5], v[2:3]
	ds_read_b128 v[2:5], v98 offset:6528
	s_waitcnt lgkmcnt(0)
	v_mul_f32_e32 v2, 0xbfb8aa3b, v2
	v_mul_f32_e32 v3, 0xbfb8aa3b, v3
	v_mul_f32_e32 v4, 0xbfb8aa3b, v4
	v_mul_f32_e32 v5, 0xbfb8aa3b, v5
	v_exp_f32_e32 v2, v2
	v_exp_f32_e32 v3, v3
	v_exp_f32_e32 v4, v4
	v_exp_f32_e32 v5, v5
	v_add_f32_e32 v2, 1.0, v2
	v_add_f32_e32 v3, 1.0, v3
	v_add_f32_e32 v4, 1.0, v4
	v_add_f32_e32 v5, 1.0, v5
	v_rcp_f32_e32 v2, v2
	v_rcp_f32_e32 v3, v3
	v_rcp_f32_e32 v4, v4
	v_rcp_f32_e32 v5, v5
	v_cvt_pk_bf16_f32 v2, v2, v3
	v_cvt_pk_bf16_f32 v3, v4, v5
	v_or_b32_e32 v4, v6, v107
	v_ashrrev_i32_e32 v5, 31, v4
	v_lshlrev_b64 v[4:5], 11, v[4:5]
	v_lshl_add_u64 v[4:5], v[0:1], 0, v[4:5]
	flat_store_dwordx2 v[4:5], v[2:3]
	ds_read_b128 v[2:5], v98 offset:7616
	v_mov_b32_e32 v98, v132
	s_waitcnt lgkmcnt(0)
	v_mul_f32_e32 v2, 0xbfb8aa3b, v2
	v_mul_f32_e32 v3, 0xbfb8aa3b, v3
	v_mul_f32_e32 v4, 0xbfb8aa3b, v4
	v_mul_f32_e32 v5, 0xbfb8aa3b, v5
	v_exp_f32_e32 v2, v2
	v_exp_f32_e32 v3, v3
	v_exp_f32_e32 v4, v4
	v_exp_f32_e32 v5, v5
	v_add_f32_e32 v2, 1.0, v2
	v_add_f32_e32 v3, 1.0, v3
	v_add_f32_e32 v4, 1.0, v4
	v_add_f32_e32 v5, 1.0, v5
	v_rcp_f32_e32 v2, v2
	v_rcp_f32_e32 v3, v3
	v_rcp_f32_e32 v4, v4
	v_rcp_f32_e32 v5, v5
	v_cvt_pk_bf16_f32 v2, v2, v3
	v_cvt_pk_bf16_f32 v3, v4, v5
	v_or_b32_e32 v4, v6, v108
	v_ashrrev_i32_e32 v5, 31, v4
	v_lshlrev_b64 v[4:5], 11, v[4:5]
	v_lshl_add_u64 v[0:1], v[0:1], 0, v[4:5]
	flat_store_dwordx2 v[0:1], v[2:3]
	v_mov_b32_e32 v0, s3
	ds_read_b128 v[0:3], v0
	s_waitcnt lgkmcnt(0)
	v_lshl_add_u64 v[4:5], v[2:3], 0, s[42:43]
	s_lshl_b64 s[42:43], s[30:31], 10
	v_lshl_add_u64 v[2:3], v[2:3], 0, s[42:43]
	v_lshl_add_u64 v[16:17], v[2:3], 0, s[12:13]
	v_lshlrev_b32_e32 v2, 4, v20
	v_and_b32_e32 v3, 32, v20
	v_bitop3_b32 v3, v2, v3, 48 bitop3:0x6c
	v_lshl_add_u64 v[14:15], v[4:5], 0, s[10:11]
	v_lshrrev_b32_e32 v5, 1, v20
	v_lshrrev_b32_e32 v3, 1, v3
	v_bfe_u32 v4, v20, 2, 4
	v_and_or_b32 v3, v5, 32, v3
	v_lshrrev_b32_e32 v5, 3, v20
	v_and_or_b32 v5, v5, s50, v4
	v_lshl_or_b32 v130, v5, 9, v3
	v_add_u32_e32 v5, 0x2000, v2
	v_lshrrev_b32_e32 v5, 7, v5
	v_and_or_b32 v5, v5, s50, v4
	v_lshl_or_b32 v6, v5, 9, v3
	v_add_u32_e32 v5, 0x4000, v2
	v_and_b32_e32 v21, 0xfffffc00, v2
	v_lshrrev_b32_e32 v5, 7, v5
	v_add_u32_e32 v2, 0x6000, v2
	v_and_or_b32 v5, v5, s50, v4
	v_lshrrev_b32_e32 v2, 7, v2
	v_add_u32_e32 v45, 0, v21
	v_lshl_or_b32 v10, v5, 9, v3
	v_and_or_b32 v2, v2, s50, v4
	v_add_u32_e32 v44, 0x8000, v45
	v_lshlrev_b64 v[4:5], 1, v[130:131]
	v_readfirstlane_b32 s60, v45
	v_lshl_or_b32 v18, v2, 9, v3
	v_lshl_add_u64 v[2:3], v[14:15], 0, v[4:5]
	s_mov_b32 m0, s60
	v_readfirstlane_b32 s58, v44
	v_add_u32_e32 v46, 0x2000, v45
	global_load_lds_dwordx4 v[2:3], off
	v_lshl_add_u64 v[4:5], v[16:17], 0, v[4:5]
	s_mov_b32 m0, s58
	v_lshlrev_b64 v[8:9], 1, v[6:7]
	v_readfirstlane_b32 s59, v46
	v_add_u32_e32 v47, 0xa000, v45
	global_load_lds_dwordx4 v[4:5], off
	v_lshl_add_u64 v[6:7], v[14:15], 0, v[8:9]
	s_mov_b32 m0, s59
	v_readfirstlane_b32 s61, v47
	v_add_u32_e32 v48, 0x4000, v45
	global_load_lds_dwordx4 v[6:7], off
	v_lshl_add_u64 v[8:9], v[16:17], 0, v[8:9]
	s_mov_b32 m0, s61
	v_lshlrev_b64 v[12:13], 1, v[10:11]
	v_readfirstlane_b32 s62, v48
	v_add_u32_e32 v49, 0xc000, v45
	v_lshlrev_b64 v[18:19], 1, v[18:19]
	v_and_b32_e32 v22, 15, v20
	global_load_lds_dwordx4 v[8:9], off
	v_lshl_add_u64 v[10:11], v[14:15], 0, v[12:13]
	s_mov_b32 m0, s62
	v_lshl_add_u64 v[12:13], v[16:17], 0, v[12:13]
	v_readfirstlane_b32 s63, v49
	v_lshl_add_u64 v[14:15], v[14:15], 0, v[18:19]
	v_add_u32_e32 v50, 0x6000, v45
	v_lshl_add_u64 v[16:17], v[16:17], 0, v[18:19]
	v_lshlrev_b32_e32 v19, 2, v20
	global_load_lds_dwordx4 v[10:11], off
	s_mov_b32 m0, s63
	v_readfirstlane_b32 s64, v50
	v_add_u32_e32 v51, 0xe000, v45
	v_and_b32_e32 v23, 48, v20
	v_lshlrev_b32_e32 v18, 6, v22
	v_and_b32_e32 v22, 32, v19
	global_load_lds_dwordx4 v[12:13], off
	s_mov_b32 m0, s64
	v_readfirstlane_b32 s65, v51
	v_bitop3_b32 v96, v18, v22, v23 bitop3:0x36
	v_lshlrev_b32_e32 v18, 7, v20
	v_add_u32_e32 v37, s46, v21
	global_load_lds_dwordx4 v[14:15], off
	s_mov_b32 m0, s65
	v_and_b32_e32 v97, 0x6000, v18
	v_lshlrev_b32_e32 v18, 6, v20
	v_add_u32_e32 v36, s47, v21
	v_readfirstlane_b32 s53, v37
	global_load_lds_dwordx4 v[16:17], off
	v_and_b32_e32 v99, 0xffffc000, v18
	v_and_b32_e32 v20, 0x3c0, v18
	v_lshl_add_u64 v[18:19], v[2:3], 0, s[6:7]
	s_mov_b32 m0, s53
	v_readfirstlane_b32 s0, v36
	v_add_u32_e32 v38, 0x2000, v37
	s_waitcnt vmcnt(0)
	s_waitcnt vmcnt(0) lgkmcnt(0)
	s_barrier
	global_load_lds_dwordx4 v[18:19], off
	v_lshl_add_u64 v[18:19], v[4:5], 0, s[6:7]
	s_mov_b32 m0, s0
	v_readfirstlane_b32 s42, v38
	v_add_u32_e32 v39, 0x2000, v36
	global_load_lds_dwordx4 v[18:19], off
	v_lshl_add_u64 v[18:19], v[6:7], 0, s[6:7]
	s_mov_b32 m0, s42
	v_readfirstlane_b32 s43, v39
	v_add_u32_e32 v40, 0x4000, v37
	global_load_lds_dwordx4 v[18:19], off
	v_lshl_add_u64 v[18:19], v[8:9], 0, s[6:7]
	s_mov_b32 m0, s43
	v_readfirstlane_b32 s54, v40
	v_add_u32_e32 v41, 0x4000, v36
	global_load_lds_dwordx4 v[18:19], off
	v_lshl_add_u64 v[18:19], v[10:11], 0, s[6:7]
	s_mov_b32 m0, s54
	v_readfirstlane_b32 s55, v41
	v_add_u32_e32 v42, 0x6000, v37
	global_load_lds_dwordx4 v[18:19], off
	v_lshl_add_u64 v[18:19], v[12:13], 0, s[6:7]
	s_mov_b32 m0, s55
	v_readfirstlane_b32 s56, v42
	v_add_u32_e32 v43, 0x6000, v36
	global_load_lds_dwordx4 v[18:19], off
	v_lshl_add_u64 v[18:19], v[14:15], 0, s[6:7]
	s_mov_b32 m0, s56
	v_readfirstlane_b32 s57, v43
	global_load_lds_dwordx4 v[18:19], off
	v_lshl_add_u64 v[18:19], v[16:17], 0, s[6:7]
	s_mov_b32 m0, s57
	v_add_u32_e32 v129, 0, v96
	global_load_lds_dwordx4 v[18:19], off
	v_add_u32_e32 v18, v129, v97
	ds_read_b128 v[24:27], v18 offset:32768
	ds_read_b128 v[56:59], v18 offset:34816
	ds_read_b128 v[64:67], v18 offset:36864
	ds_read_b128 v[72:75], v18 offset:38912
	v_bitop3_b32 v130, v20, v22, v23 bitop3:0x36
	v_add_u32_e32 v23, 0, v130
	v_or_b32_e32 v222, 0x3000, v99
	v_add_u32_e32 v20, v23, v222
	ds_read_b128 v[32:35], v20
	v_or_b32_e32 v223, 0x2800, v99
	v_add_u32_e32 v21, v23, v223
	s_waitcnt lgkmcnt(0)
	v_mfma_f32_16x16x32_bf16 v[76:79], v[24:27], v[32:35], 0
	v_or_b32_e32 v128, 0x3800, v99
	v_or_b32_e32 v218, 0x2000, v99
	v_or_b32_e32 v219, 0x1000, v99
	v_mfma_f32_16x16x32_bf16 v[80:83], v[56:59], v[32:35], 0
	v_or_b32_e32 v220, 0x1800, v99
	v_add_u32_e32 v19, v23, v128
	v_add_u32_e32 v22, v23, v218
	v_mfma_f32_16x16x32_bf16 v[84:87], v[64:67], v[32:35], 0
	ds_read_b128 v[28:31], v19
	ds_read_b128 v[112:115], v22
	v_mfma_f32_16x16x32_bf16 v[88:91], v[72:75], v[32:35], 0
	ds_read_b128 v[32:35], v21
	s_waitcnt lgkmcnt(0)
	v_mfma_f32_16x16x32_bf16 v[92:95], v[24:27], v[32:35], 0
	v_mfma_f32_16x16x32_bf16 v[100:103], v[56:59], v[32:35], 0
	v_mfma_f32_16x16x32_bf16 v[104:107], v[64:67], v[32:35], 0
	v_mfma_f32_16x16x32_bf16 v[108:111], v[72:75], v[32:35], 0
	v_add_u32_e32 v32, v129, v99
	v_or_b32_e32 v129, 0x800, v99
	v_add_u32_e32 v33, v23, v129
	v_add_u32_e32 v34, v23, v219
	v_add_u32_e32 v35, v23, v220
	ds_read_b128 v[134:137], v32
	ds_read_b128 v[150:153], v33
	ds_read_b128 v[166:169], v34
	ds_read_b128 v[182:185], v35
	s_waitcnt lgkmcnt(0)
	v_mfma_f32_16x16x32_bf16 v[178:181], v[64:67], v[166:169], 0
	v_mfma_f32_16x16x32_bf16 v[162:165], v[64:67], v[150:153], 0
	v_mfma_f32_16x16x32_bf16 v[146:149], v[64:67], v[134:137], 0
	v_mfma_f32_16x16x32_bf16 v[68:71], v[64:67], v[28:31], 0
	v_mfma_f32_16x16x32_bf16 v[124:127], v[64:67], v[112:115], 0
	v_mfma_f32_16x16x32_bf16 v[64:67], v[64:67], v[182:185], 0
	v_mfma_f32_16x16x32_bf16 v[174:177], v[56:59], v[166:169], 0
	v_mfma_f32_16x16x32_bf16 v[158:161], v[56:59], v[150:153], 0
	v_mfma_f32_16x16x32_bf16 v[142:145], v[56:59], v[134:137], 0
	v_mfma_f32_16x16x32_bf16 v[60:63], v[56:59], v[28:31], 0
	v_mfma_f32_16x16x32_bf16 v[120:123], v[56:59], v[112:115], 0
	v_mfma_f32_16x16x32_bf16 v[56:59], v[56:59], v[182:185], 0
	v_mfma_f32_16x16x32_bf16 v[170:173], v[24:27], v[166:169], 0
	v_mfma_f32_16x16x32_bf16 v[154:157], v[24:27], v[150:153], 0
	v_mfma_f32_16x16x32_bf16 v[138:141], v[24:27], v[134:137], 0
	v_mfma_f32_16x16x32_bf16 v[52:55], v[24:27], v[28:31], 0
	v_mfma_f32_16x16x32_bf16 v[116:119], v[24:27], v[112:115], 0
	v_mfma_f32_16x16x32_bf16 v[24:27], v[24:27], v[182:185], 0
	v_mfma_f32_16x16x32_bf16 v[166:169], v[72:75], v[166:169], 0
	v_mfma_f32_16x16x32_bf16 v[150:153], v[72:75], v[150:153], 0
	v_mfma_f32_16x16x32_bf16 v[134:137], v[72:75], v[134:137], 0
	v_mfma_f32_16x16x32_bf16 v[28:31], v[72:75], v[28:31], 0
	v_mfma_f32_16x16x32_bf16 v[112:115], v[72:75], v[112:115], 0
	v_mfma_f32_16x16x32_bf16 v[72:75], v[72:75], v[182:185], 0
	ds_read_b128 v[182:185], v18 offset:33792
	ds_read_b128 v[186:189], v18 offset:35840
	ds_read_b128 v[190:193], v18 offset:37888
	ds_read_b128 v[198:201], v18 offset:39936
	ds_read_b128 v[194:197], v32 offset:1024
	ds_read_b128 v[202:205], v33 offset:1024
	ds_read_b128 v[206:209], v34 offset:1024
	ds_read_b128 v[210:213], v35 offset:1024
	s_waitcnt lgkmcnt(0)
	v_mfma_f32_16x16x32_bf16 v[138:141], v[182:185], v[194:197], v[138:141]
	v_mfma_f32_16x16x32_bf16 v[142:145], v[186:189], v[194:197], v[142:145]
	v_mfma_f32_16x16x32_bf16 v[146:149], v[190:193], v[194:197], v[146:149]
	v_mfma_f32_16x16x32_bf16 v[134:137], v[198:201], v[194:197], v[134:137]
	ds_read_b128 v[194:197], v22 offset:1024
	v_mfma_f32_16x16x32_bf16 v[154:157], v[182:185], v[202:205], v[154:157]
	v_mfma_f32_16x16x32_bf16 v[158:161], v[186:189], v[202:205], v[158:161]
	v_mfma_f32_16x16x32_bf16 v[162:165], v[190:193], v[202:205], v[162:165]
	v_mfma_f32_16x16x32_bf16 v[150:153], v[198:201], v[202:205], v[150:153]
	ds_read_b128 v[202:205], v21 offset:1024
	v_mfma_f32_16x16x32_bf16 v[170:173], v[182:185], v[206:209], v[170:173]
	v_mfma_f32_16x16x32_bf16 v[174:177], v[186:189], v[206:209], v[174:177]
	v_mfma_f32_16x16x32_bf16 v[178:181], v[190:193], v[206:209], v[178:181]
	v_mfma_f32_16x16x32_bf16 v[166:169], v[198:201], v[206:209], v[166:169]
	ds_read_b128 v[206:209], v20 offset:1024
	v_mfma_f32_16x16x32_bf16 v[214:217], v[182:185], v[210:213], v[24:27]
	v_mfma_f32_16x16x32_bf16 v[56:59], v[186:189], v[210:213], v[56:59]
	v_mfma_f32_16x16x32_bf16 v[64:67], v[190:193], v[210:213], v[64:67]
	v_mfma_f32_16x16x32_bf16 v[72:75], v[198:201], v[210:213], v[72:75]
	ds_read_b128 v[24:27], v19 offset:1024
	s_waitcnt lgkmcnt(0)
	v_mfma_f32_16x16x32_bf16 v[116:119], v[182:185], v[194:197], v[116:119]
	v_mfma_f32_16x16x32_bf16 v[120:123], v[186:189], v[194:197], v[120:123]
	v_mfma_f32_16x16x32_bf16 v[124:127], v[190:193], v[194:197], v[124:127]
	v_mfma_f32_16x16x32_bf16 v[112:115], v[198:201], v[194:197], v[112:115]
	v_mfma_f32_16x16x32_bf16 v[92:95], v[182:185], v[202:205], v[92:95]
	v_mfma_f32_16x16x32_bf16 v[100:103], v[186:189], v[202:205], v[100:103]
	v_mfma_f32_16x16x32_bf16 v[104:107], v[190:193], v[202:205], v[104:107]
	v_mfma_f32_16x16x32_bf16 v[108:111], v[198:201], v[202:205], v[108:111]
	v_mfma_f32_16x16x32_bf16 v[76:79], v[182:185], v[206:209], v[76:79]
	v_mfma_f32_16x16x32_bf16 v[80:83], v[186:189], v[206:209], v[80:83]
	v_mfma_f32_16x16x32_bf16 v[84:87], v[190:193], v[206:209], v[84:87]
	v_mfma_f32_16x16x32_bf16 v[88:91], v[198:201], v[206:209], v[88:91]
	v_mfma_f32_16x16x32_bf16 v[52:55], v[182:185], v[24:27], v[52:55]
	v_mfma_f32_16x16x32_bf16 v[60:63], v[186:189], v[24:27], v[60:63]
	v_mfma_f32_16x16x32_bf16 v[68:71], v[190:193], v[24:27], v[68:71]
	v_mfma_f32_16x16x32_bf16 v[182:185], v[198:201], v[24:27], v[28:31]
	s_mov_b32 m0, s60
	v_lshl_add_u64 v[24:25], v[2:3], 0, s[14:15]
	s_waitcnt vmcnt(0)
	s_waitcnt vmcnt(0)
	s_barrier
	global_load_lds_dwordx4 v[24:25], off
	v_lshl_add_u64 v[24:25], v[4:5], 0, s[14:15]
	s_mov_b32 m0, s58
	v_add3_u32 v23, s47, v96, v97
	global_load_lds_dwordx4 v[24:25], off
	v_lshl_add_u64 v[24:25], v[6:7], 0, s[14:15]
	s_mov_b32 m0, s59
	s_nop 0
	global_load_lds_dwordx4 v[24:25], off
	v_lshl_add_u64 v[24:25], v[8:9], 0, s[14:15]
	s_mov_b32 m0, s61
	s_nop 0
	global_load_lds_dwordx4 v[24:25], off
	v_lshl_add_u64 v[24:25], v[10:11], 0, s[14:15]
	s_mov_b32 m0, s62
	s_nop 0
	global_load_lds_dwordx4 v[24:25], off
	v_lshl_add_u64 v[24:25], v[12:13], 0, s[14:15]
	s_mov_b32 m0, s63
	s_nop 0
	global_load_lds_dwordx4 v[24:25], off
	v_lshl_add_u64 v[24:25], v[14:15], 0, s[14:15]
	s_mov_b32 m0, s64
	s_nop 0
	global_load_lds_dwordx4 v[24:25], off
	v_lshl_add_u64 v[24:25], v[16:17], 0, s[14:15]
	s_mov_b32 m0, s65
	s_nop 0
	global_load_lds_dwordx4 v[24:25], off
	ds_read_b128 v[186:189], v23
	ds_read_b128 v[190:193], v23 offset:2048
	ds_read_b128 v[194:197], v23 offset:4096
	ds_read_b128 v[198:201], v23 offset:6144
	v_add3_u32 v24, s46, v96, v99
	v_add_u32_e32 v96, s46, v130
	ds_read_b128 v[28:31], v24
	v_add_u32_e32 v25, v96, v129
	v_add_u32_e32 v26, v96, v219
	v_add_u32_e32 v27, v96, v220
	ds_read_b128 v[202:205], v25
	ds_read_b128 v[206:209], v26
	ds_read_b128 v[210:213], v27
	s_waitcnt lgkmcnt(0)
	v_mfma_f32_16x16x32_bf16 v[138:141], v[186:189], v[28:31], v[138:141]
	v_mfma_f32_16x16x32_bf16 v[142:145], v[190:193], v[28:31], v[142:145]
	v_mfma_f32_16x16x32_bf16 v[146:149], v[194:197], v[28:31], v[146:149]
	v_mfma_f32_16x16x32_bf16 v[134:137], v[198:201], v[28:31], v[134:137]
	v_add_u32_e32 v28, v96, v218
	v_add_u32_e32 v29, v96, v223
	v_add_u32_e32 v30, v96, v222
	v_add_u32_e32 v31, v96, v128
	ds_read_b128 v[218:221], v28
	v_mfma_f32_16x16x32_bf16 v[154:157], v[186:189], v[202:205], v[154:157]
	v_mfma_f32_16x16x32_bf16 v[158:161], v[190:193], v[202:205], v[158:161]
	v_mfma_f32_16x16x32_bf16 v[162:165], v[194:197], v[202:205], v[162:165]
	v_mfma_f32_16x16x32_bf16 v[150:153], v[198:201], v[202:205], v[150:153]
	ds_read_b128 v[202:205], v29
	v_mfma_f32_16x16x32_bf16 v[170:173], v[186:189], v[206:209], v[170:173]
	v_mfma_f32_16x16x32_bf16 v[174:177], v[190:193], v[206:209], v[174:177]
	v_mfma_f32_16x16x32_bf16 v[178:181], v[194:197], v[206:209], v[178:181]
	v_mfma_f32_16x16x32_bf16 v[166:169], v[198:201], v[206:209], v[166:169]
	ds_read_b128 v[206:209], v30
	v_mfma_f32_16x16x32_bf16 v[214:217], v[186:189], v[210:213], v[214:217]
	v_mfma_f32_16x16x32_bf16 v[56:59], v[190:193], v[210:213], v[56:59]
	v_mfma_f32_16x16x32_bf16 v[64:67], v[194:197], v[210:213], v[64:67]
	v_mfma_f32_16x16x32_bf16 v[72:75], v[198:201], v[210:213], v[72:75]
	ds_read_b128 v[210:213], v31
	s_waitcnt lgkmcnt(0)
	v_mfma_f32_16x16x32_bf16 v[116:119], v[186:189], v[218:221], v[116:119]
	v_mfma_f32_16x16x32_bf16 v[120:123], v[190:193], v[218:221], v[120:123]
	v_mfma_f32_16x16x32_bf16 v[124:127], v[194:197], v[218:221], v[124:127]
	v_mfma_f32_16x16x32_bf16 v[112:115], v[198:201], v[218:221], v[112:115]
	v_mfma_f32_16x16x32_bf16 v[92:95], v[186:189], v[202:205], v[92:95]
	v_mfma_f32_16x16x32_bf16 v[100:103], v[190:193], v[202:205], v[100:103]
	v_mfma_f32_16x16x32_bf16 v[104:107], v[194:197], v[202:205], v[104:107]
	v_mfma_f32_16x16x32_bf16 v[108:111], v[198:201], v[202:205], v[108:111]
	v_mfma_f32_16x16x32_bf16 v[76:79], v[186:189], v[206:209], v[76:79]
	v_mfma_f32_16x16x32_bf16 v[80:83], v[190:193], v[206:209], v[80:83]
	v_mfma_f32_16x16x32_bf16 v[84:87], v[194:197], v[206:209], v[84:87]
	v_mfma_f32_16x16x32_bf16 v[88:91], v[198:201], v[206:209], v[88:91]
	v_mfma_f32_16x16x32_bf16 v[52:55], v[186:189], v[210:213], v[52:55]
	v_mfma_f32_16x16x32_bf16 v[60:63], v[190:193], v[210:213], v[60:63]
	v_mfma_f32_16x16x32_bf16 v[68:71], v[194:197], v[210:213], v[68:71]
	v_mfma_f32_16x16x32_bf16 v[182:185], v[198:201], v[210:213], v[182:185]
	ds_read_b128 v[186:189], v23 offset:1024
	ds_read_b128 v[190:193], v23 offset:3072
	ds_read_b128 v[194:197], v23 offset:5120
	ds_read_b128 v[202:205], v23 offset:7168
	ds_read_b128 v[198:201], v24 offset:1024
	ds_read_b128 v[206:209], v25 offset:1024
	ds_read_b128 v[210:213], v26 offset:1024
	ds_read_b128 v[218:221], v27 offset:1024
	s_waitcnt lgkmcnt(0)
	v_mfma_f32_16x16x32_bf16 v[138:141], v[186:189], v[198:201], v[138:141]
	v_mfma_f32_16x16x32_bf16 v[142:145], v[190:193], v[198:201], v[142:145]
	v_mfma_f32_16x16x32_bf16 v[146:149], v[194:197], v[198:201], v[146:149]
	v_mfma_f32_16x16x32_bf16 v[134:137], v[202:205], v[198:201], v[134:137]
	ds_read_b128 v[198:201], v28 offset:1024
	v_mfma_f32_16x16x32_bf16 v[154:157], v[186:189], v[206:209], v[154:157]
	v_mfma_f32_16x16x32_bf16 v[158:161], v[190:193], v[206:209], v[158:161]
	v_mfma_f32_16x16x32_bf16 v[162:165], v[194:197], v[206:209], v[162:165]
	v_mfma_f32_16x16x32_bf16 v[150:153], v[202:205], v[206:209], v[150:153]
	ds_read_b128 v[206:209], v29 offset:1024
	v_mfma_f32_16x16x32_bf16 v[170:173], v[186:189], v[210:213], v[170:173]
	v_mfma_f32_16x16x32_bf16 v[174:177], v[190:193], v[210:213], v[174:177]
	v_mfma_f32_16x16x32_bf16 v[178:181], v[194:197], v[210:213], v[178:181]
	v_mfma_f32_16x16x32_bf16 v[166:169], v[202:205], v[210:213], v[166:169]
	ds_read_b128 v[210:213], v30 offset:1024
	v_mfma_f32_16x16x32_bf16 v[214:217], v[186:189], v[218:221], v[214:217]
	v_mfma_f32_16x16x32_bf16 v[56:59], v[190:193], v[218:221], v[56:59]
	v_mfma_f32_16x16x32_bf16 v[64:67], v[194:197], v[218:221], v[64:67]
	v_mfma_f32_16x16x32_bf16 v[72:75], v[202:205], v[218:221], v[72:75]
	ds_read_b128 v[218:221], v31 offset:1024
	s_waitcnt lgkmcnt(0)
	v_mfma_f32_16x16x32_bf16 v[116:119], v[186:189], v[198:201], v[116:119]
	v_mfma_f32_16x16x32_bf16 v[120:123], v[190:193], v[198:201], v[120:123]
	v_mfma_f32_16x16x32_bf16 v[124:127], v[194:197], v[198:201], v[124:127]
	v_mfma_f32_16x16x32_bf16 v[112:115], v[202:205], v[198:201], v[112:115]
	v_mfma_f32_16x16x32_bf16 v[92:95], v[186:189], v[206:209], v[92:95]
	v_mfma_f32_16x16x32_bf16 v[100:103], v[190:193], v[206:209], v[100:103]
	v_mfma_f32_16x16x32_bf16 v[104:107], v[194:197], v[206:209], v[104:107]
	v_mfma_f32_16x16x32_bf16 v[108:111], v[202:205], v[206:209], v[108:111]
	v_mfma_f32_16x16x32_bf16 v[76:79], v[186:189], v[210:213], v[76:79]
	v_mfma_f32_16x16x32_bf16 v[80:83], v[190:193], v[210:213], v[80:83]
	v_mfma_f32_16x16x32_bf16 v[84:87], v[194:197], v[210:213], v[84:87]
	v_mfma_f32_16x16x32_bf16 v[88:91], v[202:205], v[210:213], v[88:91]
	v_mfma_f32_16x16x32_bf16 v[52:55], v[186:189], v[218:221], v[52:55]
	v_mfma_f32_16x16x32_bf16 v[60:63], v[190:193], v[218:221], v[60:63]
	v_mfma_f32_16x16x32_bf16 v[68:71], v[194:197], v[218:221], v[68:71]
	v_mfma_f32_16x16x32_bf16 v[182:185], v[202:205], v[218:221], v[182:185]
	s_mov_b32 m0, s53
	v_lshl_add_u64 v[96:97], v[2:3], 0, s[16:17]
	s_waitcnt vmcnt(0)
	s_waitcnt vmcnt(0)
	s_barrier
	global_load_lds_dwordx4 v[96:97], off
	v_lshl_add_u64 v[96:97], v[4:5], 0, s[16:17]
	s_mov_b32 m0, s0
	s_nop 0
	global_load_lds_dwordx4 v[96:97], off
	v_lshl_add_u64 v[96:97], v[6:7], 0, s[16:17]
	s_mov_b32 m0, s42
	s_nop 0
	global_load_lds_dwordx4 v[96:97], off
	v_lshl_add_u64 v[96:97], v[8:9], 0, s[16:17]
	s_mov_b32 m0, s43
	s_nop 0
	global_load_lds_dwordx4 v[96:97], off
	v_lshl_add_u64 v[96:97], v[10:11], 0, s[16:17]
	s_mov_b32 m0, s54
	s_nop 0
	global_load_lds_dwordx4 v[96:97], off
	v_lshl_add_u64 v[96:97], v[12:13], 0, s[16:17]
	s_mov_b32 m0, s55
	s_nop 0
	global_load_lds_dwordx4 v[96:97], off
	v_lshl_add_u64 v[96:97], v[14:15], 0, s[16:17]
	s_mov_b32 m0, s56
	s_nop 0
	global_load_lds_dwordx4 v[96:97], off
	v_lshl_add_u64 v[96:97], v[16:17], 0, s[16:17]
	s_mov_b32 m0, s57
	s_nop 0
	global_load_lds_dwordx4 v[96:97], off
	ds_read_b128 v[186:189], v18 offset:32768
	ds_read_b128 v[190:193], v18 offset:34816
	ds_read_b128 v[194:197], v18 offset:36864
	ds_read_b128 v[202:205], v18 offset:38912
	ds_read_b128 v[198:201], v32
	ds_read_b128 v[206:209], v33
	ds_read_b128 v[210:213], v34
	ds_read_b128 v[218:221], v35
	s_waitcnt lgkmcnt(0)
	v_mfma_f32_16x16x32_bf16 v[138:141], v[186:189], v[198:201], v[138:141]
	v_mfma_f32_16x16x32_bf16 v[142:145], v[190:193], v[198:201], v[142:145]
	v_mfma_f32_16x16x32_bf16 v[146:149], v[194:197], v[198:201], v[146:149]
	v_mfma_f32_16x16x32_bf16 v[134:137], v[202:205], v[198:201], v[134:137]
	ds_read_b128 v[198:201], v22
	v_mfma_f32_16x16x32_bf16 v[154:157], v[186:189], v[206:209], v[154:157]
	v_mfma_f32_16x16x32_bf16 v[158:161], v[190:193], v[206:209], v[158:161]
	v_mfma_f32_16x16x32_bf16 v[162:165], v[194:197], v[206:209], v[162:165]
	v_mfma_f32_16x16x32_bf16 v[150:153], v[202:205], v[206:209], v[150:153]
	ds_read_b128 v[206:209], v21
	v_mfma_f32_16x16x32_bf16 v[170:173], v[186:189], v[210:213], v[170:173]
	v_mfma_f32_16x16x32_bf16 v[174:177], v[190:193], v[210:213], v[174:177]
	v_mfma_f32_16x16x32_bf16 v[178:181], v[194:197], v[210:213], v[178:181]
	v_mfma_f32_16x16x32_bf16 v[166:169], v[202:205], v[210:213], v[166:169]
	ds_read_b128 v[210:213], v20
	v_mfma_f32_16x16x32_bf16 v[214:217], v[186:189], v[218:221], v[214:217]
	v_mfma_f32_16x16x32_bf16 v[56:59], v[190:193], v[218:221], v[56:59]
	v_mfma_f32_16x16x32_bf16 v[64:67], v[194:197], v[218:221], v[64:67]
	v_mfma_f32_16x16x32_bf16 v[72:75], v[202:205], v[218:221], v[72:75]
	ds_read_b128 v[218:221], v19
	s_waitcnt lgkmcnt(0)
	v_mfma_f32_16x16x32_bf16 v[116:119], v[186:189], v[198:201], v[116:119]
	v_mfma_f32_16x16x32_bf16 v[120:123], v[190:193], v[198:201], v[120:123]
	v_mfma_f32_16x16x32_bf16 v[124:127], v[194:197], v[198:201], v[124:127]
	v_mfma_f32_16x16x32_bf16 v[112:115], v[202:205], v[198:201], v[112:115]
	v_mfma_f32_16x16x32_bf16 v[92:95], v[186:189], v[206:209], v[92:95]
	v_mfma_f32_16x16x32_bf16 v[100:103], v[190:193], v[206:209], v[100:103]
	v_mfma_f32_16x16x32_bf16 v[104:107], v[194:197], v[206:209], v[104:107]
	v_mfma_f32_16x16x32_bf16 v[108:111], v[202:205], v[206:209], v[108:111]
	v_mfma_f32_16x16x32_bf16 v[76:79], v[186:189], v[210:213], v[76:79]
	v_mfma_f32_16x16x32_bf16 v[80:83], v[190:193], v[210:213], v[80:83]
	v_mfma_f32_16x16x32_bf16 v[84:87], v[194:197], v[210:213], v[84:87]
	v_mfma_f32_16x16x32_bf16 v[88:91], v[202:205], v[210:213], v[88:91]
	v_mfma_f32_16x16x32_bf16 v[52:55], v[186:189], v[218:221], v[52:55]
	v_mfma_f32_16x16x32_bf16 v[60:63], v[190:193], v[218:221], v[60:63]
	v_mfma_f32_16x16x32_bf16 v[68:71], v[194:197], v[218:221], v[68:71]
	v_mfma_f32_16x16x32_bf16 v[182:185], v[202:205], v[218:221], v[182:185]
	ds_read_b128 v[186:189], v18 offset:33792
	ds_read_b128 v[190:193], v18 offset:35840
	ds_read_b128 v[194:197], v18 offset:37888
	ds_read_b128 v[202:205], v18 offset:39936
	ds_read_b128 v[198:201], v32 offset:1024
	ds_read_b128 v[206:209], v33 offset:1024
	ds_read_b128 v[210:213], v34 offset:1024
	ds_read_b128 v[218:221], v35 offset:1024
	s_waitcnt lgkmcnt(0)
	v_mfma_f32_16x16x32_bf16 v[138:141], v[186:189], v[198:201], v[138:141]
	v_mfma_f32_16x16x32_bf16 v[142:145], v[190:193], v[198:201], v[142:145]
	v_mfma_f32_16x16x32_bf16 v[146:149], v[194:197], v[198:201], v[146:149]
	v_mfma_f32_16x16x32_bf16 v[134:137], v[202:205], v[198:201], v[134:137]
	ds_read_b128 v[198:201], v22 offset:1024
	v_mfma_f32_16x16x32_bf16 v[154:157], v[186:189], v[206:209], v[154:157]
	v_mfma_f32_16x16x32_bf16 v[158:161], v[190:193], v[206:209], v[158:161]
	v_mfma_f32_16x16x32_bf16 v[162:165], v[194:197], v[206:209], v[162:165]
	v_mfma_f32_16x16x32_bf16 v[150:153], v[202:205], v[206:209], v[150:153]
	ds_read_b128 v[206:209], v21 offset:1024
	v_mfma_f32_16x16x32_bf16 v[170:173], v[186:189], v[210:213], v[170:173]
	v_mfma_f32_16x16x32_bf16 v[174:177], v[190:193], v[210:213], v[174:177]
	v_mfma_f32_16x16x32_bf16 v[178:181], v[194:197], v[210:213], v[178:181]
	v_mfma_f32_16x16x32_bf16 v[166:169], v[202:205], v[210:213], v[166:169]
	ds_read_b128 v[210:213], v20 offset:1024
	v_mfma_f32_16x16x32_bf16 v[214:217], v[186:189], v[218:221], v[214:217]
	v_mfma_f32_16x16x32_bf16 v[56:59], v[190:193], v[218:221], v[56:59]
	v_mfma_f32_16x16x32_bf16 v[64:67], v[194:197], v[218:221], v[64:67]
	v_mfma_f32_16x16x32_bf16 v[72:75], v[202:205], v[218:221], v[72:75]
	ds_read_b128 v[218:221], v19 offset:1024
	s_waitcnt lgkmcnt(0)
	v_mfma_f32_16x16x32_bf16 v[116:119], v[186:189], v[198:201], v[116:119]
	v_mfma_f32_16x16x32_bf16 v[120:123], v[190:193], v[198:201], v[120:123]
	v_mfma_f32_16x16x32_bf16 v[124:127], v[194:197], v[198:201], v[124:127]
	v_mfma_f32_16x16x32_bf16 v[112:115], v[202:205], v[198:201], v[112:115]
	v_mfma_f32_16x16x32_bf16 v[92:95], v[186:189], v[206:209], v[92:95]
	v_mfma_f32_16x16x32_bf16 v[100:103], v[190:193], v[206:209], v[100:103]
	v_mfma_f32_16x16x32_bf16 v[104:107], v[194:197], v[206:209], v[104:107]
	v_mfma_f32_16x16x32_bf16 v[108:111], v[202:205], v[206:209], v[108:111]
	v_mfma_f32_16x16x32_bf16 v[76:79], v[186:189], v[210:213], v[76:79]
	v_mfma_f32_16x16x32_bf16 v[80:83], v[190:193], v[210:213], v[80:83]
	v_mfma_f32_16x16x32_bf16 v[84:87], v[194:197], v[210:213], v[84:87]
	v_mfma_f32_16x16x32_bf16 v[88:91], v[202:205], v[210:213], v[88:91]
	v_mfma_f32_16x16x32_bf16 v[52:55], v[186:189], v[218:221], v[52:55]
	v_mfma_f32_16x16x32_bf16 v[60:63], v[190:193], v[218:221], v[60:63]
	v_mfma_f32_16x16x32_bf16 v[68:71], v[194:197], v[218:221], v[68:71]
	v_mfma_f32_16x16x32_bf16 v[182:185], v[202:205], v[218:221], v[182:185]
	v_readfirstlane_b32 s56, v45
	v_lshl_add_u64 v[96:97], v[2:3], 0, s[18:19]
	s_mov_b32 m0, s56
	v_readfirstlane_b32 s0, v44
	s_waitcnt vmcnt(0)
	s_waitcnt vmcnt(0)
	s_barrier
	global_load_lds_dwordx4 v[96:97], off
	v_lshl_add_u64 v[96:97], v[4:5], 0, s[18:19]
	s_mov_b32 m0, s0
	v_readfirstlane_b32 s42, v46
	global_load_lds_dwordx4 v[96:97], off
	v_lshl_add_u64 v[44:45], v[6:7], 0, s[18:19]
	s_mov_b32 m0, s42
	v_readfirstlane_b32 s43, v47
	global_load_lds_dwordx4 v[44:45], off
	v_lshl_add_u64 v[44:45], v[8:9], 0, s[18:19]
	s_mov_b32 m0, s43
	v_readfirstlane_b32 s53, v48
	global_load_lds_dwordx4 v[44:45], off
	v_lshl_add_u64 v[44:45], v[10:11], 0, s[18:19]
	s_mov_b32 m0, s53
	v_readfirstlane_b32 s54, v49
	global_load_lds_dwordx4 v[44:45], off
	v_lshl_add_u64 v[44:45], v[12:13], 0, s[18:19]
	s_mov_b32 m0, s54
	v_readfirstlane_b32 s55, v50
	global_load_lds_dwordx4 v[44:45], off
	v_lshl_add_u64 v[44:45], v[14:15], 0, s[18:19]
	s_mov_b32 m0, s55
	v_readfirstlane_b32 s57, v51
	global_load_lds_dwordx4 v[44:45], off
	v_lshl_add_u64 v[44:45], v[16:17], 0, s[18:19]
	s_mov_b32 m0, s57
	s_nop 0
	global_load_lds_dwordx4 v[44:45], off
	ds_read_b128 v[44:47], v23
	ds_read_b128 v[48:51], v23 offset:2048
	ds_read_b128 v[186:189], v23 offset:4096
	ds_read_b128 v[194:197], v23 offset:6144
	ds_read_b128 v[190:193], v24
	ds_read_b128 v[198:201], v25
	ds_read_b128 v[202:205], v26
	ds_read_b128 v[206:209], v27
	s_waitcnt lgkmcnt(0)
	v_mfma_f32_16x16x32_bf16 v[138:141], v[44:47], v[190:193], v[138:141]
	v_mfma_f32_16x16x32_bf16 v[142:145], v[48:51], v[190:193], v[142:145]
	v_mfma_f32_16x16x32_bf16 v[146:149], v[186:189], v[190:193], v[146:149]
	v_mfma_f32_16x16x32_bf16 v[134:137], v[194:197], v[190:193], v[134:137]
	ds_read_b128 v[190:193], v28
	v_mfma_f32_16x16x32_bf16 v[154:157], v[44:47], v[198:201], v[154:157]
	v_mfma_f32_16x16x32_bf16 v[158:161], v[48:51], v[198:201], v[158:161]
	v_mfma_f32_16x16x32_bf16 v[162:165], v[186:189], v[198:201], v[162:165]
	v_mfma_f32_16x16x32_bf16 v[150:153], v[194:197], v[198:201], v[150:153]
	ds_read_b128 v[198:201], v29
	v_mfma_f32_16x16x32_bf16 v[170:173], v[44:47], v[202:205], v[170:173]
	v_mfma_f32_16x16x32_bf16 v[174:177], v[48:51], v[202:205], v[174:177]
	v_mfma_f32_16x16x32_bf16 v[178:181], v[186:189], v[202:205], v[178:181]
	v_mfma_f32_16x16x32_bf16 v[166:169], v[194:197], v[202:205], v[166:169]
	ds_read_b128 v[202:205], v30
	v_mfma_f32_16x16x32_bf16 v[210:213], v[44:47], v[206:209], v[214:217]
	v_mfma_f32_16x16x32_bf16 v[56:59], v[48:51], v[206:209], v[56:59]
	v_mfma_f32_16x16x32_bf16 v[64:67], v[186:189], v[206:209], v[64:67]
	v_mfma_f32_16x16x32_bf16 v[72:75], v[194:197], v[206:209], v[72:75]
	ds_read_b128 v[206:209], v31
	s_waitcnt lgkmcnt(0)
	v_mfma_f32_16x16x32_bf16 v[116:119], v[44:47], v[190:193], v[116:119]
	v_mfma_f32_16x16x32_bf16 v[120:123], v[48:51], v[190:193], v[120:123]
	v_mfma_f32_16x16x32_bf16 v[124:127], v[186:189], v[190:193], v[124:127]
	v_mfma_f32_16x16x32_bf16 v[112:115], v[194:197], v[190:193], v[112:115]
	v_mfma_f32_16x16x32_bf16 v[92:95], v[44:47], v[198:201], v[92:95]
	v_mfma_f32_16x16x32_bf16 v[100:103], v[48:51], v[198:201], v[100:103]
	v_mfma_f32_16x16x32_bf16 v[104:107], v[186:189], v[198:201], v[104:107]
	v_mfma_f32_16x16x32_bf16 v[108:111], v[194:197], v[198:201], v[108:111]
	v_mfma_f32_16x16x32_bf16 v[76:79], v[44:47], v[202:205], v[76:79]
	v_mfma_f32_16x16x32_bf16 v[80:83], v[48:51], v[202:205], v[80:83]
	v_mfma_f32_16x16x32_bf16 v[84:87], v[186:189], v[202:205], v[84:87]
	v_mfma_f32_16x16x32_bf16 v[88:91], v[194:197], v[202:205], v[88:91]
	v_mfma_f32_16x16x32_bf16 v[44:47], v[44:47], v[206:209], v[52:55]
	v_mfma_f32_16x16x32_bf16 v[48:51], v[48:51], v[206:209], v[60:63]
	v_mfma_f32_16x16x32_bf16 v[52:55], v[186:189], v[206:209], v[68:71]
	v_mfma_f32_16x16x32_bf16 v[60:63], v[194:197], v[206:209], v[182:185]
	s_nop 1
	ds_read_b128 v[68:71], v23 offset:1024
	ds_read_b128 v[182:185], v23 offset:3072
	ds_read_b128 v[186:189], v23 offset:5120
	ds_read_b128 v[194:197], v23 offset:7168
	ds_read_b128 v[190:193], v24 offset:1024
	ds_read_b128 v[198:201], v25 offset:1024
	ds_read_b128 v[202:205], v26 offset:1024
	ds_read_b128 v[206:209], v27 offset:1024
	s_waitcnt lgkmcnt(0)
	v_mfma_f32_16x16x32_bf16 v[138:141], v[68:71], v[190:193], v[138:141]
	v_mfma_f32_16x16x32_bf16 v[142:145], v[182:185], v[190:193], v[142:145]
	v_mfma_f32_16x16x32_bf16 v[146:149], v[186:189], v[190:193], v[146:149]
	v_mfma_f32_16x16x32_bf16 v[134:137], v[194:197], v[190:193], v[134:137]
	ds_read_b128 v[190:193], v28 offset:1024
	v_mfma_f32_16x16x32_bf16 v[154:157], v[68:71], v[198:201], v[154:157]
	v_mfma_f32_16x16x32_bf16 v[158:161], v[182:185], v[198:201], v[158:161]
	v_mfma_f32_16x16x32_bf16 v[162:165], v[186:189], v[198:201], v[162:165]
	v_mfma_f32_16x16x32_bf16 v[150:153], v[194:197], v[198:201], v[150:153]
	ds_read_b128 v[198:201], v29 offset:1024
	v_mfma_f32_16x16x32_bf16 v[170:173], v[68:71], v[202:205], v[170:173]
	v_mfma_f32_16x16x32_bf16 v[174:177], v[182:185], v[202:205], v[174:177]
	v_mfma_f32_16x16x32_bf16 v[178:181], v[186:189], v[202:205], v[178:181]
	v_mfma_f32_16x16x32_bf16 v[166:169], v[194:197], v[202:205], v[166:169]
	ds_read_b128 v[202:205], v30 offset:1024
	v_mfma_f32_16x16x32_bf16 v[210:213], v[68:71], v[206:209], v[210:213]
	v_mfma_f32_16x16x32_bf16 v[56:59], v[182:185], v[206:209], v[56:59]
	v_mfma_f32_16x16x32_bf16 v[64:67], v[186:189], v[206:209], v[64:67]
	v_mfma_f32_16x16x32_bf16 v[72:75], v[194:197], v[206:209], v[72:75]
	ds_read_b128 v[206:209], v31 offset:1024
	s_waitcnt lgkmcnt(0)
	v_mfma_f32_16x16x32_bf16 v[116:119], v[68:71], v[190:193], v[116:119]
	v_mfma_f32_16x16x32_bf16 v[120:123], v[182:185], v[190:193], v[120:123]
	v_mfma_f32_16x16x32_bf16 v[124:127], v[186:189], v[190:193], v[124:127]
	v_mfma_f32_16x16x32_bf16 v[112:115], v[194:197], v[190:193], v[112:115]
	v_mfma_f32_16x16x32_bf16 v[92:95], v[68:71], v[198:201], v[92:95]
	v_mfma_f32_16x16x32_bf16 v[100:103], v[182:185], v[198:201], v[100:103]
	v_mfma_f32_16x16x32_bf16 v[104:107], v[186:189], v[198:201], v[104:107]
	v_mfma_f32_16x16x32_bf16 v[108:111], v[194:197], v[198:201], v[108:111]
	v_mfma_f32_16x16x32_bf16 v[76:79], v[68:71], v[202:205], v[76:79]
	v_mfma_f32_16x16x32_bf16 v[80:83], v[182:185], v[202:205], v[80:83]
	v_mfma_f32_16x16x32_bf16 v[84:87], v[186:189], v[202:205], v[84:87]
	v_mfma_f32_16x16x32_bf16 v[88:91], v[194:197], v[202:205], v[88:91]
	v_mfma_f32_16x16x32_bf16 v[44:47], v[68:71], v[206:209], v[44:47]
	v_mfma_f32_16x16x32_bf16 v[48:51], v[182:185], v[206:209], v[48:51]
	v_mfma_f32_16x16x32_bf16 v[52:55], v[186:189], v[206:209], v[52:55]
	v_mfma_f32_16x16x32_bf16 v[60:63], v[194:197], v[206:209], v[60:63]
	v_readfirstlane_b32 s64, v37
	v_lshl_add_u64 v[68:69], v[2:3], 0, s[20:21]
	s_mov_b32 m0, s64
	v_readfirstlane_b32 s58, v36
	s_waitcnt vmcnt(0)
	s_waitcnt vmcnt(0)
	s_barrier
	global_load_lds_dwordx4 v[68:69], off
	v_lshl_add_u64 v[68:69], v[4:5], 0, s[20:21]
	s_mov_b32 m0, s58
	v_readfirstlane_b32 s59, v38
	global_load_lds_dwordx4 v[68:69], off
	v_lshl_add_u64 v[36:37], v[6:7], 0, s[20:21]
	s_mov_b32 m0, s59
	v_readfirstlane_b32 s60, v39
	global_load_lds_dwordx4 v[36:37], off
	v_lshl_add_u64 v[36:37], v[8:9], 0, s[20:21]
	s_mov_b32 m0, s60
	v_readfirstlane_b32 s61, v40
	global_load_lds_dwordx4 v[36:37], off
	v_lshl_add_u64 v[36:37], v[10:11], 0, s[20:21]
	s_mov_b32 m0, s61
	v_readfirstlane_b32 s62, v41
	global_load_lds_dwordx4 v[36:37], off
	v_lshl_add_u64 v[36:37], v[12:13], 0, s[20:21]
	s_mov_b32 m0, s62
	v_readfirstlane_b32 s63, v42
	global_load_lds_dwordx4 v[36:37], off
	v_lshl_add_u64 v[36:37], v[14:15], 0, s[20:21]
	s_mov_b32 m0, s63
	v_readfirstlane_b32 s65, v43
	global_load_lds_dwordx4 v[36:37], off
	v_lshl_add_u64 v[36:37], v[16:17], 0, s[20:21]
	s_mov_b32 m0, s65
	s_nop 0
	global_load_lds_dwordx4 v[36:37], off
	ds_read_b128 v[36:39], v18 offset:32768
	ds_read_b128 v[40:43], v18 offset:34816
	ds_read_b128 v[68:71], v18 offset:36864
	ds_read_b128 v[186:189], v18 offset:38912
	ds_read_b128 v[182:185], v32
	ds_read_b128 v[190:193], v33
	ds_read_b128 v[194:197], v34
	ds_read_b128 v[198:201], v35
	s_waitcnt lgkmcnt(0)
	v_mfma_f32_16x16x32_bf16 v[138:141], v[36:39], v[182:185], v[138:141]
	v_mfma_f32_16x16x32_bf16 v[142:145], v[40:43], v[182:185], v[142:145]
	v_mfma_f32_16x16x32_bf16 v[146:149], v[68:71], v[182:185], v[146:149]
	v_mfma_f32_16x16x32_bf16 v[134:137], v[186:189], v[182:185], v[134:137]
	ds_read_b128 v[182:185], v22
	v_mfma_f32_16x16x32_bf16 v[154:157], v[36:39], v[190:193], v[154:157]
	v_mfma_f32_16x16x32_bf16 v[158:161], v[40:43], v[190:193], v[158:161]
	v_mfma_f32_16x16x32_bf16 v[162:165], v[68:71], v[190:193], v[162:165]
	v_mfma_f32_16x16x32_bf16 v[150:153], v[186:189], v[190:193], v[150:153]
	ds_read_b128 v[190:193], v21
	v_mfma_f32_16x16x32_bf16 v[170:173], v[36:39], v[194:197], v[170:173]
	v_mfma_f32_16x16x32_bf16 v[174:177], v[40:43], v[194:197], v[174:177]
	v_mfma_f32_16x16x32_bf16 v[178:181], v[68:71], v[194:197], v[178:181]
	v_mfma_f32_16x16x32_bf16 v[166:169], v[186:189], v[194:197], v[166:169]
	ds_read_b128 v[194:197], v20
	v_mfma_f32_16x16x32_bf16 v[202:205], v[36:39], v[198:201], v[210:213]
	v_mfma_f32_16x16x32_bf16 v[56:59], v[40:43], v[198:201], v[56:59]
	v_mfma_f32_16x16x32_bf16 v[64:67], v[68:71], v[198:201], v[64:67]
	v_mfma_f32_16x16x32_bf16 v[72:75], v[186:189], v[198:201], v[72:75]
	ds_read_b128 v[198:201], v19
	s_waitcnt lgkmcnt(0)
	v_mfma_f32_16x16x32_bf16 v[116:119], v[36:39], v[182:185], v[116:119]
	v_mfma_f32_16x16x32_bf16 v[120:123], v[40:43], v[182:185], v[120:123]
	v_mfma_f32_16x16x32_bf16 v[124:127], v[68:71], v[182:185], v[124:127]
	v_mfma_f32_16x16x32_bf16 v[112:115], v[186:189], v[182:185], v[112:115]
	v_mfma_f32_16x16x32_bf16 v[92:95], v[36:39], v[190:193], v[92:95]
	v_mfma_f32_16x16x32_bf16 v[100:103], v[40:43], v[190:193], v[100:103]
	v_mfma_f32_16x16x32_bf16 v[104:107], v[68:71], v[190:193], v[104:107]
	v_mfma_f32_16x16x32_bf16 v[108:111], v[186:189], v[190:193], v[108:111]
	v_mfma_f32_16x16x32_bf16 v[76:79], v[36:39], v[194:197], v[76:79]
	v_mfma_f32_16x16x32_bf16 v[80:83], v[40:43], v[194:197], v[80:83]
	v_mfma_f32_16x16x32_bf16 v[84:87], v[68:71], v[194:197], v[84:87]
	v_mfma_f32_16x16x32_bf16 v[88:91], v[186:189], v[194:197], v[88:91]
	v_mfma_f32_16x16x32_bf16 v[36:39], v[36:39], v[198:201], v[44:47]
	v_mfma_f32_16x16x32_bf16 v[40:43], v[40:43], v[198:201], v[48:51]
	v_mfma_f32_16x16x32_bf16 v[44:47], v[68:71], v[198:201], v[52:55]
	v_mfma_f32_16x16x32_bf16 v[48:51], v[186:189], v[198:201], v[60:63]
	s_nop 1
	ds_read_b128 v[52:55], v18 offset:33792
	ds_read_b128 v[60:63], v18 offset:35840
	ds_read_b128 v[68:71], v18 offset:37888
	ds_read_b128 v[186:189], v18 offset:39936
	ds_read_b128 v[182:185], v32 offset:1024
	ds_read_b128 v[190:193], v33 offset:1024
	ds_read_b128 v[194:197], v34 offset:1024
	ds_read_b128 v[198:201], v35 offset:1024
	s_waitcnt lgkmcnt(0)
	v_mfma_f32_16x16x32_bf16 v[138:141], v[52:55], v[182:185], v[138:141]
	v_mfma_f32_16x16x32_bf16 v[142:145], v[60:63], v[182:185], v[142:145]
	v_mfma_f32_16x16x32_bf16 v[146:149], v[68:71], v[182:185], v[146:149]
	v_mfma_f32_16x16x32_bf16 v[134:137], v[186:189], v[182:185], v[134:137]
	ds_read_b128 v[182:185], v22 offset:1024
	v_mfma_f32_16x16x32_bf16 v[154:157], v[52:55], v[190:193], v[154:157]
	v_mfma_f32_16x16x32_bf16 v[158:161], v[60:63], v[190:193], v[158:161]
	v_mfma_f32_16x16x32_bf16 v[162:165], v[68:71], v[190:193], v[162:165]
	v_mfma_f32_16x16x32_bf16 v[150:153], v[186:189], v[190:193], v[150:153]
	ds_read_b128 v[190:193], v21 offset:1024
	v_mfma_f32_16x16x32_bf16 v[170:173], v[52:55], v[194:197], v[170:173]
	v_mfma_f32_16x16x32_bf16 v[174:177], v[60:63], v[194:197], v[174:177]
	v_mfma_f32_16x16x32_bf16 v[178:181], v[68:71], v[194:197], v[178:181]
	v_mfma_f32_16x16x32_bf16 v[166:169], v[186:189], v[194:197], v[166:169]
	ds_read_b128 v[194:197], v20 offset:1024
	v_mfma_f32_16x16x32_bf16 v[202:205], v[52:55], v[198:201], v[202:205]
	v_mfma_f32_16x16x32_bf16 v[56:59], v[60:63], v[198:201], v[56:59]
	v_mfma_f32_16x16x32_bf16 v[64:67], v[68:71], v[198:201], v[64:67]
	v_mfma_f32_16x16x32_bf16 v[72:75], v[186:189], v[198:201], v[72:75]
	ds_read_b128 v[198:201], v19 offset:1024
	s_waitcnt lgkmcnt(0)
	v_mfma_f32_16x16x32_bf16 v[116:119], v[52:55], v[182:185], v[116:119]
	v_mfma_f32_16x16x32_bf16 v[120:123], v[60:63], v[182:185], v[120:123]
	v_mfma_f32_16x16x32_bf16 v[124:127], v[68:71], v[182:185], v[124:127]
	v_mfma_f32_16x16x32_bf16 v[112:115], v[186:189], v[182:185], v[112:115]
	v_mfma_f32_16x16x32_bf16 v[92:95], v[52:55], v[190:193], v[92:95]
	v_mfma_f32_16x16x32_bf16 v[100:103], v[60:63], v[190:193], v[100:103]
	v_mfma_f32_16x16x32_bf16 v[104:107], v[68:71], v[190:193], v[104:107]
	v_mfma_f32_16x16x32_bf16 v[108:111], v[186:189], v[190:193], v[108:111]
	v_mfma_f32_16x16x32_bf16 v[76:79], v[52:55], v[194:197], v[76:79]
	v_mfma_f32_16x16x32_bf16 v[80:83], v[60:63], v[194:197], v[80:83]
	v_mfma_f32_16x16x32_bf16 v[84:87], v[68:71], v[194:197], v[84:87]
	v_mfma_f32_16x16x32_bf16 v[88:91], v[186:189], v[194:197], v[88:91]
	v_mfma_f32_16x16x32_bf16 v[36:39], v[52:55], v[198:201], v[36:39]
	v_mfma_f32_16x16x32_bf16 v[40:43], v[60:63], v[198:201], v[40:43]
	v_mfma_f32_16x16x32_bf16 v[44:47], v[68:71], v[198:201], v[44:47]
	v_mfma_f32_16x16x32_bf16 v[48:51], v[186:189], v[198:201], v[48:51]
	s_mov_b32 m0, s56
	v_lshl_add_u64 v[52:53], v[2:3], 0, s[22:23]
	s_waitcnt vmcnt(0)
	s_waitcnt vmcnt(0)
	s_barrier
	global_load_lds_dwordx4 v[52:53], off
	v_lshl_add_u64 v[52:53], v[4:5], 0, s[22:23]
	s_mov_b32 m0, s0
	s_nop 0
	global_load_lds_dwordx4 v[52:53], off
	v_lshl_add_u64 v[52:53], v[6:7], 0, s[22:23]
	s_mov_b32 m0, s42
	s_nop 0
	global_load_lds_dwordx4 v[52:53], off
	v_lshl_add_u64 v[52:53], v[8:9], 0, s[22:23]
	s_mov_b32 m0, s43
	s_nop 0
	global_load_lds_dwordx4 v[52:53], off
	v_lshl_add_u64 v[52:53], v[10:11], 0, s[22:23]
	s_mov_b32 m0, s53
	s_nop 0
	global_load_lds_dwordx4 v[52:53], off
	v_lshl_add_u64 v[52:53], v[12:13], 0, s[22:23]
	s_mov_b32 m0, s54
	s_nop 0
	global_load_lds_dwordx4 v[52:53], off
	v_lshl_add_u64 v[52:53], v[14:15], 0, s[22:23]
	s_mov_b32 m0, s55
	s_nop 0
	global_load_lds_dwordx4 v[52:53], off
	v_lshl_add_u64 v[52:53], v[16:17], 0, s[22:23]
	s_mov_b32 m0, s57
	s_nop 0
	global_load_lds_dwordx4 v[52:53], off
	ds_read_b128 v[52:55], v23
	ds_read_b128 v[60:63], v23 offset:2048
	ds_read_b128 v[68:71], v23 offset:4096
	ds_read_b128 v[186:189], v23 offset:6144
	ds_read_b128 v[182:185], v24
	ds_read_b128 v[190:193], v25
	ds_read_b128 v[194:197], v26
	ds_read_b128 v[198:201], v27
	s_waitcnt lgkmcnt(0)
	v_mfma_f32_16x16x32_bf16 v[138:141], v[52:55], v[182:185], v[138:141]
	v_mfma_f32_16x16x32_bf16 v[142:145], v[60:63], v[182:185], v[142:145]
	v_mfma_f32_16x16x32_bf16 v[146:149], v[68:71], v[182:185], v[146:149]
	v_mfma_f32_16x16x32_bf16 v[134:137], v[186:189], v[182:185], v[134:137]
	ds_read_b128 v[182:185], v28
	v_mfma_f32_16x16x32_bf16 v[154:157], v[52:55], v[190:193], v[154:157]
	v_mfma_f32_16x16x32_bf16 v[158:161], v[60:63], v[190:193], v[158:161]
	v_mfma_f32_16x16x32_bf16 v[162:165], v[68:71], v[190:193], v[162:165]
	v_mfma_f32_16x16x32_bf16 v[150:153], v[186:189], v[190:193], v[150:153]
	ds_read_b128 v[190:193], v29
	v_mfma_f32_16x16x32_bf16 v[170:173], v[52:55], v[194:197], v[170:173]
	v_mfma_f32_16x16x32_bf16 v[174:177], v[60:63], v[194:197], v[174:177]
	v_mfma_f32_16x16x32_bf16 v[178:181], v[68:71], v[194:197], v[178:181]
	v_mfma_f32_16x16x32_bf16 v[166:169], v[186:189], v[194:197], v[166:169]
	ds_read_b128 v[194:197], v30
	v_mfma_f32_16x16x32_bf16 v[202:205], v[52:55], v[198:201], v[202:205]
	v_mfma_f32_16x16x32_bf16 v[56:59], v[60:63], v[198:201], v[56:59]
	v_mfma_f32_16x16x32_bf16 v[64:67], v[68:71], v[198:201], v[64:67]
	v_mfma_f32_16x16x32_bf16 v[72:75], v[186:189], v[198:201], v[72:75]
	ds_read_b128 v[198:201], v31
	s_waitcnt lgkmcnt(0)
	v_mfma_f32_16x16x32_bf16 v[116:119], v[52:55], v[182:185], v[116:119]
	v_mfma_f32_16x16x32_bf16 v[120:123], v[60:63], v[182:185], v[120:123]
	v_mfma_f32_16x16x32_bf16 v[124:127], v[68:71], v[182:185], v[124:127]
	v_mfma_f32_16x16x32_bf16 v[112:115], v[186:189], v[182:185], v[112:115]
	v_mfma_f32_16x16x32_bf16 v[92:95], v[52:55], v[190:193], v[92:95]
	v_mfma_f32_16x16x32_bf16 v[100:103], v[60:63], v[190:193], v[100:103]
	v_mfma_f32_16x16x32_bf16 v[104:107], v[68:71], v[190:193], v[104:107]
	v_mfma_f32_16x16x32_bf16 v[108:111], v[186:189], v[190:193], v[108:111]
	v_mfma_f32_16x16x32_bf16 v[76:79], v[52:55], v[194:197], v[76:79]
	v_mfma_f32_16x16x32_bf16 v[80:83], v[60:63], v[194:197], v[80:83]
	v_mfma_f32_16x16x32_bf16 v[84:87], v[68:71], v[194:197], v[84:87]
	v_mfma_f32_16x16x32_bf16 v[88:91], v[186:189], v[194:197], v[88:91]
	v_mfma_f32_16x16x32_bf16 v[36:39], v[52:55], v[198:201], v[36:39]
	v_mfma_f32_16x16x32_bf16 v[40:43], v[60:63], v[198:201], v[40:43]
	v_mfma_f32_16x16x32_bf16 v[44:47], v[68:71], v[198:201], v[44:47]
	v_mfma_f32_16x16x32_bf16 v[48:51], v[186:189], v[198:201], v[48:51]
	ds_read_b128 v[52:55], v23 offset:1024
	ds_read_b128 v[60:63], v23 offset:3072
	ds_read_b128 v[68:71], v23 offset:5120
	ds_read_b128 v[186:189], v23 offset:7168
	ds_read_b128 v[182:185], v24 offset:1024
	ds_read_b128 v[190:193], v25 offset:1024
	ds_read_b128 v[194:197], v26 offset:1024
	ds_read_b128 v[198:201], v27 offset:1024
	s_waitcnt lgkmcnt(0)
	v_mfma_f32_16x16x32_bf16 v[138:141], v[52:55], v[182:185], v[138:141]
	v_mfma_f32_16x16x32_bf16 v[142:145], v[60:63], v[182:185], v[142:145]
	v_mfma_f32_16x16x32_bf16 v[146:149], v[68:71], v[182:185], v[146:149]
	v_mfma_f32_16x16x32_bf16 v[134:137], v[186:189], v[182:185], v[134:137]
	ds_read_b128 v[182:185], v28 offset:1024
	v_mfma_f32_16x16x32_bf16 v[154:157], v[52:55], v[190:193], v[154:157]
	v_mfma_f32_16x16x32_bf16 v[158:161], v[60:63], v[190:193], v[158:161]
	v_mfma_f32_16x16x32_bf16 v[162:165], v[68:71], v[190:193], v[162:165]
	v_mfma_f32_16x16x32_bf16 v[150:153], v[186:189], v[190:193], v[150:153]
	ds_read_b128 v[190:193], v29 offset:1024
	v_mfma_f32_16x16x32_bf16 v[170:173], v[52:55], v[194:197], v[170:173]
	v_mfma_f32_16x16x32_bf16 v[174:177], v[60:63], v[194:197], v[174:177]
	v_mfma_f32_16x16x32_bf16 v[178:181], v[68:71], v[194:197], v[178:181]
	v_mfma_f32_16x16x32_bf16 v[166:169], v[186:189], v[194:197], v[166:169]
	ds_read_b128 v[194:197], v30 offset:1024
	v_mfma_f32_16x16x32_bf16 v[202:205], v[52:55], v[198:201], v[202:205]
	v_mfma_f32_16x16x32_bf16 v[56:59], v[60:63], v[198:201], v[56:59]
	v_mfma_f32_16x16x32_bf16 v[64:67], v[68:71], v[198:201], v[64:67]
	v_mfma_f32_16x16x32_bf16 v[72:75], v[186:189], v[198:201], v[72:75]
	ds_read_b128 v[198:201], v31 offset:1024
	s_waitcnt lgkmcnt(0)
	v_mfma_f32_16x16x32_bf16 v[116:119], v[52:55], v[182:185], v[116:119]
	v_mfma_f32_16x16x32_bf16 v[120:123], v[60:63], v[182:185], v[120:123]
	v_mfma_f32_16x16x32_bf16 v[124:127], v[68:71], v[182:185], v[124:127]
	v_mfma_f32_16x16x32_bf16 v[112:115], v[186:189], v[182:185], v[112:115]
	v_mfma_f32_16x16x32_bf16 v[92:95], v[52:55], v[190:193], v[92:95]
	v_mfma_f32_16x16x32_bf16 v[100:103], v[60:63], v[190:193], v[100:103]
	v_mfma_f32_16x16x32_bf16 v[104:107], v[68:71], v[190:193], v[104:107]
	v_mfma_f32_16x16x32_bf16 v[108:111], v[186:189], v[190:193], v[108:111]
	v_mfma_f32_16x16x32_bf16 v[76:79], v[52:55], v[194:197], v[76:79]
	v_mfma_f32_16x16x32_bf16 v[80:83], v[60:63], v[194:197], v[80:83]
	v_mfma_f32_16x16x32_bf16 v[84:87], v[68:71], v[194:197], v[84:87]
	v_mfma_f32_16x16x32_bf16 v[88:91], v[186:189], v[194:197], v[88:91]
	v_mfma_f32_16x16x32_bf16 v[36:39], v[52:55], v[198:201], v[36:39]
	v_mfma_f32_16x16x32_bf16 v[40:43], v[60:63], v[198:201], v[40:43]
	v_mfma_f32_16x16x32_bf16 v[44:47], v[68:71], v[198:201], v[44:47]
	v_mfma_f32_16x16x32_bf16 v[48:51], v[186:189], v[198:201], v[48:51]
	s_mov_b32 m0, s64
	v_lshl_add_u64 v[2:3], v[2:3], 0, s[24:25]
	s_waitcnt vmcnt(0)
	s_waitcnt vmcnt(0)
	s_barrier
	global_load_lds_dwordx4 v[2:3], off
	v_lshl_add_u64 v[2:3], v[4:5], 0, s[24:25]
	s_mov_b32 m0, s58
	s_nop 0
	global_load_lds_dwordx4 v[2:3], off
	v_lshl_add_u64 v[2:3], v[6:7], 0, s[24:25]
	s_mov_b32 m0, s59
	s_nop 0
	global_load_lds_dwordx4 v[2:3], off
	v_lshl_add_u64 v[2:3], v[8:9], 0, s[24:25]
	s_mov_b32 m0, s60
	s_nop 0
	global_load_lds_dwordx4 v[2:3], off
	v_lshl_add_u64 v[2:3], v[10:11], 0, s[24:25]
	s_mov_b32 m0, s61
	s_nop 0
	global_load_lds_dwordx4 v[2:3], off
	v_lshl_add_u64 v[2:3], v[12:13], 0, s[24:25]
	s_mov_b32 m0, s62
	s_nop 0
	global_load_lds_dwordx4 v[2:3], off
	v_lshl_add_u64 v[2:3], v[14:15], 0, s[24:25]
	s_mov_b32 m0, s63
	s_nop 0
	global_load_lds_dwordx4 v[2:3], off
	v_lshl_add_u64 v[2:3], v[16:17], 0, s[24:25]
	s_mov_b32 m0, s65
	s_nop 0
	global_load_lds_dwordx4 v[2:3], off
	ds_read_b128 v[2:5], v18 offset:32768
	ds_read_b128 v[6:9], v18 offset:34816
	ds_read_b128 v[10:13], v18 offset:36864
	ds_read_b128 v[52:55], v18 offset:38912
	ds_read_b128 v[14:17], v32
	ds_read_b128 v[60:63], v33
	ds_read_b128 v[68:71], v34
	ds_read_b128 v[182:185], v35
	s_waitcnt lgkmcnt(0)
	v_mfma_f32_16x16x32_bf16 v[138:141], v[2:5], v[14:17], v[138:141]
	v_mfma_f32_16x16x32_bf16 v[142:145], v[6:9], v[14:17], v[142:145]
	v_mfma_f32_16x16x32_bf16 v[146:149], v[10:13], v[14:17], v[146:149]
	v_mfma_f32_16x16x32_bf16 v[14:17], v[52:55], v[14:17], v[134:137]
	s_nop 2
	ds_read_b128 v[134:137], v22
	v_mfma_f32_16x16x32_bf16 v[154:157], v[2:5], v[60:63], v[154:157]
	v_mfma_f32_16x16x32_bf16 v[158:161], v[6:9], v[60:63], v[158:161]
	v_mfma_f32_16x16x32_bf16 v[162:165], v[10:13], v[60:63], v[162:165]
	v_mfma_f32_16x16x32_bf16 v[60:63], v[52:55], v[60:63], v[150:153]
	s_nop 2
	ds_read_b128 v[150:153], v21
	v_mfma_f32_16x16x32_bf16 v[170:173], v[2:5], v[68:71], v[170:173]
	v_mfma_f32_16x16x32_bf16 v[174:177], v[6:9], v[68:71], v[174:177]
	v_mfma_f32_16x16x32_bf16 v[178:181], v[10:13], v[68:71], v[178:181]
	v_mfma_f32_16x16x32_bf16 v[68:71], v[52:55], v[68:71], v[166:169]
	s_nop 2
	ds_read_b128 v[166:169], v20
	v_mfma_f32_16x16x32_bf16 v[186:189], v[2:5], v[182:185], v[202:205]
	v_mfma_f32_16x16x32_bf16 v[56:59], v[6:9], v[182:185], v[56:59]
	v_mfma_f32_16x16x32_bf16 v[64:67], v[10:13], v[182:185], v[64:67]
	v_mfma_f32_16x16x32_bf16 v[72:75], v[52:55], v[182:185], v[72:75]
	ds_read_b128 v[182:185], v19
	s_waitcnt lgkmcnt(0)
	v_mfma_f32_16x16x32_bf16 v[116:119], v[2:5], v[134:137], v[116:119]
	v_mfma_f32_16x16x32_bf16 v[120:123], v[6:9], v[134:137], v[120:123]
	v_mfma_f32_16x16x32_bf16 v[124:127], v[10:13], v[134:137], v[124:127]
	v_mfma_f32_16x16x32_bf16 v[112:115], v[52:55], v[134:137], v[112:115]
	v_mfma_f32_16x16x32_bf16 v[92:95], v[2:5], v[150:153], v[92:95]
	v_mfma_f32_16x16x32_bf16 v[100:103], v[6:9], v[150:153], v[100:103]
	v_mfma_f32_16x16x32_bf16 v[104:107], v[10:13], v[150:153], v[104:107]
	v_mfma_f32_16x16x32_bf16 v[108:111], v[52:55], v[150:153], v[108:111]
	v_mfma_f32_16x16x32_bf16 v[76:79], v[2:5], v[166:169], v[76:79]
	v_mfma_f32_16x16x32_bf16 v[80:83], v[6:9], v[166:169], v[80:83]
	v_mfma_f32_16x16x32_bf16 v[84:87], v[10:13], v[166:169], v[84:87]
	v_mfma_f32_16x16x32_bf16 v[88:91], v[52:55], v[166:169], v[88:91]
	v_mfma_f32_16x16x32_bf16 v[2:5], v[2:5], v[182:185], v[36:39]
	v_mfma_f32_16x16x32_bf16 v[6:9], v[6:9], v[182:185], v[40:43]
	v_mfma_f32_16x16x32_bf16 v[10:13], v[10:13], v[182:185], v[44:47]
	v_mfma_f32_16x16x32_bf16 v[36:39], v[52:55], v[182:185], v[48:51]
	s_nop 0
	ds_read_b128 v[40:43], v18 offset:33792
	ds_read_b128 v[44:47], v18 offset:35840
	ds_read_b128 v[48:51], v18 offset:37888
	ds_read_b128 v[134:137], v18 offset:39936
	ds_read_b128 v[52:55], v32 offset:1024
	ds_read_b128 v[150:153], v33 offset:1024
	ds_read_b128 v[166:169], v34 offset:1024
	ds_read_b128 v[32:35], v35 offset:1024
	s_waitcnt lgkmcnt(0)
	v_mfma_f32_16x16x32_bf16 v[138:141], v[40:43], v[52:55], v[138:141]
	v_mfma_f32_16x16x32_bf16 v[142:145], v[44:47], v[52:55], v[142:145]
	v_mfma_f32_16x16x32_bf16 v[146:149], v[48:51], v[52:55], v[146:149]
	v_mfma_f32_16x16x32_bf16 v[14:17], v[134:137], v[52:55], v[14:17]
	ds_read_b128 v[52:55], v22 offset:1024
	v_mfma_f32_16x16x32_bf16 v[154:157], v[40:43], v[150:153], v[154:157]
	v_mfma_f32_16x16x32_bf16 v[158:161], v[44:47], v[150:153], v[158:161]
	v_mfma_f32_16x16x32_bf16 v[162:165], v[48:51], v[150:153], v[162:165]
	v_mfma_f32_16x16x32_bf16 v[60:63], v[134:137], v[150:153], v[60:63]
	ds_read_b128 v[150:153], v21 offset:1024
	v_mfma_f32_16x16x32_bf16 v[170:173], v[40:43], v[166:169], v[170:173]
	v_mfma_f32_16x16x32_bf16 v[174:177], v[44:47], v[166:169], v[174:177]
	v_mfma_f32_16x16x32_bf16 v[178:181], v[48:51], v[166:169], v[178:181]
	v_mfma_f32_16x16x32_bf16 v[68:71], v[134:137], v[166:169], v[68:71]
	ds_read_b128 v[166:169], v20 offset:1024
	v_mfma_f32_16x16x32_bf16 v[182:185], v[40:43], v[32:35], v[186:189]
	v_mfma_f32_16x16x32_bf16 v[56:59], v[44:47], v[32:35], v[56:59]
	v_mfma_f32_16x16x32_bf16 v[64:67], v[48:51], v[32:35], v[64:67]
	v_mfma_f32_16x16x32_bf16 v[32:35], v[134:137], v[32:35], v[72:75]
	ds_read_b128 v[18:21], v19 offset:1024
	s_waitcnt lgkmcnt(0)
	v_mfma_f32_16x16x32_bf16 v[72:75], v[40:43], v[52:55], v[116:119]
	v_mfma_f32_16x16x32_bf16 v[116:119], v[44:47], v[52:55], v[120:123]
	v_mfma_f32_16x16x32_bf16 v[120:123], v[48:51], v[52:55], v[124:127]
	v_mfma_f32_16x16x32_bf16 v[52:55], v[134:137], v[52:55], v[112:115]
	v_mfma_f32_16x16x32_bf16 v[92:95], v[40:43], v[150:153], v[92:95]
	v_mfma_f32_16x16x32_bf16 v[100:103], v[44:47], v[150:153], v[100:103]
	v_mfma_f32_16x16x32_bf16 v[104:107], v[48:51], v[150:153], v[104:107]
	v_mfma_f32_16x16x32_bf16 v[108:111], v[134:137], v[150:153], v[108:111]
	v_mfma_f32_16x16x32_bf16 v[76:79], v[40:43], v[166:169], v[76:79]
	v_mfma_f32_16x16x32_bf16 v[80:83], v[44:47], v[166:169], v[80:83]
	v_mfma_f32_16x16x32_bf16 v[84:87], v[48:51], v[166:169], v[84:87]
	v_mfma_f32_16x16x32_bf16 v[88:91], v[134:137], v[166:169], v[88:91]
	v_mfma_f32_16x16x32_bf16 v[2:5], v[40:43], v[18:21], v[2:5]
	v_mfma_f32_16x16x32_bf16 v[6:9], v[44:47], v[18:21], v[6:9]
	v_mfma_f32_16x16x32_bf16 v[10:13], v[48:51], v[18:21], v[10:13]
	v_mfma_f32_16x16x32_bf16 v[18:21], v[134:137], v[18:21], v[36:39]
	s_waitcnt vmcnt(0)
	s_waitcnt vmcnt(0)
	s_barrier
	s_nop 0
	ds_read_b128 v[36:39], v31
	ds_read_b128 v[40:43], v30
	ds_read_b128 v[44:47], v29
	ds_read_b128 v[48:51], v28
	ds_read_b128 v[112:115], v27
	ds_read_b128 v[124:127], v26
	ds_read_b128 v[134:137], v25
	ds_read_b128 v[150:153], v24
	ds_read_b128 v[166:169], v23
	s_waitcnt lgkmcnt(0)
	v_mfma_f32_16x16x32_bf16 v[186:189], v[166:169], v[36:39], v[2:5]
	s_nop 2
	ds_read_b128 v[2:5], v23 offset:2048
	s_waitcnt lgkmcnt(0)
	v_mfma_f32_16x16x32_bf16 v[190:193], v[2:5], v[36:39], v[6:9]
	s_nop 2
	ds_read_b128 v[6:9], v23 offset:4096
	s_waitcnt lgkmcnt(0)
	v_mfma_f32_16x16x32_bf16 v[194:197], v[6:9], v[36:39], v[10:13]
	s_nop 2
	ds_read_b128 v[10:13], v23 offset:6144
	s_waitcnt lgkmcnt(0)
	v_mfma_f32_16x16x32_bf16 v[198:201], v[10:13], v[36:39], v[18:21]
	v_mfma_f32_16x16x32_bf16 v[18:21], v[10:13], v[134:137], v[60:63]
	v_mfma_f32_16x16x32_bf16 v[36:39], v[10:13], v[124:127], v[68:71]
	v_mfma_f32_16x16x32_bf16 v[68:71], v[6:9], v[134:137], v[162:165]
	v_mfma_f32_16x16x32_bf16 v[162:165], v[6:9], v[112:115], v[64:67]
	v_mfma_f32_16x16x32_bf16 v[64:67], v[2:5], v[150:153], v[142:145]
	v_mfma_f32_16x16x32_bf16 v[142:145], v[2:5], v[134:137], v[158:161]
	v_mfma_f32_16x16x32_bf16 v[134:137], v[166:169], v[134:137], v[154:157]
	v_mfma_f32_16x16x32_bf16 v[154:157], v[166:169], v[40:43], v[76:79]
	v_mfma_f32_16x16x32_bf16 v[60:63], v[6:9], v[150:153], v[146:149]
	v_mfma_f32_16x16x32_bf16 v[146:149], v[6:9], v[124:127], v[178:181]
	v_mfma_f32_16x16x32_bf16 v[158:161], v[2:5], v[124:127], v[174:177]
	v_mfma_f32_16x16x32_bf16 v[124:127], v[166:169], v[124:127], v[170:173]
	v_mfma_f32_16x16x32_bf16 v[170:173], v[6:9], v[40:43], v[84:87]
	v_mfma_f32_16x16x32_bf16 v[138:141], v[166:169], v[150:153], v[138:141]
	v_mfma_f32_16x16x32_bf16 v[56:59], v[2:5], v[112:115], v[56:59]
	v_mfma_f32_16x16x32_bf16 v[116:119], v[2:5], v[48:51], v[116:119]
	v_mfma_f32_16x16x32_bf16 v[120:123], v[6:9], v[48:51], v[120:123]
	v_mfma_f32_16x16x32_bf16 v[14:17], v[10:13], v[150:153], v[14:17]
	v_mfma_f32_16x16x32_bf16 v[150:153], v[166:169], v[48:51], v[72:75]
	v_mfma_f32_16x16x32_bf16 v[48:51], v[10:13], v[48:51], v[52:55]
	v_mfma_f32_16x16x32_bf16 v[52:55], v[166:169], v[44:47], v[92:95]
	v_mfma_f32_16x16x32_bf16 v[32:35], v[10:13], v[112:115], v[32:35]
	v_mfma_f32_16x16x32_bf16 v[112:115], v[166:169], v[112:115], v[182:185]
	v_mfma_f32_16x16x32_bf16 v[166:169], v[2:5], v[40:43], v[80:83]
	v_mfma_f32_16x16x32_bf16 v[104:107], v[6:9], v[44:47], v[104:107]
	v_mfma_f32_16x16x32_bf16 v[108:111], v[10:13], v[44:47], v[108:111]
	v_mfma_f32_16x16x32_bf16 v[100:103], v[2:5], v[44:47], v[100:103]
	v_mfma_f32_16x16x32_bf16 v[174:177], v[10:13], v[40:43], v[88:91]
	ds_read_b128 v[178:181], v23 offset:1024
	ds_read_b128 v[182:185], v23 offset:3072
	ds_read_b128 v[202:205], v23 offset:5120
	ds_read_b128 v[206:209], v23 offset:7168
	ds_read_b128 v[2:5], v24 offset:1024
	ds_read_b128 v[6:9], v25 offset:1024
	ds_read_b128 v[10:13], v26 offset:1024
	ds_read_b128 v[22:25], v27 offset:1024
	s_waitcnt lgkmcnt(3)
	v_mfma_f32_16x16x32_bf16 v[138:141], v[178:181], v[2:5], v[138:141]
	v_mfma_f32_16x16x32_bf16 v[210:213], v[182:185], v[2:5], v[64:67]
	v_mfma_f32_16x16x32_bf16 v[214:217], v[202:205], v[2:5], v[60:63]
	v_mfma_f32_16x16x32_bf16 v[218:221], v[206:209], v[2:5], v[14:17]
	ds_read_b128 v[2:5], v28 offset:1024
	s_waitcnt lgkmcnt(3)
	v_mfma_f32_16x16x32_bf16 v[134:137], v[178:181], v[6:9], v[134:137]
	v_mfma_f32_16x16x32_bf16 v[142:145], v[182:185], v[6:9], v[142:145]
	v_mfma_f32_16x16x32_bf16 v[222:225], v[202:205], v[6:9], v[68:71]
	v_mfma_f32_16x16x32_bf16 v[226:229], v[206:209], v[6:9], v[18:21]
	ds_read_b128 v[6:9], v29 offset:1024
	s_waitcnt lgkmcnt(3)
	v_mfma_f32_16x16x32_bf16 v[66:69], v[178:181], v[10:13], v[124:127]
	v_mfma_f32_16x16x32_bf16 v[70:73], v[182:185], v[10:13], v[158:161]
	v_mfma_f32_16x16x32_bf16 v[74:77], v[202:205], v[10:13], v[146:149]
	v_mfma_f32_16x16x32_bf16 v[78:81], v[206:209], v[10:13], v[36:39]
	ds_read_b128 v[14:17], v30 offset:1024
	s_waitcnt lgkmcnt(3)
	v_mfma_f32_16x16x32_bf16 v[82:85], v[178:181], v[22:25], v[112:115]
	v_mfma_f32_16x16x32_bf16 v[86:89], v[182:185], v[22:25], v[56:59]
	v_mfma_f32_16x16x32_bf16 v[90:93], v[202:205], v[22:25], v[162:165]
	v_mfma_f32_16x16x32_bf16 v[94:97], v[206:209], v[22:25], v[32:35]
	s_nop 2
	ds_read_b128 v[30:33], v31 offset:1024
	s_waitcnt lgkmcnt(3)
	v_mfma_f32_16x16x32_bf16 v[34:37], v[178:181], v[2:5], v[150:153]
	v_mfma_f32_16x16x32_bf16 v[38:41], v[182:185], v[2:5], v[116:119]
	v_mfma_f32_16x16x32_bf16 v[42:45], v[202:205], v[2:5], v[120:123]
	v_mfma_f32_16x16x32_bf16 v[46:49], v[206:209], v[2:5], v[48:51]
	s_waitcnt lgkmcnt(2)
	v_mfma_f32_16x16x32_bf16 v[50:53], v[178:181], v[6:9], v[52:55]
	v_mfma_f32_16x16x32_bf16 v[54:57], v[182:185], v[6:9], v[100:103]
	v_mfma_f32_16x16x32_bf16 v[58:61], v[202:205], v[6:9], v[104:107]
	v_mfma_f32_16x16x32_bf16 v[62:65], v[206:209], v[6:9], v[108:111]
	s_waitcnt lgkmcnt(1)
	v_mfma_f32_16x16x32_bf16 v[2:5], v[178:181], v[14:17], v[154:157]
	v_mfma_f32_16x16x32_bf16 v[6:9], v[182:185], v[14:17], v[166:169]
	v_mfma_f32_16x16x32_bf16 v[10:13], v[202:205], v[14:17], v[170:173]
	v_mfma_f32_16x16x32_bf16 v[14:17], v[206:209], v[14:17], v[174:177]
	s_waitcnt lgkmcnt(0)
	v_mfma_f32_16x16x32_bf16 v[18:21], v[178:181], v[30:33], v[186:189]
	v_mfma_f32_16x16x32_bf16 v[22:25], v[182:185], v[30:33], v[190:193]
	v_mfma_f32_16x16x32_bf16 v[26:29], v[202:205], v[30:33], v[194:197]
	v_mfma_f32_16x16x32_bf16 v[30:33], v[206:209], v[30:33], v[198:201]
	v_lshlrev_b32_e32 v101, 2, v98
	v_and_b32_e32 v112, 60, v101
	v_ashrrev_i32_e32 v101, 1, v98
	v_lshrrev_b32_e32 v99, 6, v98
	v_and_b32_e32 v101, 0xffffff80, v101
	v_and_b32_e32 v100, 15, v98
	v_mul_lo_u32 v99, v99, s48
	v_add_u32_e32 v107, s28, v101
	v_bfe_u32 v108, v98, 4, 2
	v_add_u32_e32 v109, s46, v99
	v_and_b32_e32 v99, 48, v98
	v_and_or_b32 v102, v98, s49, v112
	v_mul_u32_u24_e32 v98, 0x110, v100
	v_or_b32_e32 v100, v107, v108
	v_lshl_add_u64 v[0:1], v[0:1], 0, s[38:39]
	v_lshlrev_b32_e32 v130, 1, v102
	v_ashrrev_i32_e32 v101, 31, v100
	v_lshl_add_u64 v[0:1], v[0:1], 0, v[130:131]
	v_add3_u32 v99, v109, v99, v98
	v_lshlrev_b64 v[100:101], 11, v[100:101]
	s_waitcnt vmcnt(0)
	s_barrier
	ds_write_b128 v99, v[138:141]
	ds_write_b128 v99, v[210:213] offset:64
	ds_write_b128 v99, v[214:217] offset:128
	ds_write_b128 v99, v[218:221] offset:192
	ds_write_b128 v99, v[134:137] offset:4352
	ds_write_b128 v99, v[142:145] offset:4416
	ds_write_b128 v99, v[222:225] offset:4480
	ds_write_b128 v99, v[226:229] offset:4544
	v_lshl_add_u64 v[114:115], v[0:1], 0, v[100:101]
	flat_load_dwordx2 v[116:117], v[114:115]
	v_or_b32_e32 v100, 4, v108
	v_or_b32_e32 v102, v107, v100
	v_ashrrev_i32_e32 v103, 31, v102
	v_lshlrev_b64 v[102:103], 11, v[102:103]
	v_lshl_add_u64 v[118:119], v[0:1], 0, v[102:103]
	flat_load_dwordx2 v[120:121], v[118:119]
	v_or_b32_e32 v101, 8, v108
	v_or_b32_e32 v102, v107, v101
	v_ashrrev_i32_e32 v103, 31, v102
	v_lshlrev_b64 v[102:103], 11, v[102:103]
	v_lshl_add_u64 v[122:123], v[0:1], 0, v[102:103]
	flat_load_dwordx2 v[124:125], v[122:123]
	v_or_b32_e32 v102, 12, v108
	v_or_b32_e32 v104, v107, v102
	v_ashrrev_i32_e32 v105, 31, v104
	v_lshlrev_b64 v[104:105], 11, v[104:105]
	v_lshl_add_u64 v[126:127], v[0:1], 0, v[104:105]
	flat_load_dwordx2 v[128:129], v[126:127]
	v_or_b32_e32 v103, 16, v108
	v_or_b32_e32 v104, v107, v103
	v_ashrrev_i32_e32 v105, 31, v104
	v_lshlrev_b64 v[104:105], 11, v[104:105]
	v_lshl_add_u64 v[134:135], v[0:1], 0, v[104:105]
	flat_load_dwordx2 v[136:137], v[134:135]
	v_or_b32_e32 v104, 20, v108
	v_or_b32_e32 v110, v107, v104
	v_ashrrev_i32_e32 v111, 31, v110
	v_lshlrev_b64 v[110:111], 11, v[110:111]
	v_lshl_add_u64 v[138:139], v[0:1], 0, v[110:111]
	flat_load_dwordx2 v[140:141], v[138:139]
	v_or_b32_e32 v105, 24, v108
	v_or_b32_e32 v110, v107, v105
	v_ashrrev_i32_e32 v111, 31, v110
	v_lshlrev_b64 v[110:111], 11, v[110:111]
	v_lshl_add_u64 v[142:143], v[0:1], 0, v[110:111]
	flat_load_dwordx2 v[144:145], v[142:143]
	v_or_b32_e32 v106, 28, v108
	v_or_b32_e32 v146, v107, v106
	v_ashrrev_i32_e32 v147, 31, v146
	v_lshlrev_b64 v[146:147], 11, v[146:147]
	v_lshl_add_u64 v[146:147], v[0:1], 0, v[146:147]
	flat_load_dwordx2 v[148:149], v[146:147]
	v_mul_u32_u24_e32 v98, 0x110, v108
	v_lshlrev_b32_e32 v110, 2, v112
	v_add3_u32 v98, v109, v110, v98
	ds_read_b128 v[110:113], v98
	s_add_i32 s0, s30, 0x1600
	s_lshl_b64 s[42:43], s[0:1], 11
	s_waitcnt vmcnt(0) lgkmcnt(0)
	v_and_b32_e32 v151, 0xffff0000, v116
	v_lshlrev_b32_e32 v150, 16, v116
	v_and_b32_e32 v153, 0xffff0000, v117
	v_lshlrev_b32_e32 v152, 16, v117
	v_pk_mul_f32 v[110:111], v[110:111], v[150:151]
	v_pk_mul_f32 v[112:113], v[112:113], v[152:153]
	v_cvt_pk_bf16_f32 v110, v110, v111
	v_cvt_pk_bf16_f32 v111, v112, v113
	flat_store_dwordx2 v[114:115], v[110:111]
	ds_read_b128 v[110:113], v98 offset:1088
	v_and_b32_e32 v115, 0xffff0000, v120
	v_lshlrev_b32_e32 v114, 16, v120
	v_and_b32_e32 v117, 0xffff0000, v121
	v_lshlrev_b32_e32 v116, 16, v121
	s_waitcnt lgkmcnt(0)
	v_pk_mul_f32 v[110:111], v[110:111], v[114:115]
	v_pk_mul_f32 v[112:113], v[112:113], v[116:117]
	v_cvt_pk_bf16_f32 v110, v110, v111
	v_cvt_pk_bf16_f32 v111, v112, v113
	flat_store_dwordx2 v[118:119], v[110:111]
	ds_read_b128 v[110:113], v98 offset:2176
	v_and_b32_e32 v115, 0xffff0000, v124
	v_lshlrev_b32_e32 v114, 16, v124
	v_and_b32_e32 v117, 0xffff0000, v125
	v_lshlrev_b32_e32 v116, 16, v125
	s_waitcnt lgkmcnt(0)
	v_pk_mul_f32 v[110:111], v[110:111], v[114:115]
	v_pk_mul_f32 v[112:113], v[112:113], v[116:117]
	v_cvt_pk_bf16_f32 v110, v110, v111
	v_cvt_pk_bf16_f32 v111, v112, v113
	flat_store_dwordx2 v[122:123], v[110:111]
	ds_read_b128 v[110:113], v98 offset:3264
	v_and_b32_e32 v115, 0xffff0000, v128
	v_lshlrev_b32_e32 v114, 16, v128
	v_mov_b32_e32 v150, v132
	s_waitcnt lgkmcnt(0)
	v_pk_mul_f32 v[110:111], v[110:111], v[114:115]
	v_and_b32_e32 v115, 0xffff0000, v129
	v_lshlrev_b32_e32 v114, 16, v129
	v_pk_mul_f32 v[112:113], v[112:113], v[114:115]
	v_cvt_pk_bf16_f32 v110, v110, v111
	v_cvt_pk_bf16_f32 v111, v112, v113
	flat_store_dwordx2 v[126:127], v[110:111]
	ds_read_b128 v[110:113], v98 offset:4352
	v_and_b32_e32 v115, 0xffff0000, v136
	v_lshlrev_b32_e32 v114, 16, v136
	s_waitcnt lgkmcnt(0)
	v_pk_mul_f32 v[110:111], v[110:111], v[114:115]
	v_and_b32_e32 v115, 0xffff0000, v137
	v_lshlrev_b32_e32 v114, 16, v137
	v_pk_mul_f32 v[112:113], v[112:113], v[114:115]
	v_cvt_pk_bf16_f32 v110, v110, v111
	v_cvt_pk_bf16_f32 v111, v112, v113
	flat_store_dwordx2 v[134:135], v[110:111]
	ds_read_b128 v[110:113], v98 offset:5440
	v_and_b32_e32 v115, 0xffff0000, v140
	v_lshlrev_b32_e32 v114, 16, v140
	s_waitcnt lgkmcnt(0)
	v_pk_mul_f32 v[110:111], v[110:111], v[114:115]
	v_and_b32_e32 v115, 0xffff0000, v141
	v_lshlrev_b32_e32 v114, 16, v141
	v_pk_mul_f32 v[112:113], v[112:113], v[114:115]
	v_cvt_pk_bf16_f32 v110, v110, v111
	v_cvt_pk_bf16_f32 v111, v112, v113
	flat_store_dwordx2 v[138:139], v[110:111]
	ds_read_b128 v[110:113], v98 offset:6528
	v_and_b32_e32 v115, 0xffff0000, v144
	v_lshlrev_b32_e32 v114, 16, v144
	s_waitcnt lgkmcnt(0)
	v_pk_mul_f32 v[110:111], v[110:111], v[114:115]
	v_and_b32_e32 v115, 0xffff0000, v145
	v_lshlrev_b32_e32 v114, 16, v145
	v_pk_mul_f32 v[112:113], v[112:113], v[114:115]
	v_cvt_pk_bf16_f32 v110, v110, v111
	v_cvt_pk_bf16_f32 v111, v112, v113
	flat_store_dwordx2 v[142:143], v[110:111]
	ds_read_b128 v[110:113], v98 offset:7616
	v_and_b32_e32 v115, 0xffff0000, v148
	v_lshlrev_b32_e32 v114, 16, v148
	s_waitcnt lgkmcnt(0)
	v_pk_mul_f32 v[110:111], v[110:111], v[114:115]
	v_and_b32_e32 v115, 0xffff0000, v149
	v_lshlrev_b32_e32 v114, 16, v149
	v_pk_mul_f32 v[112:113], v[112:113], v[114:115]
	v_cvt_pk_bf16_f32 v110, v110, v111
	v_cvt_pk_bf16_f32 v111, v112, v113
	flat_store_dwordx2 v[146:147], v[110:111]
	ds_write_b128 v99, v[66:69]
	v_or_b32_e32 v68, 32, v107
	v_or_b32_e32 v66, v68, v108
	v_ashrrev_i32_e32 v67, 31, v66
	v_lshlrev_b64 v[66:67], 11, v[66:67]
	ds_write_b128 v99, v[70:73] offset:64
	ds_write_b128 v99, v[74:77] offset:128
	ds_write_b128 v99, v[78:81] offset:192
	ds_write_b128 v99, v[82:85] offset:4352
	ds_write_b128 v99, v[86:89] offset:4416
	ds_write_b128 v99, v[90:93] offset:4480
	ds_write_b128 v99, v[94:97] offset:4544
	v_lshl_add_u64 v[70:71], v[0:1], 0, v[66:67]
	flat_load_dwordx2 v[72:73], v[70:71]
	v_or_b32_e32 v66, v68, v100
	v_ashrrev_i32_e32 v67, 31, v66
	v_lshlrev_b64 v[66:67], 11, v[66:67]
	v_lshl_add_u64 v[74:75], v[0:1], 0, v[66:67]
	flat_load_dwordx2 v[76:77], v[74:75]
	v_or_b32_e32 v66, v68, v101
	v_ashrrev_i32_e32 v67, 31, v66
	v_lshlrev_b64 v[66:67], 11, v[66:67]
	v_lshl_add_u64 v[78:79], v[0:1], 0, v[66:67]
	flat_load_dwordx2 v[80:81], v[78:79]
	v_or_b32_e32 v66, v68, v102
	v_ashrrev_i32_e32 v67, 31, v66
	v_lshlrev_b64 v[66:67], 11, v[66:67]
	v_lshl_add_u64 v[82:83], v[0:1], 0, v[66:67]
	flat_load_dwordx2 v[84:85], v[82:83]
	v_or_b32_e32 v66, v68, v103
	v_ashrrev_i32_e32 v67, 31, v66
	v_lshlrev_b64 v[66:67], 11, v[66:67]
	v_lshl_add_u64 v[86:87], v[0:1], 0, v[66:67]
	flat_load_dwordx2 v[88:89], v[86:87]
	v_or_b32_e32 v66, v68, v104
	v_ashrrev_i32_e32 v67, 31, v66
	v_lshlrev_b64 v[66:67], 11, v[66:67]
	v_lshl_add_u64 v[90:91], v[0:1], 0, v[66:67]
	flat_load_dwordx2 v[92:93], v[90:91]
	v_or_b32_e32 v66, v68, v105
	v_ashrrev_i32_e32 v67, 31, v66
	v_lshlrev_b64 v[66:67], 11, v[66:67]
	v_lshl_add_u64 v[94:95], v[0:1], 0, v[66:67]
	flat_load_dwordx2 v[96:97], v[94:95]
	v_or_b32_e32 v66, v68, v106
	v_ashrrev_i32_e32 v67, 31, v66
	v_lshlrev_b64 v[66:67], 11, v[66:67]
	v_lshl_add_u64 v[110:111], v[0:1], 0, v[66:67]
	flat_load_dwordx2 v[112:113], v[110:111]
	ds_read_b128 v[66:69], v98
	s_waitcnt vmcnt(0) lgkmcnt(0)
	v_and_b32_e32 v115, 0xffff0000, v72
	v_lshlrev_b32_e32 v114, 16, v72
	v_and_b32_e32 v117, 0xffff0000, v73
	v_lshlrev_b32_e32 v116, 16, v73
	v_pk_mul_f32 v[66:67], v[66:67], v[114:115]
	v_pk_mul_f32 v[68:69], v[68:69], v[116:117]
	v_cvt_pk_bf16_f32 v66, v66, v67
	v_cvt_pk_bf16_f32 v67, v68, v69
	flat_store_dwordx2 v[70:71], v[66:67]
	ds_read_b128 v[66:69], v98 offset:1088
	v_and_b32_e32 v71, 0xffff0000, v76
	v_lshlrev_b32_e32 v70, 16, v76
	v_and_b32_e32 v73, 0xffff0000, v77
	v_lshlrev_b32_e32 v72, 16, v77
	s_waitcnt lgkmcnt(0)
	v_pk_mul_f32 v[66:67], v[66:67], v[70:71]
	v_pk_mul_f32 v[68:69], v[68:69], v[72:73]
	v_cvt_pk_bf16_f32 v66, v66, v67
	v_cvt_pk_bf16_f32 v67, v68, v69
	flat_store_dwordx2 v[74:75], v[66:67]
	ds_read_b128 v[66:69], v98 offset:2176
	v_and_b32_e32 v71, 0xffff0000, v80
	v_lshlrev_b32_e32 v70, 16, v80
	v_and_b32_e32 v73, 0xffff0000, v81
	v_lshlrev_b32_e32 v72, 16, v81
	s_waitcnt lgkmcnt(0)
	v_pk_mul_f32 v[66:67], v[66:67], v[70:71]
	v_pk_mul_f32 v[68:69], v[68:69], v[72:73]
	v_cvt_pk_bf16_f32 v66, v66, v67
	v_cvt_pk_bf16_f32 v67, v68, v69
	flat_store_dwordx2 v[78:79], v[66:67]
	ds_read_b128 v[66:69], v98 offset:3264
	v_and_b32_e32 v71, 0xffff0000, v84
	v_lshlrev_b32_e32 v70, 16, v84
	v_and_b32_e32 v73, 0xffff0000, v85
	v_lshlrev_b32_e32 v72, 16, v85
	s_waitcnt lgkmcnt(0)
	v_pk_mul_f32 v[66:67], v[66:67], v[70:71]
	v_pk_mul_f32 v[68:69], v[68:69], v[72:73]
	v_cvt_pk_bf16_f32 v66, v66, v67
	v_cvt_pk_bf16_f32 v67, v68, v69
	flat_store_dwordx2 v[82:83], v[66:67]
	ds_read_b128 v[66:69], v98 offset:4352
	v_and_b32_e32 v71, 0xffff0000, v88
	v_lshlrev_b32_e32 v70, 16, v88
	v_and_b32_e32 v73, 0xffff0000, v89
	v_lshlrev_b32_e32 v72, 16, v89
	s_waitcnt lgkmcnt(0)
	v_pk_mul_f32 v[66:67], v[66:67], v[70:71]
	v_pk_mul_f32 v[68:69], v[68:69], v[72:73]
	v_cvt_pk_bf16_f32 v66, v66, v67
	v_cvt_pk_bf16_f32 v67, v68, v69
	flat_store_dwordx2 v[86:87], v[66:67]
	ds_read_b128 v[66:69], v98 offset:5440
	v_and_b32_e32 v71, 0xffff0000, v92
	v_lshlrev_b32_e32 v70, 16, v92
	v_and_b32_e32 v73, 0xffff0000, v93
	v_lshlrev_b32_e32 v72, 16, v93
	s_waitcnt lgkmcnt(0)
	v_pk_mul_f32 v[66:67], v[66:67], v[70:71]
	v_pk_mul_f32 v[68:69], v[68:69], v[72:73]
	v_cvt_pk_bf16_f32 v66, v66, v67
	v_cvt_pk_bf16_f32 v67, v68, v69
	flat_store_dwordx2 v[90:91], v[66:67]
	ds_read_b128 v[66:69], v98 offset:6528
	v_and_b32_e32 v71, 0xffff0000, v96
	v_lshlrev_b32_e32 v70, 16, v96
	v_and_b32_e32 v73, 0xffff0000, v97
	v_lshlrev_b32_e32 v72, 16, v97
	s_waitcnt lgkmcnt(0)
	v_pk_mul_f32 v[66:67], v[66:67], v[70:71]
	v_pk_mul_f32 v[68:69], v[68:69], v[72:73]
	v_cvt_pk_bf16_f32 v66, v66, v67
	v_cvt_pk_bf16_f32 v67, v68, v69
	flat_store_dwordx2 v[94:95], v[66:67]
	ds_read_b128 v[66:69], v98 offset:7616
	v_and_b32_e32 v71, 0xffff0000, v112
	v_lshlrev_b32_e32 v70, 16, v112
	v_and_b32_e32 v73, 0xffff0000, v113
	v_lshlrev_b32_e32 v72, 16, v113
	s_waitcnt lgkmcnt(0)
	v_pk_mul_f32 v[66:67], v[66:67], v[70:71]
	v_pk_mul_f32 v[68:69], v[68:69], v[72:73]
	v_cvt_pk_bf16_f32 v66, v66, v67
	v_cvt_pk_bf16_f32 v67, v68, v69
	flat_store_dwordx2 v[110:111], v[66:67]
	ds_write_b128 v99, v[34:37]
	v_or_b32_e32 v36, 64, v107
	v_or_b32_e32 v34, v36, v108
	v_ashrrev_i32_e32 v35, 31, v34
	v_lshlrev_b64 v[34:35], 11, v[34:35]
	ds_write_b128 v99, v[38:41] offset:64
	ds_write_b128 v99, v[42:45] offset:128
	ds_write_b128 v99, v[46:49] offset:192
	ds_write_b128 v99, v[50:53] offset:4352
	ds_write_b128 v99, v[54:57] offset:4416
	ds_write_b128 v99, v[58:61] offset:4480
	ds_write_b128 v99, v[62:65] offset:4544
	v_lshl_add_u64 v[38:39], v[0:1], 0, v[34:35]
	flat_load_dwordx2 v[40:41], v[38:39]
	v_or_b32_e32 v34, v36, v100
	v_ashrrev_i32_e32 v35, 31, v34
	v_lshlrev_b64 v[34:35], 11, v[34:35]
	v_lshl_add_u64 v[42:43], v[0:1], 0, v[34:35]
	flat_load_dwordx2 v[44:45], v[42:43]
	v_or_b32_e32 v34, v36, v101
	v_ashrrev_i32_e32 v35, 31, v34
	v_lshlrev_b64 v[34:35], 11, v[34:35]
	v_lshl_add_u64 v[46:47], v[0:1], 0, v[34:35]
	flat_load_dwordx2 v[48:49], v[46:47]
	v_or_b32_e32 v34, v36, v102
	v_ashrrev_i32_e32 v35, 31, v34
	v_lshlrev_b64 v[34:35], 11, v[34:35]
	v_lshl_add_u64 v[50:51], v[0:1], 0, v[34:35]
	flat_load_dwordx2 v[52:53], v[50:51]
	v_or_b32_e32 v34, v36, v103
	v_ashrrev_i32_e32 v35, 31, v34
	v_lshlrev_b64 v[34:35], 11, v[34:35]
	v_lshl_add_u64 v[54:55], v[0:1], 0, v[34:35]
	flat_load_dwordx2 v[56:57], v[54:55]
	v_or_b32_e32 v34, v36, v104
	v_ashrrev_i32_e32 v35, 31, v34
	v_lshlrev_b64 v[34:35], 11, v[34:35]
	v_lshl_add_u64 v[58:59], v[0:1], 0, v[34:35]
	flat_load_dwordx2 v[60:61], v[58:59]
	v_or_b32_e32 v34, v36, v105
	v_ashrrev_i32_e32 v35, 31, v34
	v_lshlrev_b64 v[34:35], 11, v[34:35]
	v_lshl_add_u64 v[62:63], v[0:1], 0, v[34:35]
	flat_load_dwordx2 v[64:65], v[62:63]
	v_or_b32_e32 v34, v36, v106
	v_ashrrev_i32_e32 v35, 31, v34
	v_lshlrev_b64 v[34:35], 11, v[34:35]
	v_lshl_add_u64 v[66:67], v[0:1], 0, v[34:35]
	flat_load_dwordx2 v[68:69], v[66:67]
	ds_read_b128 v[34:37], v98
	v_or_b32_e32 v76, 0x60, v107
	v_or_b32_e32 v70, v76, v108
	v_ashrrev_i32_e32 v71, 31, v70
	s_waitcnt vmcnt(0) lgkmcnt(0)
	v_and_b32_e32 v73, 0xffff0000, v40
	v_lshlrev_b32_e32 v72, 16, v40
	v_and_b32_e32 v75, 0xffff0000, v41
	v_lshlrev_b32_e32 v74, 16, v41
	v_pk_mul_f32 v[34:35], v[34:35], v[72:73]
	v_pk_mul_f32 v[36:37], v[36:37], v[74:75]
	v_cvt_pk_bf16_f32 v34, v34, v35
	v_cvt_pk_bf16_f32 v35, v36, v37
	flat_store_dwordx2 v[38:39], v[34:35]
	ds_read_b128 v[34:37], v98 offset:1088
	v_and_b32_e32 v39, 0xffff0000, v44
	v_lshlrev_b32_e32 v38, 16, v44
	v_and_b32_e32 v41, 0xffff0000, v45
	v_lshlrev_b32_e32 v40, 16, v45
	s_waitcnt lgkmcnt(0)
	v_pk_mul_f32 v[34:35], v[34:35], v[38:39]
	v_pk_mul_f32 v[36:37], v[36:37], v[40:41]
	v_cvt_pk_bf16_f32 v34, v34, v35
	v_cvt_pk_bf16_f32 v35, v36, v37
	flat_store_dwordx2 v[42:43], v[34:35]
	ds_read_b128 v[34:37], v98 offset:2176
	v_and_b32_e32 v39, 0xffff0000, v48
	v_lshlrev_b32_e32 v38, 16, v48
	v_and_b32_e32 v41, 0xffff0000, v49
	v_lshlrev_b32_e32 v40, 16, v49
	s_waitcnt lgkmcnt(0)
	v_pk_mul_f32 v[34:35], v[34:35], v[38:39]
	v_pk_mul_f32 v[36:37], v[36:37], v[40:41]
	v_cvt_pk_bf16_f32 v34, v34, v35
	v_cvt_pk_bf16_f32 v35, v36, v37
	flat_store_dwordx2 v[46:47], v[34:35]
	ds_read_b128 v[34:37], v98 offset:3264
	v_and_b32_e32 v39, 0xffff0000, v52
	v_lshlrev_b32_e32 v38, 16, v52
	v_and_b32_e32 v41, 0xffff0000, v53
	v_lshlrev_b32_e32 v40, 16, v53
	s_waitcnt lgkmcnt(0)
	v_pk_mul_f32 v[34:35], v[34:35], v[38:39]
	v_pk_mul_f32 v[36:37], v[36:37], v[40:41]
	v_cvt_pk_bf16_f32 v34, v34, v35
	v_cvt_pk_bf16_f32 v35, v36, v37
	flat_store_dwordx2 v[50:51], v[34:35]
	ds_read_b128 v[34:37], v98 offset:4352
	v_and_b32_e32 v39, 0xffff0000, v56
	v_lshlrev_b32_e32 v38, 16, v56
	v_and_b32_e32 v41, 0xffff0000, v57
	v_lshlrev_b32_e32 v40, 16, v57
	s_waitcnt lgkmcnt(0)
	v_pk_mul_f32 v[34:35], v[34:35], v[38:39]
	v_pk_mul_f32 v[36:37], v[36:37], v[40:41]
	v_cvt_pk_bf16_f32 v34, v34, v35
	v_cvt_pk_bf16_f32 v35, v36, v37
	flat_store_dwordx2 v[54:55], v[34:35]
	ds_read_b128 v[34:37], v98 offset:5440
	v_and_b32_e32 v39, 0xffff0000, v60
	v_lshlrev_b32_e32 v38, 16, v60
	v_and_b32_e32 v41, 0xffff0000, v61
	v_lshlrev_b32_e32 v40, 16, v61
	s_waitcnt lgkmcnt(0)
	v_pk_mul_f32 v[34:35], v[34:35], v[38:39]
	v_pk_mul_f32 v[36:37], v[36:37], v[40:41]
	v_cvt_pk_bf16_f32 v34, v34, v35
	v_cvt_pk_bf16_f32 v35, v36, v37
	flat_store_dwordx2 v[58:59], v[34:35]
	ds_read_b128 v[34:37], v98 offset:6528
	v_and_b32_e32 v39, 0xffff0000, v64
	v_lshlrev_b32_e32 v38, 16, v64
	v_and_b32_e32 v41, 0xffff0000, v65
	v_lshlrev_b32_e32 v40, 16, v65
	s_waitcnt lgkmcnt(0)
	v_pk_mul_f32 v[34:35], v[34:35], v[38:39]
	v_pk_mul_f32 v[36:37], v[36:37], v[40:41]
	v_cvt_pk_bf16_f32 v34, v34, v35
	v_cvt_pk_bf16_f32 v35, v36, v37
	flat_store_dwordx2 v[62:63], v[34:35]
	ds_read_b128 v[34:37], v98 offset:7616
	v_and_b32_e32 v39, 0xffff0000, v68
	v_lshlrev_b32_e32 v38, 16, v68
	v_and_b32_e32 v41, 0xffff0000, v69
	v_lshlrev_b32_e32 v40, 16, v69
	s_waitcnt lgkmcnt(0)
	v_pk_mul_f32 v[34:35], v[34:35], v[38:39]
	v_pk_mul_f32 v[36:37], v[36:37], v[40:41]
	v_cvt_pk_bf16_f32 v34, v34, v35
	v_cvt_pk_bf16_f32 v35, v36, v37
	flat_store_dwordx2 v[66:67], v[34:35]
	ds_write_b128 v99, v[2:5]
	v_lshlrev_b64 v[2:3], 11, v[70:71]
	ds_write_b128 v99, v[6:9] offset:64
	ds_write_b128 v99, v[10:13] offset:128
	ds_write_b128 v99, v[14:17] offset:192
	ds_write_b128 v99, v[18:21] offset:4352
	ds_write_b128 v99, v[22:25] offset:4416
	ds_write_b128 v99, v[26:29] offset:4480
	ds_write_b128 v99, v[30:33] offset:4544
	v_lshl_add_u64 v[4:5], v[0:1], 0, v[2:3]
	flat_load_dwordx2 v[6:7], v[4:5]
	v_or_b32_e32 v2, v76, v100
	v_ashrrev_i32_e32 v3, 31, v2
	v_lshlrev_b64 v[2:3], 11, v[2:3]
	v_lshl_add_u64 v[8:9], v[0:1], 0, v[2:3]
	flat_load_dwordx2 v[10:11], v[8:9]
	v_or_b32_e32 v2, v76, v101
	v_ashrrev_i32_e32 v3, 31, v2
	v_lshlrev_b64 v[2:3], 11, v[2:3]
	v_lshl_add_u64 v[12:13], v[0:1], 0, v[2:3]
	flat_load_dwordx2 v[14:15], v[12:13]
	v_or_b32_e32 v2, v76, v102
	v_ashrrev_i32_e32 v3, 31, v2
	v_lshlrev_b64 v[2:3], 11, v[2:3]
	v_lshl_add_u64 v[16:17], v[0:1], 0, v[2:3]
	flat_load_dwordx2 v[18:19], v[16:17]
	v_or_b32_e32 v2, v76, v103
	v_ashrrev_i32_e32 v3, 31, v2
	v_lshlrev_b64 v[2:3], 11, v[2:3]
	v_lshl_add_u64 v[20:21], v[0:1], 0, v[2:3]
	flat_load_dwordx2 v[22:23], v[20:21]
	v_or_b32_e32 v2, v76, v104
	v_ashrrev_i32_e32 v3, 31, v2
	v_lshlrev_b64 v[2:3], 11, v[2:3]
	v_lshl_add_u64 v[24:25], v[0:1], 0, v[2:3]
	flat_load_dwordx2 v[26:27], v[24:25]
	v_or_b32_e32 v2, v76, v105
	v_ashrrev_i32_e32 v3, 31, v2
	v_lshlrev_b64 v[2:3], 11, v[2:3]
	v_lshl_add_u64 v[28:29], v[0:1], 0, v[2:3]
	flat_load_dwordx2 v[30:31], v[28:29]
	v_or_b32_e32 v2, v76, v106
	v_ashrrev_i32_e32 v3, 31, v2
	v_lshlrev_b64 v[2:3], 11, v[2:3]
	v_lshl_add_u64 v[32:33], v[0:1], 0, v[2:3]
	flat_load_dwordx2 v[34:35], v[32:33]
	ds_read_b128 v[0:3], v98
	v_mov_b32_e32 v40, s51
	v_mov_b32_e32 v41, v132
	s_waitcnt vmcnt(0) lgkmcnt(0)
	v_and_b32_e32 v37, 0xffff0000, v6
	v_lshlrev_b32_e32 v36, 16, v6
	v_and_b32_e32 v39, 0xffff0000, v7
	v_lshlrev_b32_e32 v38, 16, v7
	v_pk_mul_f32 v[0:1], v[0:1], v[36:37]
	v_pk_mul_f32 v[2:3], v[2:3], v[38:39]
	v_cvt_pk_bf16_f32 v0, v0, v1
	v_cvt_pk_bf16_f32 v1, v2, v3
	flat_store_dwordx2 v[4:5], v[0:1]
	ds_read_b128 v[0:3], v98 offset:1088
	v_and_b32_e32 v5, 0xffff0000, v10
	v_lshlrev_b32_e32 v4, 16, v10
	v_and_b32_e32 v7, 0xffff0000, v11
	v_lshlrev_b32_e32 v6, 16, v11
	s_waitcnt lgkmcnt(0)
	v_pk_mul_f32 v[0:1], v[0:1], v[4:5]
	v_pk_mul_f32 v[2:3], v[2:3], v[6:7]
	v_cvt_pk_bf16_f32 v0, v0, v1
	v_cvt_pk_bf16_f32 v1, v2, v3
	flat_store_dwordx2 v[8:9], v[0:1]
	ds_read_b128 v[0:3], v98 offset:2176
	v_and_b32_e32 v5, 0xffff0000, v14
	v_lshlrev_b32_e32 v4, 16, v14
	v_and_b32_e32 v7, 0xffff0000, v15
	v_lshlrev_b32_e32 v6, 16, v15
	s_waitcnt lgkmcnt(0)
	v_pk_mul_f32 v[0:1], v[0:1], v[4:5]
	v_pk_mul_f32 v[2:3], v[2:3], v[6:7]
	v_cvt_pk_bf16_f32 v0, v0, v1
	v_cvt_pk_bf16_f32 v1, v2, v3
	flat_store_dwordx2 v[12:13], v[0:1]
	ds_read_b128 v[0:3], v98 offset:3264
	v_and_b32_e32 v5, 0xffff0000, v18
	v_lshlrev_b32_e32 v4, 16, v18
	v_and_b32_e32 v7, 0xffff0000, v19
	v_lshlrev_b32_e32 v6, 16, v19
	s_waitcnt lgkmcnt(0)
	v_pk_mul_f32 v[0:1], v[0:1], v[4:5]
	v_pk_mul_f32 v[2:3], v[2:3], v[6:7]
	v_cvt_pk_bf16_f32 v0, v0, v1
	v_cvt_pk_bf16_f32 v1, v2, v3
	flat_store_dwordx2 v[16:17], v[0:1]
	ds_read_b128 v[0:3], v98 offset:4352
	v_and_b32_e32 v5, 0xffff0000, v22
	v_lshlrev_b32_e32 v4, 16, v22
	v_and_b32_e32 v7, 0xffff0000, v23
	v_lshlrev_b32_e32 v6, 16, v23
	s_waitcnt lgkmcnt(0)
	v_pk_mul_f32 v[0:1], v[0:1], v[4:5]
	v_pk_mul_f32 v[2:3], v[2:3], v[6:7]
	v_cvt_pk_bf16_f32 v0, v0, v1
	v_cvt_pk_bf16_f32 v1, v2, v3
	flat_store_dwordx2 v[20:21], v[0:1]
	ds_read_b128 v[0:3], v98 offset:5440
	v_and_b32_e32 v5, 0xffff0000, v26
	v_lshlrev_b32_e32 v4, 16, v26
	v_and_b32_e32 v7, 0xffff0000, v27
	v_lshlrev_b32_e32 v6, 16, v27
	s_waitcnt lgkmcnt(0)
	v_pk_mul_f32 v[0:1], v[0:1], v[4:5]
	v_pk_mul_f32 v[2:3], v[2:3], v[6:7]
	v_cvt_pk_bf16_f32 v0, v0, v1
	v_cvt_pk_bf16_f32 v1, v2, v3
	flat_store_dwordx2 v[24:25], v[0:1]
	ds_read_b128 v[0:3], v98 offset:6528
	v_and_b32_e32 v5, 0xffff0000, v30
	v_lshlrev_b32_e32 v4, 16, v30
	v_and_b32_e32 v7, 0xffff0000, v31
	v_lshlrev_b32_e32 v6, 16, v31
	s_waitcnt lgkmcnt(0)
	v_pk_mul_f32 v[0:1], v[0:1], v[4:5]
	v_pk_mul_f32 v[2:3], v[2:3], v[6:7]
	v_cvt_pk_bf16_f32 v0, v0, v1
	v_cvt_pk_bf16_f32 v1, v2, v3
	flat_store_dwordx2 v[28:29], v[0:1]
	ds_read_b128 v[0:3], v98 offset:7616
	v_and_b32_e32 v5, 0xffff0000, v34
	v_lshlrev_b32_e32 v4, 16, v34
	v_and_b32_e32 v7, 0xffff0000, v35
	v_lshlrev_b32_e32 v6, 16, v35
	s_waitcnt lgkmcnt(0)
	v_pk_mul_f32 v[0:1], v[0:1], v[4:5]
	v_pk_mul_f32 v[2:3], v[2:3], v[6:7]
	v_cvt_pk_bf16_f32 v0, v0, v1
	v_cvt_pk_bf16_f32 v1, v2, v3
	flat_store_dwordx2 v[32:33], v[0:1]
	ds_read_b64 v[128:129], v40
	s_waitcnt lgkmcnt(0)
	v_lshl_add_u64 v[2:3], v[128:129], 0, s[42:43]
	v_lshlrev_b32_e32 v5, 4, v41
	v_and_b32_e32 v0, 32, v41
	v_lshrrev_b32_e32 v1, 1, v41
	v_bitop3_b32 v0, v5, v0, 48 bitop3:0x6c
	v_bfe_u32 v16, v41, 2, 4
	v_ashrrev_i32_e32 v17, 3, v41
	v_and_b32_e32 v9, 0xfffffc00, v5
	v_and_b32_e32 v18, 32, v1
	v_add_u32_e32 v1, 0x2000, v5
	v_lshrrev_b32_e32 v19, 1, v0
	v_add_u32_e32 v8, 0x4000, v5
	v_add_u32_e32 v5, 0x6000, v5
	v_and_or_b32 v4, v17, s44, v16
	v_ashrrev_i32_e32 v20, 7, v1
	v_or_b32_e32 v10, v19, v18
	v_ashrrev_i32_e32 v21, 7, v8
	v_ashrrev_i32_e32 v22, 7, v5
	v_and_or_b32 v6, v20, s44, v16
	v_lshl_add_u64 v[0:1], v[128:129], 0, s[36:37]
	v_lshl_or_b32 v130, v4, 10, v10
	v_and_or_b32 v8, v21, s44, v16
	v_and_or_b32 v5, v22, s44, v16
	v_add_u32_e32 v151, 0, v9
	v_lshl_or_b32 v4, v6, 10, v10
	v_lshl_add_u64 v[6:7], v[0:1], 0, s[4:5]
	v_lshl_or_b32 v8, v8, 10, v10
	v_lshl_or_b32 v10, v5, 10, v10
	v_add_u32_e32 v5, 0x8000, v151
	v_lshlrev_b64 v[12:13], 1, v[130:131]
	v_readfirstlane_b32 s0, v151
	v_lshl_add_u64 v[14:15], v[6:7], 0, v[12:13]
	s_mov_b32 m0, s0
	v_readfirstlane_b32 s0, v5
	v_mov_b32_e32 v5, v131
	v_add_u32_e32 v9, 0x2000, v151
	global_load_lds_dwordx4 v[14:15], off
	v_lshl_add_u64 v[12:13], v[2:3], 0, v[12:13]
	s_mov_b32 m0, s0
	v_lshlrev_b64 v[4:5], 1, v[4:5]
	v_readfirstlane_b32 s0, v9
	v_add_u32_e32 v9, 0xa000, v151
	global_load_lds_dwordx4 v[12:13], off
	v_lshl_add_u64 v[12:13], v[6:7], 0, v[4:5]
	s_mov_b32 m0, s0
	v_readfirstlane_b32 s0, v9
	global_load_lds_dwordx4 v[12:13], off
	v_lshl_add_u64 v[4:5], v[2:3], 0, v[4:5]
	s_mov_b32 m0, s0
	v_mov_b32_e32 v9, v131
	v_add_u32_e32 v11, 0x4000, v151
	global_load_lds_dwordx4 v[4:5], off
	v_lshlrev_b64 v[4:5], 1, v[8:9]
	v_readfirstlane_b32 s0, v11
	v_lshl_add_u64 v[8:9], v[6:7], 0, v[4:5]
	s_mov_b32 m0, s0
	v_lshl_add_u64 v[4:5], v[2:3], 0, v[4:5]
	global_load_lds_dwordx4 v[8:9], off
	v_add_u32_e32 v8, 0xc000, v151
	v_mov_b32_e32 v11, v131
	v_readfirstlane_b32 s0, v8
	s_mov_b32 m0, s0
	v_add_u32_e32 v8, 0x6000, v151
	global_load_lds_dwordx4 v[4:5], off
	v_lshlrev_b64 v[4:5], 1, v[10:11]
	v_readfirstlane_b32 s0, v8
	v_lshl_add_u64 v[6:7], v[6:7], 0, v[4:5]
	s_mov_b32 m0, s0
	v_lshl_add_u64 v[4:5], v[2:3], 0, v[4:5]
	global_load_lds_dwordx4 v[6:7], off
	v_add_u32_e32 v6, 0xe000, v151
	v_and_b32_e32 v23, 15, v41
	v_readfirstlane_b32 s0, v6
	s_mov_b32 m0, s0
	v_lshlrev_b32_e32 v6, 2, v41
	global_load_lds_dwordx4 v[4:5], off
	v_and_b32_e32 v4, 48, v41
	v_lshlrev_b32_e32 v5, 6, v23
	v_and_b32_e32 v6, 32, v6
	v_bitop3_b32 v152, v5, v6, v4 bitop3:0x36
	v_lshlrev_b32_e32 v5, 7, v41
	v_and_b32_e32 v153, 0x6000, v5
	v_lshlrev_b32_e32 v5, 6, v41
	v_and_b32_e32 v154, 0xffffc000, v5
	v_and_b32_e32 v5, 0x3c0, v5
	v_bitop3_b32 v156, v5, v6, v4 bitop3:0x36
	v_lshlrev_b32_e32 v4, 10, v22
	v_and_or_b32 v4, v4, s45, v19
	v_lshlrev_b32_e32 v10, 10, v16
	v_lshlrev_b32_e32 v6, 10, v21
	v_or3_b32 v130, v4, v10, v18
	v_and_or_b32 v6, v6, s45, v19
	v_lshlrev_b32_e32 v8, 10, v20
	v_lshlrev_b64 v[4:5], 1, v[130:131]
	v_or3_b32 v130, v6, v10, v18
	v_and_or_b32 v8, v8, s45, v19
	v_lshlrev_b32_e32 v11, 10, v17
	v_lshlrev_b64 v[6:7], 1, v[130:131]
	v_or3_b32 v130, v8, v10, v18
	v_and_or_b32 v11, v11, s45, v19
	s_nop 0
	v_lshl_add_u64 v[2:3], v[2:3], 0, s[6:7]
	v_lshlrev_b64 v[8:9], 1, v[130:131]
	v_or3_b32 v130, v11, v10, v18
	v_lshl_add_u64 v[0:1], v[0:1], 0, s[8:9]
	v_lshl_add_u64 v[138:139], v[2:3], 0, v[8:9]
	v_lshlrev_b64 v[10:11], 1, v[130:131]
	v_lshl_add_u64 v[146:147], v[0:1], 0, v[8:9]
	v_or_b32_e32 v155, 0x800, v154
	v_or_b32_e32 v157, 0x1000, v154
	v_or_b32_e32 v158, 0x1800, v154
	v_or_b32_e32 v159, 0x2000, v154
	v_or_b32_e32 v160, 0x2800, v154
	v_or_b32_e32 v161, 0x3000, v154
	v_or_b32_e32 v162, 0x3800, v154
	v_lshl_add_u64 v[134:135], v[2:3], 0, v[4:5]
	v_lshl_add_u64 v[136:137], v[2:3], 0, v[6:7]
	v_lshl_add_u64 v[140:141], v[2:3], 0, v[10:11]
	v_lshl_add_u64 v[142:143], v[0:1], 0, v[4:5]
	v_lshl_add_u64 v[144:145], v[0:1], 0, v[6:7]
	v_lshl_add_u64 v[148:149], v[0:1], 0, v[10:11]
	s_mov_b64 s[42:43], 0
	s_waitcnt vmcnt(0) lgkmcnt(0)
	s_barrier
	v_readfirstlane_b32 s100, v151
	s_and_b32 s0, s29, 0x10000
	s_xor_b32 s53, s0, 0x10000
	s_add_i32 s0, s0, 0
	v_add3_u32 v130, s0, v152, v153
	v_add3_u32 v163, s0, v152, v154
	v_add3_u32 v196, s0, v156, v155
	v_add3_u32 v197, s0, v156, v157
	v_add3_u32 v198, s0, v156, v158
	v_add3_u32 v199, s0, v156, v159
	v_add3_u32 v200, s0, v156, v160
	v_add3_u32 v201, s0, v156, v161
	v_add3_u32 v202, s0, v156, v162
	ds_read_b128 v[180:183], v130 offset:32768
	ds_read_b128 v[164:167], v163
	ds_read_b128 v[168:171], v196
	ds_read_b128 v[172:175], v197
	ds_read_b128 v[176:179], v198
	ds_read_b128 v[184:187], v130 offset:34816
	ds_read_b128 v[188:191], v130 offset:36864
	ds_read_b128 v[192:195], v130 offset:38912
	s_add_i32 s101, s100, s53
	v_readfirstlane_b32 s98, v148
	v_readfirstlane_b32 s99, v149
	v_readfirstlane_b32 vcc_lo, v140
	v_readfirstlane_b32 vcc_hi, v141
	s_sub_u32 s98, s98, 0x1000000
	s_subb_u32 s99, s99, 0
	s_sub_u32 vcc_lo, vcc_lo, 0x1000000
	s_subb_u32 vcc_hi, vcc_hi, 0
	v_subrev_u32_e32 v148, s98, v148
	v_subrev_u32_e32 v140, vcc_lo, v140
	v_subrev_u32_e32 v146, s98, v146
	v_subrev_u32_e32 v138, vcc_lo, v138
	v_subrev_u32_e32 v144, s98, v144
	v_subrev_u32_e32 v136, vcc_lo, v136
	v_subrev_u32_e32 v142, s98, v142
	v_subrev_u32_e32 v134, vcc_lo, v134
	s_mov_b32 m0, s101
	s_nop 0
	global_load_lds_dwordx4 v148, s[98:99]
	s_add_i32 m0, s101, 0x8000
	s_nop 0
	global_load_lds_dwordx4 v140, vcc
	s_add_i32 m0, s101, 0x2000
	s_nop 0
	global_load_lds_dwordx4 v146, s[98:99]
	s_add_i32 m0, s101, 0xa000
	s_nop 0
	global_load_lds_dwordx4 v138, vcc
	s_add_i32 m0, s101, 0x4000
	s_nop 0
	global_load_lds_dwordx4 v144, s[98:99]
	s_add_i32 m0, s101, 0xc000
	s_nop 0
	global_load_lds_dwordx4 v136, vcc
	s_add_i32 m0, s101, 0x6000
	s_nop 0
	global_load_lds_dwordx4 v142, s[98:99]
	s_add_i32 m0, s101, 0xe000
	s_nop 0
	global_load_lds_dwordx4 v134, vcc

.Lg2b_795:
	s_waitcnt lgkmcnt(3)
	v_mfma_f32_16x16x32_bf16 v[124:127], v[180:183], v[164:167], v[124:127]
	v_mfma_f32_16x16x32_bf16 v[108:111], v[180:183], v[168:171], v[108:111]
	v_mfma_f32_16x16x32_bf16 v[92:95], v[180:183], v[172:175], v[92:95]
	v_mfma_f32_16x16x32_bf16 v[76:79], v[180:183], v[176:179], v[76:79]
	ds_read_b128 v[240:243], v199 offset:1024
	ds_read_b128 v[244:247], v200 offset:1024
	s_waitcnt lgkmcnt(4)
	v_mfma_f32_16x16x32_bf16 v[120:123], v[184:187], v[164:167], v[120:123]
	v_mfma_f32_16x16x32_bf16 v[104:107], v[184:187], v[168:171], v[104:107]
	v_mfma_f32_16x16x32_bf16 v[88:91], v[184:187], v[172:175], v[88:91]
	v_mfma_f32_16x16x32_bf16 v[72:75], v[184:187], v[176:179], v[72:75]
	ds_read_b128 v[248:251], v201 offset:1024
	ds_read_b128 v[252:255], v202 offset:1024
	s_waitcnt lgkmcnt(5)
	v_mfma_f32_16x16x32_bf16 v[116:119], v[188:191], v[164:167], v[116:119]
	v_mfma_f32_16x16x32_bf16 v[100:103], v[188:191], v[168:171], v[100:103]
	v_mfma_f32_16x16x32_bf16 v[84:87], v[188:191], v[172:175], v[84:87]
	v_mfma_f32_16x16x32_bf16 v[68:71], v[188:191], v[176:179], v[68:71]
	s_waitcnt lgkmcnt(4)
	v_mfma_f32_16x16x32_bf16 v[112:115], v[192:195], v[164:167], v[112:115]
	v_mfma_f32_16x16x32_bf16 v[96:99], v[192:195], v[168:171], v[96:99]
	v_mfma_f32_16x16x32_bf16 v[80:83], v[192:195], v[172:175], v[80:83]
	v_mfma_f32_16x16x32_bf16 v[64:67], v[192:195], v[176:179], v[64:67]
	s_add_i32 s101, s100, s0
	s_cmpk_eq_i32 s42, 0x700
	s_cbranch_scc1 .Lg4n_795
	s_waitcnt vmcnt(0) lgkmcnt(0)
	s_barrier
	s_add_u32 s98, s98, 0x80
	s_addc_u32 s99, s99, 0
	s_add_u32 vcc_lo, vcc_lo, 0x80
	s_addc_u32 vcc_hi, vcc_hi, 0
	v_mfma_f32_16x16x32_bf16 v[60:63], v[180:183], v[240:243], v[60:63]
	v_mfma_f32_16x16x32_bf16 v[44:47], v[180:183], v[244:247], v[44:47]
	v_mfma_f32_16x16x32_bf16 v[16:19], v[180:183], v[248:251], v[16:19]
	v_mfma_f32_16x16x32_bf16 v[36:39], v[180:183], v[252:255], v[36:39]
	v_add3_u32 v130, s53, v152, v153
	ds_read_b128 v[180:183], v130 offset:32768
	v_add3_u32 v163, s53, v152, v154
	v_add3_u32 v196, s53, v156, v155
	v_add3_u32 v197, s53, v156, v157
	v_add3_u32 v198, s53, v156, v158
	ds_read_b128 v[164:167], v163
	ds_read_b128 v[168:171], v196
	ds_read_b128 v[172:175], v197
	ds_read_b128 v[176:179], v198
	s_mov_b32 m0, s101
	s_nop 0
	global_load_lds_dwordx4 v148, s[98:99]
	v_mfma_f32_16x16x32_bf16 v[56:59], v[184:187], v[240:243], v[56:59]
	v_mfma_f32_16x16x32_bf16 v[40:43], v[184:187], v[244:247], v[40:43]
	v_mfma_f32_16x16x32_bf16 v[12:15], v[184:187], v[248:251], v[12:15]
	v_mfma_f32_16x16x32_bf16 v[28:31], v[184:187], v[252:255], v[28:31]
	ds_read_b128 v[184:187], v130 offset:34816
	v_add3_u32 v199, s53, v156, v159
	v_add3_u32 v200, s53, v156, v160
	v_add3_u32 v201, s53, v156, v161
	v_add3_u32 v202, s53, v156, v162
	s_add_i32 m0, s101, 0x8000
	s_nop 0
	global_load_lds_dwordx4 v140, vcc
	v_mfma_f32_16x16x32_bf16 v[52:55], v[188:191], v[240:243], v[52:55]
	v_mfma_f32_16x16x32_bf16 v[32:35], v[188:191], v[244:247], v[32:35]
	v_mfma_f32_16x16x32_bf16 v[4:7], v[188:191], v[248:251], v[4:7]
	v_mfma_f32_16x16x32_bf16 v[20:23], v[188:191], v[252:255], v[20:23]
	ds_read_b128 v[188:191], v130 offset:36864
	s_add_i32 m0, s101, 0x2000
	s_nop 0
	global_load_lds_dwordx4 v146, s[98:99]
	v_mfma_f32_16x16x32_bf16 v[48:51], v[192:195], v[240:243], v[48:51]
	v_mfma_f32_16x16x32_bf16 v[24:27], v[192:195], v[244:247], v[24:27]
	v_mfma_f32_16x16x32_bf16 v[0:3], v[192:195], v[248:251], v[0:3]
	v_mfma_f32_16x16x32_bf16 v[8:11], v[192:195], v[252:255], v[8:11]
	ds_read_b128 v[192:195], v130 offset:38912
	s_add_i32 m0, s101, 0xa000
	s_nop 0
	global_load_lds_dwordx4 v138, vcc

.Lg1n_795:
	s_waitcnt lgkmcnt(3)
	v_mfma_f32_16x16x32_bf16 v[124:127], v[180:183], v[164:167], 0
	v_mfma_f32_16x16x32_bf16 v[108:111], v[180:183], v[168:171], 0
	v_mfma_f32_16x16x32_bf16 v[92:95], v[180:183], v[172:175], 0
	v_mfma_f32_16x16x32_bf16 v[76:79], v[180:183], v[176:179], 0
	ds_read_b128 v[240:243], v199
	ds_read_b128 v[244:247], v200
	s_waitcnt lgkmcnt(4)
	v_mfma_f32_16x16x32_bf16 v[120:123], v[184:187], v[164:167], 0
	v_mfma_f32_16x16x32_bf16 v[104:107], v[184:187], v[168:171], 0
	v_mfma_f32_16x16x32_bf16 v[88:91], v[184:187], v[172:175], 0
	v_mfma_f32_16x16x32_bf16 v[72:75], v[184:187], v[176:179], 0
	ds_read_b128 v[248:251], v201
	ds_read_b128 v[252:255], v202
	s_waitcnt lgkmcnt(5)
	v_mfma_f32_16x16x32_bf16 v[116:119], v[188:191], v[164:167], 0
	v_mfma_f32_16x16x32_bf16 v[100:103], v[188:191], v[168:171], 0
	v_mfma_f32_16x16x32_bf16 v[84:87], v[188:191], v[172:175], 0
	v_mfma_f32_16x16x32_bf16 v[68:71], v[188:191], v[176:179], 0
	s_waitcnt lgkmcnt(4)
	v_mfma_f32_16x16x32_bf16 v[112:115], v[192:195], v[164:167], 0
	v_mfma_f32_16x16x32_bf16 v[96:99], v[192:195], v[168:171], 0
	v_mfma_f32_16x16x32_bf16 v[80:83], v[192:195], v[172:175], 0
	v_mfma_f32_16x16x32_bf16 v[64:67], v[192:195], v[176:179], 0
	ds_read_b128 v[164:167], v163 offset:1024
	ds_read_b128 v[168:171], v196 offset:1024
	ds_read_b128 v[172:175], v197 offset:1024
	ds_read_b128 v[176:179], v198 offset:1024
	s_waitcnt lgkmcnt(4)
	v_mfma_f32_16x16x32_bf16 v[60:63], v[180:183], v[240:243], 0
	v_mfma_f32_16x16x32_bf16 v[44:47], v[180:183], v[244:247], 0
	v_mfma_f32_16x16x32_bf16 v[16:19], v[180:183], v[248:251], 0
	v_mfma_f32_16x16x32_bf16 v[36:39], v[180:183], v[252:255], 0
	ds_read_b128 v[180:183], v130 offset:33792
	v_mfma_f32_16x16x32_bf16 v[56:59], v[184:187], v[240:243], 0
	v_mfma_f32_16x16x32_bf16 v[40:43], v[184:187], v[244:247], 0
	v_mfma_f32_16x16x32_bf16 v[12:15], v[184:187], v[248:251], 0
	v_mfma_f32_16x16x32_bf16 v[28:31], v[184:187], v[252:255], 0
	ds_read_b128 v[184:187], v130 offset:35840
	v_mfma_f32_16x16x32_bf16 v[52:55], v[188:191], v[240:243], 0
	v_mfma_f32_16x16x32_bf16 v[32:35], v[188:191], v[244:247], 0
	v_mfma_f32_16x16x32_bf16 v[4:7], v[188:191], v[248:251], 0
	v_mfma_f32_16x16x32_bf16 v[20:23], v[188:191], v[252:255], 0
	ds_read_b128 v[188:191], v130 offset:37888
	v_mfma_f32_16x16x32_bf16 v[48:51], v[192:195], v[240:243], 0
	v_mfma_f32_16x16x32_bf16 v[24:27], v[192:195], v[244:247], 0
	v_mfma_f32_16x16x32_bf16 v[0:3], v[192:195], v[248:251], 0
	v_mfma_f32_16x16x32_bf16 v[8:11], v[192:195], v[252:255], 0
	ds_read_b128 v[192:195], v130 offset:39936
	s_branch .Lg2b_795

.Lex_795:
	s_waitcnt lgkmcnt(0)
	v_add3_u32 v130, s46, v156, v162
	v_add3_u32 v151, s46, v156, v161
	v_add3_u32 v206, s46, v156, v160
	v_add3_u32 v198, s46, v156, v159
	v_add3_u32 v186, s46, v156, v158
	v_add3_u32 v187, s46, v156, v157
	v_add3_u32 v188, s46, v156, v155
	v_add3_u32 v189, s46, v152, v154
	v_add3_u32 v190, s47, v152, v153
	ds_read_b128 v[134:137], v130
	ds_read_b128 v[138:141], v151
	ds_read_b128 v[142:145], v206
	ds_read_b128 v[146:149], v198
	ds_read_b128 v[158:161], v186
	ds_read_b128 v[162:165], v187
	ds_read_b128 v[166:169], v188
	ds_read_b128 v[154:157], v189
	ds_read_b128 v[170:173], v190
	s_waitcnt lgkmcnt(0)
	v_mfma_f32_16x16x32_bf16 v[16:19], v[170:173], v[138:141], v[16:19]
	v_mfma_f32_16x16x32_bf16 v[174:177], v[170:173], v[134:137], v[36:39]
	s_nop 2
	ds_read_b128 v[36:39], v190 offset:2048
	s_waitcnt lgkmcnt(0)
	v_mfma_f32_16x16x32_bf16 v[12:15], v[36:39], v[138:141], v[12:15]
	v_mfma_f32_16x16x32_bf16 v[60:63], v[170:173], v[146:149], v[60:63]
	v_mfma_f32_16x16x32_bf16 v[28:31], v[36:39], v[134:137], v[28:31]
	v_mfma_f32_16x16x32_bf16 v[56:59], v[36:39], v[146:149], v[56:59]
	ds_read_b128 v[178:181], v190 offset:4096
	s_waitcnt lgkmcnt(0)
	v_mfma_f32_16x16x32_bf16 v[182:185], v[178:181], v[134:137], v[20:23]
	v_mfma_f32_16x16x32_bf16 v[52:55], v[178:181], v[146:149], v[52:55]
	s_nop 1
	ds_read_b128 v[20:23], v190 offset:6144
	s_waitcnt lgkmcnt(0)
	v_mfma_f32_16x16x32_bf16 v[134:137], v[20:23], v[134:137], v[8:11]
	v_mfma_f32_16x16x32_bf16 v[8:11], v[20:23], v[154:157], v[112:115]
	v_mfma_f32_16x16x32_bf16 v[112:115], v[20:23], v[158:161], v[64:67]
	v_mfma_f32_16x16x32_bf16 v[64:67], v[178:181], v[154:157], v[116:119]
	v_mfma_f32_16x16x32_bf16 v[116:119], v[178:181], v[158:161], v[68:71]
	v_mfma_f32_16x16x32_bf16 v[68:71], v[36:39], v[154:157], v[120:123]
	v_mfma_f32_16x16x32_bf16 v[120:123], v[36:39], v[158:161], v[72:75]
	v_mfma_f32_16x16x32_bf16 v[72:75], v[170:173], v[154:157], v[124:127]
	v_mfma_f32_16x16x32_bf16 v[124:127], v[170:173], v[158:161], v[76:79]
	v_mfma_f32_16x16x32_bf16 v[48:51], v[20:23], v[146:149], v[48:51]
	v_mfma_f32_16x16x32_bf16 v[146:149], v[170:173], v[142:145], v[44:47]
	v_mfma_f32_16x16x32_bf16 v[152:155], v[36:39], v[142:145], v[40:43]
	v_mfma_f32_16x16x32_bf16 v[156:159], v[178:181], v[142:145], v[32:35]
	v_mfma_f32_16x16x32_bf16 v[24:27], v[20:23], v[142:145], v[24:27]
	v_mfma_f32_16x16x32_bf16 v[142:145], v[178:181], v[138:141], v[4:7]
	v_mfma_f32_16x16x32_bf16 v[108:111], v[170:173], v[166:169], v[108:111]
	v_mfma_f32_16x16x32_bf16 v[92:95], v[170:173], v[162:165], v[92:95]
	v_mfma_f32_16x16x32_bf16 v[104:107], v[36:39], v[166:169], v[104:107]
	v_mfma_f32_16x16x32_bf16 v[88:91], v[36:39], v[162:165], v[88:91]
	v_mfma_f32_16x16x32_bf16 v[100:103], v[178:181], v[166:169], v[100:103]
	v_mfma_f32_16x16x32_bf16 v[84:87], v[178:181], v[162:165], v[84:87]
	v_mfma_f32_16x16x32_bf16 v[96:99], v[20:23], v[166:169], v[96:99]
	v_mfma_f32_16x16x32_bf16 v[80:83], v[20:23], v[162:165], v[80:83]
	v_mfma_f32_16x16x32_bf16 v[20:23], v[20:23], v[138:141], v[0:3]
	ds_read_b128 v[138:141], v190 offset:1024
	ds_read_b128 v[160:163], v190 offset:3072
	ds_read_b128 v[164:167], v190 offset:5120
	ds_read_b128 v[168:171], v190 offset:7168
	ds_read_b128 v[0:3], v189 offset:1024
	ds_read_b128 v[4:7], v188 offset:1024
	ds_read_b128 v[32:35], v187 offset:1024
	ds_read_b128 v[36:39], v186 offset:1024
	s_waitcnt lgkmcnt(3)
	v_mfma_f32_16x16x32_bf16 v[178:181], v[138:141], v[0:3], v[72:75]
	v_mfma_f32_16x16x32_bf16 v[186:189], v[160:163], v[0:3], v[68:71]
	v_mfma_f32_16x16x32_bf16 v[190:193], v[164:167], v[0:3], v[64:67]
	v_mfma_f32_16x16x32_bf16 v[194:197], v[168:171], v[0:3], v[8:11]
	ds_read_b128 v[0:3], v198 offset:1024
	s_waitcnt lgkmcnt(3)
	v_mfma_f32_16x16x32_bf16 v[108:111], v[138:141], v[4:7], v[108:111]
	v_mfma_f32_16x16x32_bf16 v[104:107], v[160:163], v[4:7], v[104:107]
	v_mfma_f32_16x16x32_bf16 v[198:201], v[164:167], v[4:7], v[100:103]
	v_mfma_f32_16x16x32_bf16 v[202:205], v[168:171], v[4:7], v[96:99]
	ds_read_b128 v[4:7], v206 offset:1024
	s_waitcnt lgkmcnt(3)
	v_mfma_f32_16x16x32_bf16 v[64:67], v[138:141], v[32:35], v[92:95]
	v_mfma_f32_16x16x32_bf16 v[68:71], v[160:163], v[32:35], v[88:91]
	v_mfma_f32_16x16x32_bf16 v[72:75], v[164:167], v[32:35], v[84:87]
	v_mfma_f32_16x16x32_bf16 v[76:79], v[168:171], v[32:35], v[80:83]
	ds_read_b128 v[96:99], v151 offset:1024
	s_waitcnt lgkmcnt(3)
	v_mfma_f32_16x16x32_bf16 v[80:83], v[138:141], v[36:39], v[124:127]
	v_mfma_f32_16x16x32_bf16 v[84:87], v[160:163], v[36:39], v[120:123]
	v_mfma_f32_16x16x32_bf16 v[88:91], v[164:167], v[36:39], v[116:119]
	v_mfma_f32_16x16x32_bf16 v[92:95], v[168:171], v[36:39], v[112:115]
	ds_read_b128 v[100:103], v130 offset:1024
	s_waitcnt lgkmcnt(3)
	v_mfma_f32_16x16x32_bf16 v[32:35], v[138:141], v[0:3], v[60:63]
	v_mfma_f32_16x16x32_bf16 v[36:39], v[160:163], v[0:3], v[56:59]
	v_mfma_f32_16x16x32_bf16 v[40:43], v[164:167], v[0:3], v[52:55]
	v_mfma_f32_16x16x32_bf16 v[44:47], v[168:171], v[0:3], v[48:51]
	s_waitcnt lgkmcnt(2)
	v_mfma_f32_16x16x32_bf16 v[48:51], v[138:141], v[4:7], v[146:149]
	v_mfma_f32_16x16x32_bf16 v[52:55], v[160:163], v[4:7], v[152:155]
	v_mfma_f32_16x16x32_bf16 v[56:59], v[164:167], v[4:7], v[156:159]
	v_mfma_f32_16x16x32_bf16 v[60:63], v[168:171], v[4:7], v[24:27]
	s_waitcnt lgkmcnt(1)
	v_mfma_f32_16x16x32_bf16 v[0:3], v[138:141], v[96:99], v[16:19]
	v_mfma_f32_16x16x32_bf16 v[4:7], v[160:163], v[96:99], v[12:15]
	v_mfma_f32_16x16x32_bf16 v[8:11], v[164:167], v[96:99], v[142:145]
	v_mfma_f32_16x16x32_bf16 v[12:15], v[168:171], v[96:99], v[20:23]
	s_waitcnt lgkmcnt(0)
	v_mfma_f32_16x16x32_bf16 v[16:19], v[138:141], v[100:103], v[174:177]
	v_mfma_f32_16x16x32_bf16 v[20:23], v[160:163], v[100:103], v[28:31]
	v_mfma_f32_16x16x32_bf16 v[24:27], v[164:167], v[100:103], v[182:185]
	v_mfma_f32_16x16x32_bf16 v[28:31], v[168:171], v[100:103], v[134:137]
	v_lshrrev_b32_e32 v96, 6, v150
	v_lshlrev_b32_e32 v98, 2, v150
	v_and_b32_e32 v97, 15, v150
	v_mul_lo_u32 v96, v96, s48
	v_and_b32_e32 v112, 60, v98
	v_bfe_u32 v99, v150, 4, 2
	v_add_u32_e32 v96, s46, v96
	v_and_b32_e32 v100, 48, v150
	v_lshlrev_b32_e32 v98, 2, v112
	v_mul_u32_u24_e32 v101, 0x110, v99
	v_mul_u32_u24_e32 v97, 0x110, v97
	v_add3_u32 v98, v96, v98, v101
	v_add3_u32 v101, v96, v100, v97
	s_waitcnt vmcnt(0)
	s_barrier
	ds_write_b128 v101, v[178:181]
	ds_write_b128 v101, v[186:189] offset:64
	ds_write_b128 v101, v[190:193] offset:128
	ds_write_b128 v101, v[194:197] offset:192
	ds_write_b128 v101, v[108:111] offset:4352
	ds_write_b128 v101, v[104:107] offset:4416
	ds_write_b128 v101, v[198:201] offset:4480
	ds_write_b128 v101, v[202:205] offset:4544
	ds_read_b128 v[102:105], v98
	v_ashrrev_i32_e32 v113, 1, v150
	v_and_b32_e32 v96, 0xffffff80, v113
	v_and_or_b32 v106, v150, s49, v112
	v_add_u32_e32 v100, s28, v96
	s_waitcnt lgkmcnt(0)
	v_mul_f32_e32 v102, 0xbfb8aa3b, v102
	v_mul_f32_e32 v103, 0xbfb8aa3b, v103
	v_mul_f32_e32 v104, 0xbfb8aa3b, v104
	v_mul_f32_e32 v105, 0xbfb8aa3b, v105
	v_exp_f32_e32 v102, v102
	v_exp_f32_e32 v103, v103
	v_exp_f32_e32 v104, v104
	v_exp_f32_e32 v105, v105
	v_add_f32_e32 v102, 1.0, v102
	v_add_f32_e32 v103, 1.0, v103
	v_add_f32_e32 v104, 1.0, v104
	v_add_f32_e32 v105, 1.0, v105
	v_rcp_f32_e32 v102, v102
	v_rcp_f32_e32 v103, v103
	v_rcp_f32_e32 v104, v104
	v_rcp_f32_e32 v105, v105
	v_lshl_add_u64 v[96:97], v[128:129], 0, s[38:39]
	v_lshlrev_b32_e32 v130, 1, v106
	v_cvt_pk_bf16_f32 v102, v102, v103
	v_cvt_pk_bf16_f32 v103, v104, v105
	v_or_b32_e32 v104, v100, v99
	v_lshl_add_u64 v[96:97], v[96:97], 0, v[130:131]
	v_ashrrev_i32_e32 v105, 31, v104
	v_lshl_add_u64 v[96:97], v[96:97], 0, s[26:27]
	v_lshlrev_b64 v[104:105], 11, v[104:105]
	v_lshl_add_u64 v[104:105], v[96:97], 0, v[104:105]
	flat_store_dwordx2 v[104:105], v[102:103]
	ds_read_b128 v[102:105], v98 offset:1088
	v_mov_b32_e32 v150, v132
	s_waitcnt lgkmcnt(0)
	v_mul_f32_e32 v102, 0xbfb8aa3b, v102
	v_exp_f32_e32 v102, v102
	v_mul_f32_e32 v103, 0xbfb8aa3b, v103
	v_exp_f32_e32 v103, v103
	v_add_f32_e32 v102, 1.0, v102
	v_rcp_f32_e32 v106, v102
	v_add_f32_e32 v102, 1.0, v103
	v_mul_f32_e32 v103, 0xbfb8aa3b, v104
	v_exp_f32_e32 v103, v103
	v_mul_f32_e32 v104, 0xbfb8aa3b, v105
	v_exp_f32_e32 v104, v104
	v_rcp_f32_e32 v105, v102
	v_add_f32_e32 v102, 1.0, v103
	v_rcp_f32_e32 v103, v102
	v_add_f32_e32 v102, 1.0, v104
	v_rcp_f32_e32 v107, v102
	v_or_b32_e32 v102, 4, v99
	v_cvt_pk_bf16_f32 v104, v106, v105
	v_or_b32_e32 v106, v100, v102
	v_cvt_pk_bf16_f32 v105, v103, v107
	v_ashrrev_i32_e32 v107, 31, v106
	v_lshlrev_b64 v[106:107], 11, v[106:107]
	v_lshl_add_u64 v[106:107], v[96:97], 0, v[106:107]
	flat_store_dwordx2 v[106:107], v[104:105]
	ds_read_b128 v[104:107], v98 offset:2176
	s_waitcnt lgkmcnt(0)
	v_mul_f32_e32 v103, 0xbfb8aa3b, v104
	v_exp_f32_e32 v103, v103
	v_mul_f32_e32 v104, 0xbfb8aa3b, v105
	v_exp_f32_e32 v104, v104
	v_add_f32_e32 v103, 1.0, v103
	v_rcp_f32_e32 v105, v103
	v_add_f32_e32 v103, 1.0, v104
	v_mul_f32_e32 v104, 0xbfb8aa3b, v106
	v_exp_f32_e32 v104, v104
	v_mul_f32_e32 v106, 0xbfb8aa3b, v107
	v_exp_f32_e32 v106, v106
	v_rcp_f32_e32 v107, v103
	v_add_f32_e32 v103, 1.0, v104
	v_rcp_f32_e32 v108, v103
	v_add_f32_e32 v103, 1.0, v106
	v_rcp_f32_e32 v106, v103
	v_or_b32_e32 v103, 8, v99
	v_cvt_pk_bf16_f32 v104, v105, v107
	v_cvt_pk_bf16_f32 v105, v108, v106
	v_or_b32_e32 v106, v100, v103
	v_ashrrev_i32_e32 v107, 31, v106
	v_lshlrev_b64 v[106:107], 11, v[106:107]
	v_lshl_add_u64 v[106:107], v[96:97], 0, v[106:107]
	flat_store_dwordx2 v[106:107], v[104:105]
	ds_read_b128 v[104:107], v98 offset:3264
	s_waitcnt lgkmcnt(0)
	v_mul_f32_e32 v104, 0xbfb8aa3b, v104
	v_exp_f32_e32 v104, v104
	v_mul_f32_e32 v105, 0xbfb8aa3b, v105
	v_exp_f32_e32 v105, v105
	v_add_f32_e32 v104, 1.0, v104
	v_rcp_f32_e32 v108, v104
	v_add_f32_e32 v104, 1.0, v105
	v_mul_f32_e32 v105, 0xbfb8aa3b, v106
	v_exp_f32_e32 v105, v105
	v_mul_f32_e32 v106, 0xbfb8aa3b, v107
	v_exp_f32_e32 v106, v106
	v_rcp_f32_e32 v107, v104
	v_add_f32_e32 v104, 1.0, v105
	v_rcp_f32_e32 v105, v104
	v_add_f32_e32 v104, 1.0, v106
	v_rcp_f32_e32 v109, v104
	v_or_b32_e32 v104, 12, v99
	v_cvt_pk_bf16_f32 v106, v108, v107
	v_or_b32_e32 v108, v100, v104
	v_cvt_pk_bf16_f32 v107, v105, v109
	v_ashrrev_i32_e32 v109, 31, v108
	v_lshlrev_b64 v[108:109], 11, v[108:109]
	v_lshl_add_u64 v[108:109], v[96:97], 0, v[108:109]
	flat_store_dwordx2 v[108:109], v[106:107]
	ds_read_b128 v[106:109], v98 offset:4352
	s_waitcnt lgkmcnt(0)
	v_mul_f32_e32 v105, 0xbfb8aa3b, v106
	v_exp_f32_e32 v105, v105
	v_mul_f32_e32 v106, 0xbfb8aa3b, v107
	v_exp_f32_e32 v106, v106
	v_add_f32_e32 v105, 1.0, v105
	v_rcp_f32_e32 v107, v105
	v_add_f32_e32 v105, 1.0, v106
	v_mul_f32_e32 v106, 0xbfb8aa3b, v108
	v_exp_f32_e32 v106, v106
	v_mul_f32_e32 v108, 0xbfb8aa3b, v109
	v_exp_f32_e32 v108, v108
	v_rcp_f32_e32 v109, v105
	v_add_f32_e32 v105, 1.0, v106
	v_rcp_f32_e32 v110, v105
	v_add_f32_e32 v105, 1.0, v108
	v_rcp_f32_e32 v108, v105
	v_or_b32_e32 v105, 16, v99
	v_cvt_pk_bf16_f32 v106, v107, v109
	v_cvt_pk_bf16_f32 v107, v110, v108
	v_or_b32_e32 v108, v100, v105
	v_ashrrev_i32_e32 v109, 31, v108
	v_lshlrev_b64 v[108:109], 11, v[108:109]
	v_lshl_add_u64 v[108:109], v[96:97], 0, v[108:109]
	flat_store_dwordx2 v[108:109], v[106:107]
	ds_read_b128 v[106:109], v98 offset:5440
	s_waitcnt lgkmcnt(0)
	v_mul_f32_e32 v106, 0xbfb8aa3b, v106
	v_exp_f32_e32 v106, v106
	v_mul_f32_e32 v107, 0xbfb8aa3b, v107
	v_exp_f32_e32 v107, v107
	v_add_f32_e32 v106, 1.0, v106
	v_rcp_f32_e32 v110, v106
	v_add_f32_e32 v106, 1.0, v107
	v_mul_f32_e32 v107, 0xbfb8aa3b, v108
	v_exp_f32_e32 v107, v107
	v_mul_f32_e32 v108, 0xbfb8aa3b, v109
	v_exp_f32_e32 v108, v108
	v_rcp_f32_e32 v109, v106
	v_add_f32_e32 v106, 1.0, v107
	v_rcp_f32_e32 v107, v106
	v_add_f32_e32 v106, 1.0, v108
	v_rcp_f32_e32 v111, v106
	v_or_b32_e32 v106, 20, v99
	v_cvt_pk_bf16_f32 v108, v110, v109
	v_or_b32_e32 v110, v100, v106
	v_cvt_pk_bf16_f32 v109, v107, v111
	v_ashrrev_i32_e32 v111, 31, v110
	v_lshlrev_b64 v[110:111], 11, v[110:111]
	v_lshl_add_u64 v[110:111], v[96:97], 0, v[110:111]
	flat_store_dwordx2 v[110:111], v[108:109]
	ds_read_b128 v[108:111], v98 offset:6528
	s_waitcnt lgkmcnt(0)
	v_mul_f32_e32 v107, 0xbfb8aa3b, v108
	v_exp_f32_e32 v107, v107
	v_mul_f32_e32 v108, 0xbfb8aa3b, v109
	v_exp_f32_e32 v108, v108
	v_add_f32_e32 v107, 1.0, v107
	v_rcp_f32_e32 v109, v107
	v_add_f32_e32 v107, 1.0, v108
	v_mul_f32_e32 v108, 0xbfb8aa3b, v110
	v_exp_f32_e32 v108, v108
	v_mul_f32_e32 v110, 0xbfb8aa3b, v111
	v_exp_f32_e32 v110, v110
	v_rcp_f32_e32 v111, v107
	v_add_f32_e32 v107, 1.0, v108
	v_rcp_f32_e32 v112, v107
	v_add_f32_e32 v107, 1.0, v110
	v_rcp_f32_e32 v110, v107
	v_or_b32_e32 v107, 24, v99
	v_cvt_pk_bf16_f32 v108, v109, v111
	v_cvt_pk_bf16_f32 v109, v112, v110
	v_or_b32_e32 v110, v100, v107
	v_ashrrev_i32_e32 v111, 31, v110
	v_lshlrev_b64 v[110:111], 11, v[110:111]
	v_lshl_add_u64 v[110:111], v[96:97], 0, v[110:111]
	flat_store_dwordx2 v[110:111], v[108:109]
	ds_read_b128 v[108:111], v98 offset:7616
	s_waitcnt lgkmcnt(0)
	v_mul_f32_e32 v108, 0xbfb8aa3b, v108
	v_exp_f32_e32 v108, v108
	v_mul_f32_e32 v109, 0xbfb8aa3b, v109
	v_exp_f32_e32 v109, v109
	v_add_f32_e32 v108, 1.0, v108
	v_rcp_f32_e32 v112, v108
	v_add_f32_e32 v108, 1.0, v109
	v_mul_f32_e32 v109, 0xbfb8aa3b, v110
	v_exp_f32_e32 v109, v109
	v_mul_f32_e32 v110, 0xbfb8aa3b, v111
	v_exp_f32_e32 v110, v110
	v_rcp_f32_e32 v111, v108
	v_add_f32_e32 v108, 1.0, v109
	v_rcp_f32_e32 v109, v108
	v_add_f32_e32 v108, 1.0, v110
	v_rcp_f32_e32 v113, v108
	v_or_b32_e32 v108, 28, v99
	v_cvt_pk_bf16_f32 v110, v112, v111
	v_or_b32_e32 v112, v100, v108
	v_cvt_pk_bf16_f32 v111, v109, v113
	v_ashrrev_i32_e32 v113, 31, v112
	v_lshlrev_b64 v[112:113], 11, v[112:113]
	v_lshl_add_u64 v[112:113], v[96:97], 0, v[112:113]
	flat_store_dwordx2 v[112:113], v[110:111]
	ds_write_b128 v101, v[64:67]
	ds_write_b128 v101, v[68:71] offset:64
	ds_write_b128 v101, v[72:75] offset:128
	ds_write_b128 v101, v[76:79] offset:192
	ds_write_b128 v101, v[80:83] offset:4352
	ds_write_b128 v101, v[84:87] offset:4416
	ds_write_b128 v101, v[88:91] offset:4480
	ds_write_b128 v101, v[92:95] offset:4544
	ds_read_b128 v[64:67], v98
	v_or_b32_e32 v68, 32, v100
	s_waitcnt lgkmcnt(0)
	v_mul_f32_e32 v64, 0xbfb8aa3b, v64
	v_mul_f32_e32 v65, 0xbfb8aa3b, v65
	v_mul_f32_e32 v66, 0xbfb8aa3b, v66
	v_mul_f32_e32 v67, 0xbfb8aa3b, v67
	v_exp_f32_e32 v64, v64
	v_exp_f32_e32 v65, v65
	v_exp_f32_e32 v66, v66
	v_exp_f32_e32 v67, v67
	v_add_f32_e32 v64, 1.0, v64
	v_add_f32_e32 v65, 1.0, v65
	v_add_f32_e32 v66, 1.0, v66
	v_add_f32_e32 v67, 1.0, v67
	v_rcp_f32_e32 v64, v64
	v_rcp_f32_e32 v65, v65
	v_rcp_f32_e32 v66, v66
	v_rcp_f32_e32 v67, v67
	v_cvt_pk_bf16_f32 v64, v64, v65
	v_cvt_pk_bf16_f32 v65, v66, v67
	v_or_b32_e32 v66, v68, v99
	v_ashrrev_i32_e32 v67, 31, v66
	v_lshlrev_b64 v[66:67], 11, v[66:67]
	v_lshl_add_u64 v[66:67], v[96:97], 0, v[66:67]
	flat_store_dwordx2 v[66:67], v[64:65]
	ds_read_b128 v[64:67], v98 offset:1088
	s_waitcnt lgkmcnt(0)
	v_mul_f32_e32 v64, 0xbfb8aa3b, v64
	v_mul_f32_e32 v65, 0xbfb8aa3b, v65
	v_mul_f32_e32 v66, 0xbfb8aa3b, v66
	v_mul_f32_e32 v67, 0xbfb8aa3b, v67
	v_exp_f32_e32 v64, v64
	v_exp_f32_e32 v65, v65
	v_exp_f32_e32 v66, v66
	v_exp_f32_e32 v67, v67
	v_add_f32_e32 v64, 1.0, v64
	v_add_f32_e32 v65, 1.0, v65
	v_add_f32_e32 v66, 1.0, v66
	v_add_f32_e32 v67, 1.0, v67
	v_rcp_f32_e32 v64, v64
	v_rcp_f32_e32 v65, v65
	v_rcp_f32_e32 v66, v66
	v_rcp_f32_e32 v67, v67
	v_cvt_pk_bf16_f32 v64, v64, v65
	v_cvt_pk_bf16_f32 v65, v66, v67
	v_or_b32_e32 v66, v68, v102
	v_ashrrev_i32_e32 v67, 31, v66
	v_lshlrev_b64 v[66:67], 11, v[66:67]
	v_lshl_add_u64 v[66:67], v[96:97], 0, v[66:67]
	flat_store_dwordx2 v[66:67], v[64:65]
	ds_read_b128 v[64:67], v98 offset:2176
	s_waitcnt lgkmcnt(0)
	v_mul_f32_e32 v64, 0xbfb8aa3b, v64
	v_mul_f32_e32 v65, 0xbfb8aa3b, v65
	v_mul_f32_e32 v66, 0xbfb8aa3b, v66
	v_mul_f32_e32 v67, 0xbfb8aa3b, v67
	v_exp_f32_e32 v64, v64
	v_exp_f32_e32 v65, v65
	v_exp_f32_e32 v66, v66
	v_exp_f32_e32 v67, v67
	v_add_f32_e32 v64, 1.0, v64
	v_add_f32_e32 v65, 1.0, v65
	v_add_f32_e32 v66, 1.0, v66
	v_add_f32_e32 v67, 1.0, v67
	v_rcp_f32_e32 v64, v64
	v_rcp_f32_e32 v65, v65
	v_rcp_f32_e32 v66, v66
	v_rcp_f32_e32 v67, v67
	v_cvt_pk_bf16_f32 v64, v64, v65
	v_cvt_pk_bf16_f32 v65, v66, v67
	v_or_b32_e32 v66, v68, v103
	v_ashrrev_i32_e32 v67, 31, v66
	v_lshlrev_b64 v[66:67], 11, v[66:67]
	v_lshl_add_u64 v[66:67], v[96:97], 0, v[66:67]
	flat_store_dwordx2 v[66:67], v[64:65]
	ds_read_b128 v[64:67], v98 offset:3264
	s_waitcnt lgkmcnt(0)
	v_mul_f32_e32 v64, 0xbfb8aa3b, v64
	v_mul_f32_e32 v65, 0xbfb8aa3b, v65
	v_mul_f32_e32 v66, 0xbfb8aa3b, v66
	v_mul_f32_e32 v67, 0xbfb8aa3b, v67
	v_exp_f32_e32 v64, v64
	v_exp_f32_e32 v65, v65
	v_exp_f32_e32 v66, v66
	v_exp_f32_e32 v67, v67
	v_add_f32_e32 v64, 1.0, v64
	v_add_f32_e32 v65, 1.0, v65
	v_add_f32_e32 v66, 1.0, v66
	v_add_f32_e32 v67, 1.0, v67
	v_rcp_f32_e32 v64, v64
	v_rcp_f32_e32 v65, v65
	v_rcp_f32_e32 v66, v66
	v_rcp_f32_e32 v67, v67
	v_cvt_pk_bf16_f32 v64, v64, v65
	v_cvt_pk_bf16_f32 v65, v66, v67
	v_or_b32_e32 v66, v68, v104
	v_ashrrev_i32_e32 v67, 31, v66
	v_lshlrev_b64 v[66:67], 11, v[66:67]
	v_lshl_add_u64 v[66:67], v[96:97], 0, v[66:67]
	flat_store_dwordx2 v[66:67], v[64:65]
	ds_read_b128 v[64:67], v98 offset:4352
	s_waitcnt lgkmcnt(0)
	v_mul_f32_e32 v64, 0xbfb8aa3b, v64
	v_mul_f32_e32 v65, 0xbfb8aa3b, v65
	v_mul_f32_e32 v66, 0xbfb8aa3b, v66
	v_mul_f32_e32 v67, 0xbfb8aa3b, v67
	v_exp_f32_e32 v64, v64
	v_exp_f32_e32 v65, v65
	v_exp_f32_e32 v66, v66
	v_exp_f32_e32 v67, v67
	v_add_f32_e32 v64, 1.0, v64
	v_add_f32_e32 v65, 1.0, v65
	v_add_f32_e32 v66, 1.0, v66
	v_add_f32_e32 v67, 1.0, v67
	v_rcp_f32_e32 v64, v64
	v_rcp_f32_e32 v65, v65
	v_rcp_f32_e32 v66, v66
	v_rcp_f32_e32 v67, v67
	v_cvt_pk_bf16_f32 v64, v64, v65
	v_cvt_pk_bf16_f32 v65, v66, v67
	v_or_b32_e32 v66, v68, v105
	v_ashrrev_i32_e32 v67, 31, v66
	v_lshlrev_b64 v[66:67], 11, v[66:67]
	v_lshl_add_u64 v[66:67], v[96:97], 0, v[66:67]
	flat_store_dwordx2 v[66:67], v[64:65]
	ds_read_b128 v[64:67], v98 offset:5440
	s_waitcnt lgkmcnt(0)
	v_mul_f32_e32 v64, 0xbfb8aa3b, v64
	v_mul_f32_e32 v65, 0xbfb8aa3b, v65
	v_mul_f32_e32 v66, 0xbfb8aa3b, v66
	v_mul_f32_e32 v67, 0xbfb8aa3b, v67
	v_exp_f32_e32 v64, v64
	v_exp_f32_e32 v65, v65
	v_exp_f32_e32 v66, v66
	v_exp_f32_e32 v67, v67
	v_add_f32_e32 v64, 1.0, v64
	v_add_f32_e32 v65, 1.0, v65
	v_add_f32_e32 v66, 1.0, v66
	v_add_f32_e32 v67, 1.0, v67
	v_rcp_f32_e32 v64, v64
	v_rcp_f32_e32 v65, v65
	v_rcp_f32_e32 v66, v66
	v_rcp_f32_e32 v67, v67
	v_cvt_pk_bf16_f32 v64, v64, v65
	v_cvt_pk_bf16_f32 v65, v66, v67
	v_or_b32_e32 v66, v68, v106
	v_ashrrev_i32_e32 v67, 31, v66
	v_lshlrev_b64 v[66:67], 11, v[66:67]
	v_lshl_add_u64 v[66:67], v[96:97], 0, v[66:67]
	flat_store_dwordx2 v[66:67], v[64:65]
	ds_read_b128 v[64:67], v98 offset:6528
	s_waitcnt lgkmcnt(0)
	v_mul_f32_e32 v64, 0xbfb8aa3b, v64
	v_mul_f32_e32 v65, 0xbfb8aa3b, v65
	v_mul_f32_e32 v66, 0xbfb8aa3b, v66
	v_mul_f32_e32 v67, 0xbfb8aa3b, v67
	v_exp_f32_e32 v64, v64
	v_exp_f32_e32 v65, v65
	v_exp_f32_e32 v66, v66
	v_exp_f32_e32 v67, v67
	v_add_f32_e32 v64, 1.0, v64
	v_add_f32_e32 v65, 1.0, v65
	v_add_f32_e32 v66, 1.0, v66
	v_add_f32_e32 v67, 1.0, v67
	v_rcp_f32_e32 v64, v64
	v_rcp_f32_e32 v65, v65
	v_rcp_f32_e32 v66, v66
	v_rcp_f32_e32 v67, v67
	v_cvt_pk_bf16_f32 v64, v64, v65
	v_cvt_pk_bf16_f32 v65, v66, v67
	v_or_b32_e32 v66, v68, v107
	v_ashrrev_i32_e32 v67, 31, v66
	v_lshlrev_b64 v[66:67], 11, v[66:67]
	v_lshl_add_u64 v[66:67], v[96:97], 0, v[66:67]
	flat_store_dwordx2 v[66:67], v[64:65]
	ds_read_b128 v[64:67], v98 offset:7616
	s_waitcnt lgkmcnt(0)
	v_mul_f32_e32 v64, 0xbfb8aa3b, v64
	v_mul_f32_e32 v65, 0xbfb8aa3b, v65
	v_mul_f32_e32 v66, 0xbfb8aa3b, v66
	v_mul_f32_e32 v67, 0xbfb8aa3b, v67
	v_exp_f32_e32 v64, v64
	v_exp_f32_e32 v65, v65
	v_exp_f32_e32 v66, v66
	v_exp_f32_e32 v67, v67
	v_add_f32_e32 v64, 1.0, v64
	v_add_f32_e32 v65, 1.0, v65
	v_add_f32_e32 v66, 1.0, v66
	v_add_f32_e32 v67, 1.0, v67
	v_rcp_f32_e32 v64, v64
	v_rcp_f32_e32 v65, v65
	v_rcp_f32_e32 v66, v66
	v_rcp_f32_e32 v67, v67
	v_cvt_pk_bf16_f32 v64, v64, v65
	v_cvt_pk_bf16_f32 v65, v66, v67
	v_or_b32_e32 v66, v68, v108
	v_ashrrev_i32_e32 v67, 31, v66
	v_lshlrev_b64 v[66:67], 11, v[66:67]
	v_lshl_add_u64 v[66:67], v[96:97], 0, v[66:67]
	flat_store_dwordx2 v[66:67], v[64:65]
	ds_write_b128 v101, v[32:35]
	ds_write_b128 v101, v[36:39] offset:64
	ds_write_b128 v101, v[40:43] offset:128
	ds_write_b128 v101, v[44:47] offset:192
	ds_write_b128 v101, v[48:51] offset:4352
	ds_write_b128 v101, v[52:55] offset:4416
	ds_write_b128 v101, v[56:59] offset:4480
	ds_write_b128 v101, v[60:63] offset:4544
	ds_read_b128 v[32:35], v98
	v_or_b32_e32 v36, 64, v100
	s_waitcnt lgkmcnt(0)
	v_mul_f32_e32 v32, 0xbfb8aa3b, v32
	v_mul_f32_e32 v33, 0xbfb8aa3b, v33
	v_mul_f32_e32 v34, 0xbfb8aa3b, v34
	v_mul_f32_e32 v35, 0xbfb8aa3b, v35
	v_exp_f32_e32 v32, v32
	v_exp_f32_e32 v33, v33
	v_exp_f32_e32 v34, v34
	v_exp_f32_e32 v35, v35
	v_add_f32_e32 v32, 1.0, v32
	v_add_f32_e32 v33, 1.0, v33
	v_add_f32_e32 v34, 1.0, v34
	v_add_f32_e32 v35, 1.0, v35
	v_rcp_f32_e32 v32, v32
	v_rcp_f32_e32 v33, v33
	v_rcp_f32_e32 v34, v34
	v_rcp_f32_e32 v35, v35
	v_cvt_pk_bf16_f32 v32, v32, v33
	v_cvt_pk_bf16_f32 v33, v34, v35
	v_or_b32_e32 v34, v36, v99
	v_ashrrev_i32_e32 v35, 31, v34
	v_lshlrev_b64 v[34:35], 11, v[34:35]
	v_lshl_add_u64 v[34:35], v[96:97], 0, v[34:35]
	flat_store_dwordx2 v[34:35], v[32:33]
	ds_read_b128 v[32:35], v98 offset:1088
	s_waitcnt lgkmcnt(0)
	v_mul_f32_e32 v32, 0xbfb8aa3b, v32
	v_mul_f32_e32 v33, 0xbfb8aa3b, v33
	v_mul_f32_e32 v34, 0xbfb8aa3b, v34
	v_mul_f32_e32 v35, 0xbfb8aa3b, v35
	v_exp_f32_e32 v32, v32
	v_exp_f32_e32 v33, v33
	v_exp_f32_e32 v34, v34
	v_exp_f32_e32 v35, v35
	v_add_f32_e32 v32, 1.0, v32
	v_add_f32_e32 v33, 1.0, v33
	v_add_f32_e32 v34, 1.0, v34
	v_add_f32_e32 v35, 1.0, v35
	v_rcp_f32_e32 v32, v32
	v_rcp_f32_e32 v33, v33
	v_rcp_f32_e32 v34, v34
	v_rcp_f32_e32 v35, v35
	v_cvt_pk_bf16_f32 v32, v32, v33
	v_cvt_pk_bf16_f32 v33, v34, v35
	v_or_b32_e32 v34, v36, v102
	v_ashrrev_i32_e32 v35, 31, v34
	v_lshlrev_b64 v[34:35], 11, v[34:35]
	v_lshl_add_u64 v[34:35], v[96:97], 0, v[34:35]
	flat_store_dwordx2 v[34:35], v[32:33]
	ds_read_b128 v[32:35], v98 offset:2176
	s_waitcnt lgkmcnt(0)
	v_mul_f32_e32 v32, 0xbfb8aa3b, v32
	v_mul_f32_e32 v33, 0xbfb8aa3b, v33
	v_mul_f32_e32 v34, 0xbfb8aa3b, v34
	v_mul_f32_e32 v35, 0xbfb8aa3b, v35
	v_exp_f32_e32 v32, v32
	v_exp_f32_e32 v33, v33
	v_exp_f32_e32 v34, v34
	v_exp_f32_e32 v35, v35
	v_add_f32_e32 v32, 1.0, v32
	v_add_f32_e32 v33, 1.0, v33
	v_add_f32_e32 v34, 1.0, v34
	v_add_f32_e32 v35, 1.0, v35
	v_rcp_f32_e32 v32, v32
	v_rcp_f32_e32 v33, v33
	v_rcp_f32_e32 v34, v34
	v_rcp_f32_e32 v35, v35
	v_cvt_pk_bf16_f32 v32, v32, v33
	v_cvt_pk_bf16_f32 v33, v34, v35
	v_or_b32_e32 v34, v36, v103
	v_ashrrev_i32_e32 v35, 31, v34
	v_lshlrev_b64 v[34:35], 11, v[34:35]
	v_lshl_add_u64 v[34:35], v[96:97], 0, v[34:35]
	flat_store_dwordx2 v[34:35], v[32:33]
	ds_read_b128 v[32:35], v98 offset:3264
	s_waitcnt lgkmcnt(0)
	v_mul_f32_e32 v32, 0xbfb8aa3b, v32
	v_mul_f32_e32 v33, 0xbfb8aa3b, v33
	v_mul_f32_e32 v34, 0xbfb8aa3b, v34
	v_mul_f32_e32 v35, 0xbfb8aa3b, v35
	v_exp_f32_e32 v32, v32
	v_exp_f32_e32 v33, v33
	v_exp_f32_e32 v34, v34
	v_exp_f32_e32 v35, v35
	v_add_f32_e32 v32, 1.0, v32
	v_add_f32_e32 v33, 1.0, v33
	v_add_f32_e32 v34, 1.0, v34
	v_add_f32_e32 v35, 1.0, v35
	v_rcp_f32_e32 v32, v32
	v_rcp_f32_e32 v33, v33
	v_rcp_f32_e32 v34, v34
	v_rcp_f32_e32 v35, v35
	v_cvt_pk_bf16_f32 v32, v32, v33
	v_cvt_pk_bf16_f32 v33, v34, v35
	v_or_b32_e32 v34, v36, v104
	v_ashrrev_i32_e32 v35, 31, v34
	v_lshlrev_b64 v[34:35], 11, v[34:35]
	v_lshl_add_u64 v[34:35], v[96:97], 0, v[34:35]
	flat_store_dwordx2 v[34:35], v[32:33]
	ds_read_b128 v[32:35], v98 offset:4352
	s_waitcnt lgkmcnt(0)
	v_mul_f32_e32 v32, 0xbfb8aa3b, v32
	v_mul_f32_e32 v33, 0xbfb8aa3b, v33
	v_mul_f32_e32 v34, 0xbfb8aa3b, v34
	v_mul_f32_e32 v35, 0xbfb8aa3b, v35
	v_exp_f32_e32 v32, v32
	v_exp_f32_e32 v33, v33
	v_exp_f32_e32 v34, v34
	v_exp_f32_e32 v35, v35
	v_add_f32_e32 v32, 1.0, v32
	v_add_f32_e32 v33, 1.0, v33
	v_add_f32_e32 v34, 1.0, v34
	v_add_f32_e32 v35, 1.0, v35
	v_rcp_f32_e32 v32, v32
	v_rcp_f32_e32 v33, v33
	v_rcp_f32_e32 v34, v34
	v_rcp_f32_e32 v35, v35
	v_cvt_pk_bf16_f32 v32, v32, v33
	v_cvt_pk_bf16_f32 v33, v34, v35
	v_or_b32_e32 v34, v36, v105
	v_ashrrev_i32_e32 v35, 31, v34
	v_lshlrev_b64 v[34:35], 11, v[34:35]
	v_lshl_add_u64 v[34:35], v[96:97], 0, v[34:35]
	flat_store_dwordx2 v[34:35], v[32:33]
	ds_read_b128 v[32:35], v98 offset:5440
	s_waitcnt lgkmcnt(0)
	v_mul_f32_e32 v32, 0xbfb8aa3b, v32
	v_mul_f32_e32 v33, 0xbfb8aa3b, v33
	v_mul_f32_e32 v34, 0xbfb8aa3b, v34
	v_mul_f32_e32 v35, 0xbfb8aa3b, v35
	v_exp_f32_e32 v32, v32
	v_exp_f32_e32 v33, v33
	v_exp_f32_e32 v34, v34
	v_exp_f32_e32 v35, v35
	v_add_f32_e32 v32, 1.0, v32
	v_add_f32_e32 v33, 1.0, v33
	v_add_f32_e32 v34, 1.0, v34
	v_add_f32_e32 v35, 1.0, v35
	v_rcp_f32_e32 v32, v32
	v_rcp_f32_e32 v33, v33
	v_rcp_f32_e32 v34, v34
	v_rcp_f32_e32 v35, v35
	v_cvt_pk_bf16_f32 v32, v32, v33
	v_cvt_pk_bf16_f32 v33, v34, v35
	v_or_b32_e32 v34, v36, v106
	v_ashrrev_i32_e32 v35, 31, v34
	v_lshlrev_b64 v[34:35], 11, v[34:35]
	v_lshl_add_u64 v[34:35], v[96:97], 0, v[34:35]
	flat_store_dwordx2 v[34:35], v[32:33]
	ds_read_b128 v[32:35], v98 offset:6528
	s_waitcnt lgkmcnt(0)
	v_mul_f32_e32 v32, 0xbfb8aa3b, v32
	v_mul_f32_e32 v33, 0xbfb8aa3b, v33
	v_mul_f32_e32 v34, 0xbfb8aa3b, v34
	v_mul_f32_e32 v35, 0xbfb8aa3b, v35
	v_exp_f32_e32 v32, v32
	v_exp_f32_e32 v33, v33
	v_exp_f32_e32 v34, v34
	v_exp_f32_e32 v35, v35
	v_add_f32_e32 v32, 1.0, v32
	v_add_f32_e32 v33, 1.0, v33
	v_add_f32_e32 v34, 1.0, v34
	v_add_f32_e32 v35, 1.0, v35
	v_rcp_f32_e32 v32, v32
	v_rcp_f32_e32 v33, v33
	v_rcp_f32_e32 v34, v34
	v_rcp_f32_e32 v35, v35
	v_cvt_pk_bf16_f32 v32, v32, v33
	v_cvt_pk_bf16_f32 v33, v34, v35
	v_or_b32_e32 v34, v36, v107
	v_ashrrev_i32_e32 v35, 31, v34
	v_lshlrev_b64 v[34:35], 11, v[34:35]
	v_lshl_add_u64 v[34:35], v[96:97], 0, v[34:35]
	flat_store_dwordx2 v[34:35], v[32:33]
	ds_read_b128 v[32:35], v98 offset:7616
	s_waitcnt lgkmcnt(0)
	v_mul_f32_e32 v32, 0xbfb8aa3b, v32
	v_mul_f32_e32 v33, 0xbfb8aa3b, v33
	v_mul_f32_e32 v34, 0xbfb8aa3b, v34
	v_mul_f32_e32 v35, 0xbfb8aa3b, v35
	v_exp_f32_e32 v32, v32
	v_exp_f32_e32 v33, v33
	v_exp_f32_e32 v34, v34
	v_exp_f32_e32 v35, v35
	v_add_f32_e32 v32, 1.0, v32
	v_add_f32_e32 v33, 1.0, v33
	v_add_f32_e32 v34, 1.0, v34
	v_add_f32_e32 v35, 1.0, v35
	v_rcp_f32_e32 v32, v32
	v_rcp_f32_e32 v33, v33
	v_rcp_f32_e32 v34, v34
	v_rcp_f32_e32 v35, v35
	v_cvt_pk_bf16_f32 v32, v32, v33
	v_cvt_pk_bf16_f32 v33, v34, v35
	v_or_b32_e32 v34, v36, v108
	v_ashrrev_i32_e32 v35, 31, v34
	v_lshlrev_b64 v[34:35], 11, v[34:35]
	v_lshl_add_u64 v[34:35], v[96:97], 0, v[34:35]
	flat_store_dwordx2 v[34:35], v[32:33]
	ds_write_b128 v101, v[0:3]
	ds_write_b128 v101, v[4:7] offset:64
	ds_write_b128 v101, v[8:11] offset:128
	ds_write_b128 v101, v[12:15] offset:192
	ds_write_b128 v101, v[16:19] offset:4352
	ds_write_b128 v101, v[20:23] offset:4416
	ds_write_b128 v101, v[24:27] offset:4480
	ds_write_b128 v101, v[28:31] offset:4544
	ds_read_b128 v[0:3], v98
	v_or_b32_e32 v4, 0x60, v100
	v_mov_b32_e32 v12, v132
	s_waitcnt lgkmcnt(0)
	v_mul_f32_e32 v0, 0xbfb8aa3b, v0
	v_mul_f32_e32 v1, 0xbfb8aa3b, v1
	v_mul_f32_e32 v2, 0xbfb8aa3b, v2
	v_mul_f32_e32 v3, 0xbfb8aa3b, v3
	v_exp_f32_e32 v0, v0
	v_exp_f32_e32 v1, v1
	v_exp_f32_e32 v2, v2
	v_exp_f32_e32 v3, v3
	v_add_f32_e32 v0, 1.0, v0
	v_add_f32_e32 v1, 1.0, v1
	v_add_f32_e32 v2, 1.0, v2
	v_add_f32_e32 v3, 1.0, v3
	v_rcp_f32_e32 v0, v0
	v_rcp_f32_e32 v1, v1
	v_rcp_f32_e32 v2, v2
	v_rcp_f32_e32 v3, v3
	v_cvt_pk_bf16_f32 v0, v0, v1
	v_cvt_pk_bf16_f32 v1, v2, v3
	v_or_b32_e32 v2, v4, v99
	v_ashrrev_i32_e32 v3, 31, v2
	v_lshlrev_b64 v[2:3], 11, v[2:3]
	v_lshl_add_u64 v[2:3], v[96:97], 0, v[2:3]
	flat_store_dwordx2 v[2:3], v[0:1]
	ds_read_b128 v[0:3], v98 offset:1088
	s_waitcnt lgkmcnt(0)
	v_mul_f32_e32 v0, 0xbfb8aa3b, v0
	v_mul_f32_e32 v1, 0xbfb8aa3b, v1
	v_mul_f32_e32 v2, 0xbfb8aa3b, v2
	v_mul_f32_e32 v3, 0xbfb8aa3b, v3
	v_exp_f32_e32 v0, v0
	v_exp_f32_e32 v1, v1
	v_exp_f32_e32 v2, v2
	v_exp_f32_e32 v3, v3
	v_add_f32_e32 v0, 1.0, v0
	v_add_f32_e32 v1, 1.0, v1
	v_add_f32_e32 v2, 1.0, v2
	v_add_f32_e32 v3, 1.0, v3
	v_rcp_f32_e32 v0, v0
	v_rcp_f32_e32 v1, v1
	v_rcp_f32_e32 v2, v2
	v_rcp_f32_e32 v3, v3
	v_cvt_pk_bf16_f32 v0, v0, v1
	v_cvt_pk_bf16_f32 v1, v2, v3
	v_or_b32_e32 v2, v4, v102
	v_ashrrev_i32_e32 v3, 31, v2
	v_lshlrev_b64 v[2:3], 11, v[2:3]
	v_lshl_add_u64 v[2:3], v[96:97], 0, v[2:3]
	flat_store_dwordx2 v[2:3], v[0:1]
	ds_read_b128 v[0:3], v98 offset:2176
	s_waitcnt lgkmcnt(0)
	v_mul_f32_e32 v0, 0xbfb8aa3b, v0
	v_mul_f32_e32 v1, 0xbfb8aa3b, v1
	v_mul_f32_e32 v2, 0xbfb8aa3b, v2
	v_mul_f32_e32 v3, 0xbfb8aa3b, v3
	v_exp_f32_e32 v0, v0
	v_exp_f32_e32 v1, v1
	v_exp_f32_e32 v2, v2
	v_exp_f32_e32 v3, v3
	v_add_f32_e32 v0, 1.0, v0
	v_add_f32_e32 v1, 1.0, v1
	v_add_f32_e32 v2, 1.0, v2
	v_add_f32_e32 v3, 1.0, v3
	v_rcp_f32_e32 v0, v0
	v_rcp_f32_e32 v1, v1
	v_rcp_f32_e32 v2, v2
	v_rcp_f32_e32 v3, v3
	v_cvt_pk_bf16_f32 v0, v0, v1
	v_cvt_pk_bf16_f32 v1, v2, v3
	v_or_b32_e32 v2, v4, v103
	v_ashrrev_i32_e32 v3, 31, v2
	v_lshlrev_b64 v[2:3], 11, v[2:3]
	v_lshl_add_u64 v[2:3], v[96:97], 0, v[2:3]
	flat_store_dwordx2 v[2:3], v[0:1]
	ds_read_b128 v[0:3], v98 offset:3264
	s_waitcnt lgkmcnt(0)
	v_mul_f32_e32 v0, 0xbfb8aa3b, v0
	v_mul_f32_e32 v1, 0xbfb8aa3b, v1
	v_mul_f32_e32 v2, 0xbfb8aa3b, v2
	v_mul_f32_e32 v3, 0xbfb8aa3b, v3
	v_exp_f32_e32 v0, v0
	v_exp_f32_e32 v1, v1
	v_exp_f32_e32 v2, v2
	v_exp_f32_e32 v3, v3
	v_add_f32_e32 v0, 1.0, v0
	v_add_f32_e32 v1, 1.0, v1
	v_add_f32_e32 v2, 1.0, v2
	v_add_f32_e32 v3, 1.0, v3
	v_rcp_f32_e32 v0, v0
	v_rcp_f32_e32 v1, v1
	v_rcp_f32_e32 v2, v2
	v_rcp_f32_e32 v3, v3
	v_cvt_pk_bf16_f32 v0, v0, v1
	v_cvt_pk_bf16_f32 v1, v2, v3
	v_or_b32_e32 v2, v4, v104
	v_ashrrev_i32_e32 v3, 31, v2
	v_lshlrev_b64 v[2:3], 11, v[2:3]
	v_lshl_add_u64 v[2:3], v[96:97], 0, v[2:3]
	flat_store_dwordx2 v[2:3], v[0:1]
	ds_read_b128 v[0:3], v98 offset:4352
	s_waitcnt lgkmcnt(0)
	v_mul_f32_e32 v0, 0xbfb8aa3b, v0
	v_mul_f32_e32 v1, 0xbfb8aa3b, v1
	v_mul_f32_e32 v2, 0xbfb8aa3b, v2
	v_mul_f32_e32 v3, 0xbfb8aa3b, v3
	v_exp_f32_e32 v0, v0
	v_exp_f32_e32 v1, v1
	v_exp_f32_e32 v2, v2
	v_exp_f32_e32 v3, v3
	v_add_f32_e32 v0, 1.0, v0
	v_add_f32_e32 v1, 1.0, v1
	v_add_f32_e32 v2, 1.0, v2
	v_add_f32_e32 v3, 1.0, v3
	v_rcp_f32_e32 v0, v0
	v_rcp_f32_e32 v1, v1
	v_rcp_f32_e32 v2, v2
	v_rcp_f32_e32 v3, v3
	v_cvt_pk_bf16_f32 v0, v0, v1
	v_cvt_pk_bf16_f32 v1, v2, v3
	v_or_b32_e32 v2, v4, v105
	v_ashrrev_i32_e32 v3, 31, v2
	v_lshlrev_b64 v[2:3], 11, v[2:3]
	v_lshl_add_u64 v[2:3], v[96:97], 0, v[2:3]
	flat_store_dwordx2 v[2:3], v[0:1]
	ds_read_b128 v[0:3], v98 offset:5440
	s_waitcnt lgkmcnt(0)
	v_mul_f32_e32 v0, 0xbfb8aa3b, v0
	v_mul_f32_e32 v1, 0xbfb8aa3b, v1
	v_mul_f32_e32 v2, 0xbfb8aa3b, v2
	v_mul_f32_e32 v3, 0xbfb8aa3b, v3
	v_exp_f32_e32 v0, v0
	v_exp_f32_e32 v1, v1
	v_exp_f32_e32 v2, v2
	v_exp_f32_e32 v3, v3
	v_add_f32_e32 v0, 1.0, v0
	v_add_f32_e32 v1, 1.0, v1
	v_add_f32_e32 v2, 1.0, v2
	v_add_f32_e32 v3, 1.0, v3
	v_rcp_f32_e32 v0, v0
	v_rcp_f32_e32 v1, v1
	v_rcp_f32_e32 v2, v2
	v_rcp_f32_e32 v3, v3
	v_cvt_pk_bf16_f32 v0, v0, v1
	v_cvt_pk_bf16_f32 v1, v2, v3
	v_or_b32_e32 v2, v4, v106
	v_ashrrev_i32_e32 v3, 31, v2
	v_lshlrev_b64 v[2:3], 11, v[2:3]
	v_lshl_add_u64 v[2:3], v[96:97], 0, v[2:3]
	flat_store_dwordx2 v[2:3], v[0:1]
	ds_read_b128 v[0:3], v98 offset:6528
	s_waitcnt lgkmcnt(0)
	v_mul_f32_e32 v0, 0xbfb8aa3b, v0
	v_mul_f32_e32 v1, 0xbfb8aa3b, v1
	v_mul_f32_e32 v2, 0xbfb8aa3b, v2
	v_mul_f32_e32 v3, 0xbfb8aa3b, v3
	v_exp_f32_e32 v0, v0
	v_exp_f32_e32 v1, v1
	v_exp_f32_e32 v2, v2
	v_exp_f32_e32 v3, v3
	v_add_f32_e32 v0, 1.0, v0
	v_add_f32_e32 v1, 1.0, v1
	v_add_f32_e32 v2, 1.0, v2
	v_add_f32_e32 v3, 1.0, v3
	v_rcp_f32_e32 v0, v0
	v_rcp_f32_e32 v1, v1
	v_rcp_f32_e32 v2, v2
	v_rcp_f32_e32 v3, v3
	v_cvt_pk_bf16_f32 v0, v0, v1
	v_cvt_pk_bf16_f32 v1, v2, v3
	v_or_b32_e32 v2, v4, v107
	v_ashrrev_i32_e32 v3, 31, v2
	v_lshlrev_b64 v[2:3], 11, v[2:3]
	v_lshl_add_u64 v[2:3], v[96:97], 0, v[2:3]
	flat_store_dwordx2 v[2:3], v[0:1]
	ds_read_b128 v[0:3], v98 offset:7616
	s_waitcnt lgkmcnt(0)
	v_mul_f32_e32 v0, 0xbfb8aa3b, v0
	v_mul_f32_e32 v1, 0xbfb8aa3b, v1
	v_mul_f32_e32 v2, 0xbfb8aa3b, v2
	v_mul_f32_e32 v3, 0xbfb8aa3b, v3
	v_exp_f32_e32 v0, v0
	v_exp_f32_e32 v1, v1
	v_exp_f32_e32 v2, v2
	v_exp_f32_e32 v3, v3
	v_add_f32_e32 v0, 1.0, v0
	v_add_f32_e32 v1, 1.0, v1
	v_add_f32_e32 v2, 1.0, v2
	v_add_f32_e32 v3, 1.0, v3
	v_rcp_f32_e32 v0, v0
	v_rcp_f32_e32 v1, v1
	v_rcp_f32_e32 v2, v2
	v_rcp_f32_e32 v3, v3
	v_cvt_pk_bf16_f32 v0, v0, v1
	v_cvt_pk_bf16_f32 v1, v2, v3
	v_or_b32_e32 v2, v4, v108
	v_ashrrev_i32_e32 v3, 31, v2
	v_lshlrev_b64 v[2:3], 11, v[2:3]
	v_lshl_add_u64 v[2:3], v[96:97], 0, v[2:3]
	flat_store_dwordx2 v[2:3], v[0:1]
	v_mov_b32_e32 v0, s3
	ds_read_b128 v[0:3], v0
	s_waitcnt lgkmcnt(0)
	v_readfirstlane_b32 s0, v3
	v_readfirstlane_b32 s29, v2
	v_lshlrev_b32_e32 v3, 4, v12
	v_and_b32_e32 v2, 32, v12
	s_add_u32 s42, s29, s36
	v_lshrrev_b32_e32 v4, 1, v12
	v_bitop3_b32 v2, v3, v2, 48 bitop3:0x6c
	s_addc_u32 s43, s0, s37
	v_bfe_u32 v13, v12, 2, 4
	v_and_b32_e32 v14, 32, v4
	v_lshrrev_b32_e32 v15, 1, v2
	v_ashrrev_i32_e32 v16, 3, v12
	s_add_u32 s36, s42, 0x18800000
	v_or_b32_e32 v6, v15, v14
	v_and_or_b32 v2, v16, s44, v13
	s_addc_u32 s37, s43, 0
	s_lshl_b64 s[38:39], s[30:31], 11
	v_and_b32_e32 v5, 0xfffffc00, v3
	v_lshl_or_b32 v130, v2, 10, v6
	v_add_u32_e32 v2, 0x2000, v3
	v_add_u32_e32 v4, 0x4000, v3
	v_add_u32_e32 v3, 0x6000, v3
	s_add_u32 s53, s29, s38
	v_ashrrev_i32_e32 v17, 7, v2
	v_ashrrev_i32_e32 v18, 7, v4
	v_ashrrev_i32_e32 v19, 7, v3
	s_addc_u32 s54, s0, s39
	v_and_or_b32 v2, v17, s44, v13
	v_and_or_b32 v4, v18, s44, v13
	v_and_or_b32 v3, v19, s44, v13
	v_add_u32_e32 v151, 0, v5
	s_add_u32 s38, s53, 0xe00000
	v_lshl_or_b32 v2, v2, 10, v6
	v_lshl_or_b32 v4, v4, 10, v6
	v_lshl_or_b32 v6, v3, 10, v6
	v_add_u32_e32 v3, 0x8000, v151
	v_lshlrev_b64 v[8:9], 1, v[130:131]
	v_readfirstlane_b32 s55, v151
	s_addc_u32 s39, s54, 0
	v_lshl_add_u64 v[10:11], s[36:37], 0, v[8:9]
	s_mov_b32 m0, s55
	v_readfirstlane_b32 s55, v3
	v_mov_b32_e32 v3, v131
	v_add_u32_e32 v5, 0x2000, v151
	global_load_lds_dwordx4 v[10:11], off
	v_lshl_add_u64 v[8:9], s[38:39], 0, v[8:9]
	s_mov_b32 m0, s55
	v_lshlrev_b64 v[2:3], 1, v[2:3]
	v_readfirstlane_b32 s55, v5
	v_add_u32_e32 v5, 0xa000, v151
	global_load_lds_dwordx4 v[8:9], off
	v_lshl_add_u64 v[8:9], s[36:37], 0, v[2:3]
	s_mov_b32 m0, s55
	v_readfirstlane_b32 s55, v5
	global_load_lds_dwordx4 v[8:9], off
	v_lshl_add_u64 v[2:3], s[38:39], 0, v[2:3]
	s_mov_b32 m0, s55
	v_mov_b32_e32 v5, v131
	v_add_u32_e32 v7, 0x4000, v151
	global_load_lds_dwordx4 v[2:3], off
	v_lshlrev_b64 v[2:3], 1, v[4:5]
	v_readfirstlane_b32 s55, v7
	v_lshl_add_u64 v[4:5], s[36:37], 0, v[2:3]
	s_mov_b32 m0, s55
	v_lshl_add_u64 v[2:3], s[38:39], 0, v[2:3]
	global_load_lds_dwordx4 v[4:5], off
	v_add_u32_e32 v4, 0xc000, v151
	v_mov_b32_e32 v7, v131
	v_readfirstlane_b32 s55, v4
	s_mov_b32 m0, s55
	v_and_b32_e32 v20, 15, v12
	global_load_lds_dwordx4 v[2:3], off
	v_lshlrev_b64 v[2:3], 1, v[6:7]
	v_add_u32_e32 v6, 0x6000, v151
	v_lshl_add_u64 v[4:5], s[36:37], 0, v[2:3]
	v_readfirstlane_b32 s36, v6
	s_mov_b32 m0, s36
	v_lshl_add_u64 v[2:3], s[38:39], 0, v[2:3]
	global_load_lds_dwordx4 v[4:5], off
	v_add_u32_e32 v4, 0xe000, v151
	v_lshlrev_b32_e32 v8, 10, v13
	v_readfirstlane_b32 s36, v4
	s_mov_b32 m0, s36
	v_lshlrev_b32_e32 v4, 2, v12
	global_load_lds_dwordx4 v[2:3], off
	v_and_b32_e32 v2, 48, v12
	v_lshlrev_b32_e32 v3, 6, v20
	v_and_b32_e32 v4, 32, v4
	v_bitop3_b32 v152, v3, v4, v2 bitop3:0x36
	v_lshlrev_b32_e32 v3, 7, v12
	v_and_b32_e32 v153, 0x6000, v3
	v_lshlrev_b32_e32 v3, 6, v12
	v_and_b32_e32 v154, 0xffffc000, v3
	v_and_b32_e32 v3, 0x3c0, v3
	v_bitop3_b32 v156, v3, v4, v2 bitop3:0x36
	v_lshlrev_b32_e32 v2, 10, v19
	v_and_or_b32 v2, v2, s45, v15
	v_lshlrev_b32_e32 v4, 10, v18
	v_or3_b32 v130, v2, v8, v14
	v_and_or_b32 v4, v4, s45, v15
	v_lshlrev_b32_e32 v6, 10, v17
	v_lshlrev_b64 v[2:3], 1, v[130:131]
	v_or3_b32 v130, v4, v8, v14
	v_and_or_b32 v6, v6, s45, v15
	v_lshlrev_b32_e32 v9, 10, v16
	v_lshlrev_b64 v[4:5], 1, v[130:131]
	v_or3_b32 v130, v6, v8, v14
	v_and_or_b32 v9, v9, s45, v15
	s_add_u32 s36, s53, 0xe00080
	v_lshlrev_b64 v[6:7], 1, v[130:131]
	v_or3_b32 v130, v9, v8, v14
	s_addc_u32 s37, s54, 0
	v_lshlrev_b64 v[8:9], 1, v[130:131]
	s_nop 0
	v_lshl_add_u64 v[134:135], s[36:37], 0, v[2:3]
	v_lshl_add_u64 v[136:137], s[36:37], 0, v[4:5]
	v_lshl_add_u64 v[138:139], s[36:37], 0, v[6:7]
	v_lshl_add_u64 v[140:141], s[36:37], 0, v[8:9]
	s_add_u32 s36, s42, 0x18800080
	s_addc_u32 s37, s43, 0
	v_or_b32_e32 v155, 0x800, v154
	v_or_b32_e32 v157, 0x1000, v154
	v_or_b32_e32 v158, 0x1800, v154
	v_or_b32_e32 v159, 0x2000, v154
	v_or_b32_e32 v160, 0x2800, v154
	v_or_b32_e32 v161, 0x3000, v154
	v_or_b32_e32 v162, 0x3800, v154
	v_lshl_add_u64 v[142:143], s[36:37], 0, v[2:3]
	v_lshl_add_u64 v[144:145], s[36:37], 0, v[4:5]
	v_lshl_add_u64 v[146:147], s[36:37], 0, v[6:7]
	v_lshl_add_u64 v[148:149], s[36:37], 0, v[8:9]
	s_mov_b32 s38, 0
	s_mov_b64 s[36:37], 0
	s_waitcnt vmcnt(0) lgkmcnt(0)
	s_barrier
	v_readfirstlane_b32 s100, v151
	s_and_b32 s39, s38, 0x10000
	s_xor_b32 s42, s39, 0x10000
	s_add_i32 s39, s39, 0
	v_add3_u32 v130, s39, v152, v153
	v_add3_u32 v163, s39, v152, v154
	v_add3_u32 v196, s39, v156, v155
	v_add3_u32 v197, s39, v156, v157
	v_add3_u32 v198, s39, v156, v158
	v_add3_u32 v199, s39, v156, v159
	v_add3_u32 v200, s39, v156, v160
	v_add3_u32 v201, s39, v156, v161
	v_add3_u32 v202, s39, v156, v162
	ds_read_b128 v[180:183], v130 offset:32768
	ds_read_b128 v[164:167], v163
	ds_read_b128 v[168:171], v196
	ds_read_b128 v[172:175], v197
	ds_read_b128 v[176:179], v198
	ds_read_b128 v[184:187], v130 offset:34816
	ds_read_b128 v[188:191], v130 offset:36864
	ds_read_b128 v[192:195], v130 offset:38912
	s_add_i32 s101, s100, s42
	v_readfirstlane_b32 s98, v148
	v_readfirstlane_b32 s99, v149
	v_readfirstlane_b32 vcc_lo, v140
	v_readfirstlane_b32 vcc_hi, v141
	s_sub_u32 s98, s98, 0x1000000
	s_subb_u32 s99, s99, 0
	s_sub_u32 vcc_lo, vcc_lo, 0x1000000
	s_subb_u32 vcc_hi, vcc_hi, 0
	v_subrev_u32_e32 v148, s98, v148
	v_subrev_u32_e32 v140, vcc_lo, v140
	v_subrev_u32_e32 v146, s98, v146
	v_subrev_u32_e32 v138, vcc_lo, v138
	v_subrev_u32_e32 v144, s98, v144
	v_subrev_u32_e32 v136, vcc_lo, v136
	v_subrev_u32_e32 v142, s98, v142
	v_subrev_u32_e32 v134, vcc_lo, v134
	s_mov_b32 m0, s101
	s_nop 0
	global_load_lds_dwordx4 v148, s[98:99]
	s_add_i32 m0, s101, 0x8000
	s_nop 0
	global_load_lds_dwordx4 v140, vcc
	s_add_i32 m0, s101, 0x2000
	s_nop 0
	global_load_lds_dwordx4 v146, s[98:99]
	s_add_i32 m0, s101, 0xa000
	s_nop 0
	global_load_lds_dwordx4 v138, vcc
	s_add_i32 m0, s101, 0x4000
	s_nop 0
	global_load_lds_dwordx4 v144, s[98:99]
	s_add_i32 m0, s101, 0xc000
	s_nop 0
	global_load_lds_dwordx4 v136, vcc
	s_add_i32 m0, s101, 0x6000
	s_nop 0
	global_load_lds_dwordx4 v142, s[98:99]
	s_add_i32 m0, s101, 0xe000
	s_nop 0
	global_load_lds_dwordx4 v134, vcc

.Lg2b_797:
	s_waitcnt lgkmcnt(3)
	v_mfma_f32_16x16x32_bf16 v[126:129], v[180:183], v[164:167], v[126:129]
	v_mfma_f32_16x16x32_bf16 v[110:113], v[180:183], v[168:171], v[110:113]
	v_mfma_f32_16x16x32_bf16 v[94:97], v[180:183], v[172:175], v[94:97]
	v_mfma_f32_16x16x32_bf16 v[78:81], v[180:183], v[176:179], v[78:81]
	ds_read_b128 v[240:243], v199 offset:1024
	ds_read_b128 v[244:247], v200 offset:1024
	s_waitcnt lgkmcnt(4)
	v_mfma_f32_16x16x32_bf16 v[122:125], v[184:187], v[164:167], v[122:125]
	v_mfma_f32_16x16x32_bf16 v[106:109], v[184:187], v[168:171], v[106:109]
	v_mfma_f32_16x16x32_bf16 v[90:93], v[184:187], v[172:175], v[90:93]
	v_mfma_f32_16x16x32_bf16 v[74:77], v[184:187], v[176:179], v[74:77]
	ds_read_b128 v[248:251], v201 offset:1024
	ds_read_b128 v[252:255], v202 offset:1024
	s_waitcnt lgkmcnt(5)
	v_mfma_f32_16x16x32_bf16 v[118:121], v[188:191], v[164:167], v[118:121]
	v_mfma_f32_16x16x32_bf16 v[102:105], v[188:191], v[168:171], v[102:105]
	v_mfma_f32_16x16x32_bf16 v[86:89], v[188:191], v[172:175], v[86:89]
	v_mfma_f32_16x16x32_bf16 v[70:73], v[188:191], v[176:179], v[70:73]
	s_waitcnt lgkmcnt(4)
	v_mfma_f32_16x16x32_bf16 v[114:117], v[192:195], v[164:167], v[114:117]
	v_mfma_f32_16x16x32_bf16 v[98:101], v[192:195], v[168:171], v[98:101]
	v_mfma_f32_16x16x32_bf16 v[82:85], v[192:195], v[172:175], v[82:85]
	v_mfma_f32_16x16x32_bf16 v[66:69], v[192:195], v[176:179], v[66:69]
	s_add_i32 s101, s100, s39
	s_cmpk_eq_i32 s36, 0x700
	s_cbranch_scc1 .Lg4n_797
	s_waitcnt vmcnt(0) lgkmcnt(0)
	s_barrier
	s_add_u32 s98, s98, 0x80
	s_addc_u32 s99, s99, 0
	s_add_u32 vcc_lo, vcc_lo, 0x80
	s_addc_u32 vcc_hi, vcc_hi, 0
	v_mfma_f32_16x16x32_bf16 v[62:65], v[180:183], v[240:243], v[62:65]
	v_mfma_f32_16x16x32_bf16 v[46:49], v[180:183], v[244:247], v[46:49]
	v_mfma_f32_16x16x32_bf16 v[18:21], v[180:183], v[248:251], v[18:21]
	v_mfma_f32_16x16x32_bf16 v[38:41], v[180:183], v[252:255], v[38:41]
	v_add3_u32 v130, s42, v152, v153
	ds_read_b128 v[180:183], v130 offset:32768
	v_add3_u32 v163, s42, v152, v154
	v_add3_u32 v196, s42, v156, v155
	v_add3_u32 v197, s42, v156, v157
	v_add3_u32 v198, s42, v156, v158
	ds_read_b128 v[164:167], v163
	ds_read_b128 v[168:171], v196
	ds_read_b128 v[172:175], v197
	ds_read_b128 v[176:179], v198
	s_mov_b32 m0, s101
	s_nop 0
	global_load_lds_dwordx4 v148, s[98:99]
	v_mfma_f32_16x16x32_bf16 v[58:61], v[184:187], v[240:243], v[58:61]
	v_mfma_f32_16x16x32_bf16 v[42:45], v[184:187], v[244:247], v[42:45]
	v_mfma_f32_16x16x32_bf16 v[14:17], v[184:187], v[248:251], v[14:17]
	v_mfma_f32_16x16x32_bf16 v[30:33], v[184:187], v[252:255], v[30:33]
	ds_read_b128 v[184:187], v130 offset:34816
	v_add3_u32 v199, s42, v156, v159
	v_add3_u32 v200, s42, v156, v160
	v_add3_u32 v201, s42, v156, v161
	v_add3_u32 v202, s42, v156, v162
	s_add_i32 m0, s101, 0x8000
	s_nop 0
	global_load_lds_dwordx4 v140, vcc
	v_mfma_f32_16x16x32_bf16 v[54:57], v[188:191], v[240:243], v[54:57]
	v_mfma_f32_16x16x32_bf16 v[34:37], v[188:191], v[244:247], v[34:37]
	v_mfma_f32_16x16x32_bf16 v[6:9], v[188:191], v[248:251], v[6:9]
	v_mfma_f32_16x16x32_bf16 v[22:25], v[188:191], v[252:255], v[22:25]
	ds_read_b128 v[188:191], v130 offset:36864
	s_add_i32 m0, s101, 0x2000
	s_nop 0
	global_load_lds_dwordx4 v146, s[98:99]
	v_mfma_f32_16x16x32_bf16 v[50:53], v[192:195], v[240:243], v[50:53]
	v_mfma_f32_16x16x32_bf16 v[26:29], v[192:195], v[244:247], v[26:29]
	v_mfma_f32_16x16x32_bf16 v[2:5], v[192:195], v[248:251], v[2:5]
	v_mfma_f32_16x16x32_bf16 v[10:13], v[192:195], v[252:255], v[10:13]
	ds_read_b128 v[192:195], v130 offset:38912
	s_add_i32 m0, s101, 0xa000
	s_nop 0
	global_load_lds_dwordx4 v138, vcc

.Lg1n_797:
	s_waitcnt lgkmcnt(3)
	v_mfma_f32_16x16x32_bf16 v[126:129], v[180:183], v[164:167], 0
	v_mfma_f32_16x16x32_bf16 v[110:113], v[180:183], v[168:171], 0
	v_mfma_f32_16x16x32_bf16 v[94:97], v[180:183], v[172:175], 0
	v_mfma_f32_16x16x32_bf16 v[78:81], v[180:183], v[176:179], 0
	ds_read_b128 v[240:243], v199
	ds_read_b128 v[244:247], v200
	s_waitcnt lgkmcnt(4)
	v_mfma_f32_16x16x32_bf16 v[122:125], v[184:187], v[164:167], 0
	v_mfma_f32_16x16x32_bf16 v[106:109], v[184:187], v[168:171], 0
	v_mfma_f32_16x16x32_bf16 v[90:93], v[184:187], v[172:175], 0
	v_mfma_f32_16x16x32_bf16 v[74:77], v[184:187], v[176:179], 0
	ds_read_b128 v[248:251], v201
	ds_read_b128 v[252:255], v202
	s_waitcnt lgkmcnt(5)
	v_mfma_f32_16x16x32_bf16 v[118:121], v[188:191], v[164:167], 0
	v_mfma_f32_16x16x32_bf16 v[102:105], v[188:191], v[168:171], 0
	v_mfma_f32_16x16x32_bf16 v[86:89], v[188:191], v[172:175], 0
	v_mfma_f32_16x16x32_bf16 v[70:73], v[188:191], v[176:179], 0
	s_waitcnt lgkmcnt(4)
	v_mfma_f32_16x16x32_bf16 v[114:117], v[192:195], v[164:167], 0
	v_mfma_f32_16x16x32_bf16 v[98:101], v[192:195], v[168:171], 0
	v_mfma_f32_16x16x32_bf16 v[82:85], v[192:195], v[172:175], 0
	v_mfma_f32_16x16x32_bf16 v[66:69], v[192:195], v[176:179], 0
	ds_read_b128 v[164:167], v163 offset:1024
	ds_read_b128 v[168:171], v196 offset:1024
	ds_read_b128 v[172:175], v197 offset:1024
	ds_read_b128 v[176:179], v198 offset:1024
	s_waitcnt lgkmcnt(4)
	v_mfma_f32_16x16x32_bf16 v[62:65], v[180:183], v[240:243], 0
	v_mfma_f32_16x16x32_bf16 v[46:49], v[180:183], v[244:247], 0
	v_mfma_f32_16x16x32_bf16 v[18:21], v[180:183], v[248:251], 0
	v_mfma_f32_16x16x32_bf16 v[38:41], v[180:183], v[252:255], 0
	ds_read_b128 v[180:183], v130 offset:33792
	v_mfma_f32_16x16x32_bf16 v[58:61], v[184:187], v[240:243], 0
	v_mfma_f32_16x16x32_bf16 v[42:45], v[184:187], v[244:247], 0
	v_mfma_f32_16x16x32_bf16 v[14:17], v[184:187], v[248:251], 0
	v_mfma_f32_16x16x32_bf16 v[30:33], v[184:187], v[252:255], 0
	ds_read_b128 v[184:187], v130 offset:35840
	v_mfma_f32_16x16x32_bf16 v[54:57], v[188:191], v[240:243], 0
	v_mfma_f32_16x16x32_bf16 v[34:37], v[188:191], v[244:247], 0
	v_mfma_f32_16x16x32_bf16 v[6:9], v[188:191], v[248:251], 0
	v_mfma_f32_16x16x32_bf16 v[22:25], v[188:191], v[252:255], 0
	ds_read_b128 v[188:191], v130 offset:37888
	v_mfma_f32_16x16x32_bf16 v[50:53], v[192:195], v[240:243], 0
	v_mfma_f32_16x16x32_bf16 v[26:29], v[192:195], v[244:247], 0
	v_mfma_f32_16x16x32_bf16 v[2:5], v[192:195], v[248:251], 0
	v_mfma_f32_16x16x32_bf16 v[10:13], v[192:195], v[252:255], 0
	ds_read_b128 v[192:195], v130 offset:39936
	s_branch .Lg2b_797

.LBB0_845:
	s_ashr_i32 s12, s27, 31
	s_lshr_b32 s12, s12, 26
	s_add_i32 s12, s27, s12
	s_ashr_i32 s13, s12, 6
	s_and_b32 s12, s12, 0xffc0
	s_sub_i32 s12, s27, s12
	s_bfe_i32 s14, s12, 0x80000
	s_bfe_u32 s14, s14, 0x4000b
	s_add_i32 s14, s12, s14
	s_lshl_b32 s28, s13, 4
	s_and_b32 s13, s14, 0xf0
	v_mov_b32_e32 v148, v132
	v_mov_b32_e32 v18, v132
	s_sub_i32 s12, s12, s13
	ds_read_b64 v[0:1], v133
	s_bfe_i32 s15, s14, 0x80000
	v_lshlrev_b32_e32 v9, 4, v18
	v_and_b32_e32 v8, 32, v18
	s_sext_i32_i8 s12, s12
	v_lshrrev_b32_e32 v10, 1, v18
	v_bitop3_b32 v8, v9, v8, 48 bitop3:0x6c
	s_sext_i32_i16 s15, s15
	s_add_i32 s28, s28, s12
	v_bfe_u32 v19, v18, 2, 4
	v_and_b32_e32 v20, 32, v10
	v_lshrrev_b32_e32 v21, 1, v8
	v_ashrrev_i32_e32 v22, 3, v18
	s_lshl_b32 s14, s28, 8
	s_lshl_b32 s12, s15, 4
	v_or_b32_e32 v12, v21, v20
	v_and_or_b32 v8, v22, s18, v19
	s_and_b32 s12, s12, 0xffffff00
	s_ashr_i32 s15, s14, 31
	v_and_b32_e32 v11, 0xfffffc00, v9
	v_lshl_or_b32 v128, v8, 10, v12
	v_add_u32_e32 v8, 0x2000, v9
	v_add_u32_e32 v10, 0x4000, v9
	v_add_u32_e32 v9, 0x6000, v9
	s_lshl_b64 s[16:17], s[14:15], 11
	s_ashr_i32 s13, s12, 31
	v_ashrrev_i32_e32 v23, 7, v8
	v_ashrrev_i32_e32 v24, 7, v10
	v_ashrrev_i32_e32 v25, 7, v9
	s_waitcnt lgkmcnt(0)
	v_lshl_add_u64 v[2:3], v[0:1], 0, s[16:17]
	s_lshl_b64 s[16:17], s[12:13], 11
	v_and_or_b32 v8, v23, s18, v19
	v_and_or_b32 v10, v24, s18, v19
	v_and_or_b32 v9, v25, s18, v19
	v_add_u32_e32 v149, 0, v11
	v_lshl_add_u64 v[4:5], v[2:3], 0, s[4:5]
	v_lshl_add_u64 v[0:1], v[0:1], 0, s[16:17]
	v_lshl_or_b32 v8, v8, 10, v12
	v_lshl_or_b32 v10, v10, 10, v12
	v_lshl_or_b32 v12, v9, 10, v12
	v_add_u32_e32 v9, 0x8000, v149
	v_lshlrev_b64 v[14:15], 1, v[128:129]
	v_readfirstlane_b32 s15, v149
	v_lshl_add_u64 v[6:7], v[0:1], 0, s[6:7]
	v_lshl_add_u64 v[16:17], v[4:5], 0, v[14:15]
	s_mov_b32 m0, s15
	v_readfirstlane_b32 s15, v9
	v_mov_b32_e32 v9, v129
	v_add_u32_e32 v11, 0x2000, v149
	global_load_lds_dwordx4 v[16:17], off
	v_lshl_add_u64 v[14:15], v[6:7], 0, v[14:15]
	s_mov_b32 m0, s15
	v_lshlrev_b64 v[8:9], 1, v[8:9]
	v_readfirstlane_b32 s15, v11
	v_add_u32_e32 v11, 0xa000, v149
	global_load_lds_dwordx4 v[14:15], off
	v_lshl_add_u64 v[14:15], v[4:5], 0, v[8:9]
	s_mov_b32 m0, s15
	v_readfirstlane_b32 s15, v11
	global_load_lds_dwordx4 v[14:15], off
	v_lshl_add_u64 v[8:9], v[6:7], 0, v[8:9]
	s_mov_b32 m0, s15
	v_mov_b32_e32 v11, v129
	v_add_u32_e32 v13, 0x4000, v149
	global_load_lds_dwordx4 v[8:9], off
	v_lshlrev_b64 v[8:9], 1, v[10:11]
	v_readfirstlane_b32 s15, v13
	v_lshl_add_u64 v[10:11], v[4:5], 0, v[8:9]
	s_mov_b32 m0, s15
	v_lshl_add_u64 v[8:9], v[6:7], 0, v[8:9]
	global_load_lds_dwordx4 v[10:11], off
	v_add_u32_e32 v10, 0xc000, v149
	v_mov_b32_e32 v13, v129
	v_readfirstlane_b32 s15, v10
	s_mov_b32 m0, s15
	v_add_u32_e32 v10, 0x6000, v149
	global_load_lds_dwordx4 v[8:9], off
	v_lshlrev_b64 v[8:9], 1, v[12:13]
	v_readfirstlane_b32 s15, v10
	v_lshl_add_u64 v[4:5], v[4:5], 0, v[8:9]
	s_mov_b32 m0, s15
	v_and_b32_e32 v26, 15, v18
	global_load_lds_dwordx4 v[4:5], off
	v_lshl_add_u64 v[4:5], v[6:7], 0, v[8:9]
	v_add_u32_e32 v6, 0xe000, v149
	v_lshlrev_b32_e32 v10, 10, v19
	v_readfirstlane_b32 s15, v6
	s_mov_b32 m0, s15
	v_lshlrev_b32_e32 v6, 2, v18
	global_load_lds_dwordx4 v[4:5], off
	v_and_b32_e32 v4, 48, v18
	v_lshlrev_b32_e32 v5, 6, v26
	v_and_b32_e32 v6, 32, v6
	v_bitop3_b32 v150, v5, v6, v4 bitop3:0x36
	v_lshlrev_b32_e32 v5, 7, v18
	v_and_b32_e32 v151, 0x6000, v5
	v_lshlrev_b32_e32 v5, 6, v18
	v_and_b32_e32 v152, 0xffffc000, v5
	v_and_b32_e32 v5, 0x3c0, v5
	v_bitop3_b32 v154, v5, v6, v4 bitop3:0x36
	v_lshlrev_b32_e32 v4, 10, v25
	v_and_or_b32 v4, v4, s19, v21
	v_lshlrev_b32_e32 v6, 10, v24
	v_or3_b32 v128, v4, v10, v20
	v_and_or_b32 v6, v6, s19, v21
	v_lshlrev_b32_e32 v8, 10, v23
	v_lshlrev_b64 v[4:5], 1, v[128:129]
	v_or3_b32 v128, v6, v10, v20
	v_and_or_b32 v8, v8, s19, v21
	v_lshlrev_b32_e32 v11, 10, v22
	v_lshlrev_b64 v[6:7], 1, v[128:129]
	v_or3_b32 v128, v8, v10, v20
	v_and_or_b32 v11, v11, s19, v21
	v_lshlrev_b64 v[8:9], 1, v[128:129]
	v_or3_b32 v128, v11, v10, v20
	s_nop 0
	v_lshl_add_u64 v[0:1], v[0:1], 0, s[8:9]
	v_lshlrev_b64 v[10:11], 1, v[128:129]
	v_lshl_add_u64 v[130:131], v[0:1], 0, v[4:5]
	v_lshl_add_u64 v[134:135], v[0:1], 0, v[6:7]
	v_lshl_add_u64 v[136:137], v[0:1], 0, v[8:9]
	v_lshl_add_u64 v[138:139], v[0:1], 0, v[10:11]
	v_lshl_add_u64 v[0:1], v[2:3], 0, s[10:11]
	v_or_b32_e32 v153, 0x800, v152
	v_or_b32_e32 v155, 0x1000, v152
	v_or_b32_e32 v156, 0x1800, v152
	v_or_b32_e32 v157, 0x2000, v152
	v_or_b32_e32 v158, 0x2800, v152
	v_or_b32_e32 v159, 0x3000, v152
	v_or_b32_e32 v160, 0x3800, v152
	v_lshl_add_u64 v[140:141], v[0:1], 0, v[4:5]
	v_lshl_add_u64 v[142:143], v[0:1], 0, v[6:7]
	v_lshl_add_u64 v[144:145], v[0:1], 0, v[8:9]
	v_lshl_add_u64 v[146:147], v[0:1], 0, v[10:11]
	s_mov_b64 s[16:17], 0
	s_mov_b32 s15, 0
	s_waitcnt vmcnt(0) lgkmcnt(0)
	s_barrier
	v_readfirstlane_b32 s100, v149
	s_and_b32 s29, s15, 0x10000
	s_xor_b32 s30, s29, 0x10000
	s_add_i32 s29, s29, 0
	v_add3_u32 v128, s29, v150, v151
	v_add3_u32 v161, s29, v150, v152
	v_add3_u32 v194, s29, v154, v153
	v_add3_u32 v195, s29, v154, v155
	v_add3_u32 v196, s29, v154, v156
	v_add3_u32 v197, s29, v154, v157
	v_add3_u32 v198, s29, v154, v158
	v_add3_u32 v199, s29, v154, v159
	v_add3_u32 v200, s29, v154, v160
	ds_read_b128 v[178:181], v128 offset:32768
	ds_read_b128 v[162:165], v161
	ds_read_b128 v[166:169], v194
	ds_read_b128 v[170:173], v195
	ds_read_b128 v[174:177], v196
	ds_read_b128 v[182:185], v128 offset:34816
	ds_read_b128 v[186:189], v128 offset:36864
	ds_read_b128 v[190:193], v128 offset:38912
	s_add_i32 s101, s100, s30
	v_readfirstlane_b32 s98, v146
	v_readfirstlane_b32 s99, v147
	v_readfirstlane_b32 vcc_lo, v138
	v_readfirstlane_b32 vcc_hi, v139
	s_sub_u32 s98, s98, 0x1000000
	s_subb_u32 s99, s99, 0
	s_sub_u32 vcc_lo, vcc_lo, 0x1000000
	s_subb_u32 vcc_hi, vcc_hi, 0
	v_subrev_u32_e32 v146, s98, v146
	v_subrev_u32_e32 v138, vcc_lo, v138
	v_subrev_u32_e32 v144, s98, v144
	v_subrev_u32_e32 v136, vcc_lo, v136
	v_subrev_u32_e32 v142, s98, v142
	v_subrev_u32_e32 v134, vcc_lo, v134
	v_subrev_u32_e32 v140, s98, v140
	v_subrev_u32_e32 v130, vcc_lo, v130
	s_mov_b32 m0, s101
	s_nop 0
	global_load_lds_dwordx4 v146, s[98:99]
	s_add_i32 m0, s101, 0x8000
	s_nop 0
	global_load_lds_dwordx4 v138, vcc
	s_add_i32 m0, s101, 0x2000
	s_nop 0
	global_load_lds_dwordx4 v144, s[98:99]
	s_add_i32 m0, s101, 0xa000
	s_nop 0
	global_load_lds_dwordx4 v136, vcc
	s_add_i32 m0, s101, 0x4000
	s_nop 0
	global_load_lds_dwordx4 v142, s[98:99]
	s_add_i32 m0, s101, 0xc000
	s_nop 0
	global_load_lds_dwordx4 v134, vcc
	s_add_i32 m0, s101, 0x6000
	s_nop 0
	global_load_lds_dwordx4 v140, s[98:99]
	s_add_i32 m0, s101, 0xe000
	s_nop 0
	global_load_lds_dwordx4 v130, vcc

.Lg2b_846:
	s_waitcnt lgkmcnt(3)
	v_mfma_f32_16x16x32_bf16 v[124:127], v[178:181], v[162:165], v[124:127]
	v_mfma_f32_16x16x32_bf16 v[108:111], v[178:181], v[166:169], v[108:111]
	v_mfma_f32_16x16x32_bf16 v[92:95], v[178:181], v[170:173], v[92:95]
	v_mfma_f32_16x16x32_bf16 v[76:79], v[178:181], v[174:177], v[76:79]
	ds_read_b128 v[240:243], v197 offset:1024
	ds_read_b128 v[244:247], v198 offset:1024
	s_waitcnt lgkmcnt(4)
	v_mfma_f32_16x16x32_bf16 v[120:123], v[182:185], v[162:165], v[120:123]
	v_mfma_f32_16x16x32_bf16 v[104:107], v[182:185], v[166:169], v[104:107]
	v_mfma_f32_16x16x32_bf16 v[88:91], v[182:185], v[170:173], v[88:91]
	v_mfma_f32_16x16x32_bf16 v[72:75], v[182:185], v[174:177], v[72:75]
	ds_read_b128 v[248:251], v199 offset:1024
	ds_read_b128 v[252:255], v200 offset:1024
	s_waitcnt lgkmcnt(5)
	v_mfma_f32_16x16x32_bf16 v[116:119], v[186:189], v[162:165], v[116:119]
	v_mfma_f32_16x16x32_bf16 v[100:103], v[186:189], v[166:169], v[100:103]
	v_mfma_f32_16x16x32_bf16 v[84:87], v[186:189], v[170:173], v[84:87]
	v_mfma_f32_16x16x32_bf16 v[68:71], v[186:189], v[174:177], v[68:71]
	s_waitcnt lgkmcnt(4)
	v_mfma_f32_16x16x32_bf16 v[112:115], v[190:193], v[162:165], v[112:115]
	v_mfma_f32_16x16x32_bf16 v[96:99], v[190:193], v[166:169], v[96:99]
	v_mfma_f32_16x16x32_bf16 v[80:83], v[190:193], v[170:173], v[80:83]
	v_mfma_f32_16x16x32_bf16 v[64:67], v[190:193], v[174:177], v[64:67]
	s_add_i32 s101, s100, s29
	s_cmpk_eq_i32 s16, 0x700
	s_cbranch_scc1 .Lg4n_846
	s_waitcnt vmcnt(0) lgkmcnt(0)
	s_barrier
	s_add_u32 s98, s98, 0x80
	s_addc_u32 s99, s99, 0
	s_add_u32 vcc_lo, vcc_lo, 0x80
	s_addc_u32 vcc_hi, vcc_hi, 0
	v_mfma_f32_16x16x32_bf16 v[60:63], v[178:181], v[240:243], v[60:63]
	v_mfma_f32_16x16x32_bf16 v[44:47], v[178:181], v[244:247], v[44:47]
	v_mfma_f32_16x16x32_bf16 v[16:19], v[178:181], v[248:251], v[16:19]
	v_mfma_f32_16x16x32_bf16 v[36:39], v[178:181], v[252:255], v[36:39]
	v_add3_u32 v128, s30, v150, v151
	ds_read_b128 v[178:181], v128 offset:32768
	v_add3_u32 v161, s30, v150, v152
	v_add3_u32 v194, s30, v154, v153
	v_add3_u32 v195, s30, v154, v155
	v_add3_u32 v196, s30, v154, v156
	ds_read_b128 v[162:165], v161
	ds_read_b128 v[166:169], v194
	ds_read_b128 v[170:173], v195
	ds_read_b128 v[174:177], v196
	s_mov_b32 m0, s101
	s_nop 0
	global_load_lds_dwordx4 v146, s[98:99]
	v_mfma_f32_16x16x32_bf16 v[56:59], v[182:185], v[240:243], v[56:59]
	v_mfma_f32_16x16x32_bf16 v[40:43], v[182:185], v[244:247], v[40:43]
	v_mfma_f32_16x16x32_bf16 v[8:11], v[182:185], v[248:251], v[8:11]
	v_mfma_f32_16x16x32_bf16 v[28:31], v[182:185], v[252:255], v[28:31]
	ds_read_b128 v[182:185], v128 offset:34816
	v_add3_u32 v197, s30, v154, v157
	v_add3_u32 v198, s30, v154, v158
	v_add3_u32 v199, s30, v154, v159
	v_add3_u32 v200, s30, v154, v160
	s_add_i32 m0, s101, 0x8000
	s_nop 0
	global_load_lds_dwordx4 v138, vcc
	v_mfma_f32_16x16x32_bf16 v[52:55], v[186:189], v[240:243], v[52:55]
	v_mfma_f32_16x16x32_bf16 v[32:35], v[186:189], v[244:247], v[32:35]
	v_mfma_f32_16x16x32_bf16 v[4:7], v[186:189], v[248:251], v[4:7]
	v_mfma_f32_16x16x32_bf16 v[20:23], v[186:189], v[252:255], v[20:23]
	ds_read_b128 v[186:189], v128 offset:36864
	s_add_i32 m0, s101, 0x2000
	s_nop 0
	global_load_lds_dwordx4 v144, s[98:99]
	v_mfma_f32_16x16x32_bf16 v[48:51], v[190:193], v[240:243], v[48:51]
	v_mfma_f32_16x16x32_bf16 v[24:27], v[190:193], v[244:247], v[24:27]
	v_mfma_f32_16x16x32_bf16 v[0:3], v[190:193], v[248:251], v[0:3]
	v_mfma_f32_16x16x32_bf16 v[12:15], v[190:193], v[252:255], v[12:15]
	ds_read_b128 v[190:193], v128 offset:38912
	s_add_i32 m0, s101, 0xa000
	s_nop 0
	global_load_lds_dwordx4 v136, vcc

.Lg1n_846:
	s_waitcnt lgkmcnt(3)
	v_mfma_f32_16x16x32_bf16 v[124:127], v[178:181], v[162:165], 0
	v_mfma_f32_16x16x32_bf16 v[108:111], v[178:181], v[166:169], 0
	v_mfma_f32_16x16x32_bf16 v[92:95], v[178:181], v[170:173], 0
	v_mfma_f32_16x16x32_bf16 v[76:79], v[178:181], v[174:177], 0
	ds_read_b128 v[240:243], v197
	ds_read_b128 v[244:247], v198
	s_waitcnt lgkmcnt(4)
	v_mfma_f32_16x16x32_bf16 v[120:123], v[182:185], v[162:165], 0
	v_mfma_f32_16x16x32_bf16 v[104:107], v[182:185], v[166:169], 0
	v_mfma_f32_16x16x32_bf16 v[88:91], v[182:185], v[170:173], 0
	v_mfma_f32_16x16x32_bf16 v[72:75], v[182:185], v[174:177], 0
	ds_read_b128 v[248:251], v199
	ds_read_b128 v[252:255], v200
	s_waitcnt lgkmcnt(5)
	v_mfma_f32_16x16x32_bf16 v[116:119], v[186:189], v[162:165], 0
	v_mfma_f32_16x16x32_bf16 v[100:103], v[186:189], v[166:169], 0
	v_mfma_f32_16x16x32_bf16 v[84:87], v[186:189], v[170:173], 0
	v_mfma_f32_16x16x32_bf16 v[68:71], v[186:189], v[174:177], 0
	s_waitcnt lgkmcnt(4)
	v_mfma_f32_16x16x32_bf16 v[112:115], v[190:193], v[162:165], 0
	v_mfma_f32_16x16x32_bf16 v[96:99], v[190:193], v[166:169], 0
	v_mfma_f32_16x16x32_bf16 v[80:83], v[190:193], v[170:173], 0
	v_mfma_f32_16x16x32_bf16 v[64:67], v[190:193], v[174:177], 0
	ds_read_b128 v[162:165], v161 offset:1024
	ds_read_b128 v[166:169], v194 offset:1024
	ds_read_b128 v[170:173], v195 offset:1024
	ds_read_b128 v[174:177], v196 offset:1024
	s_waitcnt lgkmcnt(4)
	v_mfma_f32_16x16x32_bf16 v[60:63], v[178:181], v[240:243], 0
	v_mfma_f32_16x16x32_bf16 v[44:47], v[178:181], v[244:247], 0
	v_mfma_f32_16x16x32_bf16 v[16:19], v[178:181], v[248:251], 0
	v_mfma_f32_16x16x32_bf16 v[36:39], v[178:181], v[252:255], 0
	ds_read_b128 v[178:181], v128 offset:33792
	v_mfma_f32_16x16x32_bf16 v[56:59], v[182:185], v[240:243], 0
	v_mfma_f32_16x16x32_bf16 v[40:43], v[182:185], v[244:247], 0
	v_mfma_f32_16x16x32_bf16 v[8:11], v[182:185], v[248:251], 0
	v_mfma_f32_16x16x32_bf16 v[28:31], v[182:185], v[252:255], 0
	ds_read_b128 v[182:185], v128 offset:35840
	v_mfma_f32_16x16x32_bf16 v[52:55], v[186:189], v[240:243], 0
	v_mfma_f32_16x16x32_bf16 v[32:35], v[186:189], v[244:247], 0
	v_mfma_f32_16x16x32_bf16 v[4:7], v[186:189], v[248:251], 0
	v_mfma_f32_16x16x32_bf16 v[20:23], v[186:189], v[252:255], 0
	ds_read_b128 v[186:189], v128 offset:37888
	v_mfma_f32_16x16x32_bf16 v[48:51], v[190:193], v[240:243], 0
	v_mfma_f32_16x16x32_bf16 v[24:27], v[190:193], v[244:247], 0
	v_mfma_f32_16x16x32_bf16 v[0:3], v[190:193], v[248:251], 0
	v_mfma_f32_16x16x32_bf16 v[12:15], v[190:193], v[252:255], 0
	ds_read_b128 v[190:193], v128 offset:39936
	s_branch .Lg2b_846

.Lnxh_942_0:
	v_and_b32_e32 v4, 48, v18
	v_lshlrev_b32_e32 v5, 6, v26
	v_and_b32_e32 v6, 32, v6
	v_bitop3_b32 v150, v5, v6, v4 bitop3:0x36
	v_lshlrev_b32_e32 v5, 7, v18
	v_and_b32_e32 v151, 0x6000, v5
	v_lshlrev_b32_e32 v5, 6, v18
	v_and_b32_e32 v152, 0xffffc000, v5
	v_and_b32_e32 v5, 0x3c0, v5
	v_bitop3_b32 v154, v5, v6, v4 bitop3:0x36
	v_lshlrev_b32_e32 v4, 10, v25
	v_and_or_b32 v4, v4, s22, v21
	v_lshlrev_b32_e32 v6, 10, v24
	v_or3_b32 v128, v4, v10, v20
	v_and_or_b32 v6, v6, s22, v21
	v_lshlrev_b32_e32 v8, 10, v23
	v_lshlrev_b64 v[4:5], 1, v[128:129]
	v_or3_b32 v128, v6, v10, v20
	v_and_or_b32 v8, v8, s22, v21
	v_lshlrev_b32_e32 v11, 10, v22
	v_lshlrev_b64 v[6:7], 1, v[128:129]
	v_or3_b32 v128, v8, v10, v20
	v_and_or_b32 v11, v11, s22, v21
	v_lshlrev_b64 v[8:9], 1, v[128:129]
	v_or3_b32 v128, v11, v10, v20
	s_nop 0
	v_lshl_add_u64 v[0:1], v[0:1], 0, s[8:9]
	v_lshlrev_b64 v[10:11], 1, v[128:129]
	v_lshl_add_u64 v[130:131], v[0:1], 0, v[4:5]
	v_lshl_add_u64 v[134:135], v[0:1], 0, v[6:7]
	v_lshl_add_u64 v[136:137], v[0:1], 0, v[8:9]
	v_lshl_add_u64 v[138:139], v[0:1], 0, v[10:11]
	v_lshl_add_u64 v[0:1], v[2:3], 0, s[10:11]
	v_or_b32_e32 v153, 0x800, v152
	v_or_b32_e32 v155, 0x1000, v152
	v_or_b32_e32 v156, 0x1800, v152
	v_or_b32_e32 v157, 0x2000, v152
	v_or_b32_e32 v158, 0x2800, v152
	v_or_b32_e32 v159, 0x3000, v152
	v_or_b32_e32 v160, 0x3800, v152
	v_lshl_add_u64 v[140:141], v[0:1], 0, v[4:5]
	v_lshl_add_u64 v[142:143], v[0:1], 0, v[6:7]
	v_lshl_add_u64 v[144:145], v[0:1], 0, v[8:9]
	v_lshl_add_u64 v[146:147], v[0:1], 0, v[10:11]
	s_mov_b64 s[18:19], 0
	s_mov_b32 s15, 0
	s_cmp_lg_u32 s101, 0
	s_cbranch_scc1 .Lnxw_942
	s_waitcnt vmcnt(0)

.Lg2b_942:
	s_waitcnt lgkmcnt(3)
	v_mfma_f32_16x16x32_bf16 v[108:111], v[178:181], v[162:165], v[108:111]
	v_mfma_f32_16x16x32_bf16 v[92:95], v[178:181], v[166:169], v[92:95]
	v_mfma_f32_16x16x32_bf16 v[76:79], v[178:181], v[170:173], v[76:79]
	v_mfma_f32_16x16x32_bf16 v[60:63], v[178:181], v[174:177], v[60:63]
	ds_read_b128 v[240:243], v197 offset:1024
	ds_read_b128 v[244:247], v198 offset:1024
	s_waitcnt lgkmcnt(4)
	v_mfma_f32_16x16x32_bf16 v[104:107], v[182:185], v[162:165], v[104:107]
	v_mfma_f32_16x16x32_bf16 v[88:91], v[182:185], v[166:169], v[88:91]
	v_mfma_f32_16x16x32_bf16 v[72:75], v[182:185], v[170:173], v[72:75]
	v_mfma_f32_16x16x32_bf16 v[56:59], v[182:185], v[174:177], v[56:59]
	ds_read_b128 v[248:251], v199 offset:1024
	ds_read_b128 v[252:255], v200 offset:1024
	s_waitcnt lgkmcnt(5)
	v_mfma_f32_16x16x32_bf16 v[100:103], v[186:189], v[162:165], v[100:103]
	v_mfma_f32_16x16x32_bf16 v[84:87], v[186:189], v[166:169], v[84:87]
	v_mfma_f32_16x16x32_bf16 v[68:71], v[186:189], v[170:173], v[68:71]
	v_mfma_f32_16x16x32_bf16 v[52:55], v[186:189], v[174:177], v[52:55]
	s_waitcnt lgkmcnt(4)
	v_mfma_f32_16x16x32_bf16 v[96:99], v[190:193], v[162:165], v[96:99]
	v_mfma_f32_16x16x32_bf16 v[80:83], v[190:193], v[166:169], v[80:83]
	v_mfma_f32_16x16x32_bf16 v[64:67], v[190:193], v[170:173], v[64:67]
	v_mfma_f32_16x16x32_bf16 v[48:51], v[190:193], v[174:177], v[48:51]
	s_add_i32 s101, s100, s17
	s_cmpk_eq_i32 s18, 0x700
	s_cbranch_scc1 .Lg4n_942
	s_waitcnt vmcnt(0) lgkmcnt(0)
	s_barrier
	s_add_u32 s98, s98, 0x80
	s_addc_u32 s99, s99, 0
	s_add_u32 vcc_lo, vcc_lo, 0x80
	s_addc_u32 vcc_hi, vcc_hi, 0
	v_mfma_f32_16x16x32_bf16 v[44:47], v[178:181], v[240:243], v[44:47]
	v_mfma_f32_16x16x32_bf16 v[28:31], v[178:181], v[244:247], v[28:31]
	v_mfma_f32_16x16x32_bf16 v[12:15], v[178:181], v[248:251], v[12:15]
	v_mfma_f32_16x16x32_bf16 v[112:115], v[178:181], v[252:255], v[112:115]
	v_add3_u32 v128, s42, v150, v151
	ds_read_b128 v[178:181], v128 offset:32768
	v_add3_u32 v161, s42, v150, v152
	v_add3_u32 v194, s42, v154, v153
	v_add3_u32 v195, s42, v154, v155
	v_add3_u32 v196, s42, v154, v156
	ds_read_b128 v[162:165], v161
	ds_read_b128 v[166:169], v194
	ds_read_b128 v[170:173], v195
	ds_read_b128 v[174:177], v196
	s_mov_b32 m0, s101
	s_nop 0
	global_load_lds_dwordx4 v146, s[98:99]
	v_mfma_f32_16x16x32_bf16 v[40:43], v[182:185], v[240:243], v[40:43]
	v_mfma_f32_16x16x32_bf16 v[24:27], v[182:185], v[244:247], v[24:27]
	v_mfma_f32_16x16x32_bf16 v[8:11], v[182:185], v[248:251], v[8:11]
	v_mfma_f32_16x16x32_bf16 v[116:119], v[182:185], v[252:255], v[116:119]
	ds_read_b128 v[182:185], v128 offset:34816
	v_add3_u32 v197, s42, v154, v157
	v_add3_u32 v198, s42, v154, v158
	v_add3_u32 v199, s42, v154, v159
	v_add3_u32 v200, s42, v154, v160
	s_add_i32 m0, s101, 0x8000
	s_nop 0
	global_load_lds_dwordx4 v138, vcc
	v_mfma_f32_16x16x32_bf16 v[36:39], v[186:189], v[240:243], v[36:39]
	v_mfma_f32_16x16x32_bf16 v[20:23], v[186:189], v[244:247], v[20:23]
	v_mfma_f32_16x16x32_bf16 v[4:7], v[186:189], v[248:251], v[4:7]
	v_mfma_f32_16x16x32_bf16 v[120:123], v[186:189], v[252:255], v[120:123]
	ds_read_b128 v[186:189], v128 offset:36864
	s_add_i32 m0, s101, 0x2000
	s_nop 0
	global_load_lds_dwordx4 v144, s[98:99]
	v_mfma_f32_16x16x32_bf16 v[32:35], v[190:193], v[240:243], v[32:35]
	v_mfma_f32_16x16x32_bf16 v[16:19], v[190:193], v[244:247], v[16:19]
	v_mfma_f32_16x16x32_bf16 v[0:3], v[190:193], v[248:251], v[0:3]
	v_mfma_f32_16x16x32_bf16 v[124:127], v[190:193], v[252:255], v[124:127]
	ds_read_b128 v[190:193], v128 offset:38912
	s_add_i32 m0, s101, 0xa000
	s_nop 0
	global_load_lds_dwordx4 v136, vcc

.Lg1n_942:
	s_waitcnt lgkmcnt(3)
	v_mfma_f32_16x16x32_bf16 v[108:111], v[178:181], v[162:165], 0
	v_mfma_f32_16x16x32_bf16 v[92:95], v[178:181], v[166:169], 0
	v_mfma_f32_16x16x32_bf16 v[76:79], v[178:181], v[170:173], 0
	v_mfma_f32_16x16x32_bf16 v[60:63], v[178:181], v[174:177], 0
	ds_read_b128 v[240:243], v197
	ds_read_b128 v[244:247], v198
	s_waitcnt lgkmcnt(4)
	v_mfma_f32_16x16x32_bf16 v[104:107], v[182:185], v[162:165], 0
	v_mfma_f32_16x16x32_bf16 v[88:91], v[182:185], v[166:169], 0
	v_mfma_f32_16x16x32_bf16 v[72:75], v[182:185], v[170:173], 0
	v_mfma_f32_16x16x32_bf16 v[56:59], v[182:185], v[174:177], 0
	ds_read_b128 v[248:251], v199
	ds_read_b128 v[252:255], v200
	s_waitcnt lgkmcnt(5)
	v_mfma_f32_16x16x32_bf16 v[100:103], v[186:189], v[162:165], 0
	v_mfma_f32_16x16x32_bf16 v[84:87], v[186:189], v[166:169], 0
	v_mfma_f32_16x16x32_bf16 v[68:71], v[186:189], v[170:173], 0
	v_mfma_f32_16x16x32_bf16 v[52:55], v[186:189], v[174:177], 0
	s_waitcnt lgkmcnt(4)
	v_mfma_f32_16x16x32_bf16 v[96:99], v[190:193], v[162:165], 0
	v_mfma_f32_16x16x32_bf16 v[80:83], v[190:193], v[166:169], 0
	v_mfma_f32_16x16x32_bf16 v[64:67], v[190:193], v[170:173], 0
	v_mfma_f32_16x16x32_bf16 v[48:51], v[190:193], v[174:177], 0
	ds_read_b128 v[162:165], v161 offset:1024
	ds_read_b128 v[166:169], v194 offset:1024
	ds_read_b128 v[170:173], v195 offset:1024
	ds_read_b128 v[174:177], v196 offset:1024
	s_waitcnt lgkmcnt(4)
	v_mfma_f32_16x16x32_bf16 v[44:47], v[178:181], v[240:243], 0
	v_mfma_f32_16x16x32_bf16 v[28:31], v[178:181], v[244:247], 0
	v_mfma_f32_16x16x32_bf16 v[12:15], v[178:181], v[248:251], 0
	v_mfma_f32_16x16x32_bf16 v[112:115], v[178:181], v[252:255], 0
	ds_read_b128 v[178:181], v128 offset:33792
	v_mfma_f32_16x16x32_bf16 v[40:43], v[182:185], v[240:243], 0
	v_mfma_f32_16x16x32_bf16 v[24:27], v[182:185], v[244:247], 0
	v_mfma_f32_16x16x32_bf16 v[8:11], v[182:185], v[248:251], 0
	v_mfma_f32_16x16x32_bf16 v[116:119], v[182:185], v[252:255], 0
	ds_read_b128 v[182:185], v128 offset:35840
	v_mfma_f32_16x16x32_bf16 v[36:39], v[186:189], v[240:243], 0
	v_mfma_f32_16x16x32_bf16 v[20:23], v[186:189], v[244:247], 0
	v_mfma_f32_16x16x32_bf16 v[4:7], v[186:189], v[248:251], 0
	v_mfma_f32_16x16x32_bf16 v[120:123], v[186:189], v[252:255], 0
	ds_read_b128 v[186:189], v128 offset:37888
	v_mfma_f32_16x16x32_bf16 v[32:35], v[190:193], v[240:243], 0
	v_mfma_f32_16x16x32_bf16 v[16:19], v[190:193], v[244:247], 0
	v_mfma_f32_16x16x32_bf16 v[0:3], v[190:193], v[248:251], 0
	v_mfma_f32_16x16x32_bf16 v[124:127], v[190:193], v[252:255], 0
	ds_read_b128 v[190:193], v128 offset:39936
	s_branch .Lg2b_942

.Lnxh_1040_0:
	v_and_b32_e32 v4, 48, v18
	v_lshlrev_b32_e32 v5, 6, v26
	v_and_b32_e32 v6, 32, v6
	v_bitop3_b32 v150, v5, v6, v4 bitop3:0x36
	v_lshlrev_b32_e32 v5, 7, v18
	v_and_b32_e32 v151, 0x6000, v5
	v_lshlrev_b32_e32 v5, 6, v18
	v_and_b32_e32 v152, 0xffffc000, v5
	v_and_b32_e32 v5, 0x3c0, v5
	v_bitop3_b32 v154, v5, v6, v4 bitop3:0x36
	v_lshlrev_b32_e32 v4, 10, v25
	v_and_or_b32 v4, v4, s23, v21
	v_lshlrev_b32_e32 v6, 10, v24
	v_or3_b32 v128, v4, v10, v20
	v_and_or_b32 v6, v6, s23, v21
	v_lshlrev_b32_e32 v8, 10, v23
	v_lshlrev_b64 v[4:5], 1, v[128:129]
	v_or3_b32 v128, v6, v10, v20
	v_and_or_b32 v8, v8, s23, v21
	v_lshlrev_b32_e32 v11, 10, v22
	v_lshlrev_b64 v[6:7], 1, v[128:129]
	v_or3_b32 v128, v8, v10, v20
	v_and_or_b32 v11, v11, s23, v21
	v_lshlrev_b64 v[8:9], 1, v[128:129]
	v_or3_b32 v128, v11, v10, v20
	s_nop 0
	v_lshl_add_u64 v[0:1], v[0:1], 0, s[8:9]
	v_lshlrev_b64 v[10:11], 1, v[128:129]
	v_lshl_add_u64 v[130:131], v[0:1], 0, v[4:5]
	v_lshl_add_u64 v[134:135], v[0:1], 0, v[6:7]
	v_lshl_add_u64 v[136:137], v[0:1], 0, v[8:9]
	v_lshl_add_u64 v[138:139], v[0:1], 0, v[10:11]
	v_lshl_add_u64 v[0:1], v[2:3], 0, s[10:11]
	v_or_b32_e32 v153, 0x800, v152
	v_or_b32_e32 v155, 0x1000, v152
	v_or_b32_e32 v156, 0x1800, v152
	v_or_b32_e32 v157, 0x2000, v152
	v_or_b32_e32 v158, 0x2800, v152
	v_or_b32_e32 v159, 0x3000, v152
	v_or_b32_e32 v160, 0x3800, v152
	v_lshl_add_u64 v[140:141], v[0:1], 0, v[4:5]
	v_lshl_add_u64 v[142:143], v[0:1], 0, v[6:7]
	v_lshl_add_u64 v[144:145], v[0:1], 0, v[8:9]
	v_lshl_add_u64 v[146:147], v[0:1], 0, v[10:11]
	s_mov_b64 s[18:19], 0
	s_mov_b32 s15, 0
	s_cmp_lg_u32 s101, 0
	s_cbranch_scc1 .Lnxw_1040
	s_waitcnt vmcnt(0)

.Lg2b_1040:
	s_waitcnt lgkmcnt(3)
	v_mfma_f32_16x16x32_bf16 v[108:111], v[178:181], v[162:165], v[108:111]
	v_mfma_f32_16x16x32_bf16 v[92:95], v[178:181], v[166:169], v[92:95]
	v_mfma_f32_16x16x32_bf16 v[76:79], v[178:181], v[170:173], v[76:79]
	v_mfma_f32_16x16x32_bf16 v[60:63], v[178:181], v[174:177], v[60:63]
	ds_read_b128 v[240:243], v197 offset:1024
	ds_read_b128 v[244:247], v198 offset:1024
	s_waitcnt lgkmcnt(4)
	v_mfma_f32_16x16x32_bf16 v[104:107], v[182:185], v[162:165], v[104:107]
	v_mfma_f32_16x16x32_bf16 v[88:91], v[182:185], v[166:169], v[88:91]
	v_mfma_f32_16x16x32_bf16 v[72:75], v[182:185], v[170:173], v[72:75]
	v_mfma_f32_16x16x32_bf16 v[56:59], v[182:185], v[174:177], v[56:59]
	ds_read_b128 v[248:251], v199 offset:1024
	ds_read_b128 v[252:255], v200 offset:1024
	s_waitcnt lgkmcnt(5)
	v_mfma_f32_16x16x32_bf16 v[100:103], v[186:189], v[162:165], v[100:103]
	v_mfma_f32_16x16x32_bf16 v[84:87], v[186:189], v[166:169], v[84:87]
	v_mfma_f32_16x16x32_bf16 v[68:71], v[186:189], v[170:173], v[68:71]
	v_mfma_f32_16x16x32_bf16 v[52:55], v[186:189], v[174:177], v[52:55]
	s_waitcnt lgkmcnt(4)
	v_mfma_f32_16x16x32_bf16 v[96:99], v[190:193], v[162:165], v[96:99]
	v_mfma_f32_16x16x32_bf16 v[80:83], v[190:193], v[166:169], v[80:83]
	v_mfma_f32_16x16x32_bf16 v[64:67], v[190:193], v[170:173], v[64:67]
	v_mfma_f32_16x16x32_bf16 v[48:51], v[190:193], v[174:177], v[48:51]
	s_add_i32 s101, s100, s17
	s_cmpk_eq_i32 s18, 0x700
	s_cbranch_scc1 .Lg4n_1040
	s_waitcnt vmcnt(0) lgkmcnt(0)
	s_barrier
	s_add_u32 s98, s98, 0x80
	s_addc_u32 s99, s99, 0
	s_add_u32 vcc_lo, vcc_lo, 0x80
	s_addc_u32 vcc_hi, vcc_hi, 0
	v_mfma_f32_16x16x32_bf16 v[44:47], v[178:181], v[240:243], v[44:47]
	v_mfma_f32_16x16x32_bf16 v[28:31], v[178:181], v[244:247], v[28:31]
	v_mfma_f32_16x16x32_bf16 v[12:15], v[178:181], v[248:251], v[12:15]
	v_mfma_f32_16x16x32_bf16 v[112:115], v[178:181], v[252:255], v[112:115]
	v_add3_u32 v128, s43, v150, v151
	ds_read_b128 v[178:181], v128 offset:32768
	v_add3_u32 v161, s43, v150, v152
	v_add3_u32 v194, s43, v154, v153
	v_add3_u32 v195, s43, v154, v155
	v_add3_u32 v196, s43, v154, v156
	ds_read_b128 v[162:165], v161
	ds_read_b128 v[166:169], v194
	ds_read_b128 v[170:173], v195
	ds_read_b128 v[174:177], v196
	s_mov_b32 m0, s101
	s_nop 0
	global_load_lds_dwordx4 v146, s[98:99]
	v_mfma_f32_16x16x32_bf16 v[40:43], v[182:185], v[240:243], v[40:43]
	v_mfma_f32_16x16x32_bf16 v[24:27], v[182:185], v[244:247], v[24:27]
	v_mfma_f32_16x16x32_bf16 v[8:11], v[182:185], v[248:251], v[8:11]
	v_mfma_f32_16x16x32_bf16 v[116:119], v[182:185], v[252:255], v[116:119]
	ds_read_b128 v[182:185], v128 offset:34816
	v_add3_u32 v197, s43, v154, v157
	v_add3_u32 v198, s43, v154, v158
	v_add3_u32 v199, s43, v154, v159
	v_add3_u32 v200, s43, v154, v160
	s_add_i32 m0, s101, 0x8000
	s_nop 0
	global_load_lds_dwordx4 v138, vcc
	v_mfma_f32_16x16x32_bf16 v[36:39], v[186:189], v[240:243], v[36:39]
	v_mfma_f32_16x16x32_bf16 v[20:23], v[186:189], v[244:247], v[20:23]
	v_mfma_f32_16x16x32_bf16 v[4:7], v[186:189], v[248:251], v[4:7]
	v_mfma_f32_16x16x32_bf16 v[120:123], v[186:189], v[252:255], v[120:123]
	ds_read_b128 v[186:189], v128 offset:36864
	s_add_i32 m0, s101, 0x2000
	s_nop 0
	global_load_lds_dwordx4 v144, s[98:99]
	v_mfma_f32_16x16x32_bf16 v[32:35], v[190:193], v[240:243], v[32:35]
	v_mfma_f32_16x16x32_bf16 v[16:19], v[190:193], v[244:247], v[16:19]
	v_mfma_f32_16x16x32_bf16 v[0:3], v[190:193], v[248:251], v[0:3]
	v_mfma_f32_16x16x32_bf16 v[124:127], v[190:193], v[252:255], v[124:127]
	ds_read_b128 v[190:193], v128 offset:38912
	s_add_i32 m0, s101, 0xa000
	s_nop 0
	global_load_lds_dwordx4 v136, vcc

.LBB0_1137:
	s_ashr_i32 s10, s23, 31
	s_lshr_b32 s10, s10, 26
	s_add_i32 s10, s23, s10
	s_ashr_i32 s11, s10, 6
	s_and_b32 s10, s10, 0xffc0
	s_sub_i32 s10, s23, s10
	s_bfe_i32 s12, s10, 0x80000
	s_bfe_u32 s12, s12, 0x4000b
	v_mov_b32_e32 v148, v132
	v_mov_b32_e32 v18, v132
	s_add_i32 s12, s10, s12
	ds_read_b64 v[0:1], v133
	s_lshl_b32 s25, s11, 4
	v_lshlrev_b32_e32 v9, 4, v18
	v_and_b32_e32 v8, 32, v18
	s_and_b32 s11, s12, 0xf0
	v_bfe_u32 v19, v18, 2, 4
	v_lshrrev_b32_e32 v10, 1, v18
	v_bitop3_b32 v8, v9, v8, 48 bitop3:0x6c
	v_ashrrev_i32_e32 v22, 3, v18
	s_sub_i32 s10, s10, s11
	v_and_b32_e32 v20, 32, v10
	v_lshrrev_b32_e32 v21, 1, v8
	v_and_or_b32 v8, v22, s14, v19
	s_bfe_i32 s13, s12, 0x80000
	s_sext_i32_i8 s10, s10
	v_or_b32_e32 v12, v21, v20
	v_mul_u32_u24_e32 v8, 0xb00, v8
	s_sext_i32_i16 s13, s13
	s_add_i32 s25, s25, s10
	v_and_b32_e32 v11, 0xfffffc00, v9
	v_or_b32_e32 v128, v12, v8
	v_add_u32_e32 v8, 0x2000, v9
	v_add_u32_e32 v10, 0x4000, v9
	v_add_u32_e32 v9, 0x6000, v9
	s_ashr_i32 s26, s13, 4
	s_lshl_b32 s24, s25, 8
	v_ashrrev_i32_e32 v23, 7, v8
	v_ashrrev_i32_e32 v24, 7, v10
	v_ashrrev_i32_e32 v25, 7, v9
	s_lshl_b32 s10, s26, 8
	s_mul_i32 s12, s25, 0x160000
	s_mul_hi_i32 s13, s24, 0x1600
	v_and_or_b32 v8, v23, s14, v19
	v_and_or_b32 v10, v24, s14, v19
	v_and_or_b32 v9, v25, s14, v19
	s_waitcnt lgkmcnt(0)
	v_lshl_add_u64 v[2:3], v[0:1], 0, s[12:13]
	s_mul_i32 s12, s26, 0x160000
	s_mul_hi_i32 s13, s10, 0x1600
	v_mul_u32_u24_e32 v8, 0xb00, v8
	v_mul_u32_u24_e32 v10, 0xb00, v10
	v_mul_u32_u24_e32 v9, 0xb00, v9
	v_add_u32_e32 v149, 0, v11
	v_lshl_add_u64 v[4:5], v[2:3], 0, s[0:1]
	v_lshl_add_u64 v[0:1], v[0:1], 0, s[12:13]
	v_or_b32_e32 v8, v8, v12
	v_or_b32_e32 v10, v10, v12
	v_or_b32_e32 v12, v9, v12
	v_add_u32_e32 v9, 0x8000, v149
	v_lshlrev_b64 v[14:15], 1, v[128:129]
	v_readfirstlane_b32 s12, v149
	v_lshl_add_u64 v[6:7], v[0:1], 0, s[4:5]
	v_lshl_add_u64 v[16:17], v[4:5], 0, v[14:15]
	s_mov_b32 m0, s12
	v_readfirstlane_b32 s12, v9
	v_mov_b32_e32 v9, v129
	v_add_u32_e32 v11, 0x2000, v149
	global_load_lds_dwordx4 v[16:17], off
	v_lshl_add_u64 v[14:15], v[6:7], 0, v[14:15]
	s_mov_b32 m0, s12
	v_lshlrev_b64 v[8:9], 1, v[8:9]
	v_readfirstlane_b32 s12, v11
	v_add_u32_e32 v11, 0xa000, v149
	global_load_lds_dwordx4 v[14:15], off
	v_lshl_add_u64 v[14:15], v[4:5], 0, v[8:9]
	s_mov_b32 m0, s12
	v_readfirstlane_b32 s12, v11
	global_load_lds_dwordx4 v[14:15], off
	v_lshl_add_u64 v[8:9], v[6:7], 0, v[8:9]
	s_mov_b32 m0, s12
	v_mov_b32_e32 v11, v129
	v_add_u32_e32 v13, 0x4000, v149
	global_load_lds_dwordx4 v[8:9], off
	v_lshlrev_b64 v[8:9], 1, v[10:11]
	v_readfirstlane_b32 s12, v13
	v_lshl_add_u64 v[10:11], v[4:5], 0, v[8:9]
	s_mov_b32 m0, s12
	v_lshl_add_u64 v[8:9], v[6:7], 0, v[8:9]
	global_load_lds_dwordx4 v[10:11], off
	v_add_u32_e32 v10, 0xc000, v149
	v_mov_b32_e32 v13, v129
	v_readfirstlane_b32 s12, v10
	s_mov_b32 m0, s12
	v_add_u32_e32 v10, 0x6000, v149
	global_load_lds_dwordx4 v[8:9], off
	v_lshlrev_b64 v[8:9], 1, v[12:13]
	v_readfirstlane_b32 s12, v10
	v_lshl_add_u64 v[4:5], v[4:5], 0, v[8:9]
	s_mov_b32 m0, s12
	v_and_b32_e32 v26, 15, v18
	global_load_lds_dwordx4 v[4:5], off
	v_lshl_add_u64 v[4:5], v[6:7], 0, v[8:9]
	v_add_u32_e32 v6, 0xe000, v149
	v_lshrrev_b32_e32 v8, 4, v23
	v_readfirstlane_b32 s12, v6
	s_mov_b32 m0, s12
	v_lshlrev_b32_e32 v6, 2, v18
	global_load_lds_dwordx4 v[4:5], off
	v_and_b32_e32 v4, 48, v18
	v_lshlrev_b32_e32 v5, 6, v26
	v_and_b32_e32 v6, 32, v6
	v_bitop3_b32 v150, v5, v6, v4 bitop3:0x36
	v_lshlrev_b32_e32 v5, 7, v18
	v_and_b32_e32 v151, 0x6000, v5
	v_lshlrev_b32_e32 v5, 6, v18
	v_and_b32_e32 v152, 0xffffc000, v5
	v_and_b32_e32 v5, 0x3c0, v5
	v_bitop3_b32 v154, v5, v6, v4 bitop3:0x36
	v_lshrrev_b32_e32 v4, 4, v25
	v_mul_lo_u32 v4, v4, s16
	v_lshrrev_b32_e32 v6, 4, v24
	v_or_b32_e32 v4, v21, v4
	v_mul_lo_u32 v6, v6, s16
	v_mad_u32_u24 v4, v19, s15, v4
	v_or_b32_e32 v6, v21, v6
	v_mul_lo_u32 v8, v8, s16
	v_lshrrev_b32_e32 v10, 4, v22
	v_or_b32_e32 v128, v4, v20
	v_mad_u32_u24 v6, v19, s15, v6
	v_or_b32_e32 v8, v21, v8
	v_mul_lo_u32 v10, v10, s16
	v_lshlrev_b64 v[4:5], 1, v[128:129]
	v_or_b32_e32 v128, v6, v20
	v_mad_u32_u24 v8, v19, s15, v8
	v_or_b32_e32 v10, v21, v10
	v_lshlrev_b64 v[6:7], 1, v[128:129]
	v_or_b32_e32 v128, v8, v20
	v_mad_u32_u24 v10, v19, s15, v10
	v_lshlrev_b64 v[8:9], 1, v[128:129]
	v_or_b32_e32 v128, v10, v20
	s_nop 0
	v_lshl_add_u64 v[0:1], v[0:1], 0, s[6:7]
	v_lshlrev_b64 v[10:11], 1, v[128:129]
	v_lshl_add_u64 v[130:131], v[0:1], 0, v[4:5]
	v_lshl_add_u64 v[134:135], v[0:1], 0, v[6:7]
	v_lshl_add_u64 v[136:137], v[0:1], 0, v[8:9]
	v_lshl_add_u64 v[138:139], v[0:1], 0, v[10:11]
	v_lshl_add_u64 v[0:1], v[2:3], 0, s[8:9]
	s_ashr_i32 s11, s10, 31
	v_or_b32_e32 v153, 0x800, v152
	v_or_b32_e32 v155, 0x1000, v152
	v_or_b32_e32 v156, 0x1800, v152
	v_or_b32_e32 v157, 0x2000, v152
	v_or_b32_e32 v158, 0x2800, v152
	v_or_b32_e32 v159, 0x3000, v152
	v_or_b32_e32 v160, 0x3800, v152
	v_lshl_add_u64 v[140:141], v[0:1], 0, v[4:5]
	v_lshl_add_u64 v[142:143], v[0:1], 0, v[6:7]
	v_lshl_add_u64 v[144:145], v[0:1], 0, v[8:9]
	v_lshl_add_u64 v[146:147], v[0:1], 0, v[10:11]
	s_mov_b64 s[12:13], 0
	s_mov_b32 s26, 0
	s_waitcnt vmcnt(0) lgkmcnt(0)
	s_barrier
	v_readfirstlane_b32 s100, v149
	s_and_b32 s27, s26, 0x10000
	s_xor_b32 s28, s27, 0x10000
	s_add_i32 s27, s27, 0
	v_add3_u32 v128, s27, v150, v151
	v_add3_u32 v161, s27, v150, v152
	v_add3_u32 v194, s27, v154, v153
	v_add3_u32 v195, s27, v154, v155
	v_add3_u32 v196, s27, v154, v156
	v_add3_u32 v197, s27, v154, v157
	v_add3_u32 v198, s27, v154, v158
	v_add3_u32 v199, s27, v154, v159
	v_add3_u32 v200, s27, v154, v160
	ds_read_b128 v[178:181], v128 offset:32768
	ds_read_b128 v[162:165], v161
	ds_read_b128 v[166:169], v194
	ds_read_b128 v[170:173], v195
	ds_read_b128 v[174:177], v196
	ds_read_b128 v[182:185], v128 offset:34816
	ds_read_b128 v[186:189], v128 offset:36864
	ds_read_b128 v[190:193], v128 offset:38912
	s_add_i32 s101, s100, s28
	v_readfirstlane_b32 s98, v146
	v_readfirstlane_b32 s99, v147
	v_readfirstlane_b32 vcc_lo, v138
	v_readfirstlane_b32 vcc_hi, v139
	s_sub_u32 s98, s98, 0x1000000
	s_subb_u32 s99, s99, 0
	s_sub_u32 vcc_lo, vcc_lo, 0x1000000
	s_subb_u32 vcc_hi, vcc_hi, 0
	v_subrev_u32_e32 v146, s98, v146
	v_subrev_u32_e32 v138, vcc_lo, v138
	v_subrev_u32_e32 v144, s98, v144
	v_subrev_u32_e32 v136, vcc_lo, v136
	v_subrev_u32_e32 v142, s98, v142
	v_subrev_u32_e32 v134, vcc_lo, v134
	v_subrev_u32_e32 v140, s98, v140
	v_subrev_u32_e32 v130, vcc_lo, v130
	s_mov_b32 m0, s101
	s_nop 0
	global_load_lds_dwordx4 v146, s[98:99]
	s_add_i32 m0, s101, 0x8000
	s_nop 0
	global_load_lds_dwordx4 v138, vcc
	s_add_i32 m0, s101, 0x2000
	s_nop 0
	global_load_lds_dwordx4 v144, s[98:99]
	s_add_i32 m0, s101, 0xa000
	s_nop 0
	global_load_lds_dwordx4 v136, vcc
	s_add_i32 m0, s101, 0x4000
	s_nop 0
	global_load_lds_dwordx4 v142, s[98:99]
	s_add_i32 m0, s101, 0xc000
	s_nop 0
	global_load_lds_dwordx4 v134, vcc
	s_add_i32 m0, s101, 0x6000
	s_nop 0
	global_load_lds_dwordx4 v140, s[98:99]
	s_add_i32 m0, s101, 0xe000
	s_nop 0
	global_load_lds_dwordx4 v130, vcc

.Lg2b_1138:
	s_waitcnt lgkmcnt(3)
	v_mfma_f32_16x16x32_bf16 v[124:127], v[178:181], v[162:165], v[124:127]
	v_mfma_f32_16x16x32_bf16 v[108:111], v[178:181], v[166:169], v[108:111]
	v_mfma_f32_16x16x32_bf16 v[92:95], v[178:181], v[170:173], v[92:95]
	v_mfma_f32_16x16x32_bf16 v[76:79], v[178:181], v[174:177], v[76:79]
	ds_read_b128 v[240:243], v197 offset:1024
	ds_read_b128 v[244:247], v198 offset:1024
	s_waitcnt lgkmcnt(4)
	v_mfma_f32_16x16x32_bf16 v[120:123], v[182:185], v[162:165], v[120:123]
	v_mfma_f32_16x16x32_bf16 v[104:107], v[182:185], v[166:169], v[104:107]
	v_mfma_f32_16x16x32_bf16 v[88:91], v[182:185], v[170:173], v[88:91]
	v_mfma_f32_16x16x32_bf16 v[72:75], v[182:185], v[174:177], v[72:75]
	ds_read_b128 v[248:251], v199 offset:1024
	ds_read_b128 v[252:255], v200 offset:1024
	s_waitcnt lgkmcnt(5)
	v_mfma_f32_16x16x32_bf16 v[116:119], v[186:189], v[162:165], v[116:119]
	v_mfma_f32_16x16x32_bf16 v[100:103], v[186:189], v[166:169], v[100:103]
	v_mfma_f32_16x16x32_bf16 v[84:87], v[186:189], v[170:173], v[84:87]
	v_mfma_f32_16x16x32_bf16 v[68:71], v[186:189], v[174:177], v[68:71]
	s_waitcnt lgkmcnt(4)
	v_mfma_f32_16x16x32_bf16 v[112:115], v[190:193], v[162:165], v[112:115]
	v_mfma_f32_16x16x32_bf16 v[96:99], v[190:193], v[166:169], v[96:99]
	v_mfma_f32_16x16x32_bf16 v[80:83], v[190:193], v[170:173], v[80:83]
	v_mfma_f32_16x16x32_bf16 v[64:67], v[190:193], v[174:177], v[64:67]
	s_add_i32 s101, s100, s27
	s_cmpk_eq_i32 s12, 0x1500
	s_cbranch_scc1 .Lg4n_1138
	s_waitcnt vmcnt(0) lgkmcnt(0)
	s_barrier
	s_add_u32 s98, s98, 0x80
	s_addc_u32 s99, s99, 0
	s_add_u32 vcc_lo, vcc_lo, 0x80
	s_addc_u32 vcc_hi, vcc_hi, 0
	v_mfma_f32_16x16x32_bf16 v[60:63], v[178:181], v[240:243], v[60:63]
	v_mfma_f32_16x16x32_bf16 v[44:47], v[178:181], v[244:247], v[44:47]
	v_mfma_f32_16x16x32_bf16 v[16:19], v[178:181], v[248:251], v[16:19]
	v_mfma_f32_16x16x32_bf16 v[36:39], v[178:181], v[252:255], v[36:39]
	v_add3_u32 v128, s28, v150, v151
	ds_read_b128 v[178:181], v128 offset:32768
	v_add3_u32 v161, s28, v150, v152
	v_add3_u32 v194, s28, v154, v153
	v_add3_u32 v195, s28, v154, v155
	v_add3_u32 v196, s28, v154, v156
	ds_read_b128 v[162:165], v161
	ds_read_b128 v[166:169], v194
	ds_read_b128 v[170:173], v195
	ds_read_b128 v[174:177], v196
	s_mov_b32 m0, s101
	s_nop 0
	global_load_lds_dwordx4 v146, s[98:99]
	v_mfma_f32_16x16x32_bf16 v[56:59], v[182:185], v[240:243], v[56:59]
	v_mfma_f32_16x16x32_bf16 v[40:43], v[182:185], v[244:247], v[40:43]
	v_mfma_f32_16x16x32_bf16 v[8:11], v[182:185], v[248:251], v[8:11]
	v_mfma_f32_16x16x32_bf16 v[28:31], v[182:185], v[252:255], v[28:31]
	ds_read_b128 v[182:185], v128 offset:34816
	v_add3_u32 v197, s28, v154, v157
	v_add3_u32 v198, s28, v154, v158
	v_add3_u32 v199, s28, v154, v159
	v_add3_u32 v200, s28, v154, v160
	s_add_i32 m0, s101, 0x8000
	s_nop 0
	global_load_lds_dwordx4 v138, vcc
	v_mfma_f32_16x16x32_bf16 v[52:55], v[186:189], v[240:243], v[52:55]
	v_mfma_f32_16x16x32_bf16 v[32:35], v[186:189], v[244:247], v[32:35]
	v_mfma_f32_16x16x32_bf16 v[4:7], v[186:189], v[248:251], v[4:7]
	v_mfma_f32_16x16x32_bf16 v[20:23], v[186:189], v[252:255], v[20:23]
	ds_read_b128 v[186:189], v128 offset:36864
	s_add_i32 m0, s101, 0x2000
	s_nop 0
	global_load_lds_dwordx4 v144, s[98:99]
	v_mfma_f32_16x16x32_bf16 v[48:51], v[190:193], v[240:243], v[48:51]
	v_mfma_f32_16x16x32_bf16 v[24:27], v[190:193], v[244:247], v[24:27]
	v_mfma_f32_16x16x32_bf16 v[0:3], v[190:193], v[248:251], v[0:3]
	v_mfma_f32_16x16x32_bf16 v[12:15], v[190:193], v[252:255], v[12:15]
	ds_read_b128 v[190:193], v128 offset:38912
	s_add_i32 m0, s101, 0xa000
	s_nop 0
	global_load_lds_dwordx4 v136, vcc
